# v17 + every GEMM unit's first K-loop body peeled with C=0 on the first MFMA of each accumulator tile; the 128-register zero-fill before each unit deleted (all 17 GEMM phases)
# speedup vs baseline: 1.0070x; 1.0070x over previous
; #define PG8_STAGE(bufoff, gbase, voff) do { _Pragma("unroll") for (int _i = 0; _i < 2; ++_i) \
;         __builtin_amdgcn_global_load_lds((const unsigned*)((const char*)(gbase) + (voff)[_i]), (PG8_LAS unsigned*)(lds + (bufoff) + ldsw + _i * 8192), 16, 0, 0); } while (0)
; #define PG8_LDA(dst, b, h) do { _Pragma("unroll") for (int m = 0; m < 4; ++m) _Pragma("unroll") for (int k = 0; k < 2; ++k) dst[m][k] = *(const PG8_LAS bf16x8*)(lds + PG8_SA(b, h) + aoff + m * 2048 + k * 1024); } while (0)
; #define PG8_LDB(dst, b, h) do { _Pragma("unroll") for (int n = 0; n < 2; ++n) _Pragma("unroll") for (int k = 0; k < 2; ++k) dst[n][k] = *(const PG8_LAS bf16x8*)(lds + PG8_SB(b, h) + boff + n * 2048 + k * 1024); } while (0)
; #define PG8_WAIT_V(n) asm volatile("s_waitcnt vmcnt(" #n ")" ::: "memory")
; #define PG8_WAIT_L(n) asm volatile("s_waitcnt lgkmcnt(" #n ")" ::: "memory")
; #define PG8_BAR __builtin_amdgcn_s_barrier()
; #define PG8_SCHED __builtin_amdgcn_sched_barrier(0)
; template <class Epi, class Sched, bool ALIGN_EPI = false, bool SP2 = false>
; __device__ __forceinline__ void gemm_phase(PG8_LAS unsigned char* lds, const Gemm g, const Sched& S, const Epi& E) {
;     ...
;         const bool has_next = S.next(ui + 1, nxt);
;         const char* nA = has_next ? (const char*)g.A + (size_t)nxt.pm * tstepA : cA; const char* nB = has_next ? (const char*)g.Bt + (size_t)nxt.pn * tstepB : cB;
;         for (int t = 0; t < nt; t += 2) {
;             const bool last = (t == nt - 2);
;             const char* a1 = cA + (size_t)(t + 1) * kstep;
;             const char* a2 = last ? nA : cA + (size_t)(t + 2) * kstep; const char* b2 = last ? nB : cB + (size_t)(t + 2) * kstep;
;             const char* a3 = a2 + kstep; const char* b3 = b2 + kstep;
;             if (last && has_next) S.a_ready(nxt);
;             if constexpr (SP2) {
;             PG8_LDB(B0, 0, 0); PG8_LDB(B1, 0, 1); PG8_SCHED; PG8_LDA(At, 0, 0); PG8_STAGE(PG8_SA(1, 1), a1 + hstepA, voffA);
;             PG8_WAIT_V(8); PG8_WAIT_L(0); PG8_BAR; PG8_MMA(0, 0, At, B0); PG8_MMA(0, 1, At, B1); PG8_BAR; PG8_SCHED;
;             PG8_LDA(At, 0, 1); PG8_STAGE(PG8_SB(0, 0), b2, voffB); PG8_STAGE(PG8_SB(0, 1), b2 + hstepB, voffB); PG8_STAGE(PG8_SA(0, 0), a2, voffA);
;             PG8_WAIT_V(8); PG8_WAIT_L(0); PG8_BAR; PG8_MMA(1, 0, At, B0); PG8_MMA(1, 1, At, B1); PG8_BAR; PG8_SCHED;
.LBB0_184:
	s_ashr_i32 s27, s26, 31
	s_lshl_b64 s[28:29], s[26:27], 20
	s_add_u32 s28, s86, s28
	s_addc_u32 s29, s87, s29
	s_and_b64 s[30:31], s[8:9], exec
	s_cselect_b32 s1, s29, s35
	s_cselect_b32 s11, s28, s34
	s_ashr_i32 s25, s24, 31
	s_lshl_b64 s[30:31], s[24:25], 20
	s_add_u32 s30, s64, s30
	s_addc_u32 s31, s65, s31
	s_and_b64 s[38:39], s[8:9], exec
	s_cselect_b32 s25, s31, s37
	s_cselect_b32 s27, s30, s36
	s_add_u32 s34, s34, 0x80080
	s_addc_u32 s35, s35, 0
	s_add_u32 s40, s36, 0x100
	s_addc_u32 s41, s37, 0
	s_mov_b32 s42, -2
	ds_read_b128 v[162:165], v158
	ds_read_b128 v[166:169], v158 offset:1024
	ds_read_b128 v[170:173], v158 offset:2048
	ds_read_b128 v[174:177], v158 offset:3072
	ds_read_b128 v[178:181], v159
	ds_read_b128 v[182:185], v159 offset:1024
	ds_read_b128 v[186:189], v159 offset:2048
	ds_read_b128 v[190:193], v159 offset:3072
	s_add_u32 s36, s34, 0xfff80080
	s_addc_u32 s37, s35, -1
	s_cmp_eq_u32 s42, 28
	s_cselect_b32 s39, s1, s37
	s_cselect_b32 s38, s11, s36
	s_cselect_b32 s37, s25, s41
	s_cselect_b32 s36, s27, s40
	v_lshl_add_u64 v[156:157], s[34:35], 0, v[148:149]
	s_add_i32 m0, s45, 0xc000
	ds_read_b128 v[194:197], v160
	ds_read_b128 v[198:201], v160 offset:1024
	ds_read_b128 v[202:205], v160 offset:2048
	ds_read_b128 v[210:213], v160 offset:3072
	ds_read_b128 v[214:217], v160 offset:4096
	ds_read_b128 v[218:221], v160 offset:5120
	ds_read_b128 v[222:225], v160 offset:6144
	ds_read_b128 v[226:229], v160 offset:7168
	global_load_lds_dwordx4 v[156:157], off
	v_lshl_add_u64 v[156:157], s[34:35], 0, v[150:151]
	s_add_i32 m0, s45, 0xe000
	s_nop 0
	global_load_lds_dwordx4 v[156:157], off
	s_waitcnt vmcnt(8)
	s_waitcnt lgkmcnt(0)
	s_barrier
	s_setprio 1
	s_waitcnt lgkmcnt(0)
	v_mfma_f32_16x16x32_bf16 v[126:129], v[162:165], v[194:197], 0
	v_mfma_f32_16x16x32_bf16 v[122:125], v[170:173], v[194:197], 0
	v_mfma_f32_16x16x32_bf16 v[110:113], v[162:165], v[202:205], 0
	v_mfma_f32_16x16x32_bf16 v[106:109], v[170:173], v[202:205], 0
	v_mfma_f32_16x16x32_bf16 v[94:97], v[162:165], v[214:217], 0
	v_mfma_f32_16x16x32_bf16 v[90:93], v[170:173], v[214:217], 0
	v_mfma_f32_16x16x32_bf16 v[78:81], v[162:165], v[222:225], 0
	v_mfma_f32_16x16x32_bf16 v[74:77], v[170:173], v[222:225], 0
	v_mfma_f32_16x16x32_bf16 v[126:129], v[166:169], v[198:201], v[126:129]
	v_mfma_f32_16x16x32_bf16 v[122:125], v[174:177], v[198:201], v[122:125]
	v_mfma_f32_16x16x32_bf16 v[110:113], v[166:169], v[210:213], v[110:113]
	v_mfma_f32_16x16x32_bf16 v[106:109], v[174:177], v[210:213], v[106:109]
	v_mfma_f32_16x16x32_bf16 v[94:97], v[166:169], v[218:221], v[94:97]
	v_mfma_f32_16x16x32_bf16 v[90:93], v[174:177], v[218:221], v[90:93]
	v_mfma_f32_16x16x32_bf16 v[78:81], v[166:169], v[226:229], v[78:81]
	v_mfma_f32_16x16x32_bf16 v[74:77], v[174:177], v[226:229], v[74:77]
	s_setprio 0
	s_setprio 1
	v_mfma_f32_16x16x32_bf16 v[118:121], v[178:181], v[194:197], 0
	v_mfma_f32_16x16x32_bf16 v[114:117], v[186:189], v[194:197], 0
	v_mfma_f32_16x16x32_bf16 v[102:105], v[178:181], v[202:205], 0
	v_mfma_f32_16x16x32_bf16 v[98:101], v[186:189], v[202:205], 0
	v_mfma_f32_16x16x32_bf16 v[86:89], v[178:181], v[214:217], 0
	v_mfma_f32_16x16x32_bf16 v[82:85], v[186:189], v[214:217], 0
	v_mfma_f32_16x16x32_bf16 v[70:73], v[178:181], v[222:225], 0
	v_mfma_f32_16x16x32_bf16 v[66:69], v[186:189], v[222:225], 0
	v_mfma_f32_16x16x32_bf16 v[118:121], v[182:185], v[198:201], v[118:121]
	v_mfma_f32_16x16x32_bf16 v[114:117], v[190:193], v[198:201], v[114:117]
	v_mfma_f32_16x16x32_bf16 v[102:105], v[182:185], v[210:213], v[102:105]
	v_mfma_f32_16x16x32_bf16 v[98:101], v[190:193], v[210:213], v[98:101]
	v_mfma_f32_16x16x32_bf16 v[86:89], v[182:185], v[218:221], v[86:89]
	v_mfma_f32_16x16x32_bf16 v[82:85], v[190:193], v[218:221], v[82:85]
	v_mfma_f32_16x16x32_bf16 v[70:73], v[182:185], v[226:229], v[70:73]
	v_mfma_f32_16x16x32_bf16 v[66:69], v[190:193], v[226:229], v[66:69]
	s_setprio 0
	s_barrier
	s_add_i32 s43, s56, s44
	v_lshl_add_u64 v[156:157], s[36:37], 0, v[132:133]
	s_mov_b32 m0, s43
	ds_read_b128 v[194:197], v160 offset:16384
	ds_read_b128 v[198:201], v160 offset:17408
	ds_read_b128 v[202:205], v160 offset:18432
	ds_read_b128 v[210:213], v160 offset:19456
	ds_read_b128 v[214:217], v160 offset:20480
	ds_read_b128 v[218:221], v160 offset:21504
	ds_read_b128 v[222:225], v160 offset:22528
	ds_read_b128 v[226:229], v160 offset:23552
	global_load_lds_dwordx4 v[156:157], off
	s_add_i32 m0, s43, 0x2000
	s_add_u32 s62, s36, 0x80000
	v_lshl_add_u64 v[206:207], s[36:37], 0, v[136:137]
	s_addc_u32 s63, s37, 0
	s_add_i32 s43, s57, s44
	global_load_lds_dwordx4 v[206:207], off
	v_lshl_add_u64 v[230:231], s[62:63], 0, v[132:133]
	s_mov_b32 m0, s43
	v_lshl_add_u64 v[232:233], s[38:39], 0, v[134:135]
	global_load_lds_dwordx4 v[230:231], off
	v_lshl_add_u64 v[230:231], s[62:63], 0, v[136:137]
	s_add_i32 m0, s43, 0x2000
	s_nop 0
	global_load_lds_dwordx4 v[230:231], off
	v_lshl_add_u64 v[230:231], s[38:39], 0, v[130:131]
	s_mov_b32 m0, s45
	s_nop 0
	global_load_lds_dwordx4 v[230:231], off
	s_mov_b32 m0, s46
	s_nop 0
	global_load_lds_dwordx4 v[232:233], off
	s_waitcnt vmcnt(8)
	s_waitcnt lgkmcnt(0)
	s_barrier
; #define PG8_STAGE(bufoff, gbase, voff) do { _Pragma("unroll") for (int _i = 0; _i < 2; ++_i) \
;         __builtin_amdgcn_global_load_lds((const unsigned*)((const char*)(gbase) + (voff)[_i]), (PG8_LAS unsigned*)(lds + (bufoff) + ldsw + _i * 8192), 16, 0, 0); } while (0)
; #define PG8_LDA(dst, b, h) do { _Pragma("unroll") for (int m = 0; m < 4; ++m) _Pragma("unroll") for (int k = 0; k < 2; ++k) dst[m][k] = *(const PG8_LAS bf16x8*)(lds + PG8_SA(b, h) + aoff + m * 2048 + k * 1024); } while (0)
; #define PG8_LDB(dst, b, h) do { _Pragma("unroll") for (int n = 0; n < 2; ++n) _Pragma("unroll") for (int k = 0; k < 2; ++k) dst[n][k] = *(const PG8_LAS bf16x8*)(lds + PG8_SB(b, h) + boff + n * 2048 + k * 1024); } while (0)
; #define PG8_MMA(ai, bj, At, Bt) do { __builtin_amdgcn_s_setprio(1); _Pragma("unroll") for (int m = 0; m < 4; ++m) _Pragma("unroll") for (int n = 0; n < 2; ++n) _Pragma("unroll") for (int k = 0; k < 2; ++k) \
;         acc[ai][bj][m][n] = __builtin_amdgcn_mfma_f32_16x16x32_bf16(Bt[n][k], At[m][k], acc[ai][bj][m][n], 0, 0, 0); __builtin_amdgcn_s_setprio(0); } while (0)
; #define PG8_WAIT_V(n) asm volatile("s_waitcnt vmcnt(" #n ")" ::: "memory")
; #define PG8_WAIT_L(n) asm volatile("s_waitcnt lgkmcnt(" #n ")" ::: "memory")
; #define PG8_BAR __builtin_amdgcn_s_barrier()
; #define PG8_SCHED __builtin_amdgcn_sched_barrier(0)
; template <class Epi, class Sched, bool ALIGN_EPI = false, bool SP2 = false>
; __device__ __forceinline__ void gemm_phase(PG8_LAS unsigned char* lds, const Gemm g, const Sched& S, const Epi& E) {
;     ...
;             PG8_WAIT_V(8); PG8_WAIT_L(0); PG8_BAR; PG8_MMA(1, 0, At, B0); PG8_MMA(1, 1, At, B1); PG8_BAR; PG8_SCHED;
;             PG8_LDB(B0, 1, 0); PG8_LDB(B1, 1, 1); PG8_SCHED; PG8_LDA(At, 1, 0); PG8_STAGE(PG8_SA(0, 1), a2 + hstepA, voffA);
;             PG8_WAIT_V(8); PG8_WAIT_L(0); PG8_BAR; PG8_MMA(0, 0, At, B0); PG8_MMA(0, 1, At, B1); PG8_BAR; PG8_SCHED;
	s_setprio 1
	s_waitcnt lgkmcnt(0)
	v_mfma_f32_16x16x32_bf16 v[62:65], v[162:165], v[194:197], 0
	v_mfma_f32_16x16x32_bf16 v[58:61], v[170:173], v[194:197], 0
	v_mfma_f32_16x16x32_bf16 v[46:49], v[162:165], v[202:205], 0
	v_mfma_f32_16x16x32_bf16 v[42:45], v[170:173], v[202:205], 0
	v_mfma_f32_16x16x32_bf16 v[30:33], v[162:165], v[214:217], 0
	v_mfma_f32_16x16x32_bf16 v[26:29], v[170:173], v[214:217], 0
	v_mfma_f32_16x16x32_bf16 v[14:17], v[162:165], v[222:225], 0
	v_mfma_f32_16x16x32_bf16 v[10:13], v[170:173], v[222:225], 0
	v_mfma_f32_16x16x32_bf16 v[62:65], v[166:169], v[198:201], v[62:65]
	v_mfma_f32_16x16x32_bf16 v[58:61], v[174:177], v[198:201], v[58:61]
	v_mfma_f32_16x16x32_bf16 v[46:49], v[166:169], v[210:213], v[46:49]
	v_mfma_f32_16x16x32_bf16 v[42:45], v[174:177], v[210:213], v[42:45]
	v_mfma_f32_16x16x32_bf16 v[30:33], v[166:169], v[218:221], v[30:33]
	v_mfma_f32_16x16x32_bf16 v[26:29], v[174:177], v[218:221], v[26:29]
	v_mfma_f32_16x16x32_bf16 v[14:17], v[166:169], v[226:229], v[14:17]
	v_mfma_f32_16x16x32_bf16 v[10:13], v[174:177], v[226:229], v[10:13]
	s_setprio 0
	s_setprio 1
	v_mfma_f32_16x16x32_bf16 v[54:57], v[178:181], v[194:197], 0
	v_mfma_f32_16x16x32_bf16 v[50:53], v[186:189], v[194:197], 0
	v_mfma_f32_16x16x32_bf16 v[38:41], v[178:181], v[202:205], 0
	v_mfma_f32_16x16x32_bf16 v[34:37], v[186:189], v[202:205], 0
	v_mfma_f32_16x16x32_bf16 v[22:25], v[178:181], v[214:217], 0
	v_mfma_f32_16x16x32_bf16 v[18:21], v[186:189], v[214:217], 0
	v_mfma_f32_16x16x32_bf16 v[6:9], v[178:181], v[222:225], 0
	v_mfma_f32_16x16x32_bf16 v[2:5], v[186:189], v[222:225], 0
	v_mfma_f32_16x16x32_bf16 v[54:57], v[182:185], v[198:201], v[54:57]
	v_mfma_f32_16x16x32_bf16 v[50:53], v[190:193], v[198:201], v[50:53]
	v_mfma_f32_16x16x32_bf16 v[38:41], v[182:185], v[210:213], v[38:41]
	v_mfma_f32_16x16x32_bf16 v[34:37], v[190:193], v[210:213], v[34:37]
	v_mfma_f32_16x16x32_bf16 v[22:25], v[182:185], v[218:221], v[22:25]
	v_mfma_f32_16x16x32_bf16 v[18:21], v[190:193], v[218:221], v[18:21]
	v_mfma_f32_16x16x32_bf16 v[6:9], v[182:185], v[226:229], v[6:9]
	v_mfma_f32_16x16x32_bf16 v[2:5], v[190:193], v[226:229], v[2:5]
	s_setprio 0
	s_barrier
	s_add_i32 s43, 0, 0x18000
	v_add_u32_e32 v138, s43, v143
	s_add_i32 s61, 0, 0x1c000
	ds_read_b128 v[162:165], v138
	ds_read_b128 v[166:169], v138 offset:1024
	ds_read_b128 v[170:173], v138 offset:2048
	ds_read_b128 v[174:177], v138 offset:3072
	v_add_u32_e32 v138, s61, v143
	ds_read_b128 v[178:181], v138
	ds_read_b128 v[182:185], v138 offset:1024
	ds_read_b128 v[186:189], v138 offset:2048
	ds_read_b128 v[190:193], v138 offset:3072
	s_add_u32 s38, s38, 0x80000
	s_addc_u32 s39, s39, 0
	s_mov_b32 m0, s47
	v_lshl_add_u64 v[234:235], s[38:39], 0, v[130:131]
	ds_read_b128 v[194:197], v160 offset:32768
	ds_read_b128 v[198:201], v160 offset:33792
	ds_read_b128 v[202:205], v160 offset:34816
	ds_read_b128 v[210:213], v160 offset:35840
	ds_read_b128 v[214:217], v160 offset:36864
	ds_read_b128 v[218:221], v160 offset:37888
	ds_read_b128 v[222:225], v160 offset:38912
	ds_read_b128 v[226:229], v160 offset:39936
	global_load_lds_dwordx4 v[234:235], off
	v_lshl_add_u64 v[234:235], s[38:39], 0, v[134:135]
	s_mov_b32 m0, s48
	s_nop 0
	global_load_lds_dwordx4 v[234:235], off
	s_waitcnt vmcnt(8)
	s_waitcnt lgkmcnt(0)
	s_barrier
	s_setprio 1
	s_waitcnt lgkmcnt(0)
	v_mfma_f32_16x16x32_bf16 v[126:129], v[162:165], v[194:197], v[126:129]
	v_mfma_f32_16x16x32_bf16 v[122:125], v[170:173], v[194:197], v[122:125]
	v_mfma_f32_16x16x32_bf16 v[110:113], v[162:165], v[202:205], v[110:113]
	v_mfma_f32_16x16x32_bf16 v[106:109], v[170:173], v[202:205], v[106:109]
	v_mfma_f32_16x16x32_bf16 v[94:97], v[162:165], v[214:217], v[94:97]
	v_mfma_f32_16x16x32_bf16 v[90:93], v[170:173], v[214:217], v[90:93]
	v_mfma_f32_16x16x32_bf16 v[78:81], v[162:165], v[222:225], v[78:81]
	v_mfma_f32_16x16x32_bf16 v[74:77], v[170:173], v[222:225], v[74:77]
	v_mfma_f32_16x16x32_bf16 v[126:129], v[166:169], v[198:201], v[126:129]
	v_mfma_f32_16x16x32_bf16 v[122:125], v[174:177], v[198:201], v[122:125]
	v_mfma_f32_16x16x32_bf16 v[110:113], v[166:169], v[210:213], v[110:113]
	v_mfma_f32_16x16x32_bf16 v[106:109], v[174:177], v[210:213], v[106:109]
	v_mfma_f32_16x16x32_bf16 v[94:97], v[166:169], v[218:221], v[94:97]
	v_mfma_f32_16x16x32_bf16 v[90:93], v[174:177], v[218:221], v[90:93]
	v_mfma_f32_16x16x32_bf16 v[78:81], v[166:169], v[226:229], v[78:81]
	v_mfma_f32_16x16x32_bf16 v[74:77], v[174:177], v[226:229], v[74:77]
	s_setprio 0
	s_setprio 1
	v_mfma_f32_16x16x32_bf16 v[118:121], v[178:181], v[194:197], v[118:121]
	v_mfma_f32_16x16x32_bf16 v[114:117], v[186:189], v[194:197], v[114:117]
	v_mfma_f32_16x16x32_bf16 v[102:105], v[178:181], v[202:205], v[102:105]
	v_mfma_f32_16x16x32_bf16 v[98:101], v[186:189], v[202:205], v[98:101]
	v_mfma_f32_16x16x32_bf16 v[86:89], v[178:181], v[214:217], v[86:89]
	v_mfma_f32_16x16x32_bf16 v[82:85], v[186:189], v[214:217], v[82:85]
	v_mfma_f32_16x16x32_bf16 v[70:73], v[178:181], v[222:225], v[70:73]
	v_mfma_f32_16x16x32_bf16 v[66:69], v[186:189], v[222:225], v[66:69]
	v_mfma_f32_16x16x32_bf16 v[118:121], v[182:185], v[198:201], v[118:121]
	v_mfma_f32_16x16x32_bf16 v[114:117], v[190:193], v[198:201], v[114:117]
	v_mfma_f32_16x16x32_bf16 v[102:105], v[182:185], v[210:213], v[102:105]
	v_mfma_f32_16x16x32_bf16 v[98:101], v[190:193], v[210:213], v[98:101]
	v_mfma_f32_16x16x32_bf16 v[86:89], v[182:185], v[218:221], v[86:89]
	v_mfma_f32_16x16x32_bf16 v[82:85], v[190:193], v[218:221], v[82:85]
	v_mfma_f32_16x16x32_bf16 v[70:73], v[182:185], v[226:229], v[70:73]
	v_mfma_f32_16x16x32_bf16 v[66:69], v[190:193], v[226:229], v[66:69]
	s_setprio 0
	s_barrier
; #define PG8_STAGE(bufoff, gbase, voff) do { _Pragma("unroll") for (int _i = 0; _i < 2; ++_i) \
;         __builtin_amdgcn_global_load_lds((const unsigned*)((const char*)(gbase) + (voff)[_i]), (PG8_LAS unsigned*)(lds + (bufoff) + ldsw + _i * 8192), 16, 0, 0); } while (0)
; #define PG8_LDA(dst, b, h) do { _Pragma("unroll") for (int m = 0; m < 4; ++m) _Pragma("unroll") for (int k = 0; k < 2; ++k) dst[m][k] = *(const PG8_LAS bf16x8*)(lds + PG8_SA(b, h) + aoff + m * 2048 + k * 1024); } while (0)
; #define PG8_MMA(ai, bj, At, Bt) do { __builtin_amdgcn_s_setprio(1); _Pragma("unroll") for (int m = 0; m < 4; ++m) _Pragma("unroll") for (int n = 0; n < 2; ++n) _Pragma("unroll") for (int k = 0; k < 2; ++k) \
;         acc[ai][bj][m][n] = __builtin_amdgcn_mfma_f32_16x16x32_bf16(Bt[n][k], At[m][k], acc[ai][bj][m][n], 0, 0, 0); __builtin_amdgcn_s_setprio(0); } while (0)
; #define PG8_WAIT_V(n) asm volatile("s_waitcnt vmcnt(" #n ")" ::: "memory")
; #define PG8_WAIT_L(n) asm volatile("s_waitcnt lgkmcnt(" #n ")" ::: "memory")
; #define PG8_BAR __builtin_amdgcn_s_barrier()
; #define PG8_SCHED __builtin_amdgcn_sched_barrier(0)
; template <class Epi, class Sched, bool ALIGN_EPI = false, bool SP2 = false>
; __device__ __forceinline__ void gemm_phase(PG8_LAS unsigned char* lds, const Gemm g, const Sched& S, const Epi& E) {
;     ...
;         for (int t = 0; t < nt; t += 2) {
;     ...
;             PG8_LDA(At, 1, 1); PG8_STAGE(PG8_SB(1, 0), b3, voffB); PG8_STAGE(PG8_SB(1, 1), b3 + hstepB, voffB); PG8_STAGE(PG8_SA(1, 0), a3, voffA);
;             PG8_WAIT_V(8); PG8_WAIT_L(0); PG8_BAR; PG8_MMA(1, 0, At, B0); PG8_MMA(1, 1, At, B1); PG8_BAR; PG8_SCHED;
	s_add_i32 s38, s43, s44
	v_lshl_add_u64 v[156:157], v[156:157], 0, s[20:21]
	s_mov_b32 m0, s38
	ds_read_b128 v[194:197], v160 offset:49152
	ds_read_b128 v[198:201], v160 offset:50176
	ds_read_b128 v[202:205], v160 offset:51200
	ds_read_b128 v[210:213], v160 offset:52224
	ds_read_b128 v[214:217], v160 offset:53248
	ds_read_b128 v[218:221], v160 offset:54272
	ds_read_b128 v[222:225], v160 offset:55296
	ds_read_b128 v[226:229], v160 offset:56320
	global_load_lds_dwordx4 v[156:157], off
	s_add_i32 m0, s38, 0x2000
	s_add_u32 s36, s36, 0x80080
	v_lshl_add_u64 v[156:157], v[206:207], 0, s[20:21]
	s_addc_u32 s37, s37, 0
	s_add_i32 s38, s61, s44
	global_load_lds_dwordx4 v[156:157], off
	v_lshl_add_u64 v[156:157], s[36:37], 0, v[132:133]
	s_mov_b32 m0, s38
	s_nop 0
	global_load_lds_dwordx4 v[156:157], off
	v_lshl_add_u64 v[156:157], s[36:37], 0, v[136:137]
	s_add_i32 m0, s38, 0x2000
	s_nop 0
	global_load_lds_dwordx4 v[156:157], off
	v_lshl_add_u64 v[156:157], v[230:231], 0, s[20:21]
	s_mov_b32 m0, s52
	s_nop 0
	global_load_lds_dwordx4 v[156:157], off
	v_lshl_add_u64 v[156:157], v[232:233], 0, s[20:21]
	s_mov_b32 m0, s53
	s_nop 0
	global_load_lds_dwordx4 v[156:157], off
	s_waitcnt vmcnt(8)
	s_waitcnt lgkmcnt(0)
	s_barrier
	s_setprio 1
	s_waitcnt lgkmcnt(0)
	v_mfma_f32_16x16x32_bf16 v[62:65], v[162:165], v[194:197], v[62:65]
	v_mfma_f32_16x16x32_bf16 v[58:61], v[170:173], v[194:197], v[58:61]
	v_mfma_f32_16x16x32_bf16 v[46:49], v[162:165], v[202:205], v[46:49]
	v_mfma_f32_16x16x32_bf16 v[42:45], v[170:173], v[202:205], v[42:45]
	v_mfma_f32_16x16x32_bf16 v[30:33], v[162:165], v[214:217], v[30:33]
	v_mfma_f32_16x16x32_bf16 v[26:29], v[170:173], v[214:217], v[26:29]
	v_mfma_f32_16x16x32_bf16 v[14:17], v[162:165], v[222:225], v[14:17]
	v_mfma_f32_16x16x32_bf16 v[10:13], v[170:173], v[222:225], v[10:13]
	v_mfma_f32_16x16x32_bf16 v[62:65], v[166:169], v[198:201], v[62:65]
	v_mfma_f32_16x16x32_bf16 v[58:61], v[174:177], v[198:201], v[58:61]
	v_mfma_f32_16x16x32_bf16 v[46:49], v[166:169], v[210:213], v[46:49]
	v_mfma_f32_16x16x32_bf16 v[42:45], v[174:177], v[210:213], v[42:45]
	v_mfma_f32_16x16x32_bf16 v[30:33], v[166:169], v[218:221], v[30:33]
	v_mfma_f32_16x16x32_bf16 v[26:29], v[174:177], v[218:221], v[26:29]
	v_mfma_f32_16x16x32_bf16 v[14:17], v[166:169], v[226:229], v[14:17]
	v_mfma_f32_16x16x32_bf16 v[10:13], v[174:177], v[226:229], v[10:13]
	s_setprio 0
	s_setprio 1
	v_mfma_f32_16x16x32_bf16 v[54:57], v[178:181], v[194:197], v[54:57]
	v_mfma_f32_16x16x32_bf16 v[50:53], v[186:189], v[194:197], v[50:53]
	v_mfma_f32_16x16x32_bf16 v[38:41], v[178:181], v[202:205], v[38:41]
	v_mfma_f32_16x16x32_bf16 v[34:37], v[186:189], v[202:205], v[34:37]
	v_mfma_f32_16x16x32_bf16 v[22:25], v[178:181], v[214:217], v[22:25]
	v_mfma_f32_16x16x32_bf16 v[18:21], v[186:189], v[214:217], v[18:21]
	v_mfma_f32_16x16x32_bf16 v[6:9], v[178:181], v[222:225], v[6:9]
	v_mfma_f32_16x16x32_bf16 v[2:5], v[186:189], v[222:225], v[2:5]
	v_mfma_f32_16x16x32_bf16 v[54:57], v[182:185], v[198:201], v[54:57]
	v_mfma_f32_16x16x32_bf16 v[50:53], v[190:193], v[198:201], v[50:53]
	v_mfma_f32_16x16x32_bf16 v[38:41], v[182:185], v[210:213], v[38:41]
	v_mfma_f32_16x16x32_bf16 v[34:37], v[190:193], v[210:213], v[34:37]
	v_mfma_f32_16x16x32_bf16 v[22:25], v[182:185], v[218:221], v[22:25]
	v_mfma_f32_16x16x32_bf16 v[18:21], v[190:193], v[218:221], v[18:21]
	v_mfma_f32_16x16x32_bf16 v[6:9], v[182:185], v[226:229], v[6:9]
	v_mfma_f32_16x16x32_bf16 v[2:5], v[190:193], v[226:229], v[2:5]
	s_setprio 0
	s_barrier
	s_add_i32 s42, s42, 2
	s_add_u32 s34, s34, 0x100
	s_addc_u32 s35, s35, 0
	s_add_u32 s40, s40, 0x100
	s_addc_u32 s41, s41, 0
	s_cmp_gt_u32 s42, 29
	s_cbranch_scc1 .Lpeel_exit_2
	.p2align 6

; #define PG8_BAR __builtin_amdgcn_s_barrier()
; template <class Epi, class Sched, bool ALIGN_EPI = false, bool SP2 = false>
; __device__ __forceinline__ void gemm_phase(PG8_LAS unsigned char* lds, const Gemm g, const Sched& S, const Epi& E) {
;     ...
;         if constexpr (ALIGN_EPI) { if (wr == 0) PG8_BAR; }
.Lpeel_exit_2:
	s_and_b64 vcc, exec, s[22:23]
	s_cbranch_vccz .LBB0_188
	s_barrier

; #define PG8_STAGE(bufoff, gbase, voff) do { _Pragma("unroll") for (int _i = 0; _i < 2; ++_i) \
;         __builtin_amdgcn_global_load_lds((const unsigned*)((const char*)(gbase) + (voff)[_i]), (PG8_LAS unsigned*)(lds + (bufoff) + ldsw + _i * 8192), 16, 0, 0); } while (0)
; #define PG8_LDA(dst, b, h) do { _Pragma("unroll") for (int m = 0; m < 4; ++m) _Pragma("unroll") for (int k = 0; k < 2; ++k) dst[m][k] = *(const PG8_LAS bf16x8*)(lds + PG8_SA(b, h) + aoff + m * 2048 + k * 1024); } while (0)
; #define PG8_LDB(dst, b, h) do { _Pragma("unroll") for (int n = 0; n < 2; ++n) _Pragma("unroll") for (int k = 0; k < 2; ++k) dst[n][k] = *(const PG8_LAS bf16x8*)(lds + PG8_SB(b, h) + boff + n * 2048 + k * 1024); } while (0)
; #define PG8_WAIT_V(n) asm volatile("s_waitcnt vmcnt(" #n ")" ::: "memory")
; #define PG8_WAIT_L(n) asm volatile("s_waitcnt lgkmcnt(" #n ")" ::: "memory")
; #define PG8_BAR __builtin_amdgcn_s_barrier()
; #define PG8_SCHED __builtin_amdgcn_sched_barrier(0)
; template <class Epi, class Sched, bool ALIGN_EPI = false, bool SP2 = false>
; __device__ __forceinline__ void gemm_phase(PG8_LAS unsigned char* lds, const Gemm g, const Sched& S, const Epi& E) {
;     ...
;         const bool has_next = S.next(ui + 1, nxt);
;         const char* nA = has_next ? (const char*)g.A + (size_t)nxt.pm * tstepA : cA; const char* nB = has_next ? (const char*)g.Bt + (size_t)nxt.pn * tstepB : cB;
;         for (int t = 0; t < nt; t += 2) {
;             const bool last = (t == nt - 2);
;             const char* a1 = cA + (size_t)(t + 1) * kstep;
;             const char* a2 = last ? nA : cA + (size_t)(t + 2) * kstep; const char* b2 = last ? nB : cB + (size_t)(t + 2) * kstep;
;             const char* a3 = a2 + kstep; const char* b3 = b2 + kstep;
;             if (last && has_next) S.a_ready(nxt);
;             if constexpr (SP2) {
;             PG8_LDB(B0, 0, 0); PG8_LDB(B1, 0, 1); PG8_SCHED; PG8_LDA(At, 0, 0); PG8_STAGE(PG8_SA(1, 1), a1 + hstepA, voffA);
;             PG8_WAIT_V(8); PG8_WAIT_L(0); PG8_BAR; PG8_MMA(0, 0, At, B0); PG8_MMA(0, 1, At, B1); PG8_BAR; PG8_SCHED;
;             PG8_LDA(At, 0, 1); PG8_STAGE(PG8_SB(0, 0), b2, voffB); PG8_STAGE(PG8_SB(0, 1), b2 + hstepB, voffB); PG8_STAGE(PG8_SA(0, 0), a2, voffA);
;             PG8_WAIT_V(8); PG8_WAIT_L(0); PG8_BAR; PG8_MMA(1, 0, At, B0); PG8_MMA(1, 1, At, B1); PG8_BAR; PG8_SCHED;
.LBB0_801:
	s_ashr_i32 s31, s30, 31
	s_lshl_b64 s[34:35], s[30:31], 20
	s_add_u32 s34, s6, s34
	s_addc_u32 s35, s7, s35
	s_and_b64 s[36:37], s[4:5], exec
	s_cselect_b32 s31, s35, s39
	s_cselect_b32 s61, s34, s38
	s_ashr_i32 s29, s28, 31
	s_lshl_b64 s[36:37], s[28:29], 20
	s_add_u32 s36, s88, s36
	s_addc_u32 s37, s89, s37
	s_and_b64 s[42:43], s[4:5], exec
	s_cselect_b32 s29, s37, s41
	s_cselect_b32 s62, s36, s40
	s_add_u32 s38, s38, 0x80080
	s_addc_u32 s39, s39, 0
	s_add_u32 s63, s40, 0x100
	s_addc_u32 s64, s41, 0
	s_mov_b32 s65, -2
	ds_read_b128 v[152:155], v148
	ds_read_b128 v[156:159], v148 offset:1024
	ds_read_b128 v[160:163], v148 offset:2048
	ds_read_b128 v[164:167], v148 offset:3072
	ds_read_b128 v[168:171], v149
	ds_read_b128 v[172:175], v149 offset:1024
	ds_read_b128 v[176:179], v149 offset:2048
	ds_read_b128 v[180:183], v149 offset:3072
	s_add_u32 s40, s38, 0xfff80080
	s_addc_u32 s41, s39, -1
	s_cmp_eq_u32 s65, 28
	s_cselect_b32 s43, s31, s41
	s_cselect_b32 s42, s61, s40
	s_cselect_b32 s41, s29, s64
	s_cselect_b32 s40, s62, s63
	v_lshl_add_u64 v[218:219], s[38:39], 0, v[138:139]
	s_add_i32 m0, s27, 0xc000
	ds_read_b128 v[184:187], v150
	ds_read_b128 v[188:191], v150 offset:1024
	ds_read_b128 v[192:195], v150 offset:2048
	ds_read_b128 v[196:199], v150 offset:3072
	ds_read_b128 v[200:203], v150 offset:4096
	ds_read_b128 v[204:207], v150 offset:5120
	ds_read_b128 v[210:213], v150 offset:6144
	ds_read_b128 v[214:217], v150 offset:7168
	global_load_lds_dwordx4 v[218:219], off
	v_lshl_add_u64 v[218:219], s[38:39], 0, v[140:141]
	s_add_i32 m0, s27, 0xe000
	s_nop 0
	global_load_lds_dwordx4 v[218:219], off
	s_waitcnt vmcnt(8)
	s_waitcnt lgkmcnt(0)
	s_barrier
	s_setprio 1
	s_waitcnt lgkmcnt(0)
	v_mfma_f32_16x16x32_bf16 v[126:129], v[152:155], v[184:187], 0
	v_mfma_f32_16x16x32_bf16 v[122:125], v[160:163], v[184:187], 0
	v_mfma_f32_16x16x32_bf16 v[118:121], v[152:155], v[192:195], 0
	v_mfma_f32_16x16x32_bf16 v[114:117], v[160:163], v[192:195], 0
	v_mfma_f32_16x16x32_bf16 v[102:105], v[152:155], v[200:203], 0
	v_mfma_f32_16x16x32_bf16 v[98:101], v[160:163], v[200:203], 0
	v_mfma_f32_16x16x32_bf16 v[86:89], v[152:155], v[210:213], 0
	v_mfma_f32_16x16x32_bf16 v[82:85], v[160:163], v[210:213], 0
	v_mfma_f32_16x16x32_bf16 v[126:129], v[156:159], v[188:191], v[126:129]
	v_mfma_f32_16x16x32_bf16 v[122:125], v[164:167], v[188:191], v[122:125]
	v_mfma_f32_16x16x32_bf16 v[118:121], v[156:159], v[196:199], v[118:121]
	v_mfma_f32_16x16x32_bf16 v[114:117], v[164:167], v[196:199], v[114:117]
	v_mfma_f32_16x16x32_bf16 v[102:105], v[156:159], v[204:207], v[102:105]
	v_mfma_f32_16x16x32_bf16 v[98:101], v[164:167], v[204:207], v[98:101]
	v_mfma_f32_16x16x32_bf16 v[86:89], v[156:159], v[214:217], v[86:89]
	v_mfma_f32_16x16x32_bf16 v[82:85], v[164:167], v[214:217], v[82:85]
	s_setprio 0
	s_setprio 1
	v_mfma_f32_16x16x32_bf16 v[110:113], v[168:171], v[184:187], 0
	v_mfma_f32_16x16x32_bf16 v[106:109], v[176:179], v[184:187], 0
	v_mfma_f32_16x16x32_bf16 v[94:97], v[168:171], v[192:195], 0
	v_mfma_f32_16x16x32_bf16 v[90:93], v[176:179], v[192:195], 0
	v_mfma_f32_16x16x32_bf16 v[78:81], v[168:171], v[200:203], 0
	v_mfma_f32_16x16x32_bf16 v[74:77], v[176:179], v[200:203], 0
	v_mfma_f32_16x16x32_bf16 v[70:73], v[168:171], v[210:213], 0
	v_mfma_f32_16x16x32_bf16 v[66:69], v[176:179], v[210:213], 0
	v_mfma_f32_16x16x32_bf16 v[110:113], v[172:175], v[188:191], v[110:113]
	v_mfma_f32_16x16x32_bf16 v[106:109], v[180:183], v[188:191], v[106:109]
	v_mfma_f32_16x16x32_bf16 v[94:97], v[172:175], v[196:199], v[94:97]
	v_mfma_f32_16x16x32_bf16 v[90:93], v[180:183], v[196:199], v[90:93]
	v_mfma_f32_16x16x32_bf16 v[78:81], v[172:175], v[204:207], v[78:81]
	v_mfma_f32_16x16x32_bf16 v[74:77], v[180:183], v[204:207], v[74:77]
	v_mfma_f32_16x16x32_bf16 v[70:73], v[172:175], v[214:217], v[70:73]
	v_mfma_f32_16x16x32_bf16 v[66:69], v[180:183], v[214:217], v[66:69]
	s_setprio 0
	s_barrier
	s_add_i32 s66, s54, s44
	v_lshl_add_u64 v[218:219], s[40:41], 0, v[134:135]
	s_mov_b32 m0, s66
	ds_read_b128 v[184:187], v150 offset:16384
	ds_read_b128 v[188:191], v150 offset:17408
	ds_read_b128 v[192:195], v150 offset:18432
	ds_read_b128 v[196:199], v150 offset:19456
	ds_read_b128 v[200:203], v150 offset:20480
	ds_read_b128 v[204:207], v150 offset:21504
	ds_read_b128 v[210:213], v150 offset:22528
	ds_read_b128 v[214:217], v150 offset:23552
	global_load_lds_dwordx4 v[218:219], off
	s_add_i32 m0, s66, 0x2000
	s_add_u32 s66, s40, 0x80000
	v_lshl_add_u64 v[220:221], s[40:41], 0, v[130:131]
	s_addc_u32 s67, s41, 0
	s_add_i32 s68, s55, s44
	global_load_lds_dwordx4 v[220:221], off
	v_lshl_add_u64 v[222:223], s[66:67], 0, v[134:135]
	s_mov_b32 m0, s68
	v_lshl_add_u64 v[224:225], s[42:43], 0, v[132:133]
	global_load_lds_dwordx4 v[222:223], off
	v_lshl_add_u64 v[222:223], s[66:67], 0, v[130:131]
	s_add_i32 m0, s68, 0x2000
	s_nop 0
	global_load_lds_dwordx4 v[222:223], off
	v_lshl_add_u64 v[222:223], s[42:43], 0, v[136:137]
	s_mov_b32 m0, s27
	s_nop 0
	global_load_lds_dwordx4 v[222:223], off
	s_mov_b32 m0, s47
	s_nop 0
	global_load_lds_dwordx4 v[224:225], off
	s_waitcnt vmcnt(8)
	s_waitcnt lgkmcnt(0)
	s_barrier
; #define PG8_STAGE(bufoff, gbase, voff) do { _Pragma("unroll") for (int _i = 0; _i < 2; ++_i) \
;         __builtin_amdgcn_global_load_lds((const unsigned*)((const char*)(gbase) + (voff)[_i]), (PG8_LAS unsigned*)(lds + (bufoff) + ldsw + _i * 8192), 16, 0, 0); } while (0)
; #define PG8_LDA(dst, b, h) do { _Pragma("unroll") for (int m = 0; m < 4; ++m) _Pragma("unroll") for (int k = 0; k < 2; ++k) dst[m][k] = *(const PG8_LAS bf16x8*)(lds + PG8_SA(b, h) + aoff + m * 2048 + k * 1024); } while (0)
; #define PG8_LDB(dst, b, h) do { _Pragma("unroll") for (int n = 0; n < 2; ++n) _Pragma("unroll") for (int k = 0; k < 2; ++k) dst[n][k] = *(const PG8_LAS bf16x8*)(lds + PG8_SB(b, h) + boff + n * 2048 + k * 1024); } while (0)
; #define PG8_MMA(ai, bj, At, Bt) do { __builtin_amdgcn_s_setprio(1); _Pragma("unroll") for (int m = 0; m < 4; ++m) _Pragma("unroll") for (int n = 0; n < 2; ++n) _Pragma("unroll") for (int k = 0; k < 2; ++k) \
;         acc[ai][bj][m][n] = __builtin_amdgcn_mfma_f32_16x16x32_bf16(Bt[n][k], At[m][k], acc[ai][bj][m][n], 0, 0, 0); __builtin_amdgcn_s_setprio(0); } while (0)
; #define PG8_WAIT_V(n) asm volatile("s_waitcnt vmcnt(" #n ")" ::: "memory")
; #define PG8_WAIT_L(n) asm volatile("s_waitcnt lgkmcnt(" #n ")" ::: "memory")
; #define PG8_BAR __builtin_amdgcn_s_barrier()
; #define PG8_SCHED __builtin_amdgcn_sched_barrier(0)
; template <class Epi, class Sched, bool ALIGN_EPI = false, bool SP2 = false>
; __device__ __forceinline__ void gemm_phase(PG8_LAS unsigned char* lds, const Gemm g, const Sched& S, const Epi& E) {
;     ...
;             PG8_WAIT_V(8); PG8_WAIT_L(0); PG8_BAR; PG8_MMA(1, 0, At, B0); PG8_MMA(1, 1, At, B1); PG8_BAR; PG8_SCHED;
;             PG8_LDB(B0, 1, 0); PG8_LDB(B1, 1, 1); PG8_SCHED; PG8_LDA(At, 1, 0); PG8_STAGE(PG8_SA(0, 1), a2 + hstepA, voffA);
;             PG8_WAIT_V(8); PG8_WAIT_L(0); PG8_BAR; PG8_MMA(0, 0, At, B0); PG8_MMA(0, 1, At, B1); PG8_BAR; PG8_SCHED;
	s_setprio 1
	s_waitcnt lgkmcnt(0)
	v_mfma_f32_16x16x32_bf16 v[62:65], v[152:155], v[184:187], 0
	v_mfma_f32_16x16x32_bf16 v[58:61], v[160:163], v[184:187], 0
	v_mfma_f32_16x16x32_bf16 v[54:57], v[152:155], v[192:195], 0
	v_mfma_f32_16x16x32_bf16 v[50:53], v[160:163], v[192:195], 0
	v_mfma_f32_16x16x32_bf16 v[38:41], v[152:155], v[200:203], 0
	v_mfma_f32_16x16x32_bf16 v[34:37], v[160:163], v[200:203], 0
	v_mfma_f32_16x16x32_bf16 v[22:25], v[152:155], v[210:213], 0
	v_mfma_f32_16x16x32_bf16 v[18:21], v[160:163], v[210:213], 0
	v_mfma_f32_16x16x32_bf16 v[62:65], v[156:159], v[188:191], v[62:65]
	v_mfma_f32_16x16x32_bf16 v[58:61], v[164:167], v[188:191], v[58:61]
	v_mfma_f32_16x16x32_bf16 v[54:57], v[156:159], v[196:199], v[54:57]
	v_mfma_f32_16x16x32_bf16 v[50:53], v[164:167], v[196:199], v[50:53]
	v_mfma_f32_16x16x32_bf16 v[38:41], v[156:159], v[204:207], v[38:41]
	v_mfma_f32_16x16x32_bf16 v[34:37], v[164:167], v[204:207], v[34:37]
	v_mfma_f32_16x16x32_bf16 v[22:25], v[156:159], v[214:217], v[22:25]
	v_mfma_f32_16x16x32_bf16 v[18:21], v[164:167], v[214:217], v[18:21]
	s_setprio 0
	s_setprio 1
	v_mfma_f32_16x16x32_bf16 v[46:49], v[168:171], v[184:187], 0
	v_mfma_f32_16x16x32_bf16 v[42:45], v[176:179], v[184:187], 0
	v_mfma_f32_16x16x32_bf16 v[30:33], v[168:171], v[192:195], 0
	v_mfma_f32_16x16x32_bf16 v[26:29], v[176:179], v[192:195], 0
	v_mfma_f32_16x16x32_bf16 v[14:17], v[168:171], v[200:203], 0
	v_mfma_f32_16x16x32_bf16 v[10:13], v[176:179], v[200:203], 0
	v_mfma_f32_16x16x32_bf16 v[6:9], v[168:171], v[210:213], 0
	v_mfma_f32_16x16x32_bf16 v[2:5], v[176:179], v[210:213], 0
	v_mfma_f32_16x16x32_bf16 v[46:49], v[172:175], v[188:191], v[46:49]
	v_mfma_f32_16x16x32_bf16 v[42:45], v[180:183], v[188:191], v[42:45]
	v_mfma_f32_16x16x32_bf16 v[30:33], v[172:175], v[196:199], v[30:33]
	v_mfma_f32_16x16x32_bf16 v[26:29], v[180:183], v[196:199], v[26:29]
	v_mfma_f32_16x16x32_bf16 v[14:17], v[172:175], v[204:207], v[14:17]
	v_mfma_f32_16x16x32_bf16 v[10:13], v[180:183], v[204:207], v[10:13]
	v_mfma_f32_16x16x32_bf16 v[6:9], v[172:175], v[214:217], v[6:9]
	v_mfma_f32_16x16x32_bf16 v[2:5], v[180:183], v[214:217], v[2:5]
	s_setprio 0
	s_barrier
	s_add_i32 s66, 0, 0x18000
	v_add_u32_e32 v151, s66, v146
	s_add_i32 s67, 0, 0x1c000
	ds_read_b128 v[152:155], v151
	ds_read_b128 v[156:159], v151 offset:1024
	ds_read_b128 v[160:163], v151 offset:2048
	ds_read_b128 v[164:167], v151 offset:3072
	v_add_u32_e32 v151, s67, v146
	ds_read_b128 v[168:171], v151
	ds_read_b128 v[172:175], v151 offset:1024
	ds_read_b128 v[176:179], v151 offset:2048
	ds_read_b128 v[180:183], v151 offset:3072
	s_add_u32 s42, s42, 0x80000
	s_addc_u32 s43, s43, 0
	s_mov_b32 m0, s48
	v_lshl_add_u64 v[226:227], s[42:43], 0, v[136:137]
	ds_read_b128 v[184:187], v150 offset:32768
	ds_read_b128 v[188:191], v150 offset:33792
	ds_read_b128 v[192:195], v150 offset:34816
	ds_read_b128 v[196:199], v150 offset:35840
	ds_read_b128 v[200:203], v150 offset:36864
	ds_read_b128 v[204:207], v150 offset:37888
	ds_read_b128 v[210:213], v150 offset:38912
	ds_read_b128 v[214:217], v150 offset:39936
	global_load_lds_dwordx4 v[226:227], off
	v_lshl_add_u64 v[226:227], s[42:43], 0, v[132:133]
	s_mov_b32 m0, s49
	s_nop 0
	global_load_lds_dwordx4 v[226:227], off
	s_waitcnt vmcnt(8)
	s_waitcnt lgkmcnt(0)
	s_barrier
	s_setprio 1
	s_waitcnt lgkmcnt(0)
	v_mfma_f32_16x16x32_bf16 v[126:129], v[152:155], v[184:187], v[126:129]
	v_mfma_f32_16x16x32_bf16 v[122:125], v[160:163], v[184:187], v[122:125]
	v_mfma_f32_16x16x32_bf16 v[118:121], v[152:155], v[192:195], v[118:121]
	v_mfma_f32_16x16x32_bf16 v[114:117], v[160:163], v[192:195], v[114:117]
	v_mfma_f32_16x16x32_bf16 v[102:105], v[152:155], v[200:203], v[102:105]
	v_mfma_f32_16x16x32_bf16 v[98:101], v[160:163], v[200:203], v[98:101]
	v_mfma_f32_16x16x32_bf16 v[86:89], v[152:155], v[210:213], v[86:89]
	v_mfma_f32_16x16x32_bf16 v[82:85], v[160:163], v[210:213], v[82:85]
	v_mfma_f32_16x16x32_bf16 v[126:129], v[156:159], v[188:191], v[126:129]
	v_mfma_f32_16x16x32_bf16 v[122:125], v[164:167], v[188:191], v[122:125]
	v_mfma_f32_16x16x32_bf16 v[118:121], v[156:159], v[196:199], v[118:121]
	v_mfma_f32_16x16x32_bf16 v[114:117], v[164:167], v[196:199], v[114:117]
	v_mfma_f32_16x16x32_bf16 v[102:105], v[156:159], v[204:207], v[102:105]
	v_mfma_f32_16x16x32_bf16 v[98:101], v[164:167], v[204:207], v[98:101]
	v_mfma_f32_16x16x32_bf16 v[86:89], v[156:159], v[214:217], v[86:89]
	v_mfma_f32_16x16x32_bf16 v[82:85], v[164:167], v[214:217], v[82:85]
	s_setprio 0
	s_setprio 1
	v_mfma_f32_16x16x32_bf16 v[110:113], v[168:171], v[184:187], v[110:113]
	v_mfma_f32_16x16x32_bf16 v[106:109], v[176:179], v[184:187], v[106:109]
	v_mfma_f32_16x16x32_bf16 v[94:97], v[168:171], v[192:195], v[94:97]
	v_mfma_f32_16x16x32_bf16 v[90:93], v[176:179], v[192:195], v[90:93]
	v_mfma_f32_16x16x32_bf16 v[78:81], v[168:171], v[200:203], v[78:81]
	v_mfma_f32_16x16x32_bf16 v[74:77], v[176:179], v[200:203], v[74:77]
	v_mfma_f32_16x16x32_bf16 v[70:73], v[168:171], v[210:213], v[70:73]
	v_mfma_f32_16x16x32_bf16 v[66:69], v[176:179], v[210:213], v[66:69]
	v_mfma_f32_16x16x32_bf16 v[110:113], v[172:175], v[188:191], v[110:113]
	v_mfma_f32_16x16x32_bf16 v[106:109], v[180:183], v[188:191], v[106:109]
	v_mfma_f32_16x16x32_bf16 v[94:97], v[172:175], v[196:199], v[94:97]
	v_mfma_f32_16x16x32_bf16 v[90:93], v[180:183], v[196:199], v[90:93]
	v_mfma_f32_16x16x32_bf16 v[78:81], v[172:175], v[204:207], v[78:81]
	v_mfma_f32_16x16x32_bf16 v[74:77], v[180:183], v[204:207], v[74:77]
	v_mfma_f32_16x16x32_bf16 v[70:73], v[172:175], v[214:217], v[70:73]
	v_mfma_f32_16x16x32_bf16 v[66:69], v[180:183], v[214:217], v[66:69]
	s_setprio 0
	s_barrier
; #define PG8_STAGE(bufoff, gbase, voff) do { _Pragma("unroll") for (int _i = 0; _i < 2; ++_i) \
;         __builtin_amdgcn_global_load_lds((const unsigned*)((const char*)(gbase) + (voff)[_i]), (PG8_LAS unsigned*)(lds + (bufoff) + ldsw + _i * 8192), 16, 0, 0); } while (0)
; #define PG8_LDA(dst, b, h) do { _Pragma("unroll") for (int m = 0; m < 4; ++m) _Pragma("unroll") for (int k = 0; k < 2; ++k) dst[m][k] = *(const PG8_LAS bf16x8*)(lds + PG8_SA(b, h) + aoff + m * 2048 + k * 1024); } while (0)
; #define PG8_MMA(ai, bj, At, Bt) do { __builtin_amdgcn_s_setprio(1); _Pragma("unroll") for (int m = 0; m < 4; ++m) _Pragma("unroll") for (int n = 0; n < 2; ++n) _Pragma("unroll") for (int k = 0; k < 2; ++k) \
;         acc[ai][bj][m][n] = __builtin_amdgcn_mfma_f32_16x16x32_bf16(Bt[n][k], At[m][k], acc[ai][bj][m][n], 0, 0, 0); __builtin_amdgcn_s_setprio(0); } while (0)
; #define PG8_WAIT_V(n) asm volatile("s_waitcnt vmcnt(" #n ")" ::: "memory")
; #define PG8_WAIT_L(n) asm volatile("s_waitcnt lgkmcnt(" #n ")" ::: "memory")
; #define PG8_BAR __builtin_amdgcn_s_barrier()
; #define PG8_SCHED __builtin_amdgcn_sched_barrier(0)
; template <class Epi, class Sched, bool ALIGN_EPI = false, bool SP2 = false>
; __device__ __forceinline__ void gemm_phase(PG8_LAS unsigned char* lds, const Gemm g, const Sched& S, const Epi& E) {
;     ...
;         for (int t = 0; t < nt; t += 2) {
;     ...
;             PG8_LDA(At, 1, 1); PG8_STAGE(PG8_SB(1, 0), b3, voffB); PG8_STAGE(PG8_SB(1, 1), b3 + hstepB, voffB); PG8_STAGE(PG8_SA(1, 0), a3, voffA);
;             PG8_WAIT_V(8); PG8_WAIT_L(0); PG8_BAR; PG8_MMA(1, 0, At, B0); PG8_MMA(1, 1, At, B1); PG8_BAR; PG8_SCHED;
	s_add_i32 s42, s66, s44
	v_lshl_add_u64 v[218:219], v[218:219], 0, s[10:11]
	s_mov_b32 m0, s42
	ds_read_b128 v[184:187], v150 offset:49152
	ds_read_b128 v[188:191], v150 offset:50176
	ds_read_b128 v[192:195], v150 offset:51200
	ds_read_b128 v[196:199], v150 offset:52224
	ds_read_b128 v[200:203], v150 offset:53248
	ds_read_b128 v[204:207], v150 offset:54272
	ds_read_b128 v[210:213], v150 offset:55296
	ds_read_b128 v[214:217], v150 offset:56320
	global_load_lds_dwordx4 v[218:219], off
	s_add_i32 m0, s42, 0x2000
	s_add_u32 s40, s40, 0x80080
	v_lshl_add_u64 v[218:219], v[220:221], 0, s[10:11]
	s_addc_u32 s41, s41, 0
	s_add_i32 s42, s67, s44
	global_load_lds_dwordx4 v[218:219], off
	v_lshl_add_u64 v[218:219], s[40:41], 0, v[134:135]
	s_mov_b32 m0, s42
	s_nop 0
	global_load_lds_dwordx4 v[218:219], off
	v_lshl_add_u64 v[218:219], s[40:41], 0, v[130:131]
	s_add_i32 m0, s42, 0x2000
	s_nop 0
	global_load_lds_dwordx4 v[218:219], off
	v_lshl_add_u64 v[218:219], v[222:223], 0, s[10:11]
	s_mov_b32 m0, s51
	s_nop 0
	global_load_lds_dwordx4 v[218:219], off
	v_lshl_add_u64 v[218:219], v[224:225], 0, s[10:11]
	s_mov_b32 m0, s52
	s_nop 0
	global_load_lds_dwordx4 v[218:219], off
	s_waitcnt vmcnt(8)
	s_waitcnt lgkmcnt(0)
	s_barrier
	s_setprio 1
	s_waitcnt lgkmcnt(0)
	v_mfma_f32_16x16x32_bf16 v[62:65], v[152:155], v[184:187], v[62:65]
	v_mfma_f32_16x16x32_bf16 v[58:61], v[160:163], v[184:187], v[58:61]
	v_mfma_f32_16x16x32_bf16 v[54:57], v[152:155], v[192:195], v[54:57]
	v_mfma_f32_16x16x32_bf16 v[50:53], v[160:163], v[192:195], v[50:53]
	v_mfma_f32_16x16x32_bf16 v[38:41], v[152:155], v[200:203], v[38:41]
	v_mfma_f32_16x16x32_bf16 v[34:37], v[160:163], v[200:203], v[34:37]
	v_mfma_f32_16x16x32_bf16 v[22:25], v[152:155], v[210:213], v[22:25]
	v_mfma_f32_16x16x32_bf16 v[18:21], v[160:163], v[210:213], v[18:21]
	v_mfma_f32_16x16x32_bf16 v[62:65], v[156:159], v[188:191], v[62:65]
	v_mfma_f32_16x16x32_bf16 v[58:61], v[164:167], v[188:191], v[58:61]
	v_mfma_f32_16x16x32_bf16 v[54:57], v[156:159], v[196:199], v[54:57]
	v_mfma_f32_16x16x32_bf16 v[50:53], v[164:167], v[196:199], v[50:53]
	v_mfma_f32_16x16x32_bf16 v[38:41], v[156:159], v[204:207], v[38:41]
	v_mfma_f32_16x16x32_bf16 v[34:37], v[164:167], v[204:207], v[34:37]
	v_mfma_f32_16x16x32_bf16 v[22:25], v[156:159], v[214:217], v[22:25]
	v_mfma_f32_16x16x32_bf16 v[18:21], v[164:167], v[214:217], v[18:21]
	s_setprio 0
	s_setprio 1
	v_mfma_f32_16x16x32_bf16 v[46:49], v[168:171], v[184:187], v[46:49]
	v_mfma_f32_16x16x32_bf16 v[42:45], v[176:179], v[184:187], v[42:45]
	v_mfma_f32_16x16x32_bf16 v[30:33], v[168:171], v[192:195], v[30:33]
	v_mfma_f32_16x16x32_bf16 v[26:29], v[176:179], v[192:195], v[26:29]
	v_mfma_f32_16x16x32_bf16 v[14:17], v[168:171], v[200:203], v[14:17]
	v_mfma_f32_16x16x32_bf16 v[10:13], v[176:179], v[200:203], v[10:13]
	v_mfma_f32_16x16x32_bf16 v[6:9], v[168:171], v[210:213], v[6:9]
	v_mfma_f32_16x16x32_bf16 v[2:5], v[176:179], v[210:213], v[2:5]
	v_mfma_f32_16x16x32_bf16 v[46:49], v[172:175], v[188:191], v[46:49]
	v_mfma_f32_16x16x32_bf16 v[42:45], v[180:183], v[188:191], v[42:45]
	v_mfma_f32_16x16x32_bf16 v[30:33], v[172:175], v[196:199], v[30:33]
	v_mfma_f32_16x16x32_bf16 v[26:29], v[180:183], v[196:199], v[26:29]
	v_mfma_f32_16x16x32_bf16 v[14:17], v[172:175], v[204:207], v[14:17]
	v_mfma_f32_16x16x32_bf16 v[10:13], v[180:183], v[204:207], v[10:13]
	v_mfma_f32_16x16x32_bf16 v[6:9], v[172:175], v[214:217], v[6:9]
	v_mfma_f32_16x16x32_bf16 v[2:5], v[180:183], v[214:217], v[2:5]
	s_setprio 0
	s_barrier
	s_add_i32 s65, s65, 2
	s_add_u32 s38, s38, 0x100
	s_addc_u32 s39, s39, 0
	s_add_u32 s63, s63, 0x100
	s_addc_u32 s64, s64, 0
	s_cmp_gt_u32 s65, 29
	s_cbranch_scc1 .Lpeel_exit_6
	.p2align 6

; #define PG8_STAGE(bufoff, gbase, voff) do { _Pragma("unroll") for (int _i = 0; _i < 2; ++_i) \
;         __builtin_amdgcn_global_load_lds((const unsigned*)((const char*)(gbase) + (voff)[_i]), (PG8_LAS unsigned*)(lds + (bufoff) + ldsw + _i * 8192), 16, 0, 0); } while (0)
; #define PG8_LDA(dst, b, h) do { _Pragma("unroll") for (int m = 0; m < 4; ++m) _Pragma("unroll") for (int k = 0; k < 2; ++k) dst[m][k] = *(const PG8_LAS bf16x8*)(lds + PG8_SA(b, h) + aoff + m * 2048 + k * 1024); } while (0)
; #define PG8_LDB(dst, b, h) do { _Pragma("unroll") for (int n = 0; n < 2; ++n) _Pragma("unroll") for (int k = 0; k < 2; ++k) dst[n][k] = *(const PG8_LAS bf16x8*)(lds + PG8_SB(b, h) + boff + n * 2048 + k * 1024); } while (0)
; #define PG8_WAIT_V(n) asm volatile("s_waitcnt vmcnt(" #n ")" ::: "memory")
; #define PG8_WAIT_L(n) asm volatile("s_waitcnt lgkmcnt(" #n ")" ::: "memory")
; #define PG8_BAR __builtin_amdgcn_s_barrier()
; #define PG8_SCHED __builtin_amdgcn_sched_barrier(0)
; template <class Epi, class Sched, bool ALIGN_EPI = false, bool SP2 = false>
; __device__ __forceinline__ void gemm_phase(PG8_LAS unsigned char* lds, const Gemm g, const Sched& S, const Epi& E) {
;     ...
;         const bool has_next = S.next(ui + 1, nxt);
;         const char* nA = has_next ? (const char*)g.A + (size_t)nxt.pm * tstepA : cA; const char* nB = has_next ? (const char*)g.Bt + (size_t)nxt.pn * tstepB : cB;
;         for (int t = 0; t < nt; t += 2) {
;             const bool last = (t == nt - 2);
;             const char* a1 = cA + (size_t)(t + 1) * kstep;
;             const char* a2 = last ? nA : cA + (size_t)(t + 2) * kstep; const char* b2 = last ? nB : cB + (size_t)(t + 2) * kstep;
;             const char* a3 = a2 + kstep; const char* b3 = b2 + kstep;
;             if (last && has_next) S.a_ready(nxt);
;             if constexpr (SP2) {
;             PG8_LDB(B0, 0, 0); PG8_LDB(B1, 0, 1); PG8_SCHED; PG8_LDA(At, 0, 0); PG8_STAGE(PG8_SA(1, 1), a1 + hstepA, voffA);
;             PG8_WAIT_V(8); PG8_WAIT_L(0); PG8_BAR; PG8_MMA(0, 0, At, B0); PG8_MMA(0, 1, At, B1); PG8_BAR; PG8_SCHED;
;             PG8_LDA(At, 0, 1); PG8_STAGE(PG8_SB(0, 0), b2, voffB); PG8_STAGE(PG8_SB(0, 1), b2 + hstepB, voffB); PG8_STAGE(PG8_SA(0, 0), a2, voffA);
;             PG8_WAIT_V(8); PG8_WAIT_L(0); PG8_BAR; PG8_MMA(1, 0, At, B0); PG8_MMA(1, 1, At, B1); PG8_BAR; PG8_SCHED;
.LBB0_939:
	s_ashr_i32 s13, s12, 31
	s_lshl_b64 s[14:15], s[12:13], 20
	s_add_u32 s14, s86, s14
	s_addc_u32 s15, s87, s15
	s_and_b64 s[16:17], s[4:5], exec
	s_cselect_b32 s13, s15, s27
	s_cselect_b32 s48, s14, s26
	s_ashr_i32 s11, s10, 31
	s_lshl_b64 s[16:17], s[10:11], 20
	v_readlane_b32 s30, v254, 0
	v_readlane_b32 s31, v254, 1
	s_add_u32 s16, s30, s16
	s_addc_u32 s17, s31, s17
	s_and_b64 s[30:31], s[4:5], exec
	s_cselect_b32 s11, s17, s29
	s_cselect_b32 s49, s16, s28
	s_add_u32 s26, s26, 0x80080
	s_addc_u32 s27, s27, 0
	s_add_u32 s50, s28, 0x100
	s_addc_u32 s51, s29, 0
	s_mov_b32 s52, -2
	ds_read_b128 v[154:157], v150
	ds_read_b128 v[158:161], v150 offset:1024
	ds_read_b128 v[162:165], v150 offset:2048
	ds_read_b128 v[166:169], v150 offset:3072
	ds_read_b128 v[170:173], v151
	ds_read_b128 v[174:177], v151 offset:1024
	ds_read_b128 v[178:181], v151 offset:2048
	ds_read_b128 v[182:185], v151 offset:3072
	s_add_u32 s28, s26, 0xfff80080
	s_addc_u32 s29, s27, -1
	s_cmp_eq_u32 s52, 28
	s_cselect_b32 s31, s13, s29
	s_cselect_b32 s30, s48, s28
	s_cselect_b32 s29, s11, s51
	s_cselect_b32 s28, s49, s50
	v_lshl_add_u64 v[146:147], s[26:27], 0, v[138:139]
	s_add_i32 m0, s25, 0xc000
	ds_read_b128 v[186:189], v152
	ds_read_b128 v[190:193], v152 offset:1024
	ds_read_b128 v[194:197], v152 offset:2048
	ds_read_b128 v[198:201], v152 offset:3072
	ds_read_b128 v[202:205], v152 offset:4096
	ds_read_b128 v[210:213], v152 offset:5120
	ds_read_b128 v[214:217], v152 offset:6144
	ds_read_b128 v[218:221], v152 offset:7168
	global_load_lds_dwordx4 v[146:147], off
	v_lshl_add_u64 v[146:147], s[26:27], 0, v[140:141]
	s_add_i32 m0, s25, 0xe000
	s_nop 0
	global_load_lds_dwordx4 v[146:147], off
	s_waitcnt vmcnt(8)
	s_waitcnt lgkmcnt(0)
	s_barrier
	s_setprio 1
	s_waitcnt lgkmcnt(0)
	v_mfma_f32_16x16x32_bf16 v[126:129], v[154:157], v[186:189], 0
	v_mfma_f32_16x16x32_bf16 v[122:125], v[162:165], v[186:189], 0
	v_mfma_f32_16x16x32_bf16 v[110:113], v[154:157], v[194:197], 0
	v_mfma_f32_16x16x32_bf16 v[106:109], v[162:165], v[194:197], 0
	v_mfma_f32_16x16x32_bf16 v[94:97], v[154:157], v[202:205], 0
	v_mfma_f32_16x16x32_bf16 v[90:93], v[162:165], v[202:205], 0
	v_mfma_f32_16x16x32_bf16 v[78:81], v[154:157], v[214:217], 0
	v_mfma_f32_16x16x32_bf16 v[74:77], v[162:165], v[214:217], 0
	v_mfma_f32_16x16x32_bf16 v[126:129], v[158:161], v[190:193], v[126:129]
	v_mfma_f32_16x16x32_bf16 v[122:125], v[166:169], v[190:193], v[122:125]
	v_mfma_f32_16x16x32_bf16 v[110:113], v[158:161], v[198:201], v[110:113]
	v_mfma_f32_16x16x32_bf16 v[106:109], v[166:169], v[198:201], v[106:109]
	v_mfma_f32_16x16x32_bf16 v[94:97], v[158:161], v[210:213], v[94:97]
	v_mfma_f32_16x16x32_bf16 v[90:93], v[166:169], v[210:213], v[90:93]
	v_mfma_f32_16x16x32_bf16 v[78:81], v[158:161], v[218:221], v[78:81]
	v_mfma_f32_16x16x32_bf16 v[74:77], v[166:169], v[218:221], v[74:77]
	s_setprio 0
	s_setprio 1
	v_mfma_f32_16x16x32_bf16 v[118:121], v[170:173], v[186:189], 0
	v_mfma_f32_16x16x32_bf16 v[114:117], v[178:181], v[186:189], 0
	v_mfma_f32_16x16x32_bf16 v[102:105], v[170:173], v[194:197], 0
	v_mfma_f32_16x16x32_bf16 v[98:101], v[178:181], v[194:197], 0
	v_mfma_f32_16x16x32_bf16 v[86:89], v[170:173], v[202:205], 0
	v_mfma_f32_16x16x32_bf16 v[82:85], v[178:181], v[202:205], 0
	v_mfma_f32_16x16x32_bf16 v[70:73], v[170:173], v[214:217], 0
	v_mfma_f32_16x16x32_bf16 v[66:69], v[178:181], v[214:217], 0
	v_mfma_f32_16x16x32_bf16 v[118:121], v[174:177], v[190:193], v[118:121]
	v_mfma_f32_16x16x32_bf16 v[114:117], v[182:185], v[190:193], v[114:117]
	v_mfma_f32_16x16x32_bf16 v[102:105], v[174:177], v[198:201], v[102:105]
	v_mfma_f32_16x16x32_bf16 v[98:101], v[182:185], v[198:201], v[98:101]
	v_mfma_f32_16x16x32_bf16 v[86:89], v[174:177], v[210:213], v[86:89]
	v_mfma_f32_16x16x32_bf16 v[82:85], v[182:185], v[210:213], v[82:85]
	v_mfma_f32_16x16x32_bf16 v[70:73], v[174:177], v[218:221], v[70:73]
	v_mfma_f32_16x16x32_bf16 v[66:69], v[182:185], v[218:221], v[66:69]
	s_setprio 0
	s_barrier
	s_add_i32 s53, s44, s34
	v_lshl_add_u64 v[146:147], s[28:29], 0, v[134:135]
	s_mov_b32 m0, s53
	ds_read_b128 v[186:189], v152 offset:16384
	ds_read_b128 v[190:193], v152 offset:17408
	ds_read_b128 v[194:197], v152 offset:18432
	ds_read_b128 v[198:201], v152 offset:19456
	ds_read_b128 v[202:205], v152 offset:20480
	ds_read_b128 v[210:213], v152 offset:21504
	ds_read_b128 v[214:217], v152 offset:22528
	ds_read_b128 v[218:221], v152 offset:23552
	global_load_lds_dwordx4 v[146:147], off
	s_add_i32 m0, s53, 0x2000
	s_add_u32 s54, s28, 0x80000
	v_lshl_add_u64 v[206:207], s[28:29], 0, v[130:131]
	s_addc_u32 s55, s29, 0
	s_add_i32 s53, s45, s34
	global_load_lds_dwordx4 v[206:207], off
	v_lshl_add_u64 v[222:223], s[54:55], 0, v[134:135]
	s_mov_b32 m0, s53
	v_lshl_add_u64 v[224:225], s[30:31], 0, v[132:133]
	global_load_lds_dwordx4 v[222:223], off
	v_lshl_add_u64 v[222:223], s[54:55], 0, v[130:131]
	s_add_i32 m0, s53, 0x2000
	s_nop 0
	global_load_lds_dwordx4 v[222:223], off
	v_lshl_add_u64 v[222:223], s[30:31], 0, v[136:137]
	s_mov_b32 m0, s25
	s_nop 0
	global_load_lds_dwordx4 v[222:223], off
	s_mov_b32 m0, s37
	s_nop 0
	global_load_lds_dwordx4 v[224:225], off
	s_waitcnt vmcnt(8)
	s_waitcnt lgkmcnt(0)
	s_barrier
; #define PG8_STAGE(bufoff, gbase, voff) do { _Pragma("unroll") for (int _i = 0; _i < 2; ++_i) \
;         __builtin_amdgcn_global_load_lds((const unsigned*)((const char*)(gbase) + (voff)[_i]), (PG8_LAS unsigned*)(lds + (bufoff) + ldsw + _i * 8192), 16, 0, 0); } while (0)
; #define PG8_LDA(dst, b, h) do { _Pragma("unroll") for (int m = 0; m < 4; ++m) _Pragma("unroll") for (int k = 0; k < 2; ++k) dst[m][k] = *(const PG8_LAS bf16x8*)(lds + PG8_SA(b, h) + aoff + m * 2048 + k * 1024); } while (0)
; #define PG8_LDB(dst, b, h) do { _Pragma("unroll") for (int n = 0; n < 2; ++n) _Pragma("unroll") for (int k = 0; k < 2; ++k) dst[n][k] = *(const PG8_LAS bf16x8*)(lds + PG8_SB(b, h) + boff + n * 2048 + k * 1024); } while (0)
; #define PG8_MMA(ai, bj, At, Bt) do { __builtin_amdgcn_s_setprio(1); _Pragma("unroll") for (int m = 0; m < 4; ++m) _Pragma("unroll") for (int n = 0; n < 2; ++n) _Pragma("unroll") for (int k = 0; k < 2; ++k) \
;         acc[ai][bj][m][n] = __builtin_amdgcn_mfma_f32_16x16x32_bf16(Bt[n][k], At[m][k], acc[ai][bj][m][n], 0, 0, 0); __builtin_amdgcn_s_setprio(0); } while (0)
; #define PG8_WAIT_V(n) asm volatile("s_waitcnt vmcnt(" #n ")" ::: "memory")
; #define PG8_WAIT_L(n) asm volatile("s_waitcnt lgkmcnt(" #n ")" ::: "memory")
; #define PG8_BAR __builtin_amdgcn_s_barrier()
; #define PG8_SCHED __builtin_amdgcn_sched_barrier(0)
; template <class Epi, class Sched, bool ALIGN_EPI = false, bool SP2 = false>
; __device__ __forceinline__ void gemm_phase(PG8_LAS unsigned char* lds, const Gemm g, const Sched& S, const Epi& E) {
;     ...
;             PG8_WAIT_V(8); PG8_WAIT_L(0); PG8_BAR; PG8_MMA(1, 0, At, B0); PG8_MMA(1, 1, At, B1); PG8_BAR; PG8_SCHED;
;             PG8_LDB(B0, 1, 0); PG8_LDB(B1, 1, 1); PG8_SCHED; PG8_LDA(At, 1, 0); PG8_STAGE(PG8_SA(0, 1), a2 + hstepA, voffA);
;             PG8_WAIT_V(8); PG8_WAIT_L(0); PG8_BAR; PG8_MMA(0, 0, At, B0); PG8_MMA(0, 1, At, B1); PG8_BAR; PG8_SCHED;
	s_setprio 1
	s_waitcnt lgkmcnt(0)
	v_mfma_f32_16x16x32_bf16 v[62:65], v[154:157], v[186:189], 0
	v_mfma_f32_16x16x32_bf16 v[58:61], v[162:165], v[186:189], 0
	v_mfma_f32_16x16x32_bf16 v[46:49], v[154:157], v[194:197], 0
	v_mfma_f32_16x16x32_bf16 v[42:45], v[162:165], v[194:197], 0
	v_mfma_f32_16x16x32_bf16 v[30:33], v[154:157], v[202:205], 0
	v_mfma_f32_16x16x32_bf16 v[26:29], v[162:165], v[202:205], 0
	v_mfma_f32_16x16x32_bf16 v[14:17], v[154:157], v[214:217], 0
	v_mfma_f32_16x16x32_bf16 v[10:13], v[162:165], v[214:217], 0
	v_mfma_f32_16x16x32_bf16 v[62:65], v[158:161], v[190:193], v[62:65]
	v_mfma_f32_16x16x32_bf16 v[58:61], v[166:169], v[190:193], v[58:61]
	v_mfma_f32_16x16x32_bf16 v[46:49], v[158:161], v[198:201], v[46:49]
	v_mfma_f32_16x16x32_bf16 v[42:45], v[166:169], v[198:201], v[42:45]
	v_mfma_f32_16x16x32_bf16 v[30:33], v[158:161], v[210:213], v[30:33]
	v_mfma_f32_16x16x32_bf16 v[26:29], v[166:169], v[210:213], v[26:29]
	v_mfma_f32_16x16x32_bf16 v[14:17], v[158:161], v[218:221], v[14:17]
	v_mfma_f32_16x16x32_bf16 v[10:13], v[166:169], v[218:221], v[10:13]
	s_setprio 0
	s_setprio 1
	v_mfma_f32_16x16x32_bf16 v[54:57], v[170:173], v[186:189], 0
	v_mfma_f32_16x16x32_bf16 v[50:53], v[178:181], v[186:189], 0
	v_mfma_f32_16x16x32_bf16 v[38:41], v[170:173], v[194:197], 0
	v_mfma_f32_16x16x32_bf16 v[34:37], v[178:181], v[194:197], 0
	v_mfma_f32_16x16x32_bf16 v[22:25], v[170:173], v[202:205], 0
	v_mfma_f32_16x16x32_bf16 v[18:21], v[178:181], v[202:205], 0
	v_mfma_f32_16x16x32_bf16 v[6:9], v[170:173], v[214:217], 0
	v_mfma_f32_16x16x32_bf16 v[2:5], v[178:181], v[214:217], 0
	v_mfma_f32_16x16x32_bf16 v[54:57], v[174:177], v[190:193], v[54:57]
	v_mfma_f32_16x16x32_bf16 v[50:53], v[182:185], v[190:193], v[50:53]
	v_mfma_f32_16x16x32_bf16 v[38:41], v[174:177], v[198:201], v[38:41]
	v_mfma_f32_16x16x32_bf16 v[34:37], v[182:185], v[198:201], v[34:37]
	v_mfma_f32_16x16x32_bf16 v[22:25], v[174:177], v[210:213], v[22:25]
	v_mfma_f32_16x16x32_bf16 v[18:21], v[182:185], v[210:213], v[18:21]
	v_mfma_f32_16x16x32_bf16 v[6:9], v[174:177], v[218:221], v[6:9]
	v_mfma_f32_16x16x32_bf16 v[2:5], v[182:185], v[218:221], v[2:5]
	s_setprio 0
	s_barrier
	s_add_i32 s53, 0, 0x18000
	v_add_u32_e32 v153, s53, v148
	s_add_i32 s54, 0, 0x1c000
	ds_read_b128 v[154:157], v153
	ds_read_b128 v[158:161], v153 offset:1024
	ds_read_b128 v[162:165], v153 offset:2048
	ds_read_b128 v[166:169], v153 offset:3072
	v_add_u32_e32 v153, s54, v148
	ds_read_b128 v[170:173], v153
	ds_read_b128 v[174:177], v153 offset:1024
	ds_read_b128 v[178:181], v153 offset:2048
	ds_read_b128 v[182:185], v153 offset:3072
	s_add_u32 s30, s30, 0x80000
	s_addc_u32 s31, s31, 0
	s_mov_b32 m0, s38
	v_lshl_add_u64 v[226:227], s[30:31], 0, v[136:137]
	ds_read_b128 v[186:189], v152 offset:32768
	ds_read_b128 v[190:193], v152 offset:33792
	ds_read_b128 v[194:197], v152 offset:34816
	ds_read_b128 v[198:201], v152 offset:35840
	ds_read_b128 v[202:205], v152 offset:36864
	ds_read_b128 v[210:213], v152 offset:37888
	ds_read_b128 v[214:217], v152 offset:38912
	ds_read_b128 v[218:221], v152 offset:39936
	global_load_lds_dwordx4 v[226:227], off
	v_lshl_add_u64 v[226:227], s[30:31], 0, v[132:133]
	s_mov_b32 m0, s39
	s_nop 0
	global_load_lds_dwordx4 v[226:227], off
	s_waitcnt vmcnt(8)
	s_waitcnt lgkmcnt(0)
	s_barrier
	s_setprio 1
	s_waitcnt lgkmcnt(0)
	v_mfma_f32_16x16x32_bf16 v[126:129], v[154:157], v[186:189], v[126:129]
	v_mfma_f32_16x16x32_bf16 v[122:125], v[162:165], v[186:189], v[122:125]
	v_mfma_f32_16x16x32_bf16 v[110:113], v[154:157], v[194:197], v[110:113]
	v_mfma_f32_16x16x32_bf16 v[106:109], v[162:165], v[194:197], v[106:109]
	v_mfma_f32_16x16x32_bf16 v[94:97], v[154:157], v[202:205], v[94:97]
	v_mfma_f32_16x16x32_bf16 v[90:93], v[162:165], v[202:205], v[90:93]
	v_mfma_f32_16x16x32_bf16 v[78:81], v[154:157], v[214:217], v[78:81]
	v_mfma_f32_16x16x32_bf16 v[74:77], v[162:165], v[214:217], v[74:77]
	v_mfma_f32_16x16x32_bf16 v[126:129], v[158:161], v[190:193], v[126:129]
	v_mfma_f32_16x16x32_bf16 v[122:125], v[166:169], v[190:193], v[122:125]
	v_mfma_f32_16x16x32_bf16 v[110:113], v[158:161], v[198:201], v[110:113]
	v_mfma_f32_16x16x32_bf16 v[106:109], v[166:169], v[198:201], v[106:109]
	v_mfma_f32_16x16x32_bf16 v[94:97], v[158:161], v[210:213], v[94:97]
	v_mfma_f32_16x16x32_bf16 v[90:93], v[166:169], v[210:213], v[90:93]
	v_mfma_f32_16x16x32_bf16 v[78:81], v[158:161], v[218:221], v[78:81]
	v_mfma_f32_16x16x32_bf16 v[74:77], v[166:169], v[218:221], v[74:77]
	s_setprio 0
	s_setprio 1
	v_mfma_f32_16x16x32_bf16 v[118:121], v[170:173], v[186:189], v[118:121]
	v_mfma_f32_16x16x32_bf16 v[114:117], v[178:181], v[186:189], v[114:117]
	v_mfma_f32_16x16x32_bf16 v[102:105], v[170:173], v[194:197], v[102:105]
	v_mfma_f32_16x16x32_bf16 v[98:101], v[178:181], v[194:197], v[98:101]
	v_mfma_f32_16x16x32_bf16 v[86:89], v[170:173], v[202:205], v[86:89]
	v_mfma_f32_16x16x32_bf16 v[82:85], v[178:181], v[202:205], v[82:85]
	v_mfma_f32_16x16x32_bf16 v[70:73], v[170:173], v[214:217], v[70:73]
	v_mfma_f32_16x16x32_bf16 v[66:69], v[178:181], v[214:217], v[66:69]
	v_mfma_f32_16x16x32_bf16 v[118:121], v[174:177], v[190:193], v[118:121]
	v_mfma_f32_16x16x32_bf16 v[114:117], v[182:185], v[190:193], v[114:117]
	v_mfma_f32_16x16x32_bf16 v[102:105], v[174:177], v[198:201], v[102:105]
	v_mfma_f32_16x16x32_bf16 v[98:101], v[182:185], v[198:201], v[98:101]
	v_mfma_f32_16x16x32_bf16 v[86:89], v[174:177], v[210:213], v[86:89]
	v_mfma_f32_16x16x32_bf16 v[82:85], v[182:185], v[210:213], v[82:85]
	v_mfma_f32_16x16x32_bf16 v[70:73], v[174:177], v[218:221], v[70:73]
	v_mfma_f32_16x16x32_bf16 v[66:69], v[182:185], v[218:221], v[66:69]
	s_setprio 0
	s_barrier
; #define PG8_STAGE(bufoff, gbase, voff) do { _Pragma("unroll") for (int _i = 0; _i < 2; ++_i) \
;         __builtin_amdgcn_global_load_lds((const unsigned*)((const char*)(gbase) + (voff)[_i]), (PG8_LAS unsigned*)(lds + (bufoff) + ldsw + _i * 8192), 16, 0, 0); } while (0)
; #define PG8_LDA(dst, b, h) do { _Pragma("unroll") for (int m = 0; m < 4; ++m) _Pragma("unroll") for (int k = 0; k < 2; ++k) dst[m][k] = *(const PG8_LAS bf16x8*)(lds + PG8_SA(b, h) + aoff + m * 2048 + k * 1024); } while (0)
; #define PG8_MMA(ai, bj, At, Bt) do { __builtin_amdgcn_s_setprio(1); _Pragma("unroll") for (int m = 0; m < 4; ++m) _Pragma("unroll") for (int n = 0; n < 2; ++n) _Pragma("unroll") for (int k = 0; k < 2; ++k) \
;         acc[ai][bj][m][n] = __builtin_amdgcn_mfma_f32_16x16x32_bf16(Bt[n][k], At[m][k], acc[ai][bj][m][n], 0, 0, 0); __builtin_amdgcn_s_setprio(0); } while (0)
; #define PG8_WAIT_V(n) asm volatile("s_waitcnt vmcnt(" #n ")" ::: "memory")
; #define PG8_WAIT_L(n) asm volatile("s_waitcnt lgkmcnt(" #n ")" ::: "memory")
; #define PG8_BAR __builtin_amdgcn_s_barrier()
; #define PG8_SCHED __builtin_amdgcn_sched_barrier(0)
; template <class Epi, class Sched, bool ALIGN_EPI = false, bool SP2 = false>
; __device__ __forceinline__ void gemm_phase(PG8_LAS unsigned char* lds, const Gemm g, const Sched& S, const Epi& E) {
;     ...
;         for (int t = 0; t < nt; t += 2) {
;     ...
;             PG8_LDA(At, 1, 1); PG8_STAGE(PG8_SB(1, 0), b3, voffB); PG8_STAGE(PG8_SB(1, 1), b3 + hstepB, voffB); PG8_STAGE(PG8_SA(1, 0), a3, voffA);
;             PG8_WAIT_V(8); PG8_WAIT_L(0); PG8_BAR; PG8_MMA(1, 0, At, B0); PG8_MMA(1, 1, At, B1); PG8_BAR; PG8_SCHED;
	s_add_i32 s30, s53, s34
	v_lshl_add_u64 v[146:147], v[146:147], 0, s[2:3]
	s_mov_b32 m0, s30
	ds_read_b128 v[186:189], v152 offset:49152
	ds_read_b128 v[190:193], v152 offset:50176
	ds_read_b128 v[194:197], v152 offset:51200
	ds_read_b128 v[198:201], v152 offset:52224
	ds_read_b128 v[202:205], v152 offset:53248
	ds_read_b128 v[210:213], v152 offset:54272
	ds_read_b128 v[214:217], v152 offset:55296
	ds_read_b128 v[218:221], v152 offset:56320
	global_load_lds_dwordx4 v[146:147], off
	s_add_i32 m0, s30, 0x2000
	s_add_u32 s28, s28, 0x80080
	v_lshl_add_u64 v[146:147], v[206:207], 0, s[2:3]
	s_addc_u32 s29, s29, 0
	s_add_i32 s30, s54, s34
	global_load_lds_dwordx4 v[146:147], off
	v_lshl_add_u64 v[146:147], s[28:29], 0, v[134:135]
	s_mov_b32 m0, s30
	s_nop 0
	global_load_lds_dwordx4 v[146:147], off
	v_lshl_add_u64 v[146:147], s[28:29], 0, v[130:131]
	s_add_i32 m0, s30, 0x2000
	s_nop 0
	global_load_lds_dwordx4 v[146:147], off
	v_lshl_add_u64 v[146:147], v[222:223], 0, s[2:3]
	s_mov_b32 m0, s41
	s_nop 0
	global_load_lds_dwordx4 v[146:147], off
	v_lshl_add_u64 v[146:147], v[224:225], 0, s[2:3]
	s_mov_b32 m0, s42
	s_nop 0
	global_load_lds_dwordx4 v[146:147], off
	s_waitcnt vmcnt(8)
	s_waitcnt lgkmcnt(0)
	s_barrier
	s_setprio 1
	s_waitcnt lgkmcnt(0)
	v_mfma_f32_16x16x32_bf16 v[62:65], v[154:157], v[186:189], v[62:65]
	v_mfma_f32_16x16x32_bf16 v[58:61], v[162:165], v[186:189], v[58:61]
	v_mfma_f32_16x16x32_bf16 v[46:49], v[154:157], v[194:197], v[46:49]
	v_mfma_f32_16x16x32_bf16 v[42:45], v[162:165], v[194:197], v[42:45]
	v_mfma_f32_16x16x32_bf16 v[30:33], v[154:157], v[202:205], v[30:33]
	v_mfma_f32_16x16x32_bf16 v[26:29], v[162:165], v[202:205], v[26:29]
	v_mfma_f32_16x16x32_bf16 v[14:17], v[154:157], v[214:217], v[14:17]
	v_mfma_f32_16x16x32_bf16 v[10:13], v[162:165], v[214:217], v[10:13]
	v_mfma_f32_16x16x32_bf16 v[62:65], v[158:161], v[190:193], v[62:65]
	v_mfma_f32_16x16x32_bf16 v[58:61], v[166:169], v[190:193], v[58:61]
	v_mfma_f32_16x16x32_bf16 v[46:49], v[158:161], v[198:201], v[46:49]
	v_mfma_f32_16x16x32_bf16 v[42:45], v[166:169], v[198:201], v[42:45]
	v_mfma_f32_16x16x32_bf16 v[30:33], v[158:161], v[210:213], v[30:33]
	v_mfma_f32_16x16x32_bf16 v[26:29], v[166:169], v[210:213], v[26:29]
	v_mfma_f32_16x16x32_bf16 v[14:17], v[158:161], v[218:221], v[14:17]
	v_mfma_f32_16x16x32_bf16 v[10:13], v[166:169], v[218:221], v[10:13]
	s_setprio 0
	s_setprio 1
	v_mfma_f32_16x16x32_bf16 v[54:57], v[170:173], v[186:189], v[54:57]
	v_mfma_f32_16x16x32_bf16 v[50:53], v[178:181], v[186:189], v[50:53]
	v_mfma_f32_16x16x32_bf16 v[38:41], v[170:173], v[194:197], v[38:41]
	v_mfma_f32_16x16x32_bf16 v[34:37], v[178:181], v[194:197], v[34:37]
	v_mfma_f32_16x16x32_bf16 v[22:25], v[170:173], v[202:205], v[22:25]
	v_mfma_f32_16x16x32_bf16 v[18:21], v[178:181], v[202:205], v[18:21]
	v_mfma_f32_16x16x32_bf16 v[6:9], v[170:173], v[214:217], v[6:9]
	v_mfma_f32_16x16x32_bf16 v[2:5], v[178:181], v[214:217], v[2:5]
	v_mfma_f32_16x16x32_bf16 v[54:57], v[174:177], v[190:193], v[54:57]
	v_mfma_f32_16x16x32_bf16 v[50:53], v[182:185], v[190:193], v[50:53]
	v_mfma_f32_16x16x32_bf16 v[38:41], v[174:177], v[198:201], v[38:41]
	v_mfma_f32_16x16x32_bf16 v[34:37], v[182:185], v[198:201], v[34:37]
	v_mfma_f32_16x16x32_bf16 v[22:25], v[174:177], v[210:213], v[22:25]
	v_mfma_f32_16x16x32_bf16 v[18:21], v[182:185], v[210:213], v[18:21]
	v_mfma_f32_16x16x32_bf16 v[6:9], v[174:177], v[218:221], v[6:9]
	v_mfma_f32_16x16x32_bf16 v[2:5], v[182:185], v[218:221], v[2:5]
	s_setprio 0
	s_barrier
	s_add_i32 s52, s52, 2
	s_add_u32 s26, s26, 0x100
	s_addc_u32 s27, s27, 0
	s_add_u32 s50, s50, 0x100
	s_addc_u32 s51, s51, 0
	s_cmp_gt_u32 s52, 29
	s_cbranch_scc1 .Lpeel_exit_8
	.p2align 6

; #define PG8_STAGE(bufoff, gbase, voff) do { _Pragma("unroll") for (int _i = 0; _i < 2; ++_i) \
;         __builtin_amdgcn_global_load_lds((const unsigned*)((const char*)(gbase) + (voff)[_i]), (PG8_LAS unsigned*)(lds + (bufoff) + ldsw + _i * 8192), 16, 0, 0); } while (0)
; #define PG8_LDA(dst, b, h) do { _Pragma("unroll") for (int m = 0; m < 4; ++m) _Pragma("unroll") for (int k = 0; k < 2; ++k) dst[m][k] = *(const PG8_LAS bf16x8*)(lds + PG8_SA(b, h) + aoff + m * 2048 + k * 1024); } while (0)
; #define PG8_LDB(dst, b, h) do { _Pragma("unroll") for (int n = 0; n < 2; ++n) _Pragma("unroll") for (int k = 0; k < 2; ++k) dst[n][k] = *(const PG8_LAS bf16x8*)(lds + PG8_SB(b, h) + boff + n * 2048 + k * 1024); } while (0)
; #define PG8_WAIT_V(n) asm volatile("s_waitcnt vmcnt(" #n ")" ::: "memory")
; #define PG8_WAIT_L(n) asm volatile("s_waitcnt lgkmcnt(" #n ")" ::: "memory")
; #define PG8_BAR __builtin_amdgcn_s_barrier()
; #define PG8_SCHED __builtin_amdgcn_sched_barrier(0)
; template <class Epi, class Sched, bool ALIGN_EPI = false, bool SP2 = false>
; __device__ __forceinline__ void gemm_phase(PG8_LAS unsigned char* lds, const Gemm g, const Sched& S, const Epi& E) {
;     ...
;         const bool has_next = S.next(ui + 1, nxt);
;         const char* nA = has_next ? (const char*)g.A + (size_t)nxt.pm * tstepA : cA; const char* nB = has_next ? (const char*)g.Bt + (size_t)nxt.pn * tstepB : cB;
;         for (int t = 0; t < nt; t += 2) {
;             const bool last = (t == nt - 2);
;             const char* a1 = cA + (size_t)(t + 1) * kstep;
;             const char* a2 = last ? nA : cA + (size_t)(t + 2) * kstep; const char* b2 = last ? nB : cB + (size_t)(t + 2) * kstep;
;             const char* a3 = a2 + kstep; const char* b3 = b2 + kstep;
;             if (last && has_next) S.a_ready(nxt);
;             if constexpr (SP2) {
;             PG8_LDB(B0, 0, 0); PG8_LDB(B1, 0, 1); PG8_SCHED; PG8_LDA(At, 0, 0); PG8_STAGE(PG8_SA(1, 1), a1 + hstepA, voffA);
;             PG8_WAIT_V(8); PG8_WAIT_L(0); PG8_BAR; PG8_MMA(0, 0, At, B0); PG8_MMA(0, 1, At, B1); PG8_BAR; PG8_SCHED;
;             PG8_LDA(At, 0, 1); PG8_STAGE(PG8_SB(0, 0), b2, voffB); PG8_STAGE(PG8_SB(0, 1), b2 + hstepB, voffB); PG8_STAGE(PG8_SA(0, 0), a2, voffA);
;             PG8_WAIT_V(8); PG8_WAIT_L(0); PG8_BAR; PG8_MMA(1, 0, At, B0); PG8_MMA(1, 1, At, B1); PG8_BAR; PG8_SCHED;
.LBB0_1032:
	s_add_u32 s28, s28, 0x160080
	s_addc_u32 s29, s29, 0
	s_add_u32 s57, s30, 0x100
	s_addc_u32 s58, s31, 0
	s_mov_b32 s59, -2
	ds_read_b128 v[152:155], v148
	ds_read_b128 v[156:159], v148 offset:1024
	ds_read_b128 v[160:163], v148 offset:2048
	ds_read_b128 v[164:167], v148 offset:3072
	ds_read_b128 v[168:171], v149
	ds_read_b128 v[172:175], v149 offset:1024
	ds_read_b128 v[176:179], v149 offset:2048
	ds_read_b128 v[180:183], v149 offset:3072
	s_add_u32 s30, s28, 0xffea0080
	s_addc_u32 s31, s29, -1
	s_cmpk_eq_i32 s59, 0x54
	s_cselect_b32 s35, s7, s31
	s_cselect_b32 s34, s6, s30
	s_cselect_b32 s31, s27, s58
	s_cselect_b32 s30, s26, s57
	v_lshl_add_u64 v[218:219], s[28:29], 0, v[138:139]
	s_add_i32 m0, s39, 0xc000
	ds_read_b128 v[184:187], v150
	ds_read_b128 v[188:191], v150 offset:1024
	ds_read_b128 v[192:195], v150 offset:2048
	ds_read_b128 v[196:199], v150 offset:3072
	ds_read_b128 v[200:203], v150 offset:4096
	ds_read_b128 v[204:207], v150 offset:5120
	ds_read_b128 v[210:213], v150 offset:6144
	ds_read_b128 v[214:217], v150 offset:7168
	global_load_lds_dwordx4 v[218:219], off
	v_lshl_add_u64 v[218:219], s[28:29], 0, v[140:141]
	s_add_i32 m0, s39, 0xe000
	s_nop 0
	global_load_lds_dwordx4 v[218:219], off
	s_waitcnt vmcnt(8)
	s_waitcnt lgkmcnt(0)
	s_barrier
	s_setprio 1
	s_waitcnt lgkmcnt(0)
	v_mfma_f32_16x16x32_bf16 v[126:129], v[152:155], v[184:187], 0
	v_mfma_f32_16x16x32_bf16 v[122:125], v[160:163], v[184:187], 0
	v_mfma_f32_16x16x32_bf16 v[118:121], v[152:155], v[192:195], 0
	v_mfma_f32_16x16x32_bf16 v[114:117], v[160:163], v[192:195], 0
	v_mfma_f32_16x16x32_bf16 v[102:105], v[152:155], v[200:203], 0
	v_mfma_f32_16x16x32_bf16 v[98:101], v[160:163], v[200:203], 0
	v_mfma_f32_16x16x32_bf16 v[86:89], v[152:155], v[210:213], 0
	v_mfma_f32_16x16x32_bf16 v[82:85], v[160:163], v[210:213], 0
	v_mfma_f32_16x16x32_bf16 v[126:129], v[156:159], v[188:191], v[126:129]
	v_mfma_f32_16x16x32_bf16 v[122:125], v[164:167], v[188:191], v[122:125]
	v_mfma_f32_16x16x32_bf16 v[118:121], v[156:159], v[196:199], v[118:121]
	v_mfma_f32_16x16x32_bf16 v[114:117], v[164:167], v[196:199], v[114:117]
	v_mfma_f32_16x16x32_bf16 v[102:105], v[156:159], v[204:207], v[102:105]
	v_mfma_f32_16x16x32_bf16 v[98:101], v[164:167], v[204:207], v[98:101]
	v_mfma_f32_16x16x32_bf16 v[86:89], v[156:159], v[214:217], v[86:89]
	v_mfma_f32_16x16x32_bf16 v[82:85], v[164:167], v[214:217], v[82:85]
	s_setprio 0
	s_setprio 1
	v_mfma_f32_16x16x32_bf16 v[110:113], v[168:171], v[184:187], 0
	v_mfma_f32_16x16x32_bf16 v[106:109], v[176:179], v[184:187], 0
	v_mfma_f32_16x16x32_bf16 v[94:97], v[168:171], v[192:195], 0
	v_mfma_f32_16x16x32_bf16 v[90:93], v[176:179], v[192:195], 0
	v_mfma_f32_16x16x32_bf16 v[78:81], v[168:171], v[200:203], 0
	v_mfma_f32_16x16x32_bf16 v[74:77], v[176:179], v[200:203], 0
	v_mfma_f32_16x16x32_bf16 v[70:73], v[168:171], v[210:213], 0
	v_mfma_f32_16x16x32_bf16 v[66:69], v[176:179], v[210:213], 0
	v_mfma_f32_16x16x32_bf16 v[110:113], v[172:175], v[188:191], v[110:113]
	v_mfma_f32_16x16x32_bf16 v[106:109], v[180:183], v[188:191], v[106:109]
	v_mfma_f32_16x16x32_bf16 v[94:97], v[172:175], v[196:199], v[94:97]
	v_mfma_f32_16x16x32_bf16 v[90:93], v[180:183], v[196:199], v[90:93]
	v_mfma_f32_16x16x32_bf16 v[78:81], v[172:175], v[204:207], v[78:81]
	v_mfma_f32_16x16x32_bf16 v[74:77], v[180:183], v[204:207], v[74:77]
	v_mfma_f32_16x16x32_bf16 v[70:73], v[172:175], v[214:217], v[70:73]
	v_mfma_f32_16x16x32_bf16 v[66:69], v[180:183], v[214:217], v[66:69]
	s_setprio 0
	s_barrier
	s_add_i32 s60, s47, s36
	v_lshl_add_u64 v[218:219], s[30:31], 0, v[134:135]
	s_mov_b32 m0, s60
	ds_read_b128 v[184:187], v150 offset:16384
	ds_read_b128 v[188:191], v150 offset:17408
	ds_read_b128 v[192:195], v150 offset:18432
	ds_read_b128 v[196:199], v150 offset:19456
	ds_read_b128 v[200:203], v150 offset:20480
	ds_read_b128 v[204:207], v150 offset:21504
	ds_read_b128 v[210:213], v150 offset:22528
	ds_read_b128 v[214:217], v150 offset:23552
	global_load_lds_dwordx4 v[218:219], off
	s_add_i32 m0, s60, 0x2000
	s_add_u32 s60, s30, 0x160000
	v_lshl_add_u64 v[220:221], s[30:31], 0, v[130:131]
	s_addc_u32 s61, s31, 0
	s_add_i32 s62, s48, s36
	global_load_lds_dwordx4 v[220:221], off
	v_lshl_add_u64 v[222:223], s[60:61], 0, v[134:135]
	s_mov_b32 m0, s62
	v_lshl_add_u64 v[224:225], s[34:35], 0, v[132:133]
	global_load_lds_dwordx4 v[222:223], off
	v_lshl_add_u64 v[222:223], s[60:61], 0, v[130:131]
	s_add_i32 m0, s62, 0x2000
	s_nop 0
	global_load_lds_dwordx4 v[222:223], off
	v_lshl_add_u64 v[222:223], s[34:35], 0, v[136:137]
	s_mov_b32 m0, s39
	s_nop 0
	global_load_lds_dwordx4 v[222:223], off
	s_mov_b32 m0, s40
	s_nop 0
	global_load_lds_dwordx4 v[224:225], off
	s_waitcnt vmcnt(8)
	s_waitcnt lgkmcnt(0)
	s_barrier
; #define PG8_STAGE(bufoff, gbase, voff) do { _Pragma("unroll") for (int _i = 0; _i < 2; ++_i) \
;         __builtin_amdgcn_global_load_lds((const unsigned*)((const char*)(gbase) + (voff)[_i]), (PG8_LAS unsigned*)(lds + (bufoff) + ldsw + _i * 8192), 16, 0, 0); } while (0)
; #define PG8_LDA(dst, b, h) do { _Pragma("unroll") for (int m = 0; m < 4; ++m) _Pragma("unroll") for (int k = 0; k < 2; ++k) dst[m][k] = *(const PG8_LAS bf16x8*)(lds + PG8_SA(b, h) + aoff + m * 2048 + k * 1024); } while (0)
; #define PG8_LDB(dst, b, h) do { _Pragma("unroll") for (int n = 0; n < 2; ++n) _Pragma("unroll") for (int k = 0; k < 2; ++k) dst[n][k] = *(const PG8_LAS bf16x8*)(lds + PG8_SB(b, h) + boff + n * 2048 + k * 1024); } while (0)
; #define PG8_MMA(ai, bj, At, Bt) do { __builtin_amdgcn_s_setprio(1); _Pragma("unroll") for (int m = 0; m < 4; ++m) _Pragma("unroll") for (int n = 0; n < 2; ++n) _Pragma("unroll") for (int k = 0; k < 2; ++k) \
;         acc[ai][bj][m][n] = __builtin_amdgcn_mfma_f32_16x16x32_bf16(Bt[n][k], At[m][k], acc[ai][bj][m][n], 0, 0, 0); __builtin_amdgcn_s_setprio(0); } while (0)
; #define PG8_WAIT_V(n) asm volatile("s_waitcnt vmcnt(" #n ")" ::: "memory")
; #define PG8_WAIT_L(n) asm volatile("s_waitcnt lgkmcnt(" #n ")" ::: "memory")
; #define PG8_BAR __builtin_amdgcn_s_barrier()
; #define PG8_SCHED __builtin_amdgcn_sched_barrier(0)
; template <class Epi, class Sched, bool ALIGN_EPI = false, bool SP2 = false>
; __device__ __forceinline__ void gemm_phase(PG8_LAS unsigned char* lds, const Gemm g, const Sched& S, const Epi& E) {
;     ...
;             PG8_WAIT_V(8); PG8_WAIT_L(0); PG8_BAR; PG8_MMA(1, 0, At, B0); PG8_MMA(1, 1, At, B1); PG8_BAR; PG8_SCHED;
;             PG8_LDB(B0, 1, 0); PG8_LDB(B1, 1, 1); PG8_SCHED; PG8_LDA(At, 1, 0); PG8_STAGE(PG8_SA(0, 1), a2 + hstepA, voffA);
;             PG8_WAIT_V(8); PG8_WAIT_L(0); PG8_BAR; PG8_MMA(0, 0, At, B0); PG8_MMA(0, 1, At, B1); PG8_BAR; PG8_SCHED;
	s_setprio 1
	s_waitcnt lgkmcnt(0)
	v_mfma_f32_16x16x32_bf16 v[62:65], v[152:155], v[184:187], 0
	v_mfma_f32_16x16x32_bf16 v[58:61], v[160:163], v[184:187], 0
	v_mfma_f32_16x16x32_bf16 v[54:57], v[152:155], v[192:195], 0
	v_mfma_f32_16x16x32_bf16 v[50:53], v[160:163], v[192:195], 0
	v_mfma_f32_16x16x32_bf16 v[38:41], v[152:155], v[200:203], 0
	v_mfma_f32_16x16x32_bf16 v[34:37], v[160:163], v[200:203], 0
	v_mfma_f32_16x16x32_bf16 v[22:25], v[152:155], v[210:213], 0
	v_mfma_f32_16x16x32_bf16 v[18:21], v[160:163], v[210:213], 0
	v_mfma_f32_16x16x32_bf16 v[62:65], v[156:159], v[188:191], v[62:65]
	v_mfma_f32_16x16x32_bf16 v[58:61], v[164:167], v[188:191], v[58:61]
	v_mfma_f32_16x16x32_bf16 v[54:57], v[156:159], v[196:199], v[54:57]
	v_mfma_f32_16x16x32_bf16 v[50:53], v[164:167], v[196:199], v[50:53]
	v_mfma_f32_16x16x32_bf16 v[38:41], v[156:159], v[204:207], v[38:41]
	v_mfma_f32_16x16x32_bf16 v[34:37], v[164:167], v[204:207], v[34:37]
	v_mfma_f32_16x16x32_bf16 v[22:25], v[156:159], v[214:217], v[22:25]
	v_mfma_f32_16x16x32_bf16 v[18:21], v[164:167], v[214:217], v[18:21]
	s_setprio 0
	s_setprio 1
	v_mfma_f32_16x16x32_bf16 v[46:49], v[168:171], v[184:187], 0
	v_mfma_f32_16x16x32_bf16 v[42:45], v[176:179], v[184:187], 0
	v_mfma_f32_16x16x32_bf16 v[30:33], v[168:171], v[192:195], 0
	v_mfma_f32_16x16x32_bf16 v[26:29], v[176:179], v[192:195], 0
	v_mfma_f32_16x16x32_bf16 v[14:17], v[168:171], v[200:203], 0
	v_mfma_f32_16x16x32_bf16 v[10:13], v[176:179], v[200:203], 0
	v_mfma_f32_16x16x32_bf16 v[6:9], v[168:171], v[210:213], 0
	v_mfma_f32_16x16x32_bf16 v[2:5], v[176:179], v[210:213], 0
	v_mfma_f32_16x16x32_bf16 v[46:49], v[172:175], v[188:191], v[46:49]
	v_mfma_f32_16x16x32_bf16 v[42:45], v[180:183], v[188:191], v[42:45]
	v_mfma_f32_16x16x32_bf16 v[30:33], v[172:175], v[196:199], v[30:33]
	v_mfma_f32_16x16x32_bf16 v[26:29], v[180:183], v[196:199], v[26:29]
	v_mfma_f32_16x16x32_bf16 v[14:17], v[172:175], v[204:207], v[14:17]
	v_mfma_f32_16x16x32_bf16 v[10:13], v[180:183], v[204:207], v[10:13]
	v_mfma_f32_16x16x32_bf16 v[6:9], v[172:175], v[214:217], v[6:9]
	v_mfma_f32_16x16x32_bf16 v[2:5], v[180:183], v[214:217], v[2:5]
	s_setprio 0
	s_barrier
	s_add_i32 s60, 0, 0x18000
	v_add_u32_e32 v151, s60, v146
	s_add_i32 s61, 0, 0x1c000
	ds_read_b128 v[152:155], v151
	ds_read_b128 v[156:159], v151 offset:1024
	ds_read_b128 v[160:163], v151 offset:2048
	ds_read_b128 v[164:167], v151 offset:3072
	v_add_u32_e32 v151, s61, v146
	ds_read_b128 v[168:171], v151
	ds_read_b128 v[172:175], v151 offset:1024
	ds_read_b128 v[176:179], v151 offset:2048
	ds_read_b128 v[180:183], v151 offset:3072
	s_add_u32 s34, s34, 0x160000
	s_addc_u32 s35, s35, 0
	s_mov_b32 m0, s41
	v_lshl_add_u64 v[226:227], s[34:35], 0, v[136:137]
	ds_read_b128 v[184:187], v150 offset:32768
	ds_read_b128 v[188:191], v150 offset:33792
	ds_read_b128 v[192:195], v150 offset:34816
	ds_read_b128 v[196:199], v150 offset:35840
	ds_read_b128 v[200:203], v150 offset:36864
	ds_read_b128 v[204:207], v150 offset:37888
	ds_read_b128 v[210:213], v150 offset:38912
	ds_read_b128 v[214:217], v150 offset:39936
	global_load_lds_dwordx4 v[226:227], off
	v_lshl_add_u64 v[226:227], s[34:35], 0, v[132:133]
	s_mov_b32 m0, s42
	s_nop 0
	global_load_lds_dwordx4 v[226:227], off
	s_waitcnt vmcnt(8)
	s_waitcnt lgkmcnt(0)
	s_barrier
	s_setprio 1
	s_waitcnt lgkmcnt(0)
	v_mfma_f32_16x16x32_bf16 v[126:129], v[152:155], v[184:187], v[126:129]
	v_mfma_f32_16x16x32_bf16 v[122:125], v[160:163], v[184:187], v[122:125]
	v_mfma_f32_16x16x32_bf16 v[118:121], v[152:155], v[192:195], v[118:121]
	v_mfma_f32_16x16x32_bf16 v[114:117], v[160:163], v[192:195], v[114:117]
	v_mfma_f32_16x16x32_bf16 v[102:105], v[152:155], v[200:203], v[102:105]
	v_mfma_f32_16x16x32_bf16 v[98:101], v[160:163], v[200:203], v[98:101]
	v_mfma_f32_16x16x32_bf16 v[86:89], v[152:155], v[210:213], v[86:89]
	v_mfma_f32_16x16x32_bf16 v[82:85], v[160:163], v[210:213], v[82:85]
	v_mfma_f32_16x16x32_bf16 v[126:129], v[156:159], v[188:191], v[126:129]
	v_mfma_f32_16x16x32_bf16 v[122:125], v[164:167], v[188:191], v[122:125]
	v_mfma_f32_16x16x32_bf16 v[118:121], v[156:159], v[196:199], v[118:121]
	v_mfma_f32_16x16x32_bf16 v[114:117], v[164:167], v[196:199], v[114:117]
	v_mfma_f32_16x16x32_bf16 v[102:105], v[156:159], v[204:207], v[102:105]
	v_mfma_f32_16x16x32_bf16 v[98:101], v[164:167], v[204:207], v[98:101]
	v_mfma_f32_16x16x32_bf16 v[86:89], v[156:159], v[214:217], v[86:89]
	v_mfma_f32_16x16x32_bf16 v[82:85], v[164:167], v[214:217], v[82:85]
	s_setprio 0
	s_setprio 1
	v_mfma_f32_16x16x32_bf16 v[110:113], v[168:171], v[184:187], v[110:113]
	v_mfma_f32_16x16x32_bf16 v[106:109], v[176:179], v[184:187], v[106:109]
	v_mfma_f32_16x16x32_bf16 v[94:97], v[168:171], v[192:195], v[94:97]
	v_mfma_f32_16x16x32_bf16 v[90:93], v[176:179], v[192:195], v[90:93]
	v_mfma_f32_16x16x32_bf16 v[78:81], v[168:171], v[200:203], v[78:81]
	v_mfma_f32_16x16x32_bf16 v[74:77], v[176:179], v[200:203], v[74:77]
	v_mfma_f32_16x16x32_bf16 v[70:73], v[168:171], v[210:213], v[70:73]
	v_mfma_f32_16x16x32_bf16 v[66:69], v[176:179], v[210:213], v[66:69]
	v_mfma_f32_16x16x32_bf16 v[110:113], v[172:175], v[188:191], v[110:113]
	v_mfma_f32_16x16x32_bf16 v[106:109], v[180:183], v[188:191], v[106:109]
	v_mfma_f32_16x16x32_bf16 v[94:97], v[172:175], v[196:199], v[94:97]
	v_mfma_f32_16x16x32_bf16 v[90:93], v[180:183], v[196:199], v[90:93]
	v_mfma_f32_16x16x32_bf16 v[78:81], v[172:175], v[204:207], v[78:81]
	v_mfma_f32_16x16x32_bf16 v[74:77], v[180:183], v[204:207], v[74:77]
	v_mfma_f32_16x16x32_bf16 v[70:73], v[172:175], v[214:217], v[70:73]
	v_mfma_f32_16x16x32_bf16 v[66:69], v[180:183], v[214:217], v[66:69]
	s_setprio 0
	s_barrier
; #define PG8_STAGE(bufoff, gbase, voff) do { _Pragma("unroll") for (int _i = 0; _i < 2; ++_i) \
;         __builtin_amdgcn_global_load_lds((const unsigned*)((const char*)(gbase) + (voff)[_i]), (PG8_LAS unsigned*)(lds + (bufoff) + ldsw + _i * 8192), 16, 0, 0); } while (0)
; #define PG8_LDA(dst, b, h) do { _Pragma("unroll") for (int m = 0; m < 4; ++m) _Pragma("unroll") for (int k = 0; k < 2; ++k) dst[m][k] = *(const PG8_LAS bf16x8*)(lds + PG8_SA(b, h) + aoff + m * 2048 + k * 1024); } while (0)
; #define PG8_MMA(ai, bj, At, Bt) do { __builtin_amdgcn_s_setprio(1); _Pragma("unroll") for (int m = 0; m < 4; ++m) _Pragma("unroll") for (int n = 0; n < 2; ++n) _Pragma("unroll") for (int k = 0; k < 2; ++k) \
;         acc[ai][bj][m][n] = __builtin_amdgcn_mfma_f32_16x16x32_bf16(Bt[n][k], At[m][k], acc[ai][bj][m][n], 0, 0, 0); __builtin_amdgcn_s_setprio(0); } while (0)
; #define PG8_WAIT_V(n) asm volatile("s_waitcnt vmcnt(" #n ")" ::: "memory")
; #define PG8_WAIT_L(n) asm volatile("s_waitcnt lgkmcnt(" #n ")" ::: "memory")
; #define PG8_BAR __builtin_amdgcn_s_barrier()
; #define PG8_SCHED __builtin_amdgcn_sched_barrier(0)
; template <class Epi, class Sched, bool ALIGN_EPI = false, bool SP2 = false>
; __device__ __forceinline__ void gemm_phase(PG8_LAS unsigned char* lds, const Gemm g, const Sched& S, const Epi& E) {
;     ...
;         for (int t = 0; t < nt; t += 2) {
;     ...
;             PG8_LDA(At, 1, 1); PG8_STAGE(PG8_SB(1, 0), b3, voffB); PG8_STAGE(PG8_SB(1, 1), b3 + hstepB, voffB); PG8_STAGE(PG8_SA(1, 0), a3, voffA);
;             PG8_WAIT_V(8); PG8_WAIT_L(0); PG8_BAR; PG8_MMA(1, 0, At, B0); PG8_MMA(1, 1, At, B1); PG8_BAR; PG8_SCHED;
	s_add_i32 s34, s60, s36
	v_lshl_add_u64 v[218:219], v[218:219], 0, s[8:9]
	s_mov_b32 m0, s34
	ds_read_b128 v[184:187], v150 offset:49152
	ds_read_b128 v[188:191], v150 offset:50176
	ds_read_b128 v[192:195], v150 offset:51200
	ds_read_b128 v[196:199], v150 offset:52224
	ds_read_b128 v[200:203], v150 offset:53248
	ds_read_b128 v[204:207], v150 offset:54272
	ds_read_b128 v[210:213], v150 offset:55296
	ds_read_b128 v[214:217], v150 offset:56320
	global_load_lds_dwordx4 v[218:219], off
	s_add_i32 m0, s34, 0x2000
	s_add_u32 s30, s30, 0x160080
	v_lshl_add_u64 v[218:219], v[220:221], 0, s[8:9]
	s_addc_u32 s31, s31, 0
	s_add_i32 s34, s61, s36
	global_load_lds_dwordx4 v[218:219], off
	v_lshl_add_u64 v[218:219], s[30:31], 0, v[134:135]
	s_mov_b32 m0, s34
	s_nop 0
	global_load_lds_dwordx4 v[218:219], off
	v_lshl_add_u64 v[218:219], s[30:31], 0, v[130:131]
	s_add_i32 m0, s34, 0x2000
	s_nop 0
	global_load_lds_dwordx4 v[218:219], off
	v_lshl_add_u64 v[218:219], v[222:223], 0, s[8:9]
	s_mov_b32 m0, s44
	s_nop 0
	global_load_lds_dwordx4 v[218:219], off
	v_lshl_add_u64 v[218:219], v[224:225], 0, s[8:9]
	s_mov_b32 m0, s45
	s_nop 0
	global_load_lds_dwordx4 v[218:219], off
	s_waitcnt vmcnt(8)
	s_waitcnt lgkmcnt(0)
	s_barrier
	s_setprio 1
	s_waitcnt lgkmcnt(0)
	v_mfma_f32_16x16x32_bf16 v[62:65], v[152:155], v[184:187], v[62:65]
	v_mfma_f32_16x16x32_bf16 v[58:61], v[160:163], v[184:187], v[58:61]
	v_mfma_f32_16x16x32_bf16 v[54:57], v[152:155], v[192:195], v[54:57]
	v_mfma_f32_16x16x32_bf16 v[50:53], v[160:163], v[192:195], v[50:53]
	v_mfma_f32_16x16x32_bf16 v[38:41], v[152:155], v[200:203], v[38:41]
	v_mfma_f32_16x16x32_bf16 v[34:37], v[160:163], v[200:203], v[34:37]
	v_mfma_f32_16x16x32_bf16 v[22:25], v[152:155], v[210:213], v[22:25]
	v_mfma_f32_16x16x32_bf16 v[18:21], v[160:163], v[210:213], v[18:21]
	v_mfma_f32_16x16x32_bf16 v[62:65], v[156:159], v[188:191], v[62:65]
	v_mfma_f32_16x16x32_bf16 v[58:61], v[164:167], v[188:191], v[58:61]
	v_mfma_f32_16x16x32_bf16 v[54:57], v[156:159], v[196:199], v[54:57]
	v_mfma_f32_16x16x32_bf16 v[50:53], v[164:167], v[196:199], v[50:53]
	v_mfma_f32_16x16x32_bf16 v[38:41], v[156:159], v[204:207], v[38:41]
	v_mfma_f32_16x16x32_bf16 v[34:37], v[164:167], v[204:207], v[34:37]
	v_mfma_f32_16x16x32_bf16 v[22:25], v[156:159], v[214:217], v[22:25]
	v_mfma_f32_16x16x32_bf16 v[18:21], v[164:167], v[214:217], v[18:21]
	s_setprio 0
	s_setprio 1
	v_mfma_f32_16x16x32_bf16 v[46:49], v[168:171], v[184:187], v[46:49]
	v_mfma_f32_16x16x32_bf16 v[42:45], v[176:179], v[184:187], v[42:45]
	v_mfma_f32_16x16x32_bf16 v[30:33], v[168:171], v[192:195], v[30:33]
	v_mfma_f32_16x16x32_bf16 v[26:29], v[176:179], v[192:195], v[26:29]
	v_mfma_f32_16x16x32_bf16 v[14:17], v[168:171], v[200:203], v[14:17]
	v_mfma_f32_16x16x32_bf16 v[10:13], v[176:179], v[200:203], v[10:13]
	v_mfma_f32_16x16x32_bf16 v[6:9], v[168:171], v[210:213], v[6:9]
	v_mfma_f32_16x16x32_bf16 v[2:5], v[176:179], v[210:213], v[2:5]
	v_mfma_f32_16x16x32_bf16 v[46:49], v[172:175], v[188:191], v[46:49]
	v_mfma_f32_16x16x32_bf16 v[42:45], v[180:183], v[188:191], v[42:45]
	v_mfma_f32_16x16x32_bf16 v[30:33], v[172:175], v[196:199], v[30:33]
	v_mfma_f32_16x16x32_bf16 v[26:29], v[180:183], v[196:199], v[26:29]
	v_mfma_f32_16x16x32_bf16 v[14:17], v[172:175], v[204:207], v[14:17]
	v_mfma_f32_16x16x32_bf16 v[10:13], v[180:183], v[204:207], v[10:13]
	v_mfma_f32_16x16x32_bf16 v[6:9], v[172:175], v[214:217], v[6:9]
	v_mfma_f32_16x16x32_bf16 v[2:5], v[180:183], v[214:217], v[2:5]
	s_setprio 0
	s_barrier
	s_add_i32 s59, s59, 2
	s_add_u32 s28, s28, 0x100
	s_addc_u32 s29, s29, 0
	s_add_u32 s57, s57, 0x100
	s_addc_u32 s58, s58, 0
	s_cmpk_gt_u32 s59, 0x55
	s_cbranch_scc1 .Lpeel_exit_9
	.p2align 6

; #define PG8_STAGE(bufoff, gbase, voff) do { _Pragma("unroll") for (int _i = 0; _i < 2; ++_i) \
;         __builtin_amdgcn_global_load_lds((const unsigned*)((const char*)(gbase) + (voff)[_i]), (PG8_LAS unsigned*)(lds + (bufoff) + ldsw + _i * 8192), 16, 0, 0); } while (0)
; #define PG8_LDA(dst, b, h) do { _Pragma("unroll") for (int m = 0; m < 4; ++m) _Pragma("unroll") for (int k = 0; k < 2; ++k) dst[m][k] = *(const PG8_LAS bf16x8*)(lds + PG8_SA(b, h) + aoff + m * 2048 + k * 1024); } while (0)
; #define PG8_LDB(dst, b, h) do { _Pragma("unroll") for (int n = 0; n < 2; ++n) _Pragma("unroll") for (int k = 0; k < 2; ++k) dst[n][k] = *(const PG8_LAS bf16x8*)(lds + PG8_SB(b, h) + boff + n * 2048 + k * 1024); } while (0)
; #define PG8_WAIT_V(n) asm volatile("s_waitcnt vmcnt(" #n ")" ::: "memory")
; #define PG8_WAIT_L(n) asm volatile("s_waitcnt lgkmcnt(" #n ")" ::: "memory")
; #define PG8_BAR __builtin_amdgcn_s_barrier()
; #define PG8_SCHED __builtin_amdgcn_sched_barrier(0)
; template <class Epi, class Sched, bool ALIGN_EPI = false, bool SP2 = false>
; __device__ __forceinline__ void gemm_phase(PG8_LAS unsigned char* lds, const Gemm g, const Sched& S, const Epi& E) {
;     ...
;         const bool has_next = S.next(ui + 1, nxt);
;         const char* nA = has_next ? (const char*)g.A + (size_t)nxt.pm * tstepA : cA; const char* nB = has_next ? (const char*)g.Bt + (size_t)nxt.pn * tstepB : cB;
;         for (int t = 0; t < nt; t += 2) {
;             const bool last = (t == nt - 2);
;             const char* a1 = cA + (size_t)(t + 1) * kstep;
;             const char* a2 = last ? nA : cA + (size_t)(t + 2) * kstep; const char* b2 = last ? nB : cB + (size_t)(t + 2) * kstep;
;             const char* a3 = a2 + kstep; const char* b3 = b2 + kstep;
;             if (last && has_next) S.a_ready(nxt);
;             if constexpr (SP2) {
;             PG8_LDB(B0, 0, 0); PG8_LDB(B1, 0, 1); PG8_SCHED; PG8_LDA(At, 0, 0); PG8_STAGE(PG8_SA(1, 1), a1 + hstepA, voffA);
;             PG8_WAIT_V(8); PG8_WAIT_L(0); PG8_BAR; PG8_MMA(0, 0, At, B0); PG8_MMA(0, 1, At, B1); PG8_BAR; PG8_SCHED;
;             PG8_LDA(At, 0, 1); PG8_STAGE(PG8_SB(0, 0), b2, voffB); PG8_STAGE(PG8_SB(0, 1), b2 + hstepB, voffB); PG8_STAGE(PG8_SA(0, 0), a2, voffA);
;             PG8_WAIT_V(8); PG8_WAIT_L(0); PG8_BAR; PG8_MMA(1, 0, At, B0); PG8_MMA(1, 1, At, B1); PG8_BAR; PG8_SCHED;
.LBB0_1162:
	s_ashr_i32 s29, s28, 31
	s_lshl_b64 s[34:35], s[28:29], 18
	s_add_u32 s34, s22, s34
	s_addc_u32 s35, s23, s35
	s_and_b64 s[6:7], s[6:7], exec
	s_cselect_b32 s29, s35, s37
	s_cselect_b32 s57, s34, s36
	s_add_u32 s6, s38, 0x30080
	s_addc_u32 s7, s39, 0
	s_add_u32 s58, s36, 0x100
	s_addc_u32 s59, s37, 0
	s_mov_b32 s60, -2
	ds_read_b128 v[152:155], v149
	ds_read_b128 v[156:159], v149 offset:1024
	ds_read_b128 v[160:163], v149 offset:2048
	ds_read_b128 v[164:167], v149 offset:3072
	ds_read_b128 v[168:171], v150
	ds_read_b128 v[172:175], v150 offset:1024
	ds_read_b128 v[176:179], v150 offset:2048
	ds_read_b128 v[180:183], v150 offset:3072
	s_add_u32 s36, s6, 0xfffd0080
	s_addc_u32 s37, s7, -1
	s_cmp_eq_u32 s60, 4
	s_cselect_b32 s39, s31, s37
	s_cselect_b32 s38, s30, s36
	s_cselect_b32 s37, s29, s59
	s_cselect_b32 s36, s57, s58
	v_lshl_add_u64 v[218:219], s[6:7], 0, v[140:141]
	s_add_i32 m0, s42, 0xc000
	ds_read_b128 v[184:187], v151
	ds_read_b128 v[188:191], v151 offset:1024
	ds_read_b128 v[192:195], v151 offset:2048
	ds_read_b128 v[196:199], v151 offset:3072
	ds_read_b128 v[200:203], v151 offset:4096
	ds_read_b128 v[204:207], v151 offset:5120
	ds_read_b128 v[210:213], v151 offset:6144
	ds_read_b128 v[214:217], v151 offset:7168
	global_load_lds_dwordx4 v[218:219], off
	v_lshl_add_u64 v[218:219], s[6:7], 0, v[142:143]
	s_add_i32 m0, s42, 0xe000
	s_nop 0
	global_load_lds_dwordx4 v[218:219], off
	s_waitcnt vmcnt(8)
	s_waitcnt lgkmcnt(0)
	s_barrier
	s_setprio 1
	s_waitcnt lgkmcnt(0)
	v_mfma_f32_16x16x32_bf16 v[126:129], v[152:155], v[184:187], 0
	v_mfma_f32_16x16x32_bf16 v[122:125], v[160:163], v[184:187], 0
	v_mfma_f32_16x16x32_bf16 v[118:121], v[152:155], v[192:195], 0
	v_mfma_f32_16x16x32_bf16 v[114:117], v[160:163], v[192:195], 0
	v_mfma_f32_16x16x32_bf16 v[106:109], v[152:155], v[200:203], 0
	v_mfma_f32_16x16x32_bf16 v[98:101], v[160:163], v[200:203], 0
	v_mfma_f32_16x16x32_bf16 v[90:93], v[152:155], v[210:213], 0
	v_mfma_f32_16x16x32_bf16 v[82:85], v[160:163], v[210:213], 0
	v_mfma_f32_16x16x32_bf16 v[126:129], v[156:159], v[188:191], v[126:129]
	v_mfma_f32_16x16x32_bf16 v[122:125], v[164:167], v[188:191], v[122:125]
	v_mfma_f32_16x16x32_bf16 v[118:121], v[156:159], v[196:199], v[118:121]
	v_mfma_f32_16x16x32_bf16 v[114:117], v[164:167], v[196:199], v[114:117]
	v_mfma_f32_16x16x32_bf16 v[106:109], v[156:159], v[204:207], v[106:109]
	v_mfma_f32_16x16x32_bf16 v[98:101], v[164:167], v[204:207], v[98:101]
	v_mfma_f32_16x16x32_bf16 v[90:93], v[156:159], v[214:217], v[90:93]
	v_mfma_f32_16x16x32_bf16 v[82:85], v[164:167], v[214:217], v[82:85]
	s_setprio 0
	s_setprio 1
	v_mfma_f32_16x16x32_bf16 v[110:113], v[168:171], v[184:187], 0
	v_mfma_f32_16x16x32_bf16 v[102:105], v[176:179], v[184:187], 0
	v_mfma_f32_16x16x32_bf16 v[94:97], v[168:171], v[192:195], 0
	v_mfma_f32_16x16x32_bf16 v[86:89], v[176:179], v[192:195], 0
	v_mfma_f32_16x16x32_bf16 v[78:81], v[168:171], v[200:203], 0
	v_mfma_f32_16x16x32_bf16 v[74:77], v[176:179], v[200:203], 0
	v_mfma_f32_16x16x32_bf16 v[70:73], v[168:171], v[210:213], 0
	v_mfma_f32_16x16x32_bf16 v[66:69], v[176:179], v[210:213], 0
	v_mfma_f32_16x16x32_bf16 v[110:113], v[172:175], v[188:191], v[110:113]
	v_mfma_f32_16x16x32_bf16 v[102:105], v[180:183], v[188:191], v[102:105]
	v_mfma_f32_16x16x32_bf16 v[94:97], v[172:175], v[196:199], v[94:97]
	v_mfma_f32_16x16x32_bf16 v[86:89], v[180:183], v[196:199], v[86:89]
	v_mfma_f32_16x16x32_bf16 v[78:81], v[172:175], v[204:207], v[78:81]
	v_mfma_f32_16x16x32_bf16 v[74:77], v[180:183], v[204:207], v[74:77]
	v_mfma_f32_16x16x32_bf16 v[70:73], v[172:175], v[214:217], v[70:73]
	v_mfma_f32_16x16x32_bf16 v[66:69], v[180:183], v[214:217], v[66:69]
	s_setprio 0
	s_barrier
	s_add_i32 s61, s51, s40
	v_lshl_add_u64 v[218:219], s[36:37], 0, v[134:135]
	s_mov_b32 m0, s61
	ds_read_b128 v[184:187], v151 offset:16384
	ds_read_b128 v[188:191], v151 offset:17408
	ds_read_b128 v[192:195], v151 offset:18432
	ds_read_b128 v[196:199], v151 offset:19456
	ds_read_b128 v[200:203], v151 offset:20480
	ds_read_b128 v[204:207], v151 offset:21504
	ds_read_b128 v[210:213], v151 offset:22528
	ds_read_b128 v[214:217], v151 offset:23552
	global_load_lds_dwordx4 v[218:219], off
	s_add_i32 m0, s61, 0x2000
	s_add_u32 s62, s36, 0x20000
	v_lshl_add_u64 v[220:221], s[36:37], 0, v[130:131]
	s_addc_u32 s63, s37, 0
	s_add_i32 s61, s52, s40
	global_load_lds_dwordx4 v[220:221], off
	v_lshl_add_u64 v[222:223], s[62:63], 0, v[134:135]
	s_mov_b32 m0, s61
	v_lshl_add_u64 v[224:225], s[38:39], 0, v[132:133]
	global_load_lds_dwordx4 v[222:223], off
	v_lshl_add_u64 v[222:223], s[62:63], 0, v[130:131]
	s_add_i32 m0, s61, 0x2000
	s_nop 0
	global_load_lds_dwordx4 v[222:223], off
	v_lshl_add_u64 v[222:223], s[38:39], 0, v[136:137]
	s_mov_b32 m0, s42
	s_nop 0
	global_load_lds_dwordx4 v[222:223], off
	s_mov_b32 m0, s43
	s_nop 0
	global_load_lds_dwordx4 v[224:225], off
	s_waitcnt vmcnt(8)
	s_waitcnt lgkmcnt(0)
	s_barrier
; #define PG8_STAGE(bufoff, gbase, voff) do { _Pragma("unroll") for (int _i = 0; _i < 2; ++_i) \
;         __builtin_amdgcn_global_load_lds((const unsigned*)((const char*)(gbase) + (voff)[_i]), (PG8_LAS unsigned*)(lds + (bufoff) + ldsw + _i * 8192), 16, 0, 0); } while (0)
; #define PG8_LDA(dst, b, h) do { _Pragma("unroll") for (int m = 0; m < 4; ++m) _Pragma("unroll") for (int k = 0; k < 2; ++k) dst[m][k] = *(const PG8_LAS bf16x8*)(lds + PG8_SA(b, h) + aoff + m * 2048 + k * 1024); } while (0)
; #define PG8_LDB(dst, b, h) do { _Pragma("unroll") for (int n = 0; n < 2; ++n) _Pragma("unroll") for (int k = 0; k < 2; ++k) dst[n][k] = *(const PG8_LAS bf16x8*)(lds + PG8_SB(b, h) + boff + n * 2048 + k * 1024); } while (0)
; #define PG8_MMA(ai, bj, At, Bt) do { __builtin_amdgcn_s_setprio(1); _Pragma("unroll") for (int m = 0; m < 4; ++m) _Pragma("unroll") for (int n = 0; n < 2; ++n) _Pragma("unroll") for (int k = 0; k < 2; ++k) \
;         acc[ai][bj][m][n] = __builtin_amdgcn_mfma_f32_16x16x32_bf16(Bt[n][k], At[m][k], acc[ai][bj][m][n], 0, 0, 0); __builtin_amdgcn_s_setprio(0); } while (0)
; #define PG8_WAIT_V(n) asm volatile("s_waitcnt vmcnt(" #n ")" ::: "memory")
; #define PG8_WAIT_L(n) asm volatile("s_waitcnt lgkmcnt(" #n ")" ::: "memory")
; #define PG8_BAR __builtin_amdgcn_s_barrier()
; #define PG8_SCHED __builtin_amdgcn_sched_barrier(0)
; template <class Epi, class Sched, bool ALIGN_EPI = false, bool SP2 = false>
; __device__ __forceinline__ void gemm_phase(PG8_LAS unsigned char* lds, const Gemm g, const Sched& S, const Epi& E) {
;     ...
;             PG8_WAIT_V(8); PG8_WAIT_L(0); PG8_BAR; PG8_MMA(1, 0, At, B0); PG8_MMA(1, 1, At, B1); PG8_BAR; PG8_SCHED;
;             PG8_LDB(B0, 1, 0); PG8_LDB(B1, 1, 1); PG8_SCHED; PG8_LDA(At, 1, 0); PG8_STAGE(PG8_SA(0, 1), a2 + hstepA, voffA);
;             PG8_WAIT_V(8); PG8_WAIT_L(0); PG8_BAR; PG8_MMA(0, 0, At, B0); PG8_MMA(0, 1, At, B1); PG8_BAR; PG8_SCHED;
	s_setprio 1
	s_waitcnt lgkmcnt(0)
	v_mfma_f32_16x16x32_bf16 v[62:65], v[152:155], v[184:187], 0
	v_mfma_f32_16x16x32_bf16 v[58:61], v[160:163], v[184:187], 0
	v_mfma_f32_16x16x32_bf16 v[54:57], v[152:155], v[192:195], 0
	v_mfma_f32_16x16x32_bf16 v[50:53], v[160:163], v[192:195], 0
	v_mfma_f32_16x16x32_bf16 v[42:45], v[152:155], v[200:203], 0
	v_mfma_f32_16x16x32_bf16 v[34:37], v[160:163], v[200:203], 0
	v_mfma_f32_16x16x32_bf16 v[26:29], v[152:155], v[210:213], 0
	v_mfma_f32_16x16x32_bf16 v[18:21], v[160:163], v[210:213], 0
	v_mfma_f32_16x16x32_bf16 v[62:65], v[156:159], v[188:191], v[62:65]
	v_mfma_f32_16x16x32_bf16 v[58:61], v[164:167], v[188:191], v[58:61]
	v_mfma_f32_16x16x32_bf16 v[54:57], v[156:159], v[196:199], v[54:57]
	v_mfma_f32_16x16x32_bf16 v[50:53], v[164:167], v[196:199], v[50:53]
	v_mfma_f32_16x16x32_bf16 v[42:45], v[156:159], v[204:207], v[42:45]
	v_mfma_f32_16x16x32_bf16 v[34:37], v[164:167], v[204:207], v[34:37]
	v_mfma_f32_16x16x32_bf16 v[26:29], v[156:159], v[214:217], v[26:29]
	v_mfma_f32_16x16x32_bf16 v[18:21], v[164:167], v[214:217], v[18:21]
	s_setprio 0
	s_setprio 1
	v_mfma_f32_16x16x32_bf16 v[46:49], v[168:171], v[184:187], 0
	v_mfma_f32_16x16x32_bf16 v[38:41], v[176:179], v[184:187], 0
	v_mfma_f32_16x16x32_bf16 v[30:33], v[168:171], v[192:195], 0
	v_mfma_f32_16x16x32_bf16 v[22:25], v[176:179], v[192:195], 0
	v_mfma_f32_16x16x32_bf16 v[14:17], v[168:171], v[200:203], 0
	v_mfma_f32_16x16x32_bf16 v[10:13], v[176:179], v[200:203], 0
	v_mfma_f32_16x16x32_bf16 v[6:9], v[168:171], v[210:213], 0
	v_mfma_f32_16x16x32_bf16 v[2:5], v[176:179], v[210:213], 0
	v_mfma_f32_16x16x32_bf16 v[46:49], v[172:175], v[188:191], v[46:49]
	v_mfma_f32_16x16x32_bf16 v[38:41], v[180:183], v[188:191], v[38:41]
	v_mfma_f32_16x16x32_bf16 v[30:33], v[172:175], v[196:199], v[30:33]
	v_mfma_f32_16x16x32_bf16 v[22:25], v[180:183], v[196:199], v[22:25]
	v_mfma_f32_16x16x32_bf16 v[14:17], v[172:175], v[204:207], v[14:17]
	v_mfma_f32_16x16x32_bf16 v[10:13], v[180:183], v[204:207], v[10:13]
	v_mfma_f32_16x16x32_bf16 v[6:9], v[172:175], v[214:217], v[6:9]
	v_mfma_f32_16x16x32_bf16 v[2:5], v[180:183], v[214:217], v[2:5]
	s_setprio 0
	s_barrier
	s_add_i32 s61, 0, 0x18000
	s_add_i32 s62, 0, 0x1c000
	v_add_u32_e32 v164, s61, v148
	v_add_u32_e32 v180, s62, v148
	ds_read_b128 v[152:155], v164
	ds_read_b128 v[156:159], v164 offset:1024
	ds_read_b128 v[160:163], v164 offset:2048
	ds_read_b128 v[164:167], v164 offset:3072
	ds_read_b128 v[168:171], v180
	ds_read_b128 v[172:175], v180 offset:1024
	ds_read_b128 v[176:179], v180 offset:2048
	ds_read_b128 v[180:183], v180 offset:3072
	s_add_u32 s38, s38, 0x30000
	s_addc_u32 s39, s39, 0
	s_mov_b32 m0, s44
	v_lshl_add_u64 v[226:227], s[38:39], 0, v[136:137]
	ds_read_b128 v[184:187], v151 offset:32768
	ds_read_b128 v[188:191], v151 offset:33792
	ds_read_b128 v[192:195], v151 offset:34816
	ds_read_b128 v[196:199], v151 offset:35840
	ds_read_b128 v[200:203], v151 offset:36864
	ds_read_b128 v[204:207], v151 offset:37888
	ds_read_b128 v[210:213], v151 offset:38912
	ds_read_b128 v[214:217], v151 offset:39936
	global_load_lds_dwordx4 v[226:227], off
	v_lshl_add_u64 v[226:227], s[38:39], 0, v[132:133]
	s_mov_b32 m0, s45
	s_nop 0
	global_load_lds_dwordx4 v[226:227], off
	s_waitcnt vmcnt(8)
	s_waitcnt lgkmcnt(0)
	s_barrier
	s_setprio 1
	s_waitcnt lgkmcnt(0)
	v_mfma_f32_16x16x32_bf16 v[126:129], v[152:155], v[184:187], v[126:129]
	v_mfma_f32_16x16x32_bf16 v[122:125], v[160:163], v[184:187], v[122:125]
	v_mfma_f32_16x16x32_bf16 v[118:121], v[152:155], v[192:195], v[118:121]
	v_mfma_f32_16x16x32_bf16 v[114:117], v[160:163], v[192:195], v[114:117]
	v_mfma_f32_16x16x32_bf16 v[106:109], v[152:155], v[200:203], v[106:109]
	v_mfma_f32_16x16x32_bf16 v[98:101], v[160:163], v[200:203], v[98:101]
	v_mfma_f32_16x16x32_bf16 v[90:93], v[152:155], v[210:213], v[90:93]
	v_mfma_f32_16x16x32_bf16 v[82:85], v[160:163], v[210:213], v[82:85]
	v_mfma_f32_16x16x32_bf16 v[126:129], v[156:159], v[188:191], v[126:129]
	v_mfma_f32_16x16x32_bf16 v[122:125], v[164:167], v[188:191], v[122:125]
	v_mfma_f32_16x16x32_bf16 v[118:121], v[156:159], v[196:199], v[118:121]
	v_mfma_f32_16x16x32_bf16 v[114:117], v[164:167], v[196:199], v[114:117]
	v_mfma_f32_16x16x32_bf16 v[106:109], v[156:159], v[204:207], v[106:109]
	v_mfma_f32_16x16x32_bf16 v[98:101], v[164:167], v[204:207], v[98:101]
	v_mfma_f32_16x16x32_bf16 v[90:93], v[156:159], v[214:217], v[90:93]
	v_mfma_f32_16x16x32_bf16 v[82:85], v[164:167], v[214:217], v[82:85]
	s_setprio 0
	s_setprio 1
	v_mfma_f32_16x16x32_bf16 v[110:113], v[168:171], v[184:187], v[110:113]
	v_mfma_f32_16x16x32_bf16 v[102:105], v[176:179], v[184:187], v[102:105]
	v_mfma_f32_16x16x32_bf16 v[94:97], v[168:171], v[192:195], v[94:97]
	v_mfma_f32_16x16x32_bf16 v[86:89], v[176:179], v[192:195], v[86:89]
	v_mfma_f32_16x16x32_bf16 v[78:81], v[168:171], v[200:203], v[78:81]
	v_mfma_f32_16x16x32_bf16 v[74:77], v[176:179], v[200:203], v[74:77]
	v_mfma_f32_16x16x32_bf16 v[70:73], v[168:171], v[210:213], v[70:73]
	v_mfma_f32_16x16x32_bf16 v[66:69], v[176:179], v[210:213], v[66:69]
	v_mfma_f32_16x16x32_bf16 v[110:113], v[172:175], v[188:191], v[110:113]
	v_mfma_f32_16x16x32_bf16 v[102:105], v[180:183], v[188:191], v[102:105]
	v_mfma_f32_16x16x32_bf16 v[94:97], v[172:175], v[196:199], v[94:97]
	v_mfma_f32_16x16x32_bf16 v[86:89], v[180:183], v[196:199], v[86:89]
	v_mfma_f32_16x16x32_bf16 v[78:81], v[172:175], v[204:207], v[78:81]
	v_mfma_f32_16x16x32_bf16 v[74:77], v[180:183], v[204:207], v[74:77]
	v_mfma_f32_16x16x32_bf16 v[70:73], v[172:175], v[214:217], v[70:73]
	v_mfma_f32_16x16x32_bf16 v[66:69], v[180:183], v[214:217], v[66:69]
	s_setprio 0
	s_barrier
; #define PG8_STAGE(bufoff, gbase, voff) do { _Pragma("unroll") for (int _i = 0; _i < 2; ++_i) \
;         __builtin_amdgcn_global_load_lds((const unsigned*)((const char*)(gbase) + (voff)[_i]), (PG8_LAS unsigned*)(lds + (bufoff) + ldsw + _i * 8192), 16, 0, 0); } while (0)
; #define PG8_LDA(dst, b, h) do { _Pragma("unroll") for (int m = 0; m < 4; ++m) _Pragma("unroll") for (int k = 0; k < 2; ++k) dst[m][k] = *(const PG8_LAS bf16x8*)(lds + PG8_SA(b, h) + aoff + m * 2048 + k * 1024); } while (0)
; #define PG8_MMA(ai, bj, At, Bt) do { __builtin_amdgcn_s_setprio(1); _Pragma("unroll") for (int m = 0; m < 4; ++m) _Pragma("unroll") for (int n = 0; n < 2; ++n) _Pragma("unroll") for (int k = 0; k < 2; ++k) \
;         acc[ai][bj][m][n] = __builtin_amdgcn_mfma_f32_16x16x32_bf16(Bt[n][k], At[m][k], acc[ai][bj][m][n], 0, 0, 0); __builtin_amdgcn_s_setprio(0); } while (0)
; #define PG8_WAIT_V(n) asm volatile("s_waitcnt vmcnt(" #n ")" ::: "memory")
; #define PG8_WAIT_L(n) asm volatile("s_waitcnt lgkmcnt(" #n ")" ::: "memory")
; #define PG8_BAR __builtin_amdgcn_s_barrier()
; #define PG8_SCHED __builtin_amdgcn_sched_barrier(0)
; template <class Epi, class Sched, bool ALIGN_EPI = false, bool SP2 = false>
; __device__ __forceinline__ void gemm_phase(PG8_LAS unsigned char* lds, const Gemm g, const Sched& S, const Epi& E) {
;     ...
;         for (int t = 0; t < nt; t += 2) {
;     ...
;             PG8_LDA(At, 1, 1); PG8_STAGE(PG8_SB(1, 0), b3, voffB); PG8_STAGE(PG8_SB(1, 1), b3 + hstepB, voffB); PG8_STAGE(PG8_SA(1, 0), a3, voffA);
;             PG8_WAIT_V(8); PG8_WAIT_L(0); PG8_BAR; PG8_MMA(1, 0, At, B0); PG8_MMA(1, 1, At, B1); PG8_BAR; PG8_SCHED;
	s_add_i32 s38, s61, s40
	v_lshl_add_u64 v[218:219], v[218:219], 0, s[12:13]
	s_mov_b32 m0, s38
	ds_read_b128 v[184:187], v151 offset:49152
	ds_read_b128 v[188:191], v151 offset:50176
	ds_read_b128 v[192:195], v151 offset:51200
	ds_read_b128 v[196:199], v151 offset:52224
	ds_read_b128 v[200:203], v151 offset:53248
	ds_read_b128 v[204:207], v151 offset:54272
	ds_read_b128 v[210:213], v151 offset:55296
	ds_read_b128 v[214:217], v151 offset:56320
	global_load_lds_dwordx4 v[218:219], off
	s_add_i32 m0, s38, 0x2000
	s_add_u32 s36, s36, 0x20080
	v_lshl_add_u64 v[218:219], v[220:221], 0, s[12:13]
	s_addc_u32 s37, s37, 0
	s_add_i32 s38, s62, s40
	global_load_lds_dwordx4 v[218:219], off
	v_lshl_add_u64 v[218:219], s[36:37], 0, v[134:135]
	s_mov_b32 m0, s38
	s_nop 0
	global_load_lds_dwordx4 v[218:219], off
	v_lshl_add_u64 v[218:219], s[36:37], 0, v[130:131]
	s_add_i32 m0, s38, 0x2000
	s_nop 0
	global_load_lds_dwordx4 v[218:219], off
	v_lshl_add_u64 v[218:219], v[222:223], 0, s[12:13]
	s_mov_b32 m0, s48
	s_nop 0
	global_load_lds_dwordx4 v[218:219], off
	v_lshl_add_u64 v[218:219], v[224:225], 0, s[12:13]
	s_mov_b32 m0, s49
	s_nop 0
	global_load_lds_dwordx4 v[218:219], off
	s_waitcnt vmcnt(8)
	s_waitcnt lgkmcnt(0)
	s_barrier
	s_setprio 1
	s_waitcnt lgkmcnt(0)
	v_mfma_f32_16x16x32_bf16 v[62:65], v[152:155], v[184:187], v[62:65]
	v_mfma_f32_16x16x32_bf16 v[58:61], v[160:163], v[184:187], v[58:61]
	v_mfma_f32_16x16x32_bf16 v[54:57], v[152:155], v[192:195], v[54:57]
	v_mfma_f32_16x16x32_bf16 v[50:53], v[160:163], v[192:195], v[50:53]
	v_mfma_f32_16x16x32_bf16 v[42:45], v[152:155], v[200:203], v[42:45]
	v_mfma_f32_16x16x32_bf16 v[34:37], v[160:163], v[200:203], v[34:37]
	v_mfma_f32_16x16x32_bf16 v[26:29], v[152:155], v[210:213], v[26:29]
	v_mfma_f32_16x16x32_bf16 v[18:21], v[160:163], v[210:213], v[18:21]
	v_mfma_f32_16x16x32_bf16 v[62:65], v[156:159], v[188:191], v[62:65]
	v_mfma_f32_16x16x32_bf16 v[58:61], v[164:167], v[188:191], v[58:61]
	v_mfma_f32_16x16x32_bf16 v[54:57], v[156:159], v[196:199], v[54:57]
	v_mfma_f32_16x16x32_bf16 v[50:53], v[164:167], v[196:199], v[50:53]
	v_mfma_f32_16x16x32_bf16 v[42:45], v[156:159], v[204:207], v[42:45]
	v_mfma_f32_16x16x32_bf16 v[34:37], v[164:167], v[204:207], v[34:37]
	v_mfma_f32_16x16x32_bf16 v[26:29], v[156:159], v[214:217], v[26:29]
	v_mfma_f32_16x16x32_bf16 v[18:21], v[164:167], v[214:217], v[18:21]
	s_setprio 0
	s_setprio 1
	v_mfma_f32_16x16x32_bf16 v[46:49], v[168:171], v[184:187], v[46:49]
	v_mfma_f32_16x16x32_bf16 v[38:41], v[176:179], v[184:187], v[38:41]
	v_mfma_f32_16x16x32_bf16 v[30:33], v[168:171], v[192:195], v[30:33]
	v_mfma_f32_16x16x32_bf16 v[22:25], v[176:179], v[192:195], v[22:25]
	v_mfma_f32_16x16x32_bf16 v[14:17], v[168:171], v[200:203], v[14:17]
	v_mfma_f32_16x16x32_bf16 v[10:13], v[176:179], v[200:203], v[10:13]
	v_mfma_f32_16x16x32_bf16 v[6:9], v[168:171], v[210:213], v[6:9]
	v_mfma_f32_16x16x32_bf16 v[2:5], v[176:179], v[210:213], v[2:5]
	v_mfma_f32_16x16x32_bf16 v[46:49], v[172:175], v[188:191], v[46:49]
	v_mfma_f32_16x16x32_bf16 v[38:41], v[180:183], v[188:191], v[38:41]
	v_mfma_f32_16x16x32_bf16 v[30:33], v[172:175], v[196:199], v[30:33]
	v_mfma_f32_16x16x32_bf16 v[22:25], v[180:183], v[196:199], v[22:25]
	v_mfma_f32_16x16x32_bf16 v[14:17], v[172:175], v[204:207], v[14:17]
	v_mfma_f32_16x16x32_bf16 v[10:13], v[180:183], v[204:207], v[10:13]
	v_mfma_f32_16x16x32_bf16 v[6:9], v[172:175], v[214:217], v[6:9]
	v_mfma_f32_16x16x32_bf16 v[2:5], v[180:183], v[214:217], v[2:5]
	s_setprio 0
	s_barrier
	s_add_i32 s60, s60, 2
	s_add_u32 s6, s6, 0x100
	s_addc_u32 s7, s7, 0
	s_add_u32 s58, s58, 0x100
	s_addc_u32 s59, s59, 0
	s_cmp_gt_u32 s60, 5
	s_cbranch_scc1 .Lpeel_exit_11
	.p2align 6

; #define PG8_STAGE(bufoff, gbase, voff) do { _Pragma("unroll") for (int _i = 0; _i < 2; ++_i) \
;         __builtin_amdgcn_global_load_lds((const unsigned*)((const char*)(gbase) + (voff)[_i]), (PG8_LAS unsigned*)(lds + (bufoff) + ldsw + _i * 8192), 16, 0, 0); } while (0)
; #define PG8_LDA(dst, b, h) do { _Pragma("unroll") for (int m = 0; m < 4; ++m) _Pragma("unroll") for (int k = 0; k < 2; ++k) dst[m][k] = *(const PG8_LAS bf16x8*)(lds + PG8_SA(b, h) + aoff + m * 2048 + k * 1024); } while (0)
; #define PG8_LDB(dst, b, h) do { _Pragma("unroll") for (int n = 0; n < 2; ++n) _Pragma("unroll") for (int k = 0; k < 2; ++k) dst[n][k] = *(const PG8_LAS bf16x8*)(lds + PG8_SB(b, h) + boff + n * 2048 + k * 1024); } while (0)
; #define PG8_WAIT_V(n) asm volatile("s_waitcnt vmcnt(" #n ")" ::: "memory")
; #define PG8_WAIT_L(n) asm volatile("s_waitcnt lgkmcnt(" #n ")" ::: "memory")
; #define PG8_BAR __builtin_amdgcn_s_barrier()
; #define PG8_SCHED __builtin_amdgcn_sched_barrier(0)
; template <class Epi, class Sched, bool ALIGN_EPI = false, bool SP2 = false>
; __device__ __forceinline__ void gemm_phase(PG8_LAS unsigned char* lds, const Gemm g, const Sched& S, const Epi& E) {
;     ...
;         const bool has_next = S.next(ui + 1, nxt);
;         const char* nA = has_next ? (const char*)g.A + (size_t)nxt.pm * tstepA : cA; const char* nB = has_next ? (const char*)g.Bt + (size_t)nxt.pn * tstepB : cB;
;         for (int t = 0; t < nt; t += 2) {
;             const bool last = (t == nt - 2);
;             const char* a1 = cA + (size_t)(t + 1) * kstep;
;             const char* a2 = last ? nA : cA + (size_t)(t + 2) * kstep; const char* b2 = last ? nB : cB + (size_t)(t + 2) * kstep;
;             const char* a3 = a2 + kstep; const char* b3 = b2 + kstep;
;             if (last && has_next) S.a_ready(nxt);
;             if constexpr (SP2) {
;             PG8_LDB(B0, 0, 0); PG8_LDB(B1, 0, 1); PG8_SCHED; PG8_LDA(At, 0, 0); PG8_STAGE(PG8_SA(1, 1), a1 + hstepA, voffA);
;             PG8_WAIT_V(8); PG8_WAIT_L(0); PG8_BAR; PG8_MMA(0, 0, At, B0); PG8_MMA(0, 1, At, B1); PG8_BAR; PG8_SCHED;
;             PG8_LDA(At, 0, 1); PG8_STAGE(PG8_SB(0, 0), b2, voffB); PG8_STAGE(PG8_SB(0, 1), b2 + hstepB, voffB); PG8_STAGE(PG8_SA(0, 0), a2, voffA);
;             PG8_WAIT_V(8); PG8_WAIT_L(0); PG8_BAR; PG8_MMA(1, 0, At, B0); PG8_MMA(1, 1, At, B1); PG8_BAR; PG8_SCHED;
.LBB0_1289:
	s_add_u32 s0, s0, 0x30080
	s_addc_u32 s1, s1, 0
	s_add_u32 s40, s2, 0x100
	s_addc_u32 s41, s3, 0
	s_mov_b32 s42, -2
	ds_read_b128 v[154:157], v150
	ds_read_b128 v[158:161], v150 offset:1024
	ds_read_b128 v[162:165], v150 offset:2048
	ds_read_b128 v[166:169], v150 offset:3072
	ds_read_b128 v[170:173], v151
	ds_read_b128 v[174:177], v151 offset:1024
	ds_read_b128 v[178:181], v151 offset:2048
	ds_read_b128 v[182:185], v151 offset:3072
	s_add_u32 s2, s0, 0xfffd0080
	s_addc_u32 s3, s1, -1
	s_cmp_eq_u32 s42, 8
	s_cselect_b32 s21, s7, s3
	s_cselect_b32 s20, s6, s2
	s_cselect_b32 s3, s17, s41
	s_cselect_b32 s2, s16, s40
	v_lshl_add_u64 v[206:207], s[0:1], 0, v[140:141]
	s_add_i32 m0, s25, 0xc000
	ds_read_b128 v[186:189], v152
	ds_read_b128 v[190:193], v152 offset:1024
	ds_read_b128 v[194:197], v152 offset:2048
	ds_read_b128 v[198:201], v152 offset:3072
	ds_read_b128 v[202:205], v152 offset:4096
	ds_read_b128 v[210:213], v152 offset:5120
	ds_read_b128 v[214:217], v152 offset:6144
	ds_read_b128 v[218:221], v152 offset:7168
	global_load_lds_dwordx4 v[206:207], off
	v_lshl_add_u64 v[206:207], s[0:1], 0, v[142:143]
	s_add_i32 m0, s25, 0xe000
	s_nop 0
	global_load_lds_dwordx4 v[206:207], off
	s_waitcnt vmcnt(8)
	s_waitcnt lgkmcnt(0)
	s_barrier
	s_setprio 1
	s_waitcnt lgkmcnt(0)
	v_mfma_f32_16x16x32_bf16 v[126:129], v[154:157], v[186:189], 0
	v_mfma_f32_16x16x32_bf16 v[122:125], v[162:165], v[186:189], 0
	v_mfma_f32_16x16x32_bf16 v[110:113], v[154:157], v[194:197], 0
	v_mfma_f32_16x16x32_bf16 v[106:109], v[162:165], v[194:197], 0
	v_mfma_f32_16x16x32_bf16 v[94:97], v[154:157], v[202:205], 0
	v_mfma_f32_16x16x32_bf16 v[90:93], v[162:165], v[202:205], 0
	v_mfma_f32_16x16x32_bf16 v[78:81], v[154:157], v[214:217], 0
	v_mfma_f32_16x16x32_bf16 v[74:77], v[162:165], v[214:217], 0
	v_mfma_f32_16x16x32_bf16 v[126:129], v[158:161], v[190:193], v[126:129]
	v_mfma_f32_16x16x32_bf16 v[122:125], v[166:169], v[190:193], v[122:125]
	v_mfma_f32_16x16x32_bf16 v[110:113], v[158:161], v[198:201], v[110:113]
	v_mfma_f32_16x16x32_bf16 v[106:109], v[166:169], v[198:201], v[106:109]
	v_mfma_f32_16x16x32_bf16 v[94:97], v[158:161], v[210:213], v[94:97]
	v_mfma_f32_16x16x32_bf16 v[90:93], v[166:169], v[210:213], v[90:93]
	v_mfma_f32_16x16x32_bf16 v[78:81], v[158:161], v[218:221], v[78:81]
	v_mfma_f32_16x16x32_bf16 v[74:77], v[166:169], v[218:221], v[74:77]
	s_setprio 0
	s_setprio 1
	v_mfma_f32_16x16x32_bf16 v[118:121], v[170:173], v[186:189], 0
	v_mfma_f32_16x16x32_bf16 v[114:117], v[178:181], v[186:189], 0
	v_mfma_f32_16x16x32_bf16 v[102:105], v[170:173], v[194:197], 0
	v_mfma_f32_16x16x32_bf16 v[98:101], v[178:181], v[194:197], 0
	v_mfma_f32_16x16x32_bf16 v[86:89], v[170:173], v[202:205], 0
	v_mfma_f32_16x16x32_bf16 v[82:85], v[178:181], v[202:205], 0
	v_mfma_f32_16x16x32_bf16 v[70:73], v[170:173], v[214:217], 0
	v_mfma_f32_16x16x32_bf16 v[66:69], v[178:181], v[214:217], 0
	v_mfma_f32_16x16x32_bf16 v[118:121], v[174:177], v[190:193], v[118:121]
	v_mfma_f32_16x16x32_bf16 v[114:117], v[182:185], v[190:193], v[114:117]
	v_mfma_f32_16x16x32_bf16 v[102:105], v[174:177], v[198:201], v[102:105]
	v_mfma_f32_16x16x32_bf16 v[98:101], v[182:185], v[198:201], v[98:101]
	v_mfma_f32_16x16x32_bf16 v[86:89], v[174:177], v[210:213], v[86:89]
	v_mfma_f32_16x16x32_bf16 v[82:85], v[182:185], v[210:213], v[82:85]
	v_mfma_f32_16x16x32_bf16 v[70:73], v[174:177], v[218:221], v[70:73]
	v_mfma_f32_16x16x32_bf16 v[66:69], v[182:185], v[218:221], v[66:69]
	s_setprio 0
	s_barrier
	s_add_i32 s43, s34, s23
	v_lshl_add_u64 v[206:207], s[2:3], 0, v[134:135]
	s_mov_b32 m0, s43
	ds_read_b128 v[186:189], v152 offset:16384
	ds_read_b128 v[190:193], v152 offset:17408
	ds_read_b128 v[194:197], v152 offset:18432
	ds_read_b128 v[198:201], v152 offset:19456
	ds_read_b128 v[202:205], v152 offset:20480
	ds_read_b128 v[210:213], v152 offset:21504
	ds_read_b128 v[214:217], v152 offset:22528
	ds_read_b128 v[218:221], v152 offset:23552
	global_load_lds_dwordx4 v[206:207], off
	s_add_i32 m0, s43, 0x2000
	s_add_u32 s44, s2, 0x30000
	v_lshl_add_u64 v[222:223], s[2:3], 0, v[130:131]
	s_addc_u32 s45, s3, 0
	s_add_i32 s43, s35, s23
	global_load_lds_dwordx4 v[222:223], off
	v_lshl_add_u64 v[224:225], s[44:45], 0, v[134:135]
	s_mov_b32 m0, s43
	v_lshl_add_u64 v[226:227], s[20:21], 0, v[132:133]
	global_load_lds_dwordx4 v[224:225], off
	v_lshl_add_u64 v[224:225], s[44:45], 0, v[130:131]
	s_add_i32 m0, s43, 0x2000
	s_nop 0
	global_load_lds_dwordx4 v[224:225], off
	v_lshl_add_u64 v[224:225], s[20:21], 0, v[136:137]
	s_mov_b32 m0, s25
	s_nop 0
	global_load_lds_dwordx4 v[224:225], off
	s_mov_b32 m0, s26
	s_nop 0
	global_load_lds_dwordx4 v[226:227], off
	s_waitcnt vmcnt(8)
	s_waitcnt lgkmcnt(0)
	s_barrier
; #define PG8_STAGE(bufoff, gbase, voff) do { _Pragma("unroll") for (int _i = 0; _i < 2; ++_i) \
;         __builtin_amdgcn_global_load_lds((const unsigned*)((const char*)(gbase) + (voff)[_i]), (PG8_LAS unsigned*)(lds + (bufoff) + ldsw + _i * 8192), 16, 0, 0); } while (0)
; #define PG8_LDA(dst, b, h) do { _Pragma("unroll") for (int m = 0; m < 4; ++m) _Pragma("unroll") for (int k = 0; k < 2; ++k) dst[m][k] = *(const PG8_LAS bf16x8*)(lds + PG8_SA(b, h) + aoff + m * 2048 + k * 1024); } while (0)
; #define PG8_LDB(dst, b, h) do { _Pragma("unroll") for (int n = 0; n < 2; ++n) _Pragma("unroll") for (int k = 0; k < 2; ++k) dst[n][k] = *(const PG8_LAS bf16x8*)(lds + PG8_SB(b, h) + boff + n * 2048 + k * 1024); } while (0)
; #define PG8_MMA(ai, bj, At, Bt) do { __builtin_amdgcn_s_setprio(1); _Pragma("unroll") for (int m = 0; m < 4; ++m) _Pragma("unroll") for (int n = 0; n < 2; ++n) _Pragma("unroll") for (int k = 0; k < 2; ++k) \
;         acc[ai][bj][m][n] = __builtin_amdgcn_mfma_f32_16x16x32_bf16(Bt[n][k], At[m][k], acc[ai][bj][m][n], 0, 0, 0); __builtin_amdgcn_s_setprio(0); } while (0)
; #define PG8_WAIT_V(n) asm volatile("s_waitcnt vmcnt(" #n ")" ::: "memory")
; #define PG8_WAIT_L(n) asm volatile("s_waitcnt lgkmcnt(" #n ")" ::: "memory")
; #define PG8_BAR __builtin_amdgcn_s_barrier()
; #define PG8_SCHED __builtin_amdgcn_sched_barrier(0)
; template <class Epi, class Sched, bool ALIGN_EPI = false, bool SP2 = false>
; __device__ __forceinline__ void gemm_phase(PG8_LAS unsigned char* lds, const Gemm g, const Sched& S, const Epi& E) {
;     ...
;             PG8_WAIT_V(8); PG8_WAIT_L(0); PG8_BAR; PG8_MMA(1, 0, At, B0); PG8_MMA(1, 1, At, B1); PG8_BAR; PG8_SCHED;
;             PG8_LDB(B0, 1, 0); PG8_LDB(B1, 1, 1); PG8_SCHED; PG8_LDA(At, 1, 0); PG8_STAGE(PG8_SA(0, 1), a2 + hstepA, voffA);
;             PG8_WAIT_V(8); PG8_WAIT_L(0); PG8_BAR; PG8_MMA(0, 0, At, B0); PG8_MMA(0, 1, At, B1); PG8_BAR; PG8_SCHED;
	s_setprio 1
	s_waitcnt lgkmcnt(0)
	v_mfma_f32_16x16x32_bf16 v[62:65], v[154:157], v[186:189], 0
	v_mfma_f32_16x16x32_bf16 v[58:61], v[162:165], v[186:189], 0
	v_mfma_f32_16x16x32_bf16 v[46:49], v[154:157], v[194:197], 0
	v_mfma_f32_16x16x32_bf16 v[42:45], v[162:165], v[194:197], 0
	v_mfma_f32_16x16x32_bf16 v[30:33], v[154:157], v[202:205], 0
	v_mfma_f32_16x16x32_bf16 v[26:29], v[162:165], v[202:205], 0
	v_mfma_f32_16x16x32_bf16 v[14:17], v[154:157], v[214:217], 0
	v_mfma_f32_16x16x32_bf16 v[10:13], v[162:165], v[214:217], 0
	v_mfma_f32_16x16x32_bf16 v[62:65], v[158:161], v[190:193], v[62:65]
	v_mfma_f32_16x16x32_bf16 v[58:61], v[166:169], v[190:193], v[58:61]
	v_mfma_f32_16x16x32_bf16 v[46:49], v[158:161], v[198:201], v[46:49]
	v_mfma_f32_16x16x32_bf16 v[42:45], v[166:169], v[198:201], v[42:45]
	v_mfma_f32_16x16x32_bf16 v[30:33], v[158:161], v[210:213], v[30:33]
	v_mfma_f32_16x16x32_bf16 v[26:29], v[166:169], v[210:213], v[26:29]
	v_mfma_f32_16x16x32_bf16 v[14:17], v[158:161], v[218:221], v[14:17]
	v_mfma_f32_16x16x32_bf16 v[10:13], v[166:169], v[218:221], v[10:13]
	s_setprio 0
	s_setprio 1
	v_mfma_f32_16x16x32_bf16 v[54:57], v[170:173], v[186:189], 0
	v_mfma_f32_16x16x32_bf16 v[50:53], v[178:181], v[186:189], 0
	v_mfma_f32_16x16x32_bf16 v[38:41], v[170:173], v[194:197], 0
	v_mfma_f32_16x16x32_bf16 v[34:37], v[178:181], v[194:197], 0
	v_mfma_f32_16x16x32_bf16 v[22:25], v[170:173], v[202:205], 0
	v_mfma_f32_16x16x32_bf16 v[18:21], v[178:181], v[202:205], 0
	v_mfma_f32_16x16x32_bf16 v[6:9], v[170:173], v[214:217], 0
	v_mfma_f32_16x16x32_bf16 v[2:5], v[178:181], v[214:217], 0
	v_mfma_f32_16x16x32_bf16 v[54:57], v[174:177], v[190:193], v[54:57]
	v_mfma_f32_16x16x32_bf16 v[50:53], v[182:185], v[190:193], v[50:53]
	v_mfma_f32_16x16x32_bf16 v[38:41], v[174:177], v[198:201], v[38:41]
	v_mfma_f32_16x16x32_bf16 v[34:37], v[182:185], v[198:201], v[34:37]
	v_mfma_f32_16x16x32_bf16 v[22:25], v[174:177], v[210:213], v[22:25]
	v_mfma_f32_16x16x32_bf16 v[18:21], v[182:185], v[210:213], v[18:21]
	v_mfma_f32_16x16x32_bf16 v[6:9], v[174:177], v[218:221], v[6:9]
	v_mfma_f32_16x16x32_bf16 v[2:5], v[182:185], v[218:221], v[2:5]
	s_setprio 0
	s_barrier
	s_add_i32 s43, 0, 0x18000
	v_add_u32_e32 v153, s43, v1
	s_add_i32 s44, 0, 0x1c000
	ds_read_b128 v[154:157], v153
	ds_read_b128 v[158:161], v153 offset:1024
	ds_read_b128 v[162:165], v153 offset:2048
	ds_read_b128 v[166:169], v153 offset:3072
	v_add_u32_e32 v153, s44, v1
	ds_read_b128 v[170:173], v153
	ds_read_b128 v[174:177], v153 offset:1024
	ds_read_b128 v[178:181], v153 offset:2048
	ds_read_b128 v[182:185], v153 offset:3072
	s_add_u32 s20, s20, 0x30000
	s_addc_u32 s21, s21, 0
	s_mov_b32 m0, s27
	v_lshl_add_u64 v[228:229], s[20:21], 0, v[136:137]
	ds_read_b128 v[186:189], v152 offset:32768
	ds_read_b128 v[190:193], v152 offset:33792
	ds_read_b128 v[194:197], v152 offset:34816
	ds_read_b128 v[198:201], v152 offset:35840
	ds_read_b128 v[202:205], v152 offset:36864
	ds_read_b128 v[210:213], v152 offset:37888
	ds_read_b128 v[214:217], v152 offset:38912
	ds_read_b128 v[218:221], v152 offset:39936
	global_load_lds_dwordx4 v[228:229], off
	v_lshl_add_u64 v[228:229], s[20:21], 0, v[132:133]
	s_mov_b32 m0, s28
	s_nop 0
	global_load_lds_dwordx4 v[228:229], off
	s_waitcnt vmcnt(8)
	s_waitcnt lgkmcnt(0)
	s_barrier
	s_setprio 1
	s_waitcnt lgkmcnt(0)
	v_mfma_f32_16x16x32_bf16 v[126:129], v[154:157], v[186:189], v[126:129]
	v_mfma_f32_16x16x32_bf16 v[122:125], v[162:165], v[186:189], v[122:125]
	v_mfma_f32_16x16x32_bf16 v[110:113], v[154:157], v[194:197], v[110:113]
	v_mfma_f32_16x16x32_bf16 v[106:109], v[162:165], v[194:197], v[106:109]
	v_mfma_f32_16x16x32_bf16 v[94:97], v[154:157], v[202:205], v[94:97]
	v_mfma_f32_16x16x32_bf16 v[90:93], v[162:165], v[202:205], v[90:93]
	v_mfma_f32_16x16x32_bf16 v[78:81], v[154:157], v[214:217], v[78:81]
	v_mfma_f32_16x16x32_bf16 v[74:77], v[162:165], v[214:217], v[74:77]
	v_mfma_f32_16x16x32_bf16 v[126:129], v[158:161], v[190:193], v[126:129]
	v_mfma_f32_16x16x32_bf16 v[122:125], v[166:169], v[190:193], v[122:125]
	v_mfma_f32_16x16x32_bf16 v[110:113], v[158:161], v[198:201], v[110:113]
	v_mfma_f32_16x16x32_bf16 v[106:109], v[166:169], v[198:201], v[106:109]
	v_mfma_f32_16x16x32_bf16 v[94:97], v[158:161], v[210:213], v[94:97]
	v_mfma_f32_16x16x32_bf16 v[90:93], v[166:169], v[210:213], v[90:93]
	v_mfma_f32_16x16x32_bf16 v[78:81], v[158:161], v[218:221], v[78:81]
	v_mfma_f32_16x16x32_bf16 v[74:77], v[166:169], v[218:221], v[74:77]
	s_setprio 0
	s_setprio 1
	v_mfma_f32_16x16x32_bf16 v[118:121], v[170:173], v[186:189], v[118:121]
	v_mfma_f32_16x16x32_bf16 v[114:117], v[178:181], v[186:189], v[114:117]
	v_mfma_f32_16x16x32_bf16 v[102:105], v[170:173], v[194:197], v[102:105]
	v_mfma_f32_16x16x32_bf16 v[98:101], v[178:181], v[194:197], v[98:101]
	v_mfma_f32_16x16x32_bf16 v[86:89], v[170:173], v[202:205], v[86:89]
	v_mfma_f32_16x16x32_bf16 v[82:85], v[178:181], v[202:205], v[82:85]
	v_mfma_f32_16x16x32_bf16 v[70:73], v[170:173], v[214:217], v[70:73]
	v_mfma_f32_16x16x32_bf16 v[66:69], v[178:181], v[214:217], v[66:69]
	v_mfma_f32_16x16x32_bf16 v[118:121], v[174:177], v[190:193], v[118:121]
	v_mfma_f32_16x16x32_bf16 v[114:117], v[182:185], v[190:193], v[114:117]
	v_mfma_f32_16x16x32_bf16 v[102:105], v[174:177], v[198:201], v[102:105]
	v_mfma_f32_16x16x32_bf16 v[98:101], v[182:185], v[198:201], v[98:101]
	v_mfma_f32_16x16x32_bf16 v[86:89], v[174:177], v[210:213], v[86:89]
	v_mfma_f32_16x16x32_bf16 v[82:85], v[182:185], v[210:213], v[82:85]
	v_mfma_f32_16x16x32_bf16 v[70:73], v[174:177], v[218:221], v[70:73]
	v_mfma_f32_16x16x32_bf16 v[66:69], v[182:185], v[218:221], v[66:69]
	s_setprio 0
	s_barrier
; #define PG8_STAGE(bufoff, gbase, voff) do { _Pragma("unroll") for (int _i = 0; _i < 2; ++_i) \
;         __builtin_amdgcn_global_load_lds((const unsigned*)((const char*)(gbase) + (voff)[_i]), (PG8_LAS unsigned*)(lds + (bufoff) + ldsw + _i * 8192), 16, 0, 0); } while (0)
; #define PG8_LDA(dst, b, h) do { _Pragma("unroll") for (int m = 0; m < 4; ++m) _Pragma("unroll") for (int k = 0; k < 2; ++k) dst[m][k] = *(const PG8_LAS bf16x8*)(lds + PG8_SA(b, h) + aoff + m * 2048 + k * 1024); } while (0)
; #define PG8_MMA(ai, bj, At, Bt) do { __builtin_amdgcn_s_setprio(1); _Pragma("unroll") for (int m = 0; m < 4; ++m) _Pragma("unroll") for (int n = 0; n < 2; ++n) _Pragma("unroll") for (int k = 0; k < 2; ++k) \
;         acc[ai][bj][m][n] = __builtin_amdgcn_mfma_f32_16x16x32_bf16(Bt[n][k], At[m][k], acc[ai][bj][m][n], 0, 0, 0); __builtin_amdgcn_s_setprio(0); } while (0)
; #define PG8_WAIT_V(n) asm volatile("s_waitcnt vmcnt(" #n ")" ::: "memory")
; #define PG8_WAIT_L(n) asm volatile("s_waitcnt lgkmcnt(" #n ")" ::: "memory")
; #define PG8_BAR __builtin_amdgcn_s_barrier()
; #define PG8_SCHED __builtin_amdgcn_sched_barrier(0)
; template <class Epi, class Sched, bool ALIGN_EPI = false, bool SP2 = false>
; __device__ __forceinline__ void gemm_phase(PG8_LAS unsigned char* lds, const Gemm g, const Sched& S, const Epi& E) {
;     ...
;         for (int t = 0; t < nt; t += 2) {
;     ...
;             PG8_LDA(At, 1, 1); PG8_STAGE(PG8_SB(1, 0), b3, voffB); PG8_STAGE(PG8_SB(1, 1), b3 + hstepB, voffB); PG8_STAGE(PG8_SA(1, 0), a3, voffA);
;             PG8_WAIT_V(8); PG8_WAIT_L(0); PG8_BAR; PG8_MMA(1, 0, At, B0); PG8_MMA(1, 1, At, B1); PG8_BAR; PG8_SCHED;
	s_add_i32 s20, s43, s23
	v_lshl_add_u64 v[206:207], v[206:207], 0, s[12:13]
	s_mov_b32 m0, s20
	ds_read_b128 v[186:189], v152 offset:49152
	ds_read_b128 v[190:193], v152 offset:50176
	ds_read_b128 v[194:197], v152 offset:51200
	ds_read_b128 v[198:201], v152 offset:52224
	ds_read_b128 v[202:205], v152 offset:53248
	ds_read_b128 v[210:213], v152 offset:54272
	ds_read_b128 v[214:217], v152 offset:55296
	ds_read_b128 v[218:221], v152 offset:56320
	global_load_lds_dwordx4 v[206:207], off
	s_add_i32 m0, s20, 0x2000
	s_add_u32 s2, s2, 0x30080
	v_lshl_add_u64 v[206:207], v[222:223], 0, s[12:13]
	s_addc_u32 s3, s3, 0
	s_add_i32 s20, s44, s23
	global_load_lds_dwordx4 v[206:207], off
	v_lshl_add_u64 v[206:207], s[2:3], 0, v[134:135]
	s_mov_b32 m0, s20
	s_nop 0
	global_load_lds_dwordx4 v[206:207], off
	v_lshl_add_u64 v[206:207], s[2:3], 0, v[130:131]
	s_add_i32 m0, s20, 0x2000
	s_nop 0
	global_load_lds_dwordx4 v[206:207], off
	v_lshl_add_u64 v[206:207], v[224:225], 0, s[12:13]
	s_mov_b32 m0, s30
	s_nop 0
	global_load_lds_dwordx4 v[206:207], off
	v_lshl_add_u64 v[206:207], v[226:227], 0, s[12:13]
	s_mov_b32 m0, s31
	s_nop 0
	global_load_lds_dwordx4 v[206:207], off
	s_waitcnt vmcnt(8)
	s_waitcnt lgkmcnt(0)
	s_barrier
	s_setprio 1
	s_waitcnt lgkmcnt(0)
	v_mfma_f32_16x16x32_bf16 v[62:65], v[154:157], v[186:189], v[62:65]
	v_mfma_f32_16x16x32_bf16 v[58:61], v[162:165], v[186:189], v[58:61]
	v_mfma_f32_16x16x32_bf16 v[46:49], v[154:157], v[194:197], v[46:49]
	v_mfma_f32_16x16x32_bf16 v[42:45], v[162:165], v[194:197], v[42:45]
	v_mfma_f32_16x16x32_bf16 v[30:33], v[154:157], v[202:205], v[30:33]
	v_mfma_f32_16x16x32_bf16 v[26:29], v[162:165], v[202:205], v[26:29]
	v_mfma_f32_16x16x32_bf16 v[14:17], v[154:157], v[214:217], v[14:17]
	v_mfma_f32_16x16x32_bf16 v[10:13], v[162:165], v[214:217], v[10:13]
	v_mfma_f32_16x16x32_bf16 v[62:65], v[158:161], v[190:193], v[62:65]
	v_mfma_f32_16x16x32_bf16 v[58:61], v[166:169], v[190:193], v[58:61]
	v_mfma_f32_16x16x32_bf16 v[46:49], v[158:161], v[198:201], v[46:49]
	v_mfma_f32_16x16x32_bf16 v[42:45], v[166:169], v[198:201], v[42:45]
	v_mfma_f32_16x16x32_bf16 v[30:33], v[158:161], v[210:213], v[30:33]
	v_mfma_f32_16x16x32_bf16 v[26:29], v[166:169], v[210:213], v[26:29]
	v_mfma_f32_16x16x32_bf16 v[14:17], v[158:161], v[218:221], v[14:17]
	v_mfma_f32_16x16x32_bf16 v[10:13], v[166:169], v[218:221], v[10:13]
	s_setprio 0
	s_setprio 1
	v_mfma_f32_16x16x32_bf16 v[54:57], v[170:173], v[186:189], v[54:57]
	v_mfma_f32_16x16x32_bf16 v[50:53], v[178:181], v[186:189], v[50:53]
	v_mfma_f32_16x16x32_bf16 v[38:41], v[170:173], v[194:197], v[38:41]
	v_mfma_f32_16x16x32_bf16 v[34:37], v[178:181], v[194:197], v[34:37]
	v_mfma_f32_16x16x32_bf16 v[22:25], v[170:173], v[202:205], v[22:25]
	v_mfma_f32_16x16x32_bf16 v[18:21], v[178:181], v[202:205], v[18:21]
	v_mfma_f32_16x16x32_bf16 v[6:9], v[170:173], v[214:217], v[6:9]
	v_mfma_f32_16x16x32_bf16 v[2:5], v[178:181], v[214:217], v[2:5]
	v_mfma_f32_16x16x32_bf16 v[54:57], v[174:177], v[190:193], v[54:57]
	v_mfma_f32_16x16x32_bf16 v[50:53], v[182:185], v[190:193], v[50:53]
	v_mfma_f32_16x16x32_bf16 v[38:41], v[174:177], v[198:201], v[38:41]
	v_mfma_f32_16x16x32_bf16 v[34:37], v[182:185], v[198:201], v[34:37]
	v_mfma_f32_16x16x32_bf16 v[22:25], v[174:177], v[210:213], v[22:25]
	v_mfma_f32_16x16x32_bf16 v[18:21], v[182:185], v[210:213], v[18:21]
	v_mfma_f32_16x16x32_bf16 v[6:9], v[174:177], v[218:221], v[6:9]
	v_mfma_f32_16x16x32_bf16 v[2:5], v[182:185], v[218:221], v[2:5]
	s_setprio 0
	s_barrier
	s_add_i32 s42, s42, 2
	s_add_u32 s0, s0, 0x100
	s_addc_u32 s1, s1, 0
	s_add_u32 s40, s40, 0x100
	s_addc_u32 s41, s41, 0
	s_cmp_gt_u32 s42, 9
	s_cbranch_scc1 .Lpeel_exit_13
	.p2align 6

; #define PG8_STAGE(bufoff, gbase, voff) do { _Pragma("unroll") for (int _i = 0; _i < 2; ++_i) \
;         __builtin_amdgcn_global_load_lds((const unsigned*)((const char*)(gbase) + (voff)[_i]), (PG8_LAS unsigned*)(lds + (bufoff) + ldsw + _i * 8192), 16, 0, 0); } while (0)
; #define PG8_LDA(dst, b, h) do { _Pragma("unroll") for (int m = 0; m < 4; ++m) _Pragma("unroll") for (int k = 0; k < 2; ++k) dst[m][k] = *(const PG8_LAS bf16x8*)(lds + PG8_SA(b, h) + aoff + m * 2048 + k * 1024); } while (0)
; #define PG8_LDB(dst, b, h) do { _Pragma("unroll") for (int n = 0; n < 2; ++n) _Pragma("unroll") for (int k = 0; k < 2; ++k) dst[n][k] = *(const PG8_LAS bf16x8*)(lds + PG8_SB(b, h) + boff + n * 2048 + k * 1024); } while (0)
; #define PG8_WAIT_V(n) asm volatile("s_waitcnt vmcnt(" #n ")" ::: "memory")
; #define PG8_WAIT_L(n) asm volatile("s_waitcnt lgkmcnt(" #n ")" ::: "memory")
; #define PG8_BAR __builtin_amdgcn_s_barrier()
; #define PG8_SCHED __builtin_amdgcn_sched_barrier(0)
; template <class Epi, class Sched, bool ALIGN_EPI = false, bool SP2 = false>
; __device__ __forceinline__ void gemm_phase(PG8_LAS unsigned char* lds, const Gemm g, const Sched& S, const Epi& E) {
;     ...
;         const bool has_next = S.next(ui + 1, nxt);
;         const char* nA = has_next ? (const char*)g.A + (size_t)nxt.pm * tstepA : cA; const char* nB = has_next ? (const char*)g.Bt + (size_t)nxt.pn * tstepB : cB;
;         for (int t = 0; t < nt; t += 2) {
;             const bool last = (t == nt - 2);
;             const char* a1 = cA + (size_t)(t + 1) * kstep;
;             const char* a2 = last ? nA : cA + (size_t)(t + 2) * kstep; const char* b2 = last ? nB : cB + (size_t)(t + 2) * kstep;
;             const char* a3 = a2 + kstep; const char* b3 = b2 + kstep;
;             if (last && has_next) S.a_ready(nxt);
;             if constexpr (SP2) {
;             PG8_LDB(B0, 0, 0); PG8_LDB(B1, 0, 1); PG8_SCHED; PG8_LDA(At, 0, 0); PG8_STAGE(PG8_SA(1, 1), a1 + hstepA, voffA);
;             PG8_WAIT_V(8); PG8_WAIT_L(0); PG8_BAR; PG8_MMA(0, 0, At, B0); PG8_MMA(0, 1, At, B1); PG8_BAR; PG8_SCHED;
;             PG8_LDA(At, 0, 1); PG8_STAGE(PG8_SB(0, 0), b2, voffB); PG8_STAGE(PG8_SB(0, 1), b2 + hstepB, voffB); PG8_STAGE(PG8_SA(0, 0), a2, voffA);
;             PG8_WAIT_V(8); PG8_WAIT_L(0); PG8_BAR; PG8_MMA(1, 0, At, B0); PG8_MMA(1, 1, At, B1); PG8_BAR; PG8_SCHED;
.LBB0_1356:
	s_ashr_i32 s29, s28, 31
	s_lshl_b64 s[30:31], s[28:29], 20
	s_add_u32 s30, s86, s30
	s_addc_u32 s31, s87, s31
	s_and_b64 s[34:35], s[4:5], exec
	s_cselect_b32 s29, s31, s3
	s_cselect_b32 s53, s30, s2
	s_ashr_i32 s27, s26, 31
	s_lshl_b64 s[34:35], s[26:27], 20
	s_add_u32 s34, s88, s34
	s_addc_u32 s35, s89, s35
	s_and_b64 s[38:39], s[4:5], exec
	s_cselect_b32 s27, s35, s37
	s_cselect_b32 s54, s34, s36
	s_add_u32 s2, s2, 0x80080
	s_addc_u32 s3, s3, 0
	s_add_u32 s55, s36, 0x100
	s_addc_u32 s56, s37, 0
	s_mov_b32 s57, -2
	ds_read_b128 v[66:69], v170
	ds_read_b128 v[70:73], v170 offset:1024
	ds_read_b128 v[74:77], v170 offset:2048
	ds_read_b128 v[78:81], v170 offset:3072
	ds_read_b128 v[162:165], v171
	ds_read_b128 v[174:177], v171 offset:1024
	ds_read_b128 v[178:181], v171 offset:2048
	ds_read_b128 v[182:185], v171 offset:3072
	s_add_u32 s36, s2, 0xfff80080
	s_addc_u32 s37, s3, -1
	s_cmp_eq_u32 s57, 28
	s_cselect_b32 s39, s29, s37
	s_cselect_b32 s38, s53, s36
	s_cselect_b32 s37, s27, s56
	s_cselect_b32 s36, s54, s55
	v_lshl_add_u64 v[166:167], s[2:3], 0, v[154:155]
	s_add_i32 m0, s43, 0xc000
	ds_read_b128 v[186:189], v172
	ds_read_b128 v[190:193], v172 offset:1024
	ds_read_b128 v[194:197], v172 offset:2048
	ds_read_b128 v[198:201], v172 offset:3072
	ds_read_b128 v[202:205], v172 offset:4096
	ds_read_b128 v[210:213], v172 offset:5120
	ds_read_b128 v[214:217], v172 offset:6144
	ds_read_b128 v[218:221], v172 offset:7168
	global_load_lds_dwordx4 v[166:167], off
	v_lshl_add_u64 v[166:167], s[2:3], 0, v[156:157]
	s_add_i32 m0, s43, 0xe000
	s_nop 0
	global_load_lds_dwordx4 v[166:167], off
	s_waitcnt vmcnt(8)
	s_waitcnt lgkmcnt(0)
	s_barrier
	s_setprio 1
	s_waitcnt lgkmcnt(0)
	v_mfma_f32_16x16x32_bf16 v[142:145], v[66:69], v[186:189], 0
	v_mfma_f32_16x16x32_bf16 v[138:141], v[74:77], v[186:189], 0
	v_mfma_f32_16x16x32_bf16 v[126:129], v[66:69], v[194:197], 0
	v_mfma_f32_16x16x32_bf16 v[122:125], v[74:77], v[194:197], 0
	v_mfma_f32_16x16x32_bf16 v[110:113], v[66:69], v[202:205], 0
	v_mfma_f32_16x16x32_bf16 v[106:109], v[74:77], v[202:205], 0
	v_mfma_f32_16x16x32_bf16 v[94:97], v[66:69], v[214:217], 0
	v_mfma_f32_16x16x32_bf16 v[90:93], v[74:77], v[214:217], 0
	v_mfma_f32_16x16x32_bf16 v[142:145], v[70:73], v[190:193], v[142:145]
	v_mfma_f32_16x16x32_bf16 v[138:141], v[78:81], v[190:193], v[138:141]
	v_mfma_f32_16x16x32_bf16 v[126:129], v[70:73], v[198:201], v[126:129]
	v_mfma_f32_16x16x32_bf16 v[122:125], v[78:81], v[198:201], v[122:125]
	v_mfma_f32_16x16x32_bf16 v[110:113], v[70:73], v[210:213], v[110:113]
	v_mfma_f32_16x16x32_bf16 v[106:109], v[78:81], v[210:213], v[106:109]
	v_mfma_f32_16x16x32_bf16 v[94:97], v[70:73], v[218:221], v[94:97]
	v_mfma_f32_16x16x32_bf16 v[90:93], v[78:81], v[218:221], v[90:93]
	s_setprio 0
	s_setprio 1
	v_mfma_f32_16x16x32_bf16 v[134:137], v[162:165], v[186:189], 0
	v_mfma_f32_16x16x32_bf16 v[130:133], v[178:181], v[186:189], 0
	v_mfma_f32_16x16x32_bf16 v[118:121], v[162:165], v[194:197], 0
	v_mfma_f32_16x16x32_bf16 v[114:117], v[178:181], v[194:197], 0
	v_mfma_f32_16x16x32_bf16 v[102:105], v[162:165], v[202:205], 0
	v_mfma_f32_16x16x32_bf16 v[98:101], v[178:181], v[202:205], 0
	v_mfma_f32_16x16x32_bf16 v[86:89], v[162:165], v[214:217], 0
	v_mfma_f32_16x16x32_bf16 v[82:85], v[178:181], v[214:217], 0
	v_mfma_f32_16x16x32_bf16 v[134:137], v[174:177], v[190:193], v[134:137]
	v_mfma_f32_16x16x32_bf16 v[130:133], v[182:185], v[190:193], v[130:133]
	v_mfma_f32_16x16x32_bf16 v[118:121], v[174:177], v[198:201], v[118:121]
	v_mfma_f32_16x16x32_bf16 v[114:117], v[182:185], v[198:201], v[114:117]
	v_mfma_f32_16x16x32_bf16 v[102:105], v[174:177], v[210:213], v[102:105]
	v_mfma_f32_16x16x32_bf16 v[98:101], v[182:185], v[210:213], v[98:101]
	v_mfma_f32_16x16x32_bf16 v[86:89], v[174:177], v[218:221], v[86:89]
	v_mfma_f32_16x16x32_bf16 v[82:85], v[182:185], v[218:221], v[82:85]
	s_setprio 0
	s_barrier
	s_add_i32 s58, s51, s40
	v_lshl_add_u64 v[166:167], s[36:37], 0, v[150:151]
	s_mov_b32 m0, s58
	ds_read_b128 v[186:189], v172 offset:16384
	ds_read_b128 v[190:193], v172 offset:17408
	ds_read_b128 v[194:197], v172 offset:18432
	ds_read_b128 v[198:201], v172 offset:19456
	ds_read_b128 v[202:205], v172 offset:20480
	ds_read_b128 v[210:213], v172 offset:21504
	ds_read_b128 v[214:217], v172 offset:22528
	ds_read_b128 v[218:221], v172 offset:23552
	global_load_lds_dwordx4 v[166:167], off
	s_add_i32 m0, s58, 0x2000
	s_add_u32 s58, s36, 0x80000
	v_lshl_add_u64 v[206:207], s[36:37], 0, v[146:147]
	s_addc_u32 s59, s37, 0
	s_add_i32 s60, s52, s40
	global_load_lds_dwordx4 v[206:207], off
	v_lshl_add_u64 v[222:223], s[58:59], 0, v[150:151]
	s_mov_b32 m0, s60
	v_lshl_add_u64 v[224:225], s[38:39], 0, v[148:149]
	global_load_lds_dwordx4 v[222:223], off
	v_lshl_add_u64 v[222:223], s[58:59], 0, v[146:147]
	s_add_i32 m0, s60, 0x2000
	s_nop 0
	global_load_lds_dwordx4 v[222:223], off
	v_lshl_add_u64 v[222:223], s[38:39], 0, v[152:153]
	s_mov_b32 m0, s43
	s_nop 0
	global_load_lds_dwordx4 v[222:223], off
	s_mov_b32 m0, s44
	s_nop 0
	global_load_lds_dwordx4 v[224:225], off
	s_waitcnt vmcnt(8)
	s_waitcnt lgkmcnt(0)
	s_barrier
; #define PG8_STAGE(bufoff, gbase, voff) do { _Pragma("unroll") for (int _i = 0; _i < 2; ++_i) \
;         __builtin_amdgcn_global_load_lds((const unsigned*)((const char*)(gbase) + (voff)[_i]), (PG8_LAS unsigned*)(lds + (bufoff) + ldsw + _i * 8192), 16, 0, 0); } while (0)
; #define PG8_LDA(dst, b, h) do { _Pragma("unroll") for (int m = 0; m < 4; ++m) _Pragma("unroll") for (int k = 0; k < 2; ++k) dst[m][k] = *(const PG8_LAS bf16x8*)(lds + PG8_SA(b, h) + aoff + m * 2048 + k * 1024); } while (0)
; #define PG8_LDB(dst, b, h) do { _Pragma("unroll") for (int n = 0; n < 2; ++n) _Pragma("unroll") for (int k = 0; k < 2; ++k) dst[n][k] = *(const PG8_LAS bf16x8*)(lds + PG8_SB(b, h) + boff + n * 2048 + k * 1024); } while (0)
; #define PG8_MMA(ai, bj, At, Bt) do { __builtin_amdgcn_s_setprio(1); _Pragma("unroll") for (int m = 0; m < 4; ++m) _Pragma("unroll") for (int n = 0; n < 2; ++n) _Pragma("unroll") for (int k = 0; k < 2; ++k) \
;         acc[ai][bj][m][n] = __builtin_amdgcn_mfma_f32_16x16x32_bf16(Bt[n][k], At[m][k], acc[ai][bj][m][n], 0, 0, 0); __builtin_amdgcn_s_setprio(0); } while (0)
; #define PG8_WAIT_V(n) asm volatile("s_waitcnt vmcnt(" #n ")" ::: "memory")
; #define PG8_WAIT_L(n) asm volatile("s_waitcnt lgkmcnt(" #n ")" ::: "memory")
; #define PG8_BAR __builtin_amdgcn_s_barrier()
; #define PG8_SCHED __builtin_amdgcn_sched_barrier(0)
; template <class Epi, class Sched, bool ALIGN_EPI = false, bool SP2 = false>
; __device__ __forceinline__ void gemm_phase(PG8_LAS unsigned char* lds, const Gemm g, const Sched& S, const Epi& E) {
;     ...
;             PG8_WAIT_V(8); PG8_WAIT_L(0); PG8_BAR; PG8_MMA(1, 0, At, B0); PG8_MMA(1, 1, At, B1); PG8_BAR; PG8_SCHED;
;             PG8_LDB(B0, 1, 0); PG8_LDB(B1, 1, 1); PG8_SCHED; PG8_LDA(At, 1, 0); PG8_STAGE(PG8_SA(0, 1), a2 + hstepA, voffA);
;             PG8_WAIT_V(8); PG8_WAIT_L(0); PG8_BAR; PG8_MMA(0, 0, At, B0); PG8_MMA(0, 1, At, B1); PG8_BAR; PG8_SCHED;
	s_setprio 1
	s_waitcnt lgkmcnt(0)
	v_mfma_f32_16x16x32_bf16 v[62:65], v[66:69], v[186:189], 0
	v_mfma_f32_16x16x32_bf16 v[58:61], v[74:77], v[186:189], 0
	v_mfma_f32_16x16x32_bf16 v[46:49], v[66:69], v[194:197], 0
	v_mfma_f32_16x16x32_bf16 v[42:45], v[74:77], v[194:197], 0
	v_mfma_f32_16x16x32_bf16 v[30:33], v[66:69], v[202:205], 0
	v_mfma_f32_16x16x32_bf16 v[26:29], v[74:77], v[202:205], 0
	v_mfma_f32_16x16x32_bf16 v[14:17], v[66:69], v[214:217], 0
	v_mfma_f32_16x16x32_bf16 v[10:13], v[74:77], v[214:217], 0
	v_mfma_f32_16x16x32_bf16 v[62:65], v[70:73], v[190:193], v[62:65]
	v_mfma_f32_16x16x32_bf16 v[58:61], v[78:81], v[190:193], v[58:61]
	v_mfma_f32_16x16x32_bf16 v[46:49], v[70:73], v[198:201], v[46:49]
	v_mfma_f32_16x16x32_bf16 v[42:45], v[78:81], v[198:201], v[42:45]
	v_mfma_f32_16x16x32_bf16 v[30:33], v[70:73], v[210:213], v[30:33]
	v_mfma_f32_16x16x32_bf16 v[26:29], v[78:81], v[210:213], v[26:29]
	v_mfma_f32_16x16x32_bf16 v[14:17], v[70:73], v[218:221], v[14:17]
	v_mfma_f32_16x16x32_bf16 v[10:13], v[78:81], v[218:221], v[10:13]
	s_setprio 0
	s_setprio 1
	v_mfma_f32_16x16x32_bf16 v[54:57], v[162:165], v[186:189], 0
	v_mfma_f32_16x16x32_bf16 v[50:53], v[178:181], v[186:189], 0
	v_mfma_f32_16x16x32_bf16 v[38:41], v[162:165], v[194:197], 0
	v_mfma_f32_16x16x32_bf16 v[34:37], v[178:181], v[194:197], 0
	v_mfma_f32_16x16x32_bf16 v[22:25], v[162:165], v[202:205], 0
	v_mfma_f32_16x16x32_bf16 v[18:21], v[178:181], v[202:205], 0
	v_mfma_f32_16x16x32_bf16 v[6:9], v[162:165], v[214:217], 0
	v_mfma_f32_16x16x32_bf16 v[2:5], v[178:181], v[214:217], 0
	v_mfma_f32_16x16x32_bf16 v[54:57], v[174:177], v[190:193], v[54:57]
	v_mfma_f32_16x16x32_bf16 v[50:53], v[182:185], v[190:193], v[50:53]
	v_mfma_f32_16x16x32_bf16 v[38:41], v[174:177], v[198:201], v[38:41]
	v_mfma_f32_16x16x32_bf16 v[34:37], v[182:185], v[198:201], v[34:37]
	v_mfma_f32_16x16x32_bf16 v[22:25], v[174:177], v[210:213], v[22:25]
	v_mfma_f32_16x16x32_bf16 v[18:21], v[182:185], v[210:213], v[18:21]
	v_mfma_f32_16x16x32_bf16 v[6:9], v[174:177], v[218:221], v[6:9]
	v_mfma_f32_16x16x32_bf16 v[2:5], v[182:185], v[218:221], v[2:5]
	s_setprio 0
	s_barrier
	s_add_i32 s58, 0, 0x18000
	s_add_i32 s59, 0, 0x1c000
	v_add_u32_e32 v78, s58, v168
	v_add_u32_e32 v173, s59, v168
	ds_read_b128 v[66:69], v78
	ds_read_b128 v[70:73], v78 offset:1024
	ds_read_b128 v[74:77], v78 offset:2048
	ds_read_b128 v[78:81], v78 offset:3072
	ds_read_b128 v[162:165], v173
	ds_read_b128 v[174:177], v173 offset:1024
	ds_read_b128 v[178:181], v173 offset:2048
	ds_read_b128 v[182:185], v173 offset:3072
	s_add_u32 s38, s38, 0x80000
	s_addc_u32 s39, s39, 0
	s_mov_b32 m0, s45
	v_lshl_add_u64 v[226:227], s[38:39], 0, v[152:153]
	ds_read_b128 v[186:189], v172 offset:32768
	ds_read_b128 v[190:193], v172 offset:33792
	ds_read_b128 v[194:197], v172 offset:34816
	ds_read_b128 v[198:201], v172 offset:35840
	ds_read_b128 v[202:205], v172 offset:36864
	ds_read_b128 v[210:213], v172 offset:37888
	ds_read_b128 v[214:217], v172 offset:38912
	ds_read_b128 v[218:221], v172 offset:39936
	global_load_lds_dwordx4 v[226:227], off
	v_lshl_add_u64 v[226:227], s[38:39], 0, v[148:149]
	s_mov_b32 m0, s46
	s_nop 0
	global_load_lds_dwordx4 v[226:227], off
	s_waitcnt vmcnt(8)
	s_waitcnt lgkmcnt(0)
	s_barrier
	s_setprio 1
	s_waitcnt lgkmcnt(0)
	v_mfma_f32_16x16x32_bf16 v[142:145], v[66:69], v[186:189], v[142:145]
	v_mfma_f32_16x16x32_bf16 v[138:141], v[74:77], v[186:189], v[138:141]
	v_mfma_f32_16x16x32_bf16 v[126:129], v[66:69], v[194:197], v[126:129]
	v_mfma_f32_16x16x32_bf16 v[122:125], v[74:77], v[194:197], v[122:125]
	v_mfma_f32_16x16x32_bf16 v[110:113], v[66:69], v[202:205], v[110:113]
	v_mfma_f32_16x16x32_bf16 v[106:109], v[74:77], v[202:205], v[106:109]
	v_mfma_f32_16x16x32_bf16 v[94:97], v[66:69], v[214:217], v[94:97]
	v_mfma_f32_16x16x32_bf16 v[90:93], v[74:77], v[214:217], v[90:93]
	v_mfma_f32_16x16x32_bf16 v[142:145], v[70:73], v[190:193], v[142:145]
	v_mfma_f32_16x16x32_bf16 v[138:141], v[78:81], v[190:193], v[138:141]
	v_mfma_f32_16x16x32_bf16 v[126:129], v[70:73], v[198:201], v[126:129]
	v_mfma_f32_16x16x32_bf16 v[122:125], v[78:81], v[198:201], v[122:125]
	v_mfma_f32_16x16x32_bf16 v[110:113], v[70:73], v[210:213], v[110:113]
	v_mfma_f32_16x16x32_bf16 v[106:109], v[78:81], v[210:213], v[106:109]
	v_mfma_f32_16x16x32_bf16 v[94:97], v[70:73], v[218:221], v[94:97]
	v_mfma_f32_16x16x32_bf16 v[90:93], v[78:81], v[218:221], v[90:93]
	s_setprio 0
	s_setprio 1
	v_mfma_f32_16x16x32_bf16 v[134:137], v[162:165], v[186:189], v[134:137]
	v_mfma_f32_16x16x32_bf16 v[130:133], v[178:181], v[186:189], v[130:133]
	v_mfma_f32_16x16x32_bf16 v[118:121], v[162:165], v[194:197], v[118:121]
	v_mfma_f32_16x16x32_bf16 v[114:117], v[178:181], v[194:197], v[114:117]
	v_mfma_f32_16x16x32_bf16 v[102:105], v[162:165], v[202:205], v[102:105]
	v_mfma_f32_16x16x32_bf16 v[98:101], v[178:181], v[202:205], v[98:101]
	v_mfma_f32_16x16x32_bf16 v[86:89], v[162:165], v[214:217], v[86:89]
	v_mfma_f32_16x16x32_bf16 v[82:85], v[178:181], v[214:217], v[82:85]
	v_mfma_f32_16x16x32_bf16 v[134:137], v[174:177], v[190:193], v[134:137]
	v_mfma_f32_16x16x32_bf16 v[130:133], v[182:185], v[190:193], v[130:133]
	v_mfma_f32_16x16x32_bf16 v[118:121], v[174:177], v[198:201], v[118:121]
	v_mfma_f32_16x16x32_bf16 v[114:117], v[182:185], v[198:201], v[114:117]
	v_mfma_f32_16x16x32_bf16 v[102:105], v[174:177], v[210:213], v[102:105]
	v_mfma_f32_16x16x32_bf16 v[98:101], v[182:185], v[210:213], v[98:101]
	v_mfma_f32_16x16x32_bf16 v[86:89], v[174:177], v[218:221], v[86:89]
	v_mfma_f32_16x16x32_bf16 v[82:85], v[182:185], v[218:221], v[82:85]
	s_setprio 0
	s_barrier
; #define PG8_STAGE(bufoff, gbase, voff) do { _Pragma("unroll") for (int _i = 0; _i < 2; ++_i) \
;         __builtin_amdgcn_global_load_lds((const unsigned*)((const char*)(gbase) + (voff)[_i]), (PG8_LAS unsigned*)(lds + (bufoff) + ldsw + _i * 8192), 16, 0, 0); } while (0)
; #define PG8_LDA(dst, b, h) do { _Pragma("unroll") for (int m = 0; m < 4; ++m) _Pragma("unroll") for (int k = 0; k < 2; ++k) dst[m][k] = *(const PG8_LAS bf16x8*)(lds + PG8_SA(b, h) + aoff + m * 2048 + k * 1024); } while (0)
; #define PG8_MMA(ai, bj, At, Bt) do { __builtin_amdgcn_s_setprio(1); _Pragma("unroll") for (int m = 0; m < 4; ++m) _Pragma("unroll") for (int n = 0; n < 2; ++n) _Pragma("unroll") for (int k = 0; k < 2; ++k) \
;         acc[ai][bj][m][n] = __builtin_amdgcn_mfma_f32_16x16x32_bf16(Bt[n][k], At[m][k], acc[ai][bj][m][n], 0, 0, 0); __builtin_amdgcn_s_setprio(0); } while (0)
; #define PG8_WAIT_V(n) asm volatile("s_waitcnt vmcnt(" #n ")" ::: "memory")
; #define PG8_WAIT_L(n) asm volatile("s_waitcnt lgkmcnt(" #n ")" ::: "memory")
; #define PG8_BAR __builtin_amdgcn_s_barrier()
; #define PG8_SCHED __builtin_amdgcn_sched_barrier(0)
; template <class Epi, class Sched, bool ALIGN_EPI = false, bool SP2 = false>
; __device__ __forceinline__ void gemm_phase(PG8_LAS unsigned char* lds, const Gemm g, const Sched& S, const Epi& E) {
;     ...
;         for (int t = 0; t < nt; t += 2) {
;     ...
;             PG8_LDA(At, 1, 1); PG8_STAGE(PG8_SB(1, 0), b3, voffB); PG8_STAGE(PG8_SB(1, 1), b3 + hstepB, voffB); PG8_STAGE(PG8_SA(1, 0), a3, voffA);
;             PG8_WAIT_V(8); PG8_WAIT_L(0); PG8_BAR; PG8_MMA(1, 0, At, B0); PG8_MMA(1, 1, At, B1); PG8_BAR; PG8_SCHED;
	s_add_i32 s38, s58, s40
	v_lshl_add_u64 v[166:167], v[166:167], 0, s[14:15]
	s_mov_b32 m0, s38
	ds_read_b128 v[186:189], v172 offset:49152
	ds_read_b128 v[190:193], v172 offset:50176
	ds_read_b128 v[194:197], v172 offset:51200
	ds_read_b128 v[198:201], v172 offset:52224
	ds_read_b128 v[202:205], v172 offset:53248
	ds_read_b128 v[210:213], v172 offset:54272
	ds_read_b128 v[214:217], v172 offset:55296
	ds_read_b128 v[218:221], v172 offset:56320
	global_load_lds_dwordx4 v[166:167], off
	s_add_i32 m0, s38, 0x2000
	s_add_u32 s36, s36, 0x80080
	v_lshl_add_u64 v[166:167], v[206:207], 0, s[14:15]
	s_addc_u32 s37, s37, 0
	s_add_i32 s38, s59, s40
	global_load_lds_dwordx4 v[166:167], off
	v_lshl_add_u64 v[166:167], s[36:37], 0, v[150:151]
	s_mov_b32 m0, s38
	s_nop 0
	global_load_lds_dwordx4 v[166:167], off
	v_lshl_add_u64 v[166:167], s[36:37], 0, v[146:147]
	s_add_i32 m0, s38, 0x2000
	s_nop 0
	global_load_lds_dwordx4 v[166:167], off
	v_lshl_add_u64 v[166:167], v[222:223], 0, s[14:15]
	s_mov_b32 m0, s48
	s_nop 0
	global_load_lds_dwordx4 v[166:167], off
	v_lshl_add_u64 v[166:167], v[224:225], 0, s[14:15]
	s_mov_b32 m0, s49
	s_nop 0
	global_load_lds_dwordx4 v[166:167], off
	s_waitcnt vmcnt(8)
	s_waitcnt lgkmcnt(0)
	s_barrier
	s_setprio 1
	s_waitcnt lgkmcnt(0)
	v_mfma_f32_16x16x32_bf16 v[62:65], v[66:69], v[186:189], v[62:65]
	v_mfma_f32_16x16x32_bf16 v[58:61], v[74:77], v[186:189], v[58:61]
	v_mfma_f32_16x16x32_bf16 v[46:49], v[66:69], v[194:197], v[46:49]
	v_mfma_f32_16x16x32_bf16 v[42:45], v[74:77], v[194:197], v[42:45]
	v_mfma_f32_16x16x32_bf16 v[30:33], v[66:69], v[202:205], v[30:33]
	v_mfma_f32_16x16x32_bf16 v[26:29], v[74:77], v[202:205], v[26:29]
	v_mfma_f32_16x16x32_bf16 v[14:17], v[66:69], v[214:217], v[14:17]
	v_mfma_f32_16x16x32_bf16 v[10:13], v[74:77], v[214:217], v[10:13]
	v_mfma_f32_16x16x32_bf16 v[62:65], v[70:73], v[190:193], v[62:65]
	v_mfma_f32_16x16x32_bf16 v[58:61], v[78:81], v[190:193], v[58:61]
	v_mfma_f32_16x16x32_bf16 v[46:49], v[70:73], v[198:201], v[46:49]
	v_mfma_f32_16x16x32_bf16 v[42:45], v[78:81], v[198:201], v[42:45]
	v_mfma_f32_16x16x32_bf16 v[30:33], v[70:73], v[210:213], v[30:33]
	v_mfma_f32_16x16x32_bf16 v[26:29], v[78:81], v[210:213], v[26:29]
	v_mfma_f32_16x16x32_bf16 v[14:17], v[70:73], v[218:221], v[14:17]
	v_mfma_f32_16x16x32_bf16 v[10:13], v[78:81], v[218:221], v[10:13]
	s_setprio 0
	s_setprio 1
	v_mfma_f32_16x16x32_bf16 v[54:57], v[162:165], v[186:189], v[54:57]
	v_mfma_f32_16x16x32_bf16 v[50:53], v[178:181], v[186:189], v[50:53]
	v_mfma_f32_16x16x32_bf16 v[38:41], v[162:165], v[194:197], v[38:41]
	v_mfma_f32_16x16x32_bf16 v[34:37], v[178:181], v[194:197], v[34:37]
	v_mfma_f32_16x16x32_bf16 v[22:25], v[162:165], v[202:205], v[22:25]
	v_mfma_f32_16x16x32_bf16 v[18:21], v[178:181], v[202:205], v[18:21]
	v_mfma_f32_16x16x32_bf16 v[6:9], v[162:165], v[214:217], v[6:9]
	v_mfma_f32_16x16x32_bf16 v[2:5], v[178:181], v[214:217], v[2:5]
	v_mfma_f32_16x16x32_bf16 v[54:57], v[174:177], v[190:193], v[54:57]
	v_mfma_f32_16x16x32_bf16 v[50:53], v[182:185], v[190:193], v[50:53]
	v_mfma_f32_16x16x32_bf16 v[38:41], v[174:177], v[198:201], v[38:41]
	v_mfma_f32_16x16x32_bf16 v[34:37], v[182:185], v[198:201], v[34:37]
	v_mfma_f32_16x16x32_bf16 v[22:25], v[174:177], v[210:213], v[22:25]
	v_mfma_f32_16x16x32_bf16 v[18:21], v[182:185], v[210:213], v[18:21]
	v_mfma_f32_16x16x32_bf16 v[6:9], v[174:177], v[218:221], v[6:9]
	v_mfma_f32_16x16x32_bf16 v[2:5], v[182:185], v[218:221], v[2:5]
	s_setprio 0
	s_barrier
	s_add_i32 s57, s57, 2
	s_add_u32 s2, s2, 0x100
	s_addc_u32 s3, s3, 0
	s_add_u32 s55, s55, 0x100
	s_addc_u32 s56, s56, 0
	s_cmp_gt_u32 s57, 29
	s_cbranch_scc1 .Lpeel_exit_14
	.p2align 6

; #define PG8_STAGE(bufoff, gbase, voff) do { _Pragma("unroll") for (int _i = 0; _i < 2; ++_i) \
;         __builtin_amdgcn_global_load_lds((const unsigned*)((const char*)(gbase) + (voff)[_i]), (PG8_LAS unsigned*)(lds + (bufoff) + ldsw + _i * 8192), 16, 0, 0); } while (0)
; #define PG8_LDA(dst, b, h) do { _Pragma("unroll") for (int m = 0; m < 4; ++m) _Pragma("unroll") for (int k = 0; k < 2; ++k) dst[m][k] = *(const PG8_LAS bf16x8*)(lds + PG8_SA(b, h) + aoff + m * 2048 + k * 1024); } while (0)
; #define PG8_LDB(dst, b, h) do { _Pragma("unroll") for (int n = 0; n < 2; ++n) _Pragma("unroll") for (int k = 0; k < 2; ++k) dst[n][k] = *(const PG8_LAS bf16x8*)(lds + PG8_SB(b, h) + boff + n * 2048 + k * 1024); } while (0)
; #define PG8_WAIT_V(n) asm volatile("s_waitcnt vmcnt(" #n ")" ::: "memory")
; #define PG8_WAIT_L(n) asm volatile("s_waitcnt lgkmcnt(" #n ")" ::: "memory")
; #define PG8_BAR __builtin_amdgcn_s_barrier()
; #define PG8_SCHED __builtin_amdgcn_sched_barrier(0)
; template <class Epi, class Sched, bool ALIGN_EPI = false, bool SP2 = false>
; __device__ __forceinline__ void gemm_phase(PG8_LAS unsigned char* lds, const Gemm g, const Sched& S, const Epi& E) {
;     ...
;         const bool has_next = S.next(ui + 1, nxt);
;         const char* nA = has_next ? (const char*)g.A + (size_t)nxt.pm * tstepA : cA; const char* nB = has_next ? (const char*)g.Bt + (size_t)nxt.pn * tstepB : cB;
;         for (int t = 0; t < nt; t += 2) {
;             const bool last = (t == nt - 2);
;             const char* a1 = cA + (size_t)(t + 1) * kstep;
;             const char* a2 = last ? nA : cA + (size_t)(t + 2) * kstep; const char* b2 = last ? nB : cB + (size_t)(t + 2) * kstep;
;             const char* a3 = a2 + kstep; const char* b3 = b2 + kstep;
;             if (last && has_next) S.a_ready(nxt);
;             if constexpr (SP2) {
;             PG8_LDB(B0, 0, 0); PG8_LDB(B1, 0, 1); PG8_SCHED; PG8_LDA(At, 0, 0); PG8_STAGE(PG8_SA(1, 1), a1 + hstepA, voffA);
;             PG8_WAIT_V(8); PG8_WAIT_L(0); PG8_BAR; PG8_MMA(0, 0, At, B0); PG8_MMA(0, 1, At, B1); PG8_BAR; PG8_SCHED;
;             PG8_LDA(At, 0, 1); PG8_STAGE(PG8_SB(0, 0), b2, voffB); PG8_STAGE(PG8_SB(0, 1), b2 + hstepB, voffB); PG8_STAGE(PG8_SA(0, 0), a2, voffA);
;             PG8_WAIT_V(8); PG8_WAIT_L(0); PG8_BAR; PG8_MMA(1, 0, At, B0); PG8_MMA(1, 1, At, B1); PG8_BAR; PG8_SCHED;
.LBB0_1486:
	s_ashr_i32 s13, s12, 31
	s_lshl_b64 s[14:15], s[12:13], 20
	s_add_u32 s14, s86, s14
	s_addc_u32 s15, s87, s15
	s_and_b64 s[16:17], s[4:5], exec
	s_cselect_b32 s13, s15, s23
	s_cselect_b32 s46, s14, s22
	s_ashr_i32 s11, s10, 31
	s_lshl_b64 s[16:17], s[10:11], 20
	s_add_u32 s16, s29, s16
	s_addc_u32 s17, s30, s17
	s_and_b64 s[26:27], s[4:5], exec
	s_cselect_b32 s11, s17, s25
	s_cselect_b32 s47, s16, s24
	s_add_u32 s22, s22, 0x80080
	s_addc_u32 s23, s23, 0
	s_add_u32 s48, s24, 0x100
	s_addc_u32 s49, s25, 0
	s_mov_b32 s50, -2
	ds_read_b128 v[154:157], v150
	ds_read_b128 v[158:161], v150 offset:1024
	ds_read_b128 v[162:165], v150 offset:2048
	ds_read_b128 v[166:169], v150 offset:3072
	ds_read_b128 v[170:173], v151
	ds_read_b128 v[174:177], v151 offset:1024
	ds_read_b128 v[178:181], v151 offset:2048
	ds_read_b128 v[182:185], v151 offset:3072
	s_add_u32 s24, s22, 0xfff80080
	s_addc_u32 s25, s23, -1
	s_cmp_eq_u32 s50, 28
	s_cselect_b32 s27, s13, s25
	s_cselect_b32 s26, s46, s24
	s_cselect_b32 s25, s11, s49
	s_cselect_b32 s24, s47, s48
	v_lshl_add_u64 v[146:147], s[22:23], 0, v[138:139]
	s_add_i32 m0, s21, 0xc000
	ds_read_b128 v[186:189], v152
	ds_read_b128 v[190:193], v152 offset:1024
	ds_read_b128 v[194:197], v152 offset:2048
	ds_read_b128 v[198:201], v152 offset:3072
	ds_read_b128 v[202:205], v152 offset:4096
	ds_read_b128 v[210:213], v152 offset:5120
	ds_read_b128 v[214:217], v152 offset:6144
	ds_read_b128 v[218:221], v152 offset:7168
	global_load_lds_dwordx4 v[146:147], off
	v_lshl_add_u64 v[146:147], s[22:23], 0, v[140:141]
	s_add_i32 m0, s21, 0xe000
	s_nop 0
	global_load_lds_dwordx4 v[146:147], off
	s_waitcnt vmcnt(8)
	s_waitcnt lgkmcnt(0)
	s_barrier
	s_setprio 1
	s_waitcnt lgkmcnt(0)
	v_mfma_f32_16x16x32_bf16 v[126:129], v[154:157], v[186:189], 0
	v_mfma_f32_16x16x32_bf16 v[122:125], v[162:165], v[186:189], 0
	v_mfma_f32_16x16x32_bf16 v[110:113], v[154:157], v[194:197], 0
	v_mfma_f32_16x16x32_bf16 v[106:109], v[162:165], v[194:197], 0
	v_mfma_f32_16x16x32_bf16 v[94:97], v[154:157], v[202:205], 0
	v_mfma_f32_16x16x32_bf16 v[90:93], v[162:165], v[202:205], 0
	v_mfma_f32_16x16x32_bf16 v[78:81], v[154:157], v[214:217], 0
	v_mfma_f32_16x16x32_bf16 v[74:77], v[162:165], v[214:217], 0
	v_mfma_f32_16x16x32_bf16 v[126:129], v[158:161], v[190:193], v[126:129]
	v_mfma_f32_16x16x32_bf16 v[122:125], v[166:169], v[190:193], v[122:125]
	v_mfma_f32_16x16x32_bf16 v[110:113], v[158:161], v[198:201], v[110:113]
	v_mfma_f32_16x16x32_bf16 v[106:109], v[166:169], v[198:201], v[106:109]
	v_mfma_f32_16x16x32_bf16 v[94:97], v[158:161], v[210:213], v[94:97]
	v_mfma_f32_16x16x32_bf16 v[90:93], v[166:169], v[210:213], v[90:93]
	v_mfma_f32_16x16x32_bf16 v[78:81], v[158:161], v[218:221], v[78:81]
	v_mfma_f32_16x16x32_bf16 v[74:77], v[166:169], v[218:221], v[74:77]
	s_setprio 0
	s_setprio 1
	v_mfma_f32_16x16x32_bf16 v[118:121], v[170:173], v[186:189], 0
	v_mfma_f32_16x16x32_bf16 v[114:117], v[178:181], v[186:189], 0
	v_mfma_f32_16x16x32_bf16 v[102:105], v[170:173], v[194:197], 0
	v_mfma_f32_16x16x32_bf16 v[98:101], v[178:181], v[194:197], 0
	v_mfma_f32_16x16x32_bf16 v[86:89], v[170:173], v[202:205], 0
	v_mfma_f32_16x16x32_bf16 v[82:85], v[178:181], v[202:205], 0
	v_mfma_f32_16x16x32_bf16 v[70:73], v[170:173], v[214:217], 0
	v_mfma_f32_16x16x32_bf16 v[66:69], v[178:181], v[214:217], 0
	v_mfma_f32_16x16x32_bf16 v[118:121], v[174:177], v[190:193], v[118:121]
	v_mfma_f32_16x16x32_bf16 v[114:117], v[182:185], v[190:193], v[114:117]
	v_mfma_f32_16x16x32_bf16 v[102:105], v[174:177], v[198:201], v[102:105]
	v_mfma_f32_16x16x32_bf16 v[98:101], v[182:185], v[198:201], v[98:101]
	v_mfma_f32_16x16x32_bf16 v[86:89], v[174:177], v[210:213], v[86:89]
	v_mfma_f32_16x16x32_bf16 v[82:85], v[182:185], v[210:213], v[82:85]
	v_mfma_f32_16x16x32_bf16 v[70:73], v[174:177], v[218:221], v[70:73]
	v_mfma_f32_16x16x32_bf16 v[66:69], v[182:185], v[218:221], v[66:69]
	s_setprio 0
	s_barrier
	s_add_i32 s51, s42, s31
	v_lshl_add_u64 v[146:147], s[24:25], 0, v[134:135]
	s_mov_b32 m0, s51
	ds_read_b128 v[186:189], v152 offset:16384
	ds_read_b128 v[190:193], v152 offset:17408
	ds_read_b128 v[194:197], v152 offset:18432
	ds_read_b128 v[198:201], v152 offset:19456
	ds_read_b128 v[202:205], v152 offset:20480
	ds_read_b128 v[210:213], v152 offset:21504
	ds_read_b128 v[214:217], v152 offset:22528
	ds_read_b128 v[218:221], v152 offset:23552
	global_load_lds_dwordx4 v[146:147], off
	s_add_i32 m0, s51, 0x2000
	s_add_u32 s52, s24, 0x80000
	v_lshl_add_u64 v[206:207], s[24:25], 0, v[130:131]
	s_addc_u32 s53, s25, 0
	s_add_i32 s51, s43, s31
	global_load_lds_dwordx4 v[206:207], off
	v_lshl_add_u64 v[222:223], s[52:53], 0, v[134:135]
	s_mov_b32 m0, s51
	v_lshl_add_u64 v[224:225], s[26:27], 0, v[132:133]
	global_load_lds_dwordx4 v[222:223], off
	v_lshl_add_u64 v[222:223], s[52:53], 0, v[130:131]
	s_add_i32 m0, s51, 0x2000
	s_nop 0
	global_load_lds_dwordx4 v[222:223], off
	v_lshl_add_u64 v[222:223], s[26:27], 0, v[136:137]
	s_mov_b32 m0, s21
	s_nop 0
	global_load_lds_dwordx4 v[222:223], off
	s_mov_b32 m0, s35
	s_nop 0
	global_load_lds_dwordx4 v[224:225], off
	s_waitcnt vmcnt(8)
	s_waitcnt lgkmcnt(0)
	s_barrier
; #define PG8_STAGE(bufoff, gbase, voff) do { _Pragma("unroll") for (int _i = 0; _i < 2; ++_i) \
;         __builtin_amdgcn_global_load_lds((const unsigned*)((const char*)(gbase) + (voff)[_i]), (PG8_LAS unsigned*)(lds + (bufoff) + ldsw + _i * 8192), 16, 0, 0); } while (0)
; #define PG8_LDA(dst, b, h) do { _Pragma("unroll") for (int m = 0; m < 4; ++m) _Pragma("unroll") for (int k = 0; k < 2; ++k) dst[m][k] = *(const PG8_LAS bf16x8*)(lds + PG8_SA(b, h) + aoff + m * 2048 + k * 1024); } while (0)
; #define PG8_LDB(dst, b, h) do { _Pragma("unroll") for (int n = 0; n < 2; ++n) _Pragma("unroll") for (int k = 0; k < 2; ++k) dst[n][k] = *(const PG8_LAS bf16x8*)(lds + PG8_SB(b, h) + boff + n * 2048 + k * 1024); } while (0)
; #define PG8_MMA(ai, bj, At, Bt) do { __builtin_amdgcn_s_setprio(1); _Pragma("unroll") for (int m = 0; m < 4; ++m) _Pragma("unroll") for (int n = 0; n < 2; ++n) _Pragma("unroll") for (int k = 0; k < 2; ++k) \
;         acc[ai][bj][m][n] = __builtin_amdgcn_mfma_f32_16x16x32_bf16(Bt[n][k], At[m][k], acc[ai][bj][m][n], 0, 0, 0); __builtin_amdgcn_s_setprio(0); } while (0)
; #define PG8_WAIT_V(n) asm volatile("s_waitcnt vmcnt(" #n ")" ::: "memory")
; #define PG8_WAIT_L(n) asm volatile("s_waitcnt lgkmcnt(" #n ")" ::: "memory")
; #define PG8_BAR __builtin_amdgcn_s_barrier()
; #define PG8_SCHED __builtin_amdgcn_sched_barrier(0)
; template <class Epi, class Sched, bool ALIGN_EPI = false, bool SP2 = false>
; __device__ __forceinline__ void gemm_phase(PG8_LAS unsigned char* lds, const Gemm g, const Sched& S, const Epi& E) {
;     ...
;             PG8_WAIT_V(8); PG8_WAIT_L(0); PG8_BAR; PG8_MMA(1, 0, At, B0); PG8_MMA(1, 1, At, B1); PG8_BAR; PG8_SCHED;
;             PG8_LDB(B0, 1, 0); PG8_LDB(B1, 1, 1); PG8_SCHED; PG8_LDA(At, 1, 0); PG8_STAGE(PG8_SA(0, 1), a2 + hstepA, voffA);
;             PG8_WAIT_V(8); PG8_WAIT_L(0); PG8_BAR; PG8_MMA(0, 0, At, B0); PG8_MMA(0, 1, At, B1); PG8_BAR; PG8_SCHED;
	s_setprio 1
	s_waitcnt lgkmcnt(0)
	v_mfma_f32_16x16x32_bf16 v[62:65], v[154:157], v[186:189], 0
	v_mfma_f32_16x16x32_bf16 v[58:61], v[162:165], v[186:189], 0
	v_mfma_f32_16x16x32_bf16 v[46:49], v[154:157], v[194:197], 0
	v_mfma_f32_16x16x32_bf16 v[42:45], v[162:165], v[194:197], 0
	v_mfma_f32_16x16x32_bf16 v[30:33], v[154:157], v[202:205], 0
	v_mfma_f32_16x16x32_bf16 v[26:29], v[162:165], v[202:205], 0
	v_mfma_f32_16x16x32_bf16 v[14:17], v[154:157], v[214:217], 0
	v_mfma_f32_16x16x32_bf16 v[10:13], v[162:165], v[214:217], 0
	v_mfma_f32_16x16x32_bf16 v[62:65], v[158:161], v[190:193], v[62:65]
	v_mfma_f32_16x16x32_bf16 v[58:61], v[166:169], v[190:193], v[58:61]
	v_mfma_f32_16x16x32_bf16 v[46:49], v[158:161], v[198:201], v[46:49]
	v_mfma_f32_16x16x32_bf16 v[42:45], v[166:169], v[198:201], v[42:45]
	v_mfma_f32_16x16x32_bf16 v[30:33], v[158:161], v[210:213], v[30:33]
	v_mfma_f32_16x16x32_bf16 v[26:29], v[166:169], v[210:213], v[26:29]
	v_mfma_f32_16x16x32_bf16 v[14:17], v[158:161], v[218:221], v[14:17]
	v_mfma_f32_16x16x32_bf16 v[10:13], v[166:169], v[218:221], v[10:13]
	s_setprio 0
	s_setprio 1
	v_mfma_f32_16x16x32_bf16 v[54:57], v[170:173], v[186:189], 0
	v_mfma_f32_16x16x32_bf16 v[50:53], v[178:181], v[186:189], 0
	v_mfma_f32_16x16x32_bf16 v[38:41], v[170:173], v[194:197], 0
	v_mfma_f32_16x16x32_bf16 v[34:37], v[178:181], v[194:197], 0
	v_mfma_f32_16x16x32_bf16 v[22:25], v[170:173], v[202:205], 0
	v_mfma_f32_16x16x32_bf16 v[18:21], v[178:181], v[202:205], 0
	v_mfma_f32_16x16x32_bf16 v[6:9], v[170:173], v[214:217], 0
	v_mfma_f32_16x16x32_bf16 v[2:5], v[178:181], v[214:217], 0
	v_mfma_f32_16x16x32_bf16 v[54:57], v[174:177], v[190:193], v[54:57]
	v_mfma_f32_16x16x32_bf16 v[50:53], v[182:185], v[190:193], v[50:53]
	v_mfma_f32_16x16x32_bf16 v[38:41], v[174:177], v[198:201], v[38:41]
	v_mfma_f32_16x16x32_bf16 v[34:37], v[182:185], v[198:201], v[34:37]
	v_mfma_f32_16x16x32_bf16 v[22:25], v[174:177], v[210:213], v[22:25]
	v_mfma_f32_16x16x32_bf16 v[18:21], v[182:185], v[210:213], v[18:21]
	v_mfma_f32_16x16x32_bf16 v[6:9], v[174:177], v[218:221], v[6:9]
	v_mfma_f32_16x16x32_bf16 v[2:5], v[182:185], v[218:221], v[2:5]
	s_setprio 0
	s_barrier
	s_add_i32 s51, 0, 0x18000
	v_add_u32_e32 v153, s51, v148
	s_add_i32 s52, 0, 0x1c000
	ds_read_b128 v[154:157], v153
	ds_read_b128 v[158:161], v153 offset:1024
	ds_read_b128 v[162:165], v153 offset:2048
	ds_read_b128 v[166:169], v153 offset:3072
	v_add_u32_e32 v153, s52, v148
	ds_read_b128 v[170:173], v153
	ds_read_b128 v[174:177], v153 offset:1024
	ds_read_b128 v[178:181], v153 offset:2048
	ds_read_b128 v[182:185], v153 offset:3072
	s_add_u32 s26, s26, 0x80000
	s_addc_u32 s27, s27, 0
	s_mov_b32 m0, s36
	v_lshl_add_u64 v[226:227], s[26:27], 0, v[136:137]
	ds_read_b128 v[186:189], v152 offset:32768
	ds_read_b128 v[190:193], v152 offset:33792
	ds_read_b128 v[194:197], v152 offset:34816
	ds_read_b128 v[198:201], v152 offset:35840
	ds_read_b128 v[202:205], v152 offset:36864
	ds_read_b128 v[210:213], v152 offset:37888
	ds_read_b128 v[214:217], v152 offset:38912
	ds_read_b128 v[218:221], v152 offset:39936
	global_load_lds_dwordx4 v[226:227], off
	v_lshl_add_u64 v[226:227], s[26:27], 0, v[132:133]
	s_mov_b32 m0, s37
	s_nop 0
	global_load_lds_dwordx4 v[226:227], off
	s_waitcnt vmcnt(8)
	s_waitcnt lgkmcnt(0)
	s_barrier
	s_setprio 1
	s_waitcnt lgkmcnt(0)
	v_mfma_f32_16x16x32_bf16 v[126:129], v[154:157], v[186:189], v[126:129]
	v_mfma_f32_16x16x32_bf16 v[122:125], v[162:165], v[186:189], v[122:125]
	v_mfma_f32_16x16x32_bf16 v[110:113], v[154:157], v[194:197], v[110:113]
	v_mfma_f32_16x16x32_bf16 v[106:109], v[162:165], v[194:197], v[106:109]
	v_mfma_f32_16x16x32_bf16 v[94:97], v[154:157], v[202:205], v[94:97]
	v_mfma_f32_16x16x32_bf16 v[90:93], v[162:165], v[202:205], v[90:93]
	v_mfma_f32_16x16x32_bf16 v[78:81], v[154:157], v[214:217], v[78:81]
	v_mfma_f32_16x16x32_bf16 v[74:77], v[162:165], v[214:217], v[74:77]
	v_mfma_f32_16x16x32_bf16 v[126:129], v[158:161], v[190:193], v[126:129]
	v_mfma_f32_16x16x32_bf16 v[122:125], v[166:169], v[190:193], v[122:125]
	v_mfma_f32_16x16x32_bf16 v[110:113], v[158:161], v[198:201], v[110:113]
	v_mfma_f32_16x16x32_bf16 v[106:109], v[166:169], v[198:201], v[106:109]
	v_mfma_f32_16x16x32_bf16 v[94:97], v[158:161], v[210:213], v[94:97]
	v_mfma_f32_16x16x32_bf16 v[90:93], v[166:169], v[210:213], v[90:93]
	v_mfma_f32_16x16x32_bf16 v[78:81], v[158:161], v[218:221], v[78:81]
	v_mfma_f32_16x16x32_bf16 v[74:77], v[166:169], v[218:221], v[74:77]
	s_setprio 0
	s_setprio 1
	v_mfma_f32_16x16x32_bf16 v[118:121], v[170:173], v[186:189], v[118:121]
	v_mfma_f32_16x16x32_bf16 v[114:117], v[178:181], v[186:189], v[114:117]
	v_mfma_f32_16x16x32_bf16 v[102:105], v[170:173], v[194:197], v[102:105]
	v_mfma_f32_16x16x32_bf16 v[98:101], v[178:181], v[194:197], v[98:101]
	v_mfma_f32_16x16x32_bf16 v[86:89], v[170:173], v[202:205], v[86:89]
	v_mfma_f32_16x16x32_bf16 v[82:85], v[178:181], v[202:205], v[82:85]
	v_mfma_f32_16x16x32_bf16 v[70:73], v[170:173], v[214:217], v[70:73]
	v_mfma_f32_16x16x32_bf16 v[66:69], v[178:181], v[214:217], v[66:69]
	v_mfma_f32_16x16x32_bf16 v[118:121], v[174:177], v[190:193], v[118:121]
	v_mfma_f32_16x16x32_bf16 v[114:117], v[182:185], v[190:193], v[114:117]
	v_mfma_f32_16x16x32_bf16 v[102:105], v[174:177], v[198:201], v[102:105]
	v_mfma_f32_16x16x32_bf16 v[98:101], v[182:185], v[198:201], v[98:101]
	v_mfma_f32_16x16x32_bf16 v[86:89], v[174:177], v[210:213], v[86:89]
	v_mfma_f32_16x16x32_bf16 v[82:85], v[182:185], v[210:213], v[82:85]
	v_mfma_f32_16x16x32_bf16 v[70:73], v[174:177], v[218:221], v[70:73]
	v_mfma_f32_16x16x32_bf16 v[66:69], v[182:185], v[218:221], v[66:69]
	s_setprio 0
	s_barrier
; #define PG8_STAGE(bufoff, gbase, voff) do { _Pragma("unroll") for (int _i = 0; _i < 2; ++_i) \
;         __builtin_amdgcn_global_load_lds((const unsigned*)((const char*)(gbase) + (voff)[_i]), (PG8_LAS unsigned*)(lds + (bufoff) + ldsw + _i * 8192), 16, 0, 0); } while (0)
; #define PG8_LDA(dst, b, h) do { _Pragma("unroll") for (int m = 0; m < 4; ++m) _Pragma("unroll") for (int k = 0; k < 2; ++k) dst[m][k] = *(const PG8_LAS bf16x8*)(lds + PG8_SA(b, h) + aoff + m * 2048 + k * 1024); } while (0)
; #define PG8_LDB(dst, b, h) do { _Pragma("unroll") for (int n = 0; n < 2; ++n) _Pragma("unroll") for (int k = 0; k < 2; ++k) dst[n][k] = *(const PG8_LAS bf16x8*)(lds + PG8_SB(b, h) + boff + n * 2048 + k * 1024); } while (0)
; template <class Epi, class Sched, bool ALIGN_EPI = false, bool SP2 = false>
; __device__ __forceinline__ void gemm_phase(PG8_LAS unsigned char* lds, const Gemm g, const Sched& S, const Epi& E) {
;     ...
;         for (int t = 0; t < nt; t += 2) {
;             const bool last = (t == nt - 2);
;             const char* a1 = cA + (size_t)(t + 1) * kstep;
;             const char* a2 = last ? nA : cA + (size_t)(t + 2) * kstep; const char* b2 = last ? nB : cB + (size_t)(t + 2) * kstep;
;             const char* a3 = a2 + kstep; const char* b3 = b2 + kstep;
;             if (last && has_next) S.a_ready(nxt);
;             if constexpr (SP2) {
;             PG8_LDB(B0, 0, 0); PG8_LDB(B1, 0, 1); PG8_SCHED; PG8_LDA(At, 0, 0); PG8_STAGE(PG8_SA(1, 1), a1 + hstepA, voffA);
;             PG8_WAIT_V(8); PG8_WAIT_L(0); PG8_BAR; PG8_MMA(0, 0, At, B0); PG8_MMA(0, 1, At, B1); PG8_BAR; PG8_SCHED;
;             PG8_LDA(At, 0, 1); PG8_STAGE(PG8_SB(0, 0), b2, voffB); PG8_STAGE(PG8_SB(0, 1), b2 + hstepB, voffB); PG8_STAGE(PG8_SA(0, 0), a2, voffA);
;             PG8_WAIT_V(8); PG8_WAIT_L(0); PG8_BAR; PG8_MMA(1, 0, At, B0); PG8_MMA(1, 1, At, B1); PG8_BAR; PG8_SCHED;
;             PG8_LDB(B0, 1, 0); PG8_LDB(B1, 1, 1); PG8_SCHED; PG8_LDA(At, 1, 0); PG8_STAGE(PG8_SA(0, 1), a2 + hstepA, voffA);
;             PG8_WAIT_V(8); PG8_WAIT_L(0); PG8_BAR; PG8_MMA(0, 0, At, B0); PG8_MMA(0, 1, At, B1); PG8_BAR; PG8_SCHED;
;             PG8_LDA(At, 1, 1); PG8_STAGE(PG8_SB(1, 0), b3, voffB); PG8_STAGE(PG8_SB(1, 1), b3 + hstepB, voffB); PG8_STAGE(PG8_SA(1, 0), a3, voffA);
;             PG8_WAIT_V(8); PG8_WAIT_L(0); PG8_BAR; PG8_MMA(1, 0, At, B0); PG8_MMA(1, 1, At, B1); PG8_BAR; PG8_SCHED;
	s_add_i32 s26, s51, s31
	v_lshl_add_u64 v[146:147], v[146:147], 0, s[2:3]
	s_mov_b32 m0, s26
	ds_read_b128 v[186:189], v152 offset:49152
	ds_read_b128 v[190:193], v152 offset:50176
	ds_read_b128 v[194:197], v152 offset:51200
	ds_read_b128 v[198:201], v152 offset:52224
	ds_read_b128 v[202:205], v152 offset:53248
	ds_read_b128 v[210:213], v152 offset:54272
	ds_read_b128 v[214:217], v152 offset:55296
	ds_read_b128 v[218:221], v152 offset:56320
	global_load_lds_dwordx4 v[146:147], off
	s_add_i32 m0, s26, 0x2000
	s_add_u32 s24, s24, 0x80080
	v_lshl_add_u64 v[146:147], v[206:207], 0, s[2:3]
	s_addc_u32 s25, s25, 0
	s_add_i32 s26, s52, s31
	global_load_lds_dwordx4 v[146:147], off
	v_lshl_add_u64 v[146:147], s[24:25], 0, v[134:135]
	s_mov_b32 m0, s26
	s_nop 0
	global_load_lds_dwordx4 v[146:147], off
	v_lshl_add_u64 v[146:147], s[24:25], 0, v[130:131]
	s_add_i32 m0, s26, 0x2000
	s_nop 0
	global_load_lds_dwordx4 v[146:147], off
	v_lshl_add_u64 v[146:147], v[222:223], 0, s[2:3]
	s_mov_b32 m0, s39
	s_nop 0
	global_load_lds_dwordx4 v[146:147], off
	v_lshl_add_u64 v[146:147], v[224:225], 0, s[2:3]
	s_mov_b32 m0, s40
	s_nop 0
	global_load_lds_dwordx4 v[146:147], off
	s_waitcnt vmcnt(8)
	s_waitcnt lgkmcnt(0)
	s_barrier
	s_setprio 1
	s_waitcnt lgkmcnt(0)
	v_mfma_f32_16x16x32_bf16 v[62:65], v[154:157], v[186:189], v[62:65]
	v_mfma_f32_16x16x32_bf16 v[58:61], v[162:165], v[186:189], v[58:61]
	v_mfma_f32_16x16x32_bf16 v[46:49], v[154:157], v[194:197], v[46:49]
	v_mfma_f32_16x16x32_bf16 v[42:45], v[162:165], v[194:197], v[42:45]
	v_mfma_f32_16x16x32_bf16 v[30:33], v[154:157], v[202:205], v[30:33]
	v_mfma_f32_16x16x32_bf16 v[26:29], v[162:165], v[202:205], v[26:29]
	v_mfma_f32_16x16x32_bf16 v[14:17], v[154:157], v[214:217], v[14:17]
	v_mfma_f32_16x16x32_bf16 v[10:13], v[162:165], v[214:217], v[10:13]
	v_mfma_f32_16x16x32_bf16 v[62:65], v[158:161], v[190:193], v[62:65]
	v_mfma_f32_16x16x32_bf16 v[58:61], v[166:169], v[190:193], v[58:61]
	v_mfma_f32_16x16x32_bf16 v[46:49], v[158:161], v[198:201], v[46:49]
	v_mfma_f32_16x16x32_bf16 v[42:45], v[166:169], v[198:201], v[42:45]
	v_mfma_f32_16x16x32_bf16 v[30:33], v[158:161], v[210:213], v[30:33]
	v_mfma_f32_16x16x32_bf16 v[26:29], v[166:169], v[210:213], v[26:29]
	v_mfma_f32_16x16x32_bf16 v[14:17], v[158:161], v[218:221], v[14:17]
	v_mfma_f32_16x16x32_bf16 v[10:13], v[166:169], v[218:221], v[10:13]
	s_setprio 0
	s_setprio 1
	v_mfma_f32_16x16x32_bf16 v[54:57], v[170:173], v[186:189], v[54:57]
	v_mfma_f32_16x16x32_bf16 v[50:53], v[178:181], v[186:189], v[50:53]
	v_mfma_f32_16x16x32_bf16 v[38:41], v[170:173], v[194:197], v[38:41]
	v_mfma_f32_16x16x32_bf16 v[34:37], v[178:181], v[194:197], v[34:37]
	v_mfma_f32_16x16x32_bf16 v[22:25], v[170:173], v[202:205], v[22:25]
	v_mfma_f32_16x16x32_bf16 v[18:21], v[178:181], v[202:205], v[18:21]
	v_mfma_f32_16x16x32_bf16 v[6:9], v[170:173], v[214:217], v[6:9]
	v_mfma_f32_16x16x32_bf16 v[2:5], v[178:181], v[214:217], v[2:5]
	v_mfma_f32_16x16x32_bf16 v[54:57], v[174:177], v[190:193], v[54:57]
	v_mfma_f32_16x16x32_bf16 v[50:53], v[182:185], v[190:193], v[50:53]
	v_mfma_f32_16x16x32_bf16 v[38:41], v[174:177], v[198:201], v[38:41]
	v_mfma_f32_16x16x32_bf16 v[34:37], v[182:185], v[198:201], v[34:37]
	v_mfma_f32_16x16x32_bf16 v[22:25], v[174:177], v[210:213], v[22:25]
	v_mfma_f32_16x16x32_bf16 v[18:21], v[182:185], v[210:213], v[18:21]
	v_mfma_f32_16x16x32_bf16 v[6:9], v[174:177], v[218:221], v[6:9]
	v_mfma_f32_16x16x32_bf16 v[2:5], v[182:185], v[218:221], v[2:5]
	s_setprio 0
	s_barrier
	s_add_i32 s50, s50, 2
	s_add_u32 s22, s22, 0x100
	s_addc_u32 s23, s23, 0
	s_add_u32 s48, s48, 0x100
	s_addc_u32 s49, s49, 0
	s_cmp_gt_u32 s50, 29
	s_cbranch_scc1 .Lpeel_exit_16
	.p2align 6

; #define PG8_STAGE(bufoff, gbase, voff) do { _Pragma("unroll") for (int _i = 0; _i < 2; ++_i) \
;         __builtin_amdgcn_global_load_lds((const unsigned*)((const char*)(gbase) + (voff)[_i]), (PG8_LAS unsigned*)(lds + (bufoff) + ldsw + _i * 8192), 16, 0, 0); } while (0)
; #define PG8_LDA(dst, b, h) do { _Pragma("unroll") for (int m = 0; m < 4; ++m) _Pragma("unroll") for (int k = 0; k < 2; ++k) dst[m][k] = *(const PG8_LAS bf16x8*)(lds + PG8_SA(b, h) + aoff + m * 2048 + k * 1024); } while (0)
; #define PG8_LDB(dst, b, h) do { _Pragma("unroll") for (int n = 0; n < 2; ++n) _Pragma("unroll") for (int k = 0; k < 2; ++k) dst[n][k] = *(const PG8_LAS bf16x8*)(lds + PG8_SB(b, h) + boff + n * 2048 + k * 1024); } while (0)
; #define PG8_MMA(ai, bj, At, Bt) do { __builtin_amdgcn_s_setprio(1); _Pragma("unroll") for (int m = 0; m < 4; ++m) _Pragma("unroll") for (int n = 0; n < 2; ++n) _Pragma("unroll") for (int k = 0; k < 2; ++k) \
;         acc[ai][bj][m][n] = __builtin_amdgcn_mfma_f32_16x16x32_bf16(Bt[n][k], At[m][k], acc[ai][bj][m][n], 0, 0, 0); __builtin_amdgcn_s_setprio(0); } while (0)
; #define PG8_BAR __builtin_amdgcn_s_barrier()
; template <class Epi, class Sched, bool ALIGN_EPI = false, bool SP2 = false>
; __device__ __forceinline__ void gemm_phase(PG8_LAS unsigned char* lds, const Gemm g, const Sched& S, const Epi& E) {
;     ...
;         const bool has_next = S.next(ui + 1, nxt);
;         const char* nA = has_next ? (const char*)g.A + (size_t)nxt.pm * tstepA : cA; const char* nB = has_next ? (const char*)g.Bt + (size_t)nxt.pn * tstepB : cB;
;         for (int t = 0; t < nt; t += 2) {
;             const bool last = (t == nt - 2);
;             const char* a1 = cA + (size_t)(t + 1) * kstep;
;             const char* a2 = last ? nA : cA + (size_t)(t + 2) * kstep; const char* b2 = last ? nB : cB + (size_t)(t + 2) * kstep;
;             const char* a3 = a2 + kstep; const char* b3 = b2 + kstep;
;             if (last && has_next) S.a_ready(nxt);
;             if constexpr (SP2) {
;             PG8_LDB(B0, 0, 0); PG8_LDB(B1, 0, 1); PG8_SCHED; PG8_LDA(At, 0, 0); PG8_STAGE(PG8_SA(1, 1), a1 + hstepA, voffA);
;             PG8_WAIT_V(8); PG8_WAIT_L(0); PG8_BAR; PG8_MMA(0, 0, At, B0); PG8_MMA(0, 1, At, B1); PG8_BAR; PG8_SCHED;
;             PG8_LDA(At, 0, 1); PG8_STAGE(PG8_SB(0, 0), b2, voffB); PG8_STAGE(PG8_SB(0, 1), b2 + hstepB, voffB); PG8_STAGE(PG8_SA(0, 0), a2, voffA);
.LBB0_1707:
	s_add_u32 s24, s24, 0x160080
	s_addc_u32 s25, s25, 0
	s_add_u32 s55, s26, 0x100
	s_addc_u32 s56, s27, 0
	s_mov_b32 s57, -2
	ds_read_b128 v[152:155], v148
	ds_read_b128 v[156:159], v148 offset:1024
	ds_read_b128 v[160:163], v148 offset:2048
	ds_read_b128 v[164:167], v148 offset:3072
	ds_read_b128 v[168:171], v149
	ds_read_b128 v[172:175], v149 offset:1024
	ds_read_b128 v[176:179], v149 offset:2048
	ds_read_b128 v[180:183], v149 offset:3072
	s_add_u32 s26, s24, 0xffea0080
	s_addc_u32 s27, s25, -1
	s_cmpk_eq_i32 s57, 0x54
	s_cselect_b32 s29, s7, s27
	s_cselect_b32 s28, s6, s26
	s_cselect_b32 s27, s23, s56
	s_cselect_b32 s26, s22, s55
	v_lshl_add_u64 v[218:219], s[24:25], 0, v[138:139]
	s_add_i32 m0, s37, 0xc000
	ds_read_b128 v[184:187], v150
	ds_read_b128 v[188:191], v150 offset:1024
	ds_read_b128 v[192:195], v150 offset:2048
	ds_read_b128 v[196:199], v150 offset:3072
	ds_read_b128 v[200:203], v150 offset:4096
	ds_read_b128 v[204:207], v150 offset:5120
	ds_read_b128 v[210:213], v150 offset:6144
	ds_read_b128 v[214:217], v150 offset:7168
	global_load_lds_dwordx4 v[218:219], off
	v_lshl_add_u64 v[218:219], s[24:25], 0, v[140:141]
	s_add_i32 m0, s37, 0xe000
	s_nop 0
	global_load_lds_dwordx4 v[218:219], off
	s_waitcnt vmcnt(8)
	s_waitcnt lgkmcnt(0)
	s_barrier
	s_setprio 1
	s_waitcnt lgkmcnt(0)
	v_mfma_f32_16x16x32_bf16 v[126:129], v[152:155], v[184:187], 0
	v_mfma_f32_16x16x32_bf16 v[122:125], v[160:163], v[184:187], 0
	v_mfma_f32_16x16x32_bf16 v[118:121], v[152:155], v[192:195], 0
	v_mfma_f32_16x16x32_bf16 v[114:117], v[160:163], v[192:195], 0
	v_mfma_f32_16x16x32_bf16 v[102:105], v[152:155], v[200:203], 0
	v_mfma_f32_16x16x32_bf16 v[98:101], v[160:163], v[200:203], 0
	v_mfma_f32_16x16x32_bf16 v[86:89], v[152:155], v[210:213], 0
	v_mfma_f32_16x16x32_bf16 v[82:85], v[160:163], v[210:213], 0
	v_mfma_f32_16x16x32_bf16 v[126:129], v[156:159], v[188:191], v[126:129]
	v_mfma_f32_16x16x32_bf16 v[122:125], v[164:167], v[188:191], v[122:125]
	v_mfma_f32_16x16x32_bf16 v[118:121], v[156:159], v[196:199], v[118:121]
	v_mfma_f32_16x16x32_bf16 v[114:117], v[164:167], v[196:199], v[114:117]
	v_mfma_f32_16x16x32_bf16 v[102:105], v[156:159], v[204:207], v[102:105]
	v_mfma_f32_16x16x32_bf16 v[98:101], v[164:167], v[204:207], v[98:101]
	v_mfma_f32_16x16x32_bf16 v[86:89], v[156:159], v[214:217], v[86:89]
	v_mfma_f32_16x16x32_bf16 v[82:85], v[164:167], v[214:217], v[82:85]
	s_setprio 0
	s_setprio 1
	v_mfma_f32_16x16x32_bf16 v[110:113], v[168:171], v[184:187], 0
	v_mfma_f32_16x16x32_bf16 v[106:109], v[176:179], v[184:187], 0
	v_mfma_f32_16x16x32_bf16 v[94:97], v[168:171], v[192:195], 0
	v_mfma_f32_16x16x32_bf16 v[90:93], v[176:179], v[192:195], 0
	v_mfma_f32_16x16x32_bf16 v[78:81], v[168:171], v[200:203], 0
	v_mfma_f32_16x16x32_bf16 v[74:77], v[176:179], v[200:203], 0
	v_mfma_f32_16x16x32_bf16 v[70:73], v[168:171], v[210:213], 0
	v_mfma_f32_16x16x32_bf16 v[66:69], v[176:179], v[210:213], 0
	v_mfma_f32_16x16x32_bf16 v[110:113], v[172:175], v[188:191], v[110:113]
	v_mfma_f32_16x16x32_bf16 v[106:109], v[180:183], v[188:191], v[106:109]
	v_mfma_f32_16x16x32_bf16 v[94:97], v[172:175], v[196:199], v[94:97]
	v_mfma_f32_16x16x32_bf16 v[90:93], v[180:183], v[196:199], v[90:93]
	v_mfma_f32_16x16x32_bf16 v[78:81], v[172:175], v[204:207], v[78:81]
	v_mfma_f32_16x16x32_bf16 v[74:77], v[180:183], v[204:207], v[74:77]
	v_mfma_f32_16x16x32_bf16 v[70:73], v[172:175], v[214:217], v[70:73]
	v_mfma_f32_16x16x32_bf16 v[66:69], v[180:183], v[214:217], v[66:69]
	s_setprio 0
	s_barrier
	s_add_i32 s58, s45, s34
	v_lshl_add_u64 v[218:219], s[26:27], 0, v[134:135]
	s_mov_b32 m0, s58
	ds_read_b128 v[184:187], v150 offset:16384
	ds_read_b128 v[188:191], v150 offset:17408
	ds_read_b128 v[192:195], v150 offset:18432
	ds_read_b128 v[196:199], v150 offset:19456
	ds_read_b128 v[200:203], v150 offset:20480
	ds_read_b128 v[204:207], v150 offset:21504
	ds_read_b128 v[210:213], v150 offset:22528
	ds_read_b128 v[214:217], v150 offset:23552
	global_load_lds_dwordx4 v[218:219], off
	s_add_i32 m0, s58, 0x2000
	s_add_u32 s58, s26, 0x160000
	v_lshl_add_u64 v[220:221], s[26:27], 0, v[130:131]
	s_addc_u32 s59, s27, 0
	s_add_i32 s60, s46, s34
	global_load_lds_dwordx4 v[220:221], off
	v_lshl_add_u64 v[222:223], s[58:59], 0, v[134:135]
	s_mov_b32 m0, s60
	v_lshl_add_u64 v[224:225], s[28:29], 0, v[132:133]
	global_load_lds_dwordx4 v[222:223], off
	v_lshl_add_u64 v[222:223], s[58:59], 0, v[130:131]
	s_add_i32 m0, s60, 0x2000
	s_nop 0
	global_load_lds_dwordx4 v[222:223], off
	v_lshl_add_u64 v[222:223], s[28:29], 0, v[136:137]
	s_mov_b32 m0, s37
	s_nop 0
	global_load_lds_dwordx4 v[222:223], off
	s_mov_b32 m0, s38
	s_nop 0
	global_load_lds_dwordx4 v[224:225], off
	s_waitcnt vmcnt(8)
	s_waitcnt lgkmcnt(0)
	s_barrier
; #define PG8_STAGE(bufoff, gbase, voff) do { _Pragma("unroll") for (int _i = 0; _i < 2; ++_i) \
;         __builtin_amdgcn_global_load_lds((const unsigned*)((const char*)(gbase) + (voff)[_i]), (PG8_LAS unsigned*)(lds + (bufoff) + ldsw + _i * 8192), 16, 0, 0); } while (0)
; #define PG8_LDA(dst, b, h) do { _Pragma("unroll") for (int m = 0; m < 4; ++m) _Pragma("unroll") for (int k = 0; k < 2; ++k) dst[m][k] = *(const PG8_LAS bf16x8*)(lds + PG8_SA(b, h) + aoff + m * 2048 + k * 1024); } while (0)
; #define PG8_LDB(dst, b, h) do { _Pragma("unroll") for (int n = 0; n < 2; ++n) _Pragma("unroll") for (int k = 0; k < 2; ++k) dst[n][k] = *(const PG8_LAS bf16x8*)(lds + PG8_SB(b, h) + boff + n * 2048 + k * 1024); } while (0)
; #define PG8_MMA(ai, bj, At, Bt) do { __builtin_amdgcn_s_setprio(1); _Pragma("unroll") for (int m = 0; m < 4; ++m) _Pragma("unroll") for (int n = 0; n < 2; ++n) _Pragma("unroll") for (int k = 0; k < 2; ++k) \
;         acc[ai][bj][m][n] = __builtin_amdgcn_mfma_f32_16x16x32_bf16(Bt[n][k], At[m][k], acc[ai][bj][m][n], 0, 0, 0); __builtin_amdgcn_s_setprio(0); } while (0)
; #define PG8_WAIT_V(n) asm volatile("s_waitcnt vmcnt(" #n ")" ::: "memory")
; #define PG8_WAIT_L(n) asm volatile("s_waitcnt lgkmcnt(" #n ")" ::: "memory")
; #define PG8_BAR __builtin_amdgcn_s_barrier()
; #define PG8_SCHED __builtin_amdgcn_sched_barrier(0)
; template <class Epi, class Sched, bool ALIGN_EPI = false, bool SP2 = false>
; __device__ __forceinline__ void gemm_phase(PG8_LAS unsigned char* lds, const Gemm g, const Sched& S, const Epi& E) {
;     ...
;             PG8_LDA(At, 0, 1); PG8_STAGE(PG8_SB(0, 0), b2, voffB); PG8_STAGE(PG8_SB(0, 1), b2 + hstepB, voffB); PG8_STAGE(PG8_SA(0, 0), a2, voffA);
;             PG8_WAIT_V(8); PG8_WAIT_L(0); PG8_BAR; PG8_MMA(1, 0, At, B0); PG8_MMA(1, 1, At, B1); PG8_BAR; PG8_SCHED;
;             PG8_LDB(B0, 1, 0); PG8_LDB(B1, 1, 1); PG8_SCHED; PG8_LDA(At, 1, 0); PG8_STAGE(PG8_SA(0, 1), a2 + hstepA, voffA);
;             PG8_WAIT_V(8); PG8_WAIT_L(0); PG8_BAR; PG8_MMA(0, 0, At, B0); PG8_MMA(0, 1, At, B1); PG8_BAR; PG8_SCHED;
	s_setprio 1
	s_waitcnt lgkmcnt(0)
	v_mfma_f32_16x16x32_bf16 v[62:65], v[152:155], v[184:187], 0
	v_mfma_f32_16x16x32_bf16 v[58:61], v[160:163], v[184:187], 0
	v_mfma_f32_16x16x32_bf16 v[54:57], v[152:155], v[192:195], 0
	v_mfma_f32_16x16x32_bf16 v[50:53], v[160:163], v[192:195], 0
	v_mfma_f32_16x16x32_bf16 v[38:41], v[152:155], v[200:203], 0
	v_mfma_f32_16x16x32_bf16 v[34:37], v[160:163], v[200:203], 0
	v_mfma_f32_16x16x32_bf16 v[22:25], v[152:155], v[210:213], 0
	v_mfma_f32_16x16x32_bf16 v[18:21], v[160:163], v[210:213], 0
	v_mfma_f32_16x16x32_bf16 v[62:65], v[156:159], v[188:191], v[62:65]
	v_mfma_f32_16x16x32_bf16 v[58:61], v[164:167], v[188:191], v[58:61]
	v_mfma_f32_16x16x32_bf16 v[54:57], v[156:159], v[196:199], v[54:57]
	v_mfma_f32_16x16x32_bf16 v[50:53], v[164:167], v[196:199], v[50:53]
	v_mfma_f32_16x16x32_bf16 v[38:41], v[156:159], v[204:207], v[38:41]
	v_mfma_f32_16x16x32_bf16 v[34:37], v[164:167], v[204:207], v[34:37]
	v_mfma_f32_16x16x32_bf16 v[22:25], v[156:159], v[214:217], v[22:25]
	v_mfma_f32_16x16x32_bf16 v[18:21], v[164:167], v[214:217], v[18:21]
	s_setprio 0
	s_setprio 1
	v_mfma_f32_16x16x32_bf16 v[46:49], v[168:171], v[184:187], 0
	v_mfma_f32_16x16x32_bf16 v[42:45], v[176:179], v[184:187], 0
	v_mfma_f32_16x16x32_bf16 v[30:33], v[168:171], v[192:195], 0
	v_mfma_f32_16x16x32_bf16 v[26:29], v[176:179], v[192:195], 0
	v_mfma_f32_16x16x32_bf16 v[14:17], v[168:171], v[200:203], 0
	v_mfma_f32_16x16x32_bf16 v[10:13], v[176:179], v[200:203], 0
	v_mfma_f32_16x16x32_bf16 v[6:9], v[168:171], v[210:213], 0
	v_mfma_f32_16x16x32_bf16 v[2:5], v[176:179], v[210:213], 0
	v_mfma_f32_16x16x32_bf16 v[46:49], v[172:175], v[188:191], v[46:49]
	v_mfma_f32_16x16x32_bf16 v[42:45], v[180:183], v[188:191], v[42:45]
	v_mfma_f32_16x16x32_bf16 v[30:33], v[172:175], v[196:199], v[30:33]
	v_mfma_f32_16x16x32_bf16 v[26:29], v[180:183], v[196:199], v[26:29]
	v_mfma_f32_16x16x32_bf16 v[14:17], v[172:175], v[204:207], v[14:17]
	v_mfma_f32_16x16x32_bf16 v[10:13], v[180:183], v[204:207], v[10:13]
	v_mfma_f32_16x16x32_bf16 v[6:9], v[172:175], v[214:217], v[6:9]
	v_mfma_f32_16x16x32_bf16 v[2:5], v[180:183], v[214:217], v[2:5]
	s_setprio 0
	s_barrier
	s_add_i32 s58, 0, 0x18000
	v_add_u32_e32 v151, s58, v146
	s_add_i32 s59, 0, 0x1c000
	ds_read_b128 v[152:155], v151
	ds_read_b128 v[156:159], v151 offset:1024
	ds_read_b128 v[160:163], v151 offset:2048
	ds_read_b128 v[164:167], v151 offset:3072
	v_add_u32_e32 v151, s59, v146
	ds_read_b128 v[168:171], v151
	ds_read_b128 v[172:175], v151 offset:1024
	ds_read_b128 v[176:179], v151 offset:2048
	ds_read_b128 v[180:183], v151 offset:3072
	s_add_u32 s28, s28, 0x160000
	s_addc_u32 s29, s29, 0
	s_mov_b32 m0, s39
	v_lshl_add_u64 v[226:227], s[28:29], 0, v[136:137]
	ds_read_b128 v[184:187], v150 offset:32768
	ds_read_b128 v[188:191], v150 offset:33792
	ds_read_b128 v[192:195], v150 offset:34816
	ds_read_b128 v[196:199], v150 offset:35840
	ds_read_b128 v[200:203], v150 offset:36864
	ds_read_b128 v[204:207], v150 offset:37888
	ds_read_b128 v[210:213], v150 offset:38912
	ds_read_b128 v[214:217], v150 offset:39936
	global_load_lds_dwordx4 v[226:227], off
	v_lshl_add_u64 v[226:227], s[28:29], 0, v[132:133]
	s_mov_b32 m0, s40
	s_nop 0
	global_load_lds_dwordx4 v[226:227], off
	s_waitcnt vmcnt(8)
	s_waitcnt lgkmcnt(0)
	s_barrier
	s_setprio 1
	s_waitcnt lgkmcnt(0)
	v_mfma_f32_16x16x32_bf16 v[126:129], v[152:155], v[184:187], v[126:129]
	v_mfma_f32_16x16x32_bf16 v[122:125], v[160:163], v[184:187], v[122:125]
	v_mfma_f32_16x16x32_bf16 v[118:121], v[152:155], v[192:195], v[118:121]
	v_mfma_f32_16x16x32_bf16 v[114:117], v[160:163], v[192:195], v[114:117]
	v_mfma_f32_16x16x32_bf16 v[102:105], v[152:155], v[200:203], v[102:105]
	v_mfma_f32_16x16x32_bf16 v[98:101], v[160:163], v[200:203], v[98:101]
	v_mfma_f32_16x16x32_bf16 v[86:89], v[152:155], v[210:213], v[86:89]
	v_mfma_f32_16x16x32_bf16 v[82:85], v[160:163], v[210:213], v[82:85]
	v_mfma_f32_16x16x32_bf16 v[126:129], v[156:159], v[188:191], v[126:129]
	v_mfma_f32_16x16x32_bf16 v[122:125], v[164:167], v[188:191], v[122:125]
	v_mfma_f32_16x16x32_bf16 v[118:121], v[156:159], v[196:199], v[118:121]
	v_mfma_f32_16x16x32_bf16 v[114:117], v[164:167], v[196:199], v[114:117]
	v_mfma_f32_16x16x32_bf16 v[102:105], v[156:159], v[204:207], v[102:105]
	v_mfma_f32_16x16x32_bf16 v[98:101], v[164:167], v[204:207], v[98:101]
	v_mfma_f32_16x16x32_bf16 v[86:89], v[156:159], v[214:217], v[86:89]
	v_mfma_f32_16x16x32_bf16 v[82:85], v[164:167], v[214:217], v[82:85]
	s_setprio 0
	s_setprio 1
	v_mfma_f32_16x16x32_bf16 v[110:113], v[168:171], v[184:187], v[110:113]
	v_mfma_f32_16x16x32_bf16 v[106:109], v[176:179], v[184:187], v[106:109]
	v_mfma_f32_16x16x32_bf16 v[94:97], v[168:171], v[192:195], v[94:97]
	v_mfma_f32_16x16x32_bf16 v[90:93], v[176:179], v[192:195], v[90:93]
	v_mfma_f32_16x16x32_bf16 v[78:81], v[168:171], v[200:203], v[78:81]
	v_mfma_f32_16x16x32_bf16 v[74:77], v[176:179], v[200:203], v[74:77]
	v_mfma_f32_16x16x32_bf16 v[70:73], v[168:171], v[210:213], v[70:73]
	v_mfma_f32_16x16x32_bf16 v[66:69], v[176:179], v[210:213], v[66:69]
	v_mfma_f32_16x16x32_bf16 v[110:113], v[172:175], v[188:191], v[110:113]
	v_mfma_f32_16x16x32_bf16 v[106:109], v[180:183], v[188:191], v[106:109]
	v_mfma_f32_16x16x32_bf16 v[94:97], v[172:175], v[196:199], v[94:97]
	v_mfma_f32_16x16x32_bf16 v[90:93], v[180:183], v[196:199], v[90:93]
	v_mfma_f32_16x16x32_bf16 v[78:81], v[172:175], v[204:207], v[78:81]
	v_mfma_f32_16x16x32_bf16 v[74:77], v[180:183], v[204:207], v[74:77]
	v_mfma_f32_16x16x32_bf16 v[70:73], v[172:175], v[214:217], v[70:73]
	v_mfma_f32_16x16x32_bf16 v[66:69], v[180:183], v[214:217], v[66:69]
	s_setprio 0
	s_barrier
; #define PG8_STAGE(bufoff, gbase, voff) do { _Pragma("unroll") for (int _i = 0; _i < 2; ++_i) \
;         __builtin_amdgcn_global_load_lds((const unsigned*)((const char*)(gbase) + (voff)[_i]), (PG8_LAS unsigned*)(lds + (bufoff) + ldsw + _i * 8192), 16, 0, 0); } while (0)
; #define PG8_LDA(dst, b, h) do { _Pragma("unroll") for (int m = 0; m < 4; ++m) _Pragma("unroll") for (int k = 0; k < 2; ++k) dst[m][k] = *(const PG8_LAS bf16x8*)(lds + PG8_SA(b, h) + aoff + m * 2048 + k * 1024); } while (0)
; #define PG8_LDB(dst, b, h) do { _Pragma("unroll") for (int n = 0; n < 2; ++n) _Pragma("unroll") for (int k = 0; k < 2; ++k) dst[n][k] = *(const PG8_LAS bf16x8*)(lds + PG8_SB(b, h) + boff + n * 2048 + k * 1024); } while (0)
; template <class Epi, class Sched, bool ALIGN_EPI = false, bool SP2 = false>
; __device__ __forceinline__ void gemm_phase(PG8_LAS unsigned char* lds, const Gemm g, const Sched& S, const Epi& E) {
;     ...
;         for (int t = 0; t < nt; t += 2) {
;             const bool last = (t == nt - 2);
;             const char* a1 = cA + (size_t)(t + 1) * kstep;
;             const char* a2 = last ? nA : cA + (size_t)(t + 2) * kstep; const char* b2 = last ? nB : cB + (size_t)(t + 2) * kstep;
;             const char* a3 = a2 + kstep; const char* b3 = b2 + kstep;
;             if (last && has_next) S.a_ready(nxt);
;             if constexpr (SP2) {
;             PG8_LDB(B0, 0, 0); PG8_LDB(B1, 0, 1); PG8_SCHED; PG8_LDA(At, 0, 0); PG8_STAGE(PG8_SA(1, 1), a1 + hstepA, voffA);
;             PG8_WAIT_V(8); PG8_WAIT_L(0); PG8_BAR; PG8_MMA(0, 0, At, B0); PG8_MMA(0, 1, At, B1); PG8_BAR; PG8_SCHED;
;             PG8_LDA(At, 0, 1); PG8_STAGE(PG8_SB(0, 0), b2, voffB); PG8_STAGE(PG8_SB(0, 1), b2 + hstepB, voffB); PG8_STAGE(PG8_SA(0, 0), a2, voffA);
;             PG8_WAIT_V(8); PG8_WAIT_L(0); PG8_BAR; PG8_MMA(1, 0, At, B0); PG8_MMA(1, 1, At, B1); PG8_BAR; PG8_SCHED;
;             PG8_LDB(B0, 1, 0); PG8_LDB(B1, 1, 1); PG8_SCHED; PG8_LDA(At, 1, 0); PG8_STAGE(PG8_SA(0, 1), a2 + hstepA, voffA);
;             PG8_WAIT_V(8); PG8_WAIT_L(0); PG8_BAR; PG8_MMA(0, 0, At, B0); PG8_MMA(0, 1, At, B1); PG8_BAR; PG8_SCHED;
;             PG8_LDA(At, 1, 1); PG8_STAGE(PG8_SB(1, 0), b3, voffB); PG8_STAGE(PG8_SB(1, 1), b3 + hstepB, voffB); PG8_STAGE(PG8_SA(1, 0), a3, voffA);
;             PG8_WAIT_V(8); PG8_WAIT_L(0); PG8_BAR; PG8_MMA(1, 0, At, B0); PG8_MMA(1, 1, At, B1); PG8_BAR; PG8_SCHED;
	s_add_i32 s28, s58, s34
	v_lshl_add_u64 v[218:219], v[218:219], 0, s[8:9]
	s_mov_b32 m0, s28
	ds_read_b128 v[184:187], v150 offset:49152
	ds_read_b128 v[188:191], v150 offset:50176
	ds_read_b128 v[192:195], v150 offset:51200
	ds_read_b128 v[196:199], v150 offset:52224
	ds_read_b128 v[200:203], v150 offset:53248
	ds_read_b128 v[204:207], v150 offset:54272
	ds_read_b128 v[210:213], v150 offset:55296
	ds_read_b128 v[214:217], v150 offset:56320
	global_load_lds_dwordx4 v[218:219], off
	s_add_i32 m0, s28, 0x2000
	s_add_u32 s26, s26, 0x160080
	v_lshl_add_u64 v[218:219], v[220:221], 0, s[8:9]
	s_addc_u32 s27, s27, 0
	s_add_i32 s28, s59, s34
	global_load_lds_dwordx4 v[218:219], off
	v_lshl_add_u64 v[218:219], s[26:27], 0, v[134:135]
	s_mov_b32 m0, s28
	s_nop 0
	global_load_lds_dwordx4 v[218:219], off
	v_lshl_add_u64 v[218:219], s[26:27], 0, v[130:131]
	s_add_i32 m0, s28, 0x2000
	s_nop 0
	global_load_lds_dwordx4 v[218:219], off
	v_lshl_add_u64 v[218:219], v[222:223], 0, s[8:9]
	s_mov_b32 m0, s42
	s_nop 0
	global_load_lds_dwordx4 v[218:219], off
	v_lshl_add_u64 v[218:219], v[224:225], 0, s[8:9]
	s_mov_b32 m0, s43
	s_nop 0
	global_load_lds_dwordx4 v[218:219], off
	s_waitcnt vmcnt(8)
	s_waitcnt lgkmcnt(0)
	s_barrier
	s_setprio 1
	s_waitcnt lgkmcnt(0)
	v_mfma_f32_16x16x32_bf16 v[62:65], v[152:155], v[184:187], v[62:65]
	v_mfma_f32_16x16x32_bf16 v[58:61], v[160:163], v[184:187], v[58:61]
	v_mfma_f32_16x16x32_bf16 v[54:57], v[152:155], v[192:195], v[54:57]
	v_mfma_f32_16x16x32_bf16 v[50:53], v[160:163], v[192:195], v[50:53]
	v_mfma_f32_16x16x32_bf16 v[38:41], v[152:155], v[200:203], v[38:41]
	v_mfma_f32_16x16x32_bf16 v[34:37], v[160:163], v[200:203], v[34:37]
	v_mfma_f32_16x16x32_bf16 v[22:25], v[152:155], v[210:213], v[22:25]
	v_mfma_f32_16x16x32_bf16 v[18:21], v[160:163], v[210:213], v[18:21]
	v_mfma_f32_16x16x32_bf16 v[62:65], v[156:159], v[188:191], v[62:65]
	v_mfma_f32_16x16x32_bf16 v[58:61], v[164:167], v[188:191], v[58:61]
	v_mfma_f32_16x16x32_bf16 v[54:57], v[156:159], v[196:199], v[54:57]
	v_mfma_f32_16x16x32_bf16 v[50:53], v[164:167], v[196:199], v[50:53]
	v_mfma_f32_16x16x32_bf16 v[38:41], v[156:159], v[204:207], v[38:41]
	v_mfma_f32_16x16x32_bf16 v[34:37], v[164:167], v[204:207], v[34:37]
	v_mfma_f32_16x16x32_bf16 v[22:25], v[156:159], v[214:217], v[22:25]
	v_mfma_f32_16x16x32_bf16 v[18:21], v[164:167], v[214:217], v[18:21]
	s_setprio 0
	s_setprio 1
	v_mfma_f32_16x16x32_bf16 v[46:49], v[168:171], v[184:187], v[46:49]
	v_mfma_f32_16x16x32_bf16 v[42:45], v[176:179], v[184:187], v[42:45]
	v_mfma_f32_16x16x32_bf16 v[30:33], v[168:171], v[192:195], v[30:33]
	v_mfma_f32_16x16x32_bf16 v[26:29], v[176:179], v[192:195], v[26:29]
	v_mfma_f32_16x16x32_bf16 v[14:17], v[168:171], v[200:203], v[14:17]
	v_mfma_f32_16x16x32_bf16 v[10:13], v[176:179], v[200:203], v[10:13]
	v_mfma_f32_16x16x32_bf16 v[6:9], v[168:171], v[210:213], v[6:9]
	v_mfma_f32_16x16x32_bf16 v[2:5], v[176:179], v[210:213], v[2:5]
	v_mfma_f32_16x16x32_bf16 v[46:49], v[172:175], v[188:191], v[46:49]
	v_mfma_f32_16x16x32_bf16 v[42:45], v[180:183], v[188:191], v[42:45]
	v_mfma_f32_16x16x32_bf16 v[30:33], v[172:175], v[196:199], v[30:33]
	v_mfma_f32_16x16x32_bf16 v[26:29], v[180:183], v[196:199], v[26:29]
	v_mfma_f32_16x16x32_bf16 v[14:17], v[172:175], v[204:207], v[14:17]
	v_mfma_f32_16x16x32_bf16 v[10:13], v[180:183], v[204:207], v[10:13]
	v_mfma_f32_16x16x32_bf16 v[6:9], v[172:175], v[214:217], v[6:9]
	v_mfma_f32_16x16x32_bf16 v[2:5], v[180:183], v[214:217], v[2:5]
	s_setprio 0
	s_barrier
	s_add_i32 s57, s57, 2
	s_add_u32 s24, s24, 0x100
	s_addc_u32 s25, s25, 0
	s_add_u32 s55, s55, 0x100
	s_addc_u32 s56, s56, 0
	s_cmpk_gt_u32 s57, 0x55
	s_cbranch_scc1 .Lpeel_exit_17
	.p2align 6

; #define PG8_STAGE(bufoff, gbase, voff) do { _Pragma("unroll") for (int _i = 0; _i < 2; ++_i) \
;         __builtin_amdgcn_global_load_lds((const unsigned*)((const char*)(gbase) + (voff)[_i]), (PG8_LAS unsigned*)(lds + (bufoff) + ldsw + _i * 8192), 16, 0, 0); } while (0)
; #define PG8_LDA(dst, b, h) do { _Pragma("unroll") for (int m = 0; m < 4; ++m) _Pragma("unroll") for (int k = 0; k < 2; ++k) dst[m][k] = *(const PG8_LAS bf16x8*)(lds + PG8_SA(b, h) + aoff + m * 2048 + k * 1024); } while (0)
; #define PG8_LDB(dst, b, h) do { _Pragma("unroll") for (int n = 0; n < 2; ++n) _Pragma("unroll") for (int k = 0; k < 2; ++k) dst[n][k] = *(const PG8_LAS bf16x8*)(lds + PG8_SB(b, h) + boff + n * 2048 + k * 1024); } while (0)
; #define PG8_MMA(ai, bj, At, Bt) do { __builtin_amdgcn_s_setprio(1); _Pragma("unroll") for (int m = 0; m < 4; ++m) _Pragma("unroll") for (int n = 0; n < 2; ++n) _Pragma("unroll") for (int k = 0; k < 2; ++k) \
;         acc[ai][bj][m][n] = __builtin_amdgcn_mfma_f32_16x16x32_bf16(Bt[n][k], At[m][k], acc[ai][bj][m][n], 0, 0, 0); __builtin_amdgcn_s_setprio(0); } while (0)
; #define PG8_BAR __builtin_amdgcn_s_barrier()
; template <class Epi, class Sched, bool ALIGN_EPI = false, bool SP2 = false>
; __device__ __forceinline__ void gemm_phase(PG8_LAS unsigned char* lds, const Gemm g, const Sched& S, const Epi& E) {
;     ...
;         const bool has_next = S.next(ui + 1, nxt);
;         const char* nA = has_next ? (const char*)g.A + (size_t)nxt.pm * tstepA : cA; const char* nB = has_next ? (const char*)g.Bt + (size_t)nxt.pn * tstepB : cB;
;         for (int t = 0; t < nt; t += 2) {
;             const bool last = (t == nt - 2);
;             const char* a1 = cA + (size_t)(t + 1) * kstep;
;             const char* a2 = last ? nA : cA + (size_t)(t + 2) * kstep; const char* b2 = last ? nB : cB + (size_t)(t + 2) * kstep;
;             const char* a3 = a2 + kstep; const char* b3 = b2 + kstep;
;             if (last && has_next) S.a_ready(nxt);
;             if constexpr (SP2) {
;             PG8_LDB(B0, 0, 0); PG8_LDB(B1, 0, 1); PG8_SCHED; PG8_LDA(At, 0, 0); PG8_STAGE(PG8_SA(1, 1), a1 + hstepA, voffA);
;             PG8_WAIT_V(8); PG8_WAIT_L(0); PG8_BAR; PG8_MMA(0, 0, At, B0); PG8_MMA(0, 1, At, B1); PG8_BAR; PG8_SCHED;
;             PG8_LDA(At, 0, 1); PG8_STAGE(PG8_SB(0, 0), b2, voffB); PG8_STAGE(PG8_SB(0, 1), b2 + hstepB, voffB); PG8_STAGE(PG8_SA(0, 0), a2, voffA);
.LBB0_1838:
	s_ashr_i32 s25, s24, 31
	s_lshl_b64 s[26:27], s[24:25], 20
	s_add_u32 s26, s86, s26
	s_addc_u32 s27, s87, s27
	s_and_b64 s[28:29], s[8:9], exec
	s_cselect_b32 s11, s27, s13
	s_cselect_b32 s25, s26, s12
	s_ashr_i32 s23, s22, 31
	s_lshl_b64 s[28:29], s[22:23], 20
	v_readlane_b32 s34, v254, 2
	v_readlane_b32 s35, v254, 3
	s_add_u32 s28, s34, s28
	s_addc_u32 s29, s35, s29
	s_and_b64 s[34:35], s[8:9], exec
	s_cselect_b32 s23, s29, s31
	s_cselect_b32 s36, s28, s30
	s_add_u32 s12, s12, 0x80080
	s_addc_u32 s13, s13, 0
	s_add_u32 s37, s30, 0x100
	s_addc_u32 s38, s31, 0
	s_mov_b32 s39, -2
	ds_read_b128 v[160:163], v143
	ds_read_b128 v[164:167], v143 offset:1024
	ds_read_b128 v[168:171], v143 offset:2048
	ds_read_b128 v[172:175], v143 offset:3072
	ds_read_b128 v[176:179], v156
	ds_read_b128 v[180:183], v156 offset:1024
	ds_read_b128 v[184:187], v156 offset:2048
	ds_read_b128 v[188:191], v156 offset:3072
	s_add_u32 s30, s12, 0xfff80080
	s_addc_u32 s31, s13, -1
	s_cmp_eq_u32 s39, 28
	s_cselect_b32 s35, s11, s31
	s_cselect_b32 s34, s25, s30
	s_cselect_b32 s31, s23, s38
	s_cselect_b32 s30, s36, s37
	v_lshl_add_u64 v[226:227], s[12:13], 0, v[148:149]
	s_add_i32 m0, s17, 0xc000
	ds_read_b128 v[192:195], v157
	ds_read_b128 v[196:199], v157 offset:1024
	ds_read_b128 v[200:203], v157 offset:2048
	ds_read_b128 v[204:207], v157 offset:3072
	ds_read_b128 v[210:213], v157 offset:4096
	ds_read_b128 v[214:217], v157 offset:5120
	ds_read_b128 v[218:221], v157 offset:6144
	ds_read_b128 v[222:225], v157 offset:7168
	global_load_lds_dwordx4 v[226:227], off
	v_lshl_add_u64 v[226:227], s[12:13], 0, v[150:151]
	s_add_i32 m0, s17, 0xe000
	s_nop 0
	global_load_lds_dwordx4 v[226:227], off
	s_waitcnt vmcnt(8)
	s_waitcnt lgkmcnt(0)
	s_barrier
	s_setprio 1
	s_waitcnt lgkmcnt(0)
	v_mfma_f32_16x16x32_bf16 v[126:129], v[160:163], v[192:195], 0
	v_mfma_f32_16x16x32_bf16 v[122:125], v[168:171], v[192:195], 0
	v_mfma_f32_16x16x32_bf16 v[110:113], v[160:163], v[200:203], 0
	v_mfma_f32_16x16x32_bf16 v[106:109], v[168:171], v[200:203], 0
	v_mfma_f32_16x16x32_bf16 v[94:97], v[160:163], v[210:213], 0
	v_mfma_f32_16x16x32_bf16 v[90:93], v[168:171], v[210:213], 0
	v_mfma_f32_16x16x32_bf16 v[78:81], v[160:163], v[218:221], 0
	v_mfma_f32_16x16x32_bf16 v[74:77], v[168:171], v[218:221], 0
	v_mfma_f32_16x16x32_bf16 v[126:129], v[164:167], v[196:199], v[126:129]
	v_mfma_f32_16x16x32_bf16 v[122:125], v[172:175], v[196:199], v[122:125]
	v_mfma_f32_16x16x32_bf16 v[110:113], v[164:167], v[204:207], v[110:113]
	v_mfma_f32_16x16x32_bf16 v[106:109], v[172:175], v[204:207], v[106:109]
	v_mfma_f32_16x16x32_bf16 v[94:97], v[164:167], v[214:217], v[94:97]
	v_mfma_f32_16x16x32_bf16 v[90:93], v[172:175], v[214:217], v[90:93]
	v_mfma_f32_16x16x32_bf16 v[78:81], v[164:167], v[222:225], v[78:81]
	v_mfma_f32_16x16x32_bf16 v[74:77], v[172:175], v[222:225], v[74:77]
	s_setprio 0
	s_setprio 1
	v_mfma_f32_16x16x32_bf16 v[118:121], v[176:179], v[192:195], 0
	v_mfma_f32_16x16x32_bf16 v[114:117], v[184:187], v[192:195], 0
	v_mfma_f32_16x16x32_bf16 v[102:105], v[176:179], v[200:203], 0
	v_mfma_f32_16x16x32_bf16 v[98:101], v[184:187], v[200:203], 0
	v_mfma_f32_16x16x32_bf16 v[86:89], v[176:179], v[210:213], 0
	v_mfma_f32_16x16x32_bf16 v[82:85], v[184:187], v[210:213], 0
	v_mfma_f32_16x16x32_bf16 v[70:73], v[176:179], v[218:221], 0
	v_mfma_f32_16x16x32_bf16 v[66:69], v[184:187], v[218:221], 0
	v_mfma_f32_16x16x32_bf16 v[118:121], v[180:183], v[196:199], v[118:121]
	v_mfma_f32_16x16x32_bf16 v[114:117], v[188:191], v[196:199], v[114:117]
	v_mfma_f32_16x16x32_bf16 v[102:105], v[180:183], v[204:207], v[102:105]
	v_mfma_f32_16x16x32_bf16 v[98:101], v[188:191], v[204:207], v[98:101]
	v_mfma_f32_16x16x32_bf16 v[86:89], v[180:183], v[214:217], v[86:89]
	v_mfma_f32_16x16x32_bf16 v[82:85], v[188:191], v[214:217], v[82:85]
	v_mfma_f32_16x16x32_bf16 v[70:73], v[180:183], v[222:225], v[70:73]
	v_mfma_f32_16x16x32_bf16 v[66:69], v[188:191], v[222:225], v[66:69]
	s_setprio 0
	s_barrier
	s_add_i32 s58, s50, s40
	v_lshl_add_u64 v[226:227], s[30:31], 0, v[132:133]
	s_mov_b32 m0, s58
	ds_read_b128 v[192:195], v157 offset:16384
	ds_read_b128 v[196:199], v157 offset:17408
	ds_read_b128 v[200:203], v157 offset:18432
	ds_read_b128 v[204:207], v157 offset:19456
	ds_read_b128 v[210:213], v157 offset:20480
	ds_read_b128 v[214:217], v157 offset:21504
	ds_read_b128 v[218:221], v157 offset:22528
	ds_read_b128 v[222:225], v157 offset:23552
	global_load_lds_dwordx4 v[226:227], off
	s_add_i32 m0, s58, 0x2000
	s_add_u32 s58, s30, 0x80000
	v_lshl_add_u64 v[228:229], s[30:31], 0, v[136:137]
	s_addc_u32 s59, s31, 0
	s_add_i32 s60, s51, s40
	global_load_lds_dwordx4 v[228:229], off
	v_lshl_add_u64 v[230:231], s[58:59], 0, v[132:133]
	s_mov_b32 m0, s60
	v_lshl_add_u64 v[232:233], s[34:35], 0, v[134:135]
	global_load_lds_dwordx4 v[230:231], off
	v_lshl_add_u64 v[230:231], s[58:59], 0, v[136:137]
	s_add_i32 m0, s60, 0x2000
	s_nop 0
	global_load_lds_dwordx4 v[230:231], off
	v_lshl_add_u64 v[230:231], s[34:35], 0, v[130:131]
	s_mov_b32 m0, s17
	s_nop 0
	global_load_lds_dwordx4 v[230:231], off
	s_mov_b32 m0, s41
	s_nop 0
	global_load_lds_dwordx4 v[232:233], off
	s_waitcnt vmcnt(8)
	s_waitcnt lgkmcnt(0)
	s_barrier
; #define PG8_STAGE(bufoff, gbase, voff) do { _Pragma("unroll") for (int _i = 0; _i < 2; ++_i) \
;         __builtin_amdgcn_global_load_lds((const unsigned*)((const char*)(gbase) + (voff)[_i]), (PG8_LAS unsigned*)(lds + (bufoff) + ldsw + _i * 8192), 16, 0, 0); } while (0)
; #define PG8_LDA(dst, b, h) do { _Pragma("unroll") for (int m = 0; m < 4; ++m) _Pragma("unroll") for (int k = 0; k < 2; ++k) dst[m][k] = *(const PG8_LAS bf16x8*)(lds + PG8_SA(b, h) + aoff + m * 2048 + k * 1024); } while (0)
; #define PG8_LDB(dst, b, h) do { _Pragma("unroll") for (int n = 0; n < 2; ++n) _Pragma("unroll") for (int k = 0; k < 2; ++k) dst[n][k] = *(const PG8_LAS bf16x8*)(lds + PG8_SB(b, h) + boff + n * 2048 + k * 1024); } while (0)
; #define PG8_MMA(ai, bj, At, Bt) do { __builtin_amdgcn_s_setprio(1); _Pragma("unroll") for (int m = 0; m < 4; ++m) _Pragma("unroll") for (int n = 0; n < 2; ++n) _Pragma("unroll") for (int k = 0; k < 2; ++k) \
;         acc[ai][bj][m][n] = __builtin_amdgcn_mfma_f32_16x16x32_bf16(Bt[n][k], At[m][k], acc[ai][bj][m][n], 0, 0, 0); __builtin_amdgcn_s_setprio(0); } while (0)
; #define PG8_WAIT_V(n) asm volatile("s_waitcnt vmcnt(" #n ")" ::: "memory")
; #define PG8_WAIT_L(n) asm volatile("s_waitcnt lgkmcnt(" #n ")" ::: "memory")
; #define PG8_BAR __builtin_amdgcn_s_barrier()
; #define PG8_SCHED __builtin_amdgcn_sched_barrier(0)
; template <class Epi, class Sched, bool ALIGN_EPI = false, bool SP2 = false>
; __device__ __forceinline__ void gemm_phase(PG8_LAS unsigned char* lds, const Gemm g, const Sched& S, const Epi& E) {
;     ...
;             PG8_LDA(At, 0, 1); PG8_STAGE(PG8_SB(0, 0), b2, voffB); PG8_STAGE(PG8_SB(0, 1), b2 + hstepB, voffB); PG8_STAGE(PG8_SA(0, 0), a2, voffA);
;             PG8_WAIT_V(8); PG8_WAIT_L(0); PG8_BAR; PG8_MMA(1, 0, At, B0); PG8_MMA(1, 1, At, B1); PG8_BAR; PG8_SCHED;
;             PG8_LDB(B0, 1, 0); PG8_LDB(B1, 1, 1); PG8_SCHED; PG8_LDA(At, 1, 0); PG8_STAGE(PG8_SA(0, 1), a2 + hstepA, voffA);
;             PG8_WAIT_V(8); PG8_WAIT_L(0); PG8_BAR; PG8_MMA(0, 0, At, B0); PG8_MMA(0, 1, At, B1); PG8_BAR; PG8_SCHED;
	s_setprio 1
	s_waitcnt lgkmcnt(0)
	v_mfma_f32_16x16x32_bf16 v[62:65], v[160:163], v[192:195], 0
	v_mfma_f32_16x16x32_bf16 v[58:61], v[168:171], v[192:195], 0
	v_mfma_f32_16x16x32_bf16 v[46:49], v[160:163], v[200:203], 0
	v_mfma_f32_16x16x32_bf16 v[42:45], v[168:171], v[200:203], 0
	v_mfma_f32_16x16x32_bf16 v[30:33], v[160:163], v[210:213], 0
	v_mfma_f32_16x16x32_bf16 v[26:29], v[168:171], v[210:213], 0
	v_mfma_f32_16x16x32_bf16 v[14:17], v[160:163], v[218:221], 0
	v_mfma_f32_16x16x32_bf16 v[10:13], v[168:171], v[218:221], 0
	v_mfma_f32_16x16x32_bf16 v[62:65], v[164:167], v[196:199], v[62:65]
	v_mfma_f32_16x16x32_bf16 v[58:61], v[172:175], v[196:199], v[58:61]
	v_mfma_f32_16x16x32_bf16 v[46:49], v[164:167], v[204:207], v[46:49]
	v_mfma_f32_16x16x32_bf16 v[42:45], v[172:175], v[204:207], v[42:45]
	v_mfma_f32_16x16x32_bf16 v[30:33], v[164:167], v[214:217], v[30:33]
	v_mfma_f32_16x16x32_bf16 v[26:29], v[172:175], v[214:217], v[26:29]
	v_mfma_f32_16x16x32_bf16 v[14:17], v[164:167], v[222:225], v[14:17]
	v_mfma_f32_16x16x32_bf16 v[10:13], v[172:175], v[222:225], v[10:13]
	s_setprio 0
	s_setprio 1
	v_mfma_f32_16x16x32_bf16 v[54:57], v[176:179], v[192:195], 0
	v_mfma_f32_16x16x32_bf16 v[50:53], v[184:187], v[192:195], 0
	v_mfma_f32_16x16x32_bf16 v[38:41], v[176:179], v[200:203], 0
	v_mfma_f32_16x16x32_bf16 v[34:37], v[184:187], v[200:203], 0
	v_mfma_f32_16x16x32_bf16 v[22:25], v[176:179], v[210:213], 0
	v_mfma_f32_16x16x32_bf16 v[18:21], v[184:187], v[210:213], 0
	v_mfma_f32_16x16x32_bf16 v[6:9], v[176:179], v[218:221], 0
	v_mfma_f32_16x16x32_bf16 v[2:5], v[184:187], v[218:221], 0
	v_mfma_f32_16x16x32_bf16 v[54:57], v[180:183], v[196:199], v[54:57]
	v_mfma_f32_16x16x32_bf16 v[50:53], v[188:191], v[196:199], v[50:53]
	v_mfma_f32_16x16x32_bf16 v[38:41], v[180:183], v[204:207], v[38:41]
	v_mfma_f32_16x16x32_bf16 v[34:37], v[188:191], v[204:207], v[34:37]
	v_mfma_f32_16x16x32_bf16 v[22:25], v[180:183], v[214:217], v[22:25]
	v_mfma_f32_16x16x32_bf16 v[18:21], v[188:191], v[214:217], v[18:21]
	v_mfma_f32_16x16x32_bf16 v[6:9], v[180:183], v[222:225], v[6:9]
	v_mfma_f32_16x16x32_bf16 v[2:5], v[188:191], v[222:225], v[2:5]
	s_setprio 0
	s_barrier
	s_add_i32 s58, 0, 0x18000
	v_add_u32_e32 v138, s58, v1
	s_add_i32 s59, 0, 0x1c000
	ds_read_b128 v[160:163], v138
	ds_read_b128 v[164:167], v138 offset:1024
	ds_read_b128 v[168:171], v138 offset:2048
	ds_read_b128 v[172:175], v138 offset:3072
	v_add_u32_e32 v138, s59, v1
	ds_read_b128 v[176:179], v138
	ds_read_b128 v[180:183], v138 offset:1024
	ds_read_b128 v[184:187], v138 offset:2048
	ds_read_b128 v[188:191], v138 offset:3072
	s_add_u32 s34, s34, 0x80000
	s_addc_u32 s35, s35, 0
	s_mov_b32 m0, s42
	v_lshl_add_u64 v[234:235], s[34:35], 0, v[130:131]
	ds_read_b128 v[192:195], v157 offset:32768
	ds_read_b128 v[196:199], v157 offset:33792
	ds_read_b128 v[200:203], v157 offset:34816
	ds_read_b128 v[204:207], v157 offset:35840
	ds_read_b128 v[210:213], v157 offset:36864
	ds_read_b128 v[214:217], v157 offset:37888
	ds_read_b128 v[218:221], v157 offset:38912
	ds_read_b128 v[222:225], v157 offset:39936
	global_load_lds_dwordx4 v[234:235], off
	v_lshl_add_u64 v[234:235], s[34:35], 0, v[134:135]
	s_mov_b32 m0, s43
	s_nop 0
	global_load_lds_dwordx4 v[234:235], off
	s_waitcnt vmcnt(8)
	s_waitcnt lgkmcnt(0)
	s_barrier
	s_setprio 1
	s_waitcnt lgkmcnt(0)
	v_mfma_f32_16x16x32_bf16 v[126:129], v[160:163], v[192:195], v[126:129]
	v_mfma_f32_16x16x32_bf16 v[122:125], v[168:171], v[192:195], v[122:125]
	v_mfma_f32_16x16x32_bf16 v[110:113], v[160:163], v[200:203], v[110:113]
	v_mfma_f32_16x16x32_bf16 v[106:109], v[168:171], v[200:203], v[106:109]
	v_mfma_f32_16x16x32_bf16 v[94:97], v[160:163], v[210:213], v[94:97]
	v_mfma_f32_16x16x32_bf16 v[90:93], v[168:171], v[210:213], v[90:93]
	v_mfma_f32_16x16x32_bf16 v[78:81], v[160:163], v[218:221], v[78:81]
	v_mfma_f32_16x16x32_bf16 v[74:77], v[168:171], v[218:221], v[74:77]
	v_mfma_f32_16x16x32_bf16 v[126:129], v[164:167], v[196:199], v[126:129]
	v_mfma_f32_16x16x32_bf16 v[122:125], v[172:175], v[196:199], v[122:125]
	v_mfma_f32_16x16x32_bf16 v[110:113], v[164:167], v[204:207], v[110:113]
	v_mfma_f32_16x16x32_bf16 v[106:109], v[172:175], v[204:207], v[106:109]
	v_mfma_f32_16x16x32_bf16 v[94:97], v[164:167], v[214:217], v[94:97]
	v_mfma_f32_16x16x32_bf16 v[90:93], v[172:175], v[214:217], v[90:93]
	v_mfma_f32_16x16x32_bf16 v[78:81], v[164:167], v[222:225], v[78:81]
	v_mfma_f32_16x16x32_bf16 v[74:77], v[172:175], v[222:225], v[74:77]
	s_setprio 0
	s_setprio 1
	v_mfma_f32_16x16x32_bf16 v[118:121], v[176:179], v[192:195], v[118:121]
	v_mfma_f32_16x16x32_bf16 v[114:117], v[184:187], v[192:195], v[114:117]
	v_mfma_f32_16x16x32_bf16 v[102:105], v[176:179], v[200:203], v[102:105]
	v_mfma_f32_16x16x32_bf16 v[98:101], v[184:187], v[200:203], v[98:101]
	v_mfma_f32_16x16x32_bf16 v[86:89], v[176:179], v[210:213], v[86:89]
	v_mfma_f32_16x16x32_bf16 v[82:85], v[184:187], v[210:213], v[82:85]
	v_mfma_f32_16x16x32_bf16 v[70:73], v[176:179], v[218:221], v[70:73]
	v_mfma_f32_16x16x32_bf16 v[66:69], v[184:187], v[218:221], v[66:69]
	v_mfma_f32_16x16x32_bf16 v[118:121], v[180:183], v[196:199], v[118:121]
	v_mfma_f32_16x16x32_bf16 v[114:117], v[188:191], v[196:199], v[114:117]
	v_mfma_f32_16x16x32_bf16 v[102:105], v[180:183], v[204:207], v[102:105]
	v_mfma_f32_16x16x32_bf16 v[98:101], v[188:191], v[204:207], v[98:101]
	v_mfma_f32_16x16x32_bf16 v[86:89], v[180:183], v[214:217], v[86:89]
	v_mfma_f32_16x16x32_bf16 v[82:85], v[188:191], v[214:217], v[82:85]
	v_mfma_f32_16x16x32_bf16 v[70:73], v[180:183], v[222:225], v[70:73]
	v_mfma_f32_16x16x32_bf16 v[66:69], v[188:191], v[222:225], v[66:69]
	s_setprio 0
	s_barrier
; #define PG8_STAGE(bufoff, gbase, voff) do { _Pragma("unroll") for (int _i = 0; _i < 2; ++_i) \
;         __builtin_amdgcn_global_load_lds((const unsigned*)((const char*)(gbase) + (voff)[_i]), (PG8_LAS unsigned*)(lds + (bufoff) + ldsw + _i * 8192), 16, 0, 0); } while (0)
; #define PG8_LDA(dst, b, h) do { _Pragma("unroll") for (int m = 0; m < 4; ++m) _Pragma("unroll") for (int k = 0; k < 2; ++k) dst[m][k] = *(const PG8_LAS bf16x8*)(lds + PG8_SA(b, h) + aoff + m * 2048 + k * 1024); } while (0)
; #define PG8_LDB(dst, b, h) do { _Pragma("unroll") for (int n = 0; n < 2; ++n) _Pragma("unroll") for (int k = 0; k < 2; ++k) dst[n][k] = *(const PG8_LAS bf16x8*)(lds + PG8_SB(b, h) + boff + n * 2048 + k * 1024); } while (0)
; template <class Epi, class Sched, bool ALIGN_EPI = false, bool SP2 = false>
; __device__ __forceinline__ void gemm_phase(PG8_LAS unsigned char* lds, const Gemm g, const Sched& S, const Epi& E) {
;     ...
;         for (int t = 0; t < nt; t += 2) {
;             const bool last = (t == nt - 2);
;             const char* a1 = cA + (size_t)(t + 1) * kstep;
;             const char* a2 = last ? nA : cA + (size_t)(t + 2) * kstep; const char* b2 = last ? nB : cB + (size_t)(t + 2) * kstep;
;             const char* a3 = a2 + kstep; const char* b3 = b2 + kstep;
;             if (last && has_next) S.a_ready(nxt);
;             if constexpr (SP2) {
;             PG8_LDB(B0, 0, 0); PG8_LDB(B1, 0, 1); PG8_SCHED; PG8_LDA(At, 0, 0); PG8_STAGE(PG8_SA(1, 1), a1 + hstepA, voffA);
;             PG8_WAIT_V(8); PG8_WAIT_L(0); PG8_BAR; PG8_MMA(0, 0, At, B0); PG8_MMA(0, 1, At, B1); PG8_BAR; PG8_SCHED;
;             PG8_LDA(At, 0, 1); PG8_STAGE(PG8_SB(0, 0), b2, voffB); PG8_STAGE(PG8_SB(0, 1), b2 + hstepB, voffB); PG8_STAGE(PG8_SA(0, 0), a2, voffA);
;             PG8_WAIT_V(8); PG8_WAIT_L(0); PG8_BAR; PG8_MMA(1, 0, At, B0); PG8_MMA(1, 1, At, B1); PG8_BAR; PG8_SCHED;
;             PG8_LDB(B0, 1, 0); PG8_LDB(B1, 1, 1); PG8_SCHED; PG8_LDA(At, 1, 0); PG8_STAGE(PG8_SA(0, 1), a2 + hstepA, voffA);
;             PG8_WAIT_V(8); PG8_WAIT_L(0); PG8_BAR; PG8_MMA(0, 0, At, B0); PG8_MMA(0, 1, At, B1); PG8_BAR; PG8_SCHED;
;             PG8_LDA(At, 1, 1); PG8_STAGE(PG8_SB(1, 0), b3, voffB); PG8_STAGE(PG8_SB(1, 1), b3 + hstepB, voffB); PG8_STAGE(PG8_SA(1, 0), a3, voffA);
;             PG8_WAIT_V(8); PG8_WAIT_L(0); PG8_BAR; PG8_MMA(1, 0, At, B0); PG8_MMA(1, 1, At, B1); PG8_BAR; PG8_SCHED;
	s_add_i32 s34, s58, s40
	v_lshl_add_u64 v[226:227], v[226:227], 0, s[14:15]
	s_mov_b32 m0, s34
	ds_read_b128 v[192:195], v157 offset:49152
	ds_read_b128 v[196:199], v157 offset:50176
	ds_read_b128 v[200:203], v157 offset:51200
	ds_read_b128 v[204:207], v157 offset:52224
	ds_read_b128 v[210:213], v157 offset:53248
	ds_read_b128 v[214:217], v157 offset:54272
	ds_read_b128 v[218:221], v157 offset:55296
	ds_read_b128 v[222:225], v157 offset:56320
	global_load_lds_dwordx4 v[226:227], off
	s_add_i32 m0, s34, 0x2000
	s_add_u32 s30, s30, 0x80080
	v_lshl_add_u64 v[226:227], v[228:229], 0, s[14:15]
	s_addc_u32 s31, s31, 0
	s_add_i32 s34, s59, s40
	global_load_lds_dwordx4 v[226:227], off
	v_lshl_add_u64 v[226:227], s[30:31], 0, v[132:133]
	s_mov_b32 m0, s34
	s_nop 0
	global_load_lds_dwordx4 v[226:227], off
	v_lshl_add_u64 v[226:227], s[30:31], 0, v[136:137]
	s_add_i32 m0, s34, 0x2000
	s_nop 0
	global_load_lds_dwordx4 v[226:227], off
	v_lshl_add_u64 v[226:227], v[230:231], 0, s[14:15]
	s_mov_b32 m0, s46
	s_nop 0
	global_load_lds_dwordx4 v[226:227], off
	v_lshl_add_u64 v[226:227], v[232:233], 0, s[14:15]
	s_mov_b32 m0, s47
	s_nop 0
	global_load_lds_dwordx4 v[226:227], off
	s_waitcnt vmcnt(8)
	s_waitcnt lgkmcnt(0)
	s_barrier
	s_setprio 1
	s_waitcnt lgkmcnt(0)
	v_mfma_f32_16x16x32_bf16 v[62:65], v[160:163], v[192:195], v[62:65]
	v_mfma_f32_16x16x32_bf16 v[58:61], v[168:171], v[192:195], v[58:61]
	v_mfma_f32_16x16x32_bf16 v[46:49], v[160:163], v[200:203], v[46:49]
	v_mfma_f32_16x16x32_bf16 v[42:45], v[168:171], v[200:203], v[42:45]
	v_mfma_f32_16x16x32_bf16 v[30:33], v[160:163], v[210:213], v[30:33]
	v_mfma_f32_16x16x32_bf16 v[26:29], v[168:171], v[210:213], v[26:29]
	v_mfma_f32_16x16x32_bf16 v[14:17], v[160:163], v[218:221], v[14:17]
	v_mfma_f32_16x16x32_bf16 v[10:13], v[168:171], v[218:221], v[10:13]
	v_mfma_f32_16x16x32_bf16 v[62:65], v[164:167], v[196:199], v[62:65]
	v_mfma_f32_16x16x32_bf16 v[58:61], v[172:175], v[196:199], v[58:61]
	v_mfma_f32_16x16x32_bf16 v[46:49], v[164:167], v[204:207], v[46:49]
	v_mfma_f32_16x16x32_bf16 v[42:45], v[172:175], v[204:207], v[42:45]
	v_mfma_f32_16x16x32_bf16 v[30:33], v[164:167], v[214:217], v[30:33]
	v_mfma_f32_16x16x32_bf16 v[26:29], v[172:175], v[214:217], v[26:29]
	v_mfma_f32_16x16x32_bf16 v[14:17], v[164:167], v[222:225], v[14:17]
	v_mfma_f32_16x16x32_bf16 v[10:13], v[172:175], v[222:225], v[10:13]
	s_setprio 0
	s_setprio 1
	v_mfma_f32_16x16x32_bf16 v[54:57], v[176:179], v[192:195], v[54:57]
	v_mfma_f32_16x16x32_bf16 v[50:53], v[184:187], v[192:195], v[50:53]
	v_mfma_f32_16x16x32_bf16 v[38:41], v[176:179], v[200:203], v[38:41]
	v_mfma_f32_16x16x32_bf16 v[34:37], v[184:187], v[200:203], v[34:37]
	v_mfma_f32_16x16x32_bf16 v[22:25], v[176:179], v[210:213], v[22:25]
	v_mfma_f32_16x16x32_bf16 v[18:21], v[184:187], v[210:213], v[18:21]
	v_mfma_f32_16x16x32_bf16 v[6:9], v[176:179], v[218:221], v[6:9]
	v_mfma_f32_16x16x32_bf16 v[2:5], v[184:187], v[218:221], v[2:5]
	v_mfma_f32_16x16x32_bf16 v[54:57], v[180:183], v[196:199], v[54:57]
	v_mfma_f32_16x16x32_bf16 v[50:53], v[188:191], v[196:199], v[50:53]
	v_mfma_f32_16x16x32_bf16 v[38:41], v[180:183], v[204:207], v[38:41]
	v_mfma_f32_16x16x32_bf16 v[34:37], v[188:191], v[204:207], v[34:37]
	v_mfma_f32_16x16x32_bf16 v[22:25], v[180:183], v[214:217], v[22:25]
	v_mfma_f32_16x16x32_bf16 v[18:21], v[188:191], v[214:217], v[18:21]
	v_mfma_f32_16x16x32_bf16 v[6:9], v[180:183], v[222:225], v[6:9]
	v_mfma_f32_16x16x32_bf16 v[2:5], v[188:191], v[222:225], v[2:5]
	s_setprio 0
	s_barrier
	s_add_i32 s39, s39, 2
	s_add_u32 s12, s12, 0x100
	s_addc_u32 s13, s13, 0
	s_add_u32 s37, s37, 0x100
	s_addc_u32 s38, s38, 0
	s_cmp_gt_u32 s39, 29
	s_cbranch_scc1 .Lpeel_exit_19
	.p2align 6

; #define PG8_BAR __builtin_amdgcn_s_barrier()
; template <class Epi, class Sched, bool ALIGN_EPI = false, bool SP2 = false>
; __device__ __forceinline__ void gemm_phase(PG8_LAS unsigned char* lds, const Gemm g, const Sched& S, const Epi& E) {
;     ...
;         if constexpr (ALIGN_EPI) { if (wr == 0) PG8_BAR; }
.Lpeel_exit_19:
	s_and_b64 vcc, exec, s[20:21]
	s_cbranch_vccz .LBB0_1842
	s_barrier

; #define PG8_STAGE(bufoff, gbase, voff) do { _Pragma("unroll") for (int _i = 0; _i < 2; ++_i) \
;         __builtin_amdgcn_global_load_lds((const unsigned*)((const char*)(gbase) + (voff)[_i]), (PG8_LAS unsigned*)(lds + (bufoff) + ldsw + _i * 8192), 16, 0, 0); } while (0)
; #define PG8_LDA(dst, b, h) do { _Pragma("unroll") for (int m = 0; m < 4; ++m) _Pragma("unroll") for (int k = 0; k < 2; ++k) dst[m][k] = *(const PG8_LAS bf16x8*)(lds + PG8_SA(b, h) + aoff + m * 2048 + k * 1024); } while (0)
; #define PG8_LDB(dst, b, h) do { _Pragma("unroll") for (int n = 0; n < 2; ++n) _Pragma("unroll") for (int k = 0; k < 2; ++k) dst[n][k] = *(const PG8_LAS bf16x8*)(lds + PG8_SB(b, h) + boff + n * 2048 + k * 1024); } while (0)
; #define PG8_MMA(ai, bj, At, Bt) do { __builtin_amdgcn_s_setprio(1); _Pragma("unroll") for (int m = 0; m < 4; ++m) _Pragma("unroll") for (int n = 0; n < 2; ++n) _Pragma("unroll") for (int k = 0; k < 2; ++k) \
;         acc[ai][bj][m][n] = __builtin_amdgcn_mfma_f32_16x16x32_bf16(Bt[n][k], At[m][k], acc[ai][bj][m][n], 0, 0, 0); __builtin_amdgcn_s_setprio(0); } while (0)
; #define PG8_BAR __builtin_amdgcn_s_barrier()
; template <class Epi, class Sched, bool ALIGN_EPI = false, bool SP2 = false>
; __device__ __forceinline__ void gemm_phase(PG8_LAS unsigned char* lds, const Gemm g, const Sched& S, const Epi& E) {
;     ...
;         const bool has_next = S.next(ui + 1, nxt);
;         const char* nA = has_next ? (const char*)g.A + (size_t)nxt.pm * tstepA : cA; const char* nB = has_next ? (const char*)g.Bt + (size_t)nxt.pn * tstepB : cB;
;         for (int t = 0; t < nt; t += 2) {
;             const bool last = (t == nt - 2);
;             const char* a1 = cA + (size_t)(t + 1) * kstep;
;             const char* a2 = last ? nA : cA + (size_t)(t + 2) * kstep; const char* b2 = last ? nB : cB + (size_t)(t + 2) * kstep;
;             const char* a3 = a2 + kstep; const char* b3 = b2 + kstep;
;             if (last && has_next) S.a_ready(nxt);
;             if constexpr (SP2) {
;             PG8_LDB(B0, 0, 0); PG8_LDB(B1, 0, 1); PG8_SCHED; PG8_LDA(At, 0, 0); PG8_STAGE(PG8_SA(1, 1), a1 + hstepA, voffA);
;             PG8_WAIT_V(8); PG8_WAIT_L(0); PG8_BAR; PG8_MMA(0, 0, At, B0); PG8_MMA(0, 1, At, B1); PG8_BAR; PG8_SCHED;
;             PG8_LDA(At, 0, 1); PG8_STAGE(PG8_SB(0, 0), b2, voffB); PG8_STAGE(PG8_SB(0, 1), b2 + hstepB, voffB); PG8_STAGE(PG8_SA(0, 0), a2, voffA);
.LBB0_2258:
	s_ashr_i32 s23, s22, 31
	s_lshl_b64 s[24:25], s[22:23], 21
	s_add_u32 s24, s86, s24
	s_addc_u32 s25, s87, s25
	s_and_b64 s[26:27], s[4:5], exec
	s_cselect_b32 s23, s25, s29
	s_cselect_b32 s53, s24, s28
	s_ashr_i32 s21, s20, 31
	s_lshl_b64 s[26:27], s[20:21], 21
	s_add_u32 s26, s88, s26
	s_addc_u32 s27, s89, s27
	s_and_b64 s[34:35], s[4:5], exec
	s_cselect_b32 s21, s27, s31
	s_cselect_b32 s54, s26, s30
	s_add_u32 s28, s28, 0x100080
	s_addc_u32 s29, s29, 0
	s_add_u32 s55, s30, 0x100
	s_addc_u32 s56, s31, 0
	s_mov_b32 s57, -2
	ds_read_b128 v[152:155], v148
	ds_read_b128 v[156:159], v148 offset:1024
	ds_read_b128 v[160:163], v148 offset:2048
	ds_read_b128 v[164:167], v148 offset:3072
	ds_read_b128 v[168:171], v149
	ds_read_b128 v[172:175], v149 offset:1024
	ds_read_b128 v[176:179], v149 offset:2048
	ds_read_b128 v[180:183], v149 offset:3072
	s_add_u32 s30, s28, 0xfff00080
	s_addc_u32 s31, s29, -1
	s_cmp_eq_u32 s57, 60
	s_cselect_b32 s35, s23, s31
	s_cselect_b32 s34, s53, s30
	s_cselect_b32 s31, s21, s56
	s_cselect_b32 s30, s54, s55
	v_lshl_add_u64 v[218:219], s[28:29], 0, v[138:139]
	s_add_i32 m0, s19, 0xc000
	ds_read_b128 v[184:187], v150
	ds_read_b128 v[188:191], v150 offset:1024
	ds_read_b128 v[192:195], v150 offset:2048
	ds_read_b128 v[196:199], v150 offset:3072
	ds_read_b128 v[200:203], v150 offset:4096
	ds_read_b128 v[204:207], v150 offset:5120
	ds_read_b128 v[210:213], v150 offset:6144
	ds_read_b128 v[214:217], v150 offset:7168
	global_load_lds_dwordx4 v[218:219], off
	v_lshl_add_u64 v[218:219], s[28:29], 0, v[140:141]
	s_add_i32 m0, s19, 0xe000
	s_nop 0
	global_load_lds_dwordx4 v[218:219], off
	s_waitcnt vmcnt(8)
	s_waitcnt lgkmcnt(0)
	s_barrier
	s_setprio 1
	s_waitcnt lgkmcnt(0)
	v_mfma_f32_16x16x32_bf16 v[126:129], v[152:155], v[184:187], 0
	v_mfma_f32_16x16x32_bf16 v[122:125], v[160:163], v[184:187], 0
	v_mfma_f32_16x16x32_bf16 v[118:121], v[152:155], v[192:195], 0
	v_mfma_f32_16x16x32_bf16 v[114:117], v[160:163], v[192:195], 0
	v_mfma_f32_16x16x32_bf16 v[102:105], v[152:155], v[200:203], 0
	v_mfma_f32_16x16x32_bf16 v[98:101], v[160:163], v[200:203], 0
	v_mfma_f32_16x16x32_bf16 v[86:89], v[152:155], v[210:213], 0
	v_mfma_f32_16x16x32_bf16 v[82:85], v[160:163], v[210:213], 0
	v_mfma_f32_16x16x32_bf16 v[126:129], v[156:159], v[188:191], v[126:129]
	v_mfma_f32_16x16x32_bf16 v[122:125], v[164:167], v[188:191], v[122:125]
	v_mfma_f32_16x16x32_bf16 v[118:121], v[156:159], v[196:199], v[118:121]
	v_mfma_f32_16x16x32_bf16 v[114:117], v[164:167], v[196:199], v[114:117]
	v_mfma_f32_16x16x32_bf16 v[102:105], v[156:159], v[204:207], v[102:105]
	v_mfma_f32_16x16x32_bf16 v[98:101], v[164:167], v[204:207], v[98:101]
	v_mfma_f32_16x16x32_bf16 v[86:89], v[156:159], v[214:217], v[86:89]
	v_mfma_f32_16x16x32_bf16 v[82:85], v[164:167], v[214:217], v[82:85]
	s_setprio 0
	s_setprio 1
	v_mfma_f32_16x16x32_bf16 v[110:113], v[168:171], v[184:187], 0
	v_mfma_f32_16x16x32_bf16 v[106:109], v[176:179], v[184:187], 0
	v_mfma_f32_16x16x32_bf16 v[94:97], v[168:171], v[192:195], 0
	v_mfma_f32_16x16x32_bf16 v[90:93], v[176:179], v[192:195], 0
	v_mfma_f32_16x16x32_bf16 v[78:81], v[168:171], v[200:203], 0
	v_mfma_f32_16x16x32_bf16 v[74:77], v[176:179], v[200:203], 0
	v_mfma_f32_16x16x32_bf16 v[70:73], v[168:171], v[210:213], 0
	v_mfma_f32_16x16x32_bf16 v[66:69], v[176:179], v[210:213], 0
	v_mfma_f32_16x16x32_bf16 v[110:113], v[172:175], v[188:191], v[110:113]
	v_mfma_f32_16x16x32_bf16 v[106:109], v[180:183], v[188:191], v[106:109]
	v_mfma_f32_16x16x32_bf16 v[94:97], v[172:175], v[196:199], v[94:97]
	v_mfma_f32_16x16x32_bf16 v[90:93], v[180:183], v[196:199], v[90:93]
	v_mfma_f32_16x16x32_bf16 v[78:81], v[172:175], v[204:207], v[78:81]
	v_mfma_f32_16x16x32_bf16 v[74:77], v[180:183], v[204:207], v[74:77]
	v_mfma_f32_16x16x32_bf16 v[70:73], v[172:175], v[214:217], v[70:73]
	v_mfma_f32_16x16x32_bf16 v[66:69], v[180:183], v[214:217], v[66:69]
	s_setprio 0
	s_barrier
	s_add_i32 s58, s46, s36
	v_lshl_add_u64 v[218:219], s[30:31], 0, v[134:135]
	s_mov_b32 m0, s58
	ds_read_b128 v[184:187], v150 offset:16384
	ds_read_b128 v[188:191], v150 offset:17408
	ds_read_b128 v[192:195], v150 offset:18432
	ds_read_b128 v[196:199], v150 offset:19456
	ds_read_b128 v[200:203], v150 offset:20480
	ds_read_b128 v[204:207], v150 offset:21504
	ds_read_b128 v[210:213], v150 offset:22528
	ds_read_b128 v[214:217], v150 offset:23552
	global_load_lds_dwordx4 v[218:219], off
	s_add_i32 m0, s58, 0x2000
	s_add_u32 s58, s30, 0x100000
	v_lshl_add_u64 v[220:221], s[30:31], 0, v[130:131]
	s_addc_u32 s59, s31, 0
	s_add_i32 s60, s47, s36
	global_load_lds_dwordx4 v[220:221], off
	v_lshl_add_u64 v[222:223], s[58:59], 0, v[134:135]
	s_mov_b32 m0, s60
	v_lshl_add_u64 v[224:225], s[34:35], 0, v[132:133]
	global_load_lds_dwordx4 v[222:223], off
	v_lshl_add_u64 v[222:223], s[58:59], 0, v[130:131]
	s_add_i32 m0, s60, 0x2000
	s_nop 0
	global_load_lds_dwordx4 v[222:223], off
	v_lshl_add_u64 v[222:223], s[34:35], 0, v[136:137]
	s_mov_b32 m0, s19
	s_nop 0
	global_load_lds_dwordx4 v[222:223], off
	s_mov_b32 m0, s39
	s_nop 0
	global_load_lds_dwordx4 v[224:225], off
	s_waitcnt vmcnt(8)
	s_waitcnt lgkmcnt(0)
	s_barrier
; #define PG8_STAGE(bufoff, gbase, voff) do { _Pragma("unroll") for (int _i = 0; _i < 2; ++_i) \
;         __builtin_amdgcn_global_load_lds((const unsigned*)((const char*)(gbase) + (voff)[_i]), (PG8_LAS unsigned*)(lds + (bufoff) + ldsw + _i * 8192), 16, 0, 0); } while (0)
; #define PG8_LDA(dst, b, h) do { _Pragma("unroll") for (int m = 0; m < 4; ++m) _Pragma("unroll") for (int k = 0; k < 2; ++k) dst[m][k] = *(const PG8_LAS bf16x8*)(lds + PG8_SA(b, h) + aoff + m * 2048 + k * 1024); } while (0)
; #define PG8_LDB(dst, b, h) do { _Pragma("unroll") for (int n = 0; n < 2; ++n) _Pragma("unroll") for (int k = 0; k < 2; ++k) dst[n][k] = *(const PG8_LAS bf16x8*)(lds + PG8_SB(b, h) + boff + n * 2048 + k * 1024); } while (0)
; #define PG8_MMA(ai, bj, At, Bt) do { __builtin_amdgcn_s_setprio(1); _Pragma("unroll") for (int m = 0; m < 4; ++m) _Pragma("unroll") for (int n = 0; n < 2; ++n) _Pragma("unroll") for (int k = 0; k < 2; ++k) \
;         acc[ai][bj][m][n] = __builtin_amdgcn_mfma_f32_16x16x32_bf16(Bt[n][k], At[m][k], acc[ai][bj][m][n], 0, 0, 0); __builtin_amdgcn_s_setprio(0); } while (0)
; #define PG8_WAIT_V(n) asm volatile("s_waitcnt vmcnt(" #n ")" ::: "memory")
; #define PG8_WAIT_L(n) asm volatile("s_waitcnt lgkmcnt(" #n ")" ::: "memory")
; #define PG8_BAR __builtin_amdgcn_s_barrier()
; #define PG8_SCHED __builtin_amdgcn_sched_barrier(0)
; template <class Epi, class Sched, bool ALIGN_EPI = false, bool SP2 = false>
; __device__ __forceinline__ void gemm_phase(PG8_LAS unsigned char* lds, const Gemm g, const Sched& S, const Epi& E) {
;     ...
;             PG8_LDA(At, 0, 1); PG8_STAGE(PG8_SB(0, 0), b2, voffB); PG8_STAGE(PG8_SB(0, 1), b2 + hstepB, voffB); PG8_STAGE(PG8_SA(0, 0), a2, voffA);
;             PG8_WAIT_V(8); PG8_WAIT_L(0); PG8_BAR; PG8_MMA(1, 0, At, B0); PG8_MMA(1, 1, At, B1); PG8_BAR; PG8_SCHED;
;             PG8_LDB(B0, 1, 0); PG8_LDB(B1, 1, 1); PG8_SCHED; PG8_LDA(At, 1, 0); PG8_STAGE(PG8_SA(0, 1), a2 + hstepA, voffA);
;             PG8_WAIT_V(8); PG8_WAIT_L(0); PG8_BAR; PG8_MMA(0, 0, At, B0); PG8_MMA(0, 1, At, B1); PG8_BAR; PG8_SCHED;
	s_setprio 1
	s_waitcnt lgkmcnt(0)
	v_mfma_f32_16x16x32_bf16 v[62:65], v[152:155], v[184:187], 0
	v_mfma_f32_16x16x32_bf16 v[58:61], v[160:163], v[184:187], 0
	v_mfma_f32_16x16x32_bf16 v[54:57], v[152:155], v[192:195], 0
	v_mfma_f32_16x16x32_bf16 v[50:53], v[160:163], v[192:195], 0
	v_mfma_f32_16x16x32_bf16 v[38:41], v[152:155], v[200:203], 0
	v_mfma_f32_16x16x32_bf16 v[34:37], v[160:163], v[200:203], 0
	v_mfma_f32_16x16x32_bf16 v[22:25], v[152:155], v[210:213], 0
	v_mfma_f32_16x16x32_bf16 v[18:21], v[160:163], v[210:213], 0
	v_mfma_f32_16x16x32_bf16 v[62:65], v[156:159], v[188:191], v[62:65]
	v_mfma_f32_16x16x32_bf16 v[58:61], v[164:167], v[188:191], v[58:61]
	v_mfma_f32_16x16x32_bf16 v[54:57], v[156:159], v[196:199], v[54:57]
	v_mfma_f32_16x16x32_bf16 v[50:53], v[164:167], v[196:199], v[50:53]
	v_mfma_f32_16x16x32_bf16 v[38:41], v[156:159], v[204:207], v[38:41]
	v_mfma_f32_16x16x32_bf16 v[34:37], v[164:167], v[204:207], v[34:37]
	v_mfma_f32_16x16x32_bf16 v[22:25], v[156:159], v[214:217], v[22:25]
	v_mfma_f32_16x16x32_bf16 v[18:21], v[164:167], v[214:217], v[18:21]
	s_setprio 0
	s_setprio 1
	v_mfma_f32_16x16x32_bf16 v[46:49], v[168:171], v[184:187], 0
	v_mfma_f32_16x16x32_bf16 v[42:45], v[176:179], v[184:187], 0
	v_mfma_f32_16x16x32_bf16 v[30:33], v[168:171], v[192:195], 0
	v_mfma_f32_16x16x32_bf16 v[26:29], v[176:179], v[192:195], 0
	v_mfma_f32_16x16x32_bf16 v[14:17], v[168:171], v[200:203], 0
	v_mfma_f32_16x16x32_bf16 v[10:13], v[176:179], v[200:203], 0
	v_mfma_f32_16x16x32_bf16 v[6:9], v[168:171], v[210:213], 0
	v_mfma_f32_16x16x32_bf16 v[2:5], v[176:179], v[210:213], 0
	v_mfma_f32_16x16x32_bf16 v[46:49], v[172:175], v[188:191], v[46:49]
	v_mfma_f32_16x16x32_bf16 v[42:45], v[180:183], v[188:191], v[42:45]
	v_mfma_f32_16x16x32_bf16 v[30:33], v[172:175], v[196:199], v[30:33]
	v_mfma_f32_16x16x32_bf16 v[26:29], v[180:183], v[196:199], v[26:29]
	v_mfma_f32_16x16x32_bf16 v[14:17], v[172:175], v[204:207], v[14:17]
	v_mfma_f32_16x16x32_bf16 v[10:13], v[180:183], v[204:207], v[10:13]
	v_mfma_f32_16x16x32_bf16 v[6:9], v[172:175], v[214:217], v[6:9]
	v_mfma_f32_16x16x32_bf16 v[2:5], v[180:183], v[214:217], v[2:5]
	s_setprio 0
	s_barrier
	s_add_i32 s58, 0, 0x18000
	v_add_u32_e32 v151, s58, v146
	s_add_i32 s59, 0, 0x1c000
	ds_read_b128 v[152:155], v151
	ds_read_b128 v[156:159], v151 offset:1024
	ds_read_b128 v[160:163], v151 offset:2048
	ds_read_b128 v[164:167], v151 offset:3072
	v_add_u32_e32 v151, s59, v146
	ds_read_b128 v[168:171], v151
	ds_read_b128 v[172:175], v151 offset:1024
	ds_read_b128 v[176:179], v151 offset:2048
	ds_read_b128 v[180:183], v151 offset:3072
	s_add_u32 s34, s34, 0x100000
	s_addc_u32 s35, s35, 0
	s_mov_b32 m0, s40
	v_lshl_add_u64 v[226:227], s[34:35], 0, v[136:137]
	ds_read_b128 v[184:187], v150 offset:32768
	ds_read_b128 v[188:191], v150 offset:33792
	ds_read_b128 v[192:195], v150 offset:34816
	ds_read_b128 v[196:199], v150 offset:35840
	ds_read_b128 v[200:203], v150 offset:36864
	ds_read_b128 v[204:207], v150 offset:37888
	ds_read_b128 v[210:213], v150 offset:38912
	ds_read_b128 v[214:217], v150 offset:39936
	global_load_lds_dwordx4 v[226:227], off
	v_lshl_add_u64 v[226:227], s[34:35], 0, v[132:133]
	s_mov_b32 m0, s41
	s_nop 0
	global_load_lds_dwordx4 v[226:227], off
	s_waitcnt vmcnt(8)
	s_waitcnt lgkmcnt(0)
	s_barrier
	s_setprio 1
	s_waitcnt lgkmcnt(0)
	v_mfma_f32_16x16x32_bf16 v[126:129], v[152:155], v[184:187], v[126:129]
	v_mfma_f32_16x16x32_bf16 v[122:125], v[160:163], v[184:187], v[122:125]
	v_mfma_f32_16x16x32_bf16 v[118:121], v[152:155], v[192:195], v[118:121]
	v_mfma_f32_16x16x32_bf16 v[114:117], v[160:163], v[192:195], v[114:117]
	v_mfma_f32_16x16x32_bf16 v[102:105], v[152:155], v[200:203], v[102:105]
	v_mfma_f32_16x16x32_bf16 v[98:101], v[160:163], v[200:203], v[98:101]
	v_mfma_f32_16x16x32_bf16 v[86:89], v[152:155], v[210:213], v[86:89]
	v_mfma_f32_16x16x32_bf16 v[82:85], v[160:163], v[210:213], v[82:85]
	v_mfma_f32_16x16x32_bf16 v[126:129], v[156:159], v[188:191], v[126:129]
	v_mfma_f32_16x16x32_bf16 v[122:125], v[164:167], v[188:191], v[122:125]
	v_mfma_f32_16x16x32_bf16 v[118:121], v[156:159], v[196:199], v[118:121]
	v_mfma_f32_16x16x32_bf16 v[114:117], v[164:167], v[196:199], v[114:117]
	v_mfma_f32_16x16x32_bf16 v[102:105], v[156:159], v[204:207], v[102:105]
	v_mfma_f32_16x16x32_bf16 v[98:101], v[164:167], v[204:207], v[98:101]
	v_mfma_f32_16x16x32_bf16 v[86:89], v[156:159], v[214:217], v[86:89]
	v_mfma_f32_16x16x32_bf16 v[82:85], v[164:167], v[214:217], v[82:85]
	s_setprio 0
	s_setprio 1
	v_mfma_f32_16x16x32_bf16 v[110:113], v[168:171], v[184:187], v[110:113]
	v_mfma_f32_16x16x32_bf16 v[106:109], v[176:179], v[184:187], v[106:109]
	v_mfma_f32_16x16x32_bf16 v[94:97], v[168:171], v[192:195], v[94:97]
	v_mfma_f32_16x16x32_bf16 v[90:93], v[176:179], v[192:195], v[90:93]
	v_mfma_f32_16x16x32_bf16 v[78:81], v[168:171], v[200:203], v[78:81]
	v_mfma_f32_16x16x32_bf16 v[74:77], v[176:179], v[200:203], v[74:77]
	v_mfma_f32_16x16x32_bf16 v[70:73], v[168:171], v[210:213], v[70:73]
	v_mfma_f32_16x16x32_bf16 v[66:69], v[176:179], v[210:213], v[66:69]
	v_mfma_f32_16x16x32_bf16 v[110:113], v[172:175], v[188:191], v[110:113]
	v_mfma_f32_16x16x32_bf16 v[106:109], v[180:183], v[188:191], v[106:109]
	v_mfma_f32_16x16x32_bf16 v[94:97], v[172:175], v[196:199], v[94:97]
	v_mfma_f32_16x16x32_bf16 v[90:93], v[180:183], v[196:199], v[90:93]
	v_mfma_f32_16x16x32_bf16 v[78:81], v[172:175], v[204:207], v[78:81]
	v_mfma_f32_16x16x32_bf16 v[74:77], v[180:183], v[204:207], v[74:77]
	v_mfma_f32_16x16x32_bf16 v[70:73], v[172:175], v[214:217], v[70:73]
	v_mfma_f32_16x16x32_bf16 v[66:69], v[180:183], v[214:217], v[66:69]
	s_setprio 0
	s_barrier
; #define PG8_STAGE(bufoff, gbase, voff) do { _Pragma("unroll") for (int _i = 0; _i < 2; ++_i) \
;         __builtin_amdgcn_global_load_lds((const unsigned*)((const char*)(gbase) + (voff)[_i]), (PG8_LAS unsigned*)(lds + (bufoff) + ldsw + _i * 8192), 16, 0, 0); } while (0)
; #define PG8_LDA(dst, b, h) do { _Pragma("unroll") for (int m = 0; m < 4; ++m) _Pragma("unroll") for (int k = 0; k < 2; ++k) dst[m][k] = *(const PG8_LAS bf16x8*)(lds + PG8_SA(b, h) + aoff + m * 2048 + k * 1024); } while (0)
; #define PG8_LDB(dst, b, h) do { _Pragma("unroll") for (int n = 0; n < 2; ++n) _Pragma("unroll") for (int k = 0; k < 2; ++k) dst[n][k] = *(const PG8_LAS bf16x8*)(lds + PG8_SB(b, h) + boff + n * 2048 + k * 1024); } while (0)
; template <class Epi, class Sched, bool ALIGN_EPI = false, bool SP2 = false>
; __device__ __forceinline__ void gemm_phase(PG8_LAS unsigned char* lds, const Gemm g, const Sched& S, const Epi& E) {
;     ...
;         for (int t = 0; t < nt; t += 2) {
;             const bool last = (t == nt - 2);
;             const char* a1 = cA + (size_t)(t + 1) * kstep;
;             const char* a2 = last ? nA : cA + (size_t)(t + 2) * kstep; const char* b2 = last ? nB : cB + (size_t)(t + 2) * kstep;
;             const char* a3 = a2 + kstep; const char* b3 = b2 + kstep;
;             if (last && has_next) S.a_ready(nxt);
;             if constexpr (SP2) {
;             PG8_LDB(B0, 0, 0); PG8_LDB(B1, 0, 1); PG8_SCHED; PG8_LDA(At, 0, 0); PG8_STAGE(PG8_SA(1, 1), a1 + hstepA, voffA);
;             PG8_WAIT_V(8); PG8_WAIT_L(0); PG8_BAR; PG8_MMA(0, 0, At, B0); PG8_MMA(0, 1, At, B1); PG8_BAR; PG8_SCHED;
;             PG8_LDA(At, 0, 1); PG8_STAGE(PG8_SB(0, 0), b2, voffB); PG8_STAGE(PG8_SB(0, 1), b2 + hstepB, voffB); PG8_STAGE(PG8_SA(0, 0), a2, voffA);
;             PG8_WAIT_V(8); PG8_WAIT_L(0); PG8_BAR; PG8_MMA(1, 0, At, B0); PG8_MMA(1, 1, At, B1); PG8_BAR; PG8_SCHED;
;             PG8_LDB(B0, 1, 0); PG8_LDB(B1, 1, 1); PG8_SCHED; PG8_LDA(At, 1, 0); PG8_STAGE(PG8_SA(0, 1), a2 + hstepA, voffA);
;             PG8_WAIT_V(8); PG8_WAIT_L(0); PG8_BAR; PG8_MMA(0, 0, At, B0); PG8_MMA(0, 1, At, B1); PG8_BAR; PG8_SCHED;
;             PG8_LDA(At, 1, 1); PG8_STAGE(PG8_SB(1, 0), b3, voffB); PG8_STAGE(PG8_SB(1, 1), b3 + hstepB, voffB); PG8_STAGE(PG8_SA(1, 0), a3, voffA);
;             PG8_WAIT_V(8); PG8_WAIT_L(0); PG8_BAR; PG8_MMA(1, 0, At, B0); PG8_MMA(1, 1, At, B1); PG8_BAR; PG8_SCHED;
	s_add_i32 s34, s58, s36
	v_lshl_add_u64 v[218:219], v[218:219], 0, s[6:7]
	s_mov_b32 m0, s34
	ds_read_b128 v[184:187], v150 offset:49152
	ds_read_b128 v[188:191], v150 offset:50176
	ds_read_b128 v[192:195], v150 offset:51200
	ds_read_b128 v[196:199], v150 offset:52224
	ds_read_b128 v[200:203], v150 offset:53248
	ds_read_b128 v[204:207], v150 offset:54272
	ds_read_b128 v[210:213], v150 offset:55296
	ds_read_b128 v[214:217], v150 offset:56320
	global_load_lds_dwordx4 v[218:219], off
	s_add_i32 m0, s34, 0x2000
	s_add_u32 s30, s30, 0x100080
	v_lshl_add_u64 v[218:219], v[220:221], 0, s[6:7]
	s_addc_u32 s31, s31, 0
	s_add_i32 s34, s59, s36
	global_load_lds_dwordx4 v[218:219], off
	v_lshl_add_u64 v[218:219], s[30:31], 0, v[134:135]
	s_mov_b32 m0, s34
	s_nop 0
	global_load_lds_dwordx4 v[218:219], off
	v_lshl_add_u64 v[218:219], s[30:31], 0, v[130:131]
	s_add_i32 m0, s34, 0x2000
	s_nop 0
	global_load_lds_dwordx4 v[218:219], off
	v_lshl_add_u64 v[218:219], v[222:223], 0, s[6:7]
	s_mov_b32 m0, s43
	s_nop 0
	global_load_lds_dwordx4 v[218:219], off
	v_lshl_add_u64 v[218:219], v[224:225], 0, s[6:7]
	s_mov_b32 m0, s44
	s_nop 0
	global_load_lds_dwordx4 v[218:219], off
	s_waitcnt vmcnt(8)
	s_waitcnt lgkmcnt(0)
	s_barrier
	s_setprio 1
	s_waitcnt lgkmcnt(0)
	v_mfma_f32_16x16x32_bf16 v[62:65], v[152:155], v[184:187], v[62:65]
	v_mfma_f32_16x16x32_bf16 v[58:61], v[160:163], v[184:187], v[58:61]
	v_mfma_f32_16x16x32_bf16 v[54:57], v[152:155], v[192:195], v[54:57]
	v_mfma_f32_16x16x32_bf16 v[50:53], v[160:163], v[192:195], v[50:53]
	v_mfma_f32_16x16x32_bf16 v[38:41], v[152:155], v[200:203], v[38:41]
	v_mfma_f32_16x16x32_bf16 v[34:37], v[160:163], v[200:203], v[34:37]
	v_mfma_f32_16x16x32_bf16 v[22:25], v[152:155], v[210:213], v[22:25]
	v_mfma_f32_16x16x32_bf16 v[18:21], v[160:163], v[210:213], v[18:21]
	v_mfma_f32_16x16x32_bf16 v[62:65], v[156:159], v[188:191], v[62:65]
	v_mfma_f32_16x16x32_bf16 v[58:61], v[164:167], v[188:191], v[58:61]
	v_mfma_f32_16x16x32_bf16 v[54:57], v[156:159], v[196:199], v[54:57]
	v_mfma_f32_16x16x32_bf16 v[50:53], v[164:167], v[196:199], v[50:53]
	v_mfma_f32_16x16x32_bf16 v[38:41], v[156:159], v[204:207], v[38:41]
	v_mfma_f32_16x16x32_bf16 v[34:37], v[164:167], v[204:207], v[34:37]
	v_mfma_f32_16x16x32_bf16 v[22:25], v[156:159], v[214:217], v[22:25]
	v_mfma_f32_16x16x32_bf16 v[18:21], v[164:167], v[214:217], v[18:21]
	s_setprio 0
	s_setprio 1
	v_mfma_f32_16x16x32_bf16 v[46:49], v[168:171], v[184:187], v[46:49]
	v_mfma_f32_16x16x32_bf16 v[42:45], v[176:179], v[184:187], v[42:45]
	v_mfma_f32_16x16x32_bf16 v[30:33], v[168:171], v[192:195], v[30:33]
	v_mfma_f32_16x16x32_bf16 v[26:29], v[176:179], v[192:195], v[26:29]
	v_mfma_f32_16x16x32_bf16 v[14:17], v[168:171], v[200:203], v[14:17]
	v_mfma_f32_16x16x32_bf16 v[10:13], v[176:179], v[200:203], v[10:13]
	v_mfma_f32_16x16x32_bf16 v[6:9], v[168:171], v[210:213], v[6:9]
	v_mfma_f32_16x16x32_bf16 v[2:5], v[176:179], v[210:213], v[2:5]
	v_mfma_f32_16x16x32_bf16 v[46:49], v[172:175], v[188:191], v[46:49]
	v_mfma_f32_16x16x32_bf16 v[42:45], v[180:183], v[188:191], v[42:45]
	v_mfma_f32_16x16x32_bf16 v[30:33], v[172:175], v[196:199], v[30:33]
	v_mfma_f32_16x16x32_bf16 v[26:29], v[180:183], v[196:199], v[26:29]
	v_mfma_f32_16x16x32_bf16 v[14:17], v[172:175], v[204:207], v[14:17]
	v_mfma_f32_16x16x32_bf16 v[10:13], v[180:183], v[204:207], v[10:13]
	v_mfma_f32_16x16x32_bf16 v[6:9], v[172:175], v[214:217], v[6:9]
	v_mfma_f32_16x16x32_bf16 v[2:5], v[180:183], v[214:217], v[2:5]
	s_setprio 0
	s_barrier
	s_add_i32 s57, s57, 2
	s_add_u32 s28, s28, 0x100
	s_addc_u32 s29, s29, 0
	s_add_u32 s55, s55, 0x100
	s_addc_u32 s56, s56, 0
	s_cmp_gt_u32 s57, 61
	s_cbranch_scc1 .Lpeel_exit_23
	.p2align 6

; #define PG8_STAGE(bufoff, gbase, voff) do { _Pragma("unroll") for (int _i = 0; _i < 2; ++_i) \
;         __builtin_amdgcn_global_load_lds((const unsigned*)((const char*)(gbase) + (voff)[_i]), (PG8_LAS unsigned*)(lds + (bufoff) + ldsw + _i * 8192), 16, 0, 0); } while (0)
; #define PG8_LDA(dst, b, h) do { _Pragma("unroll") for (int m = 0; m < 4; ++m) _Pragma("unroll") for (int k = 0; k < 2; ++k) dst[m][k] = *(const PG8_LAS bf16x8*)(lds + PG8_SA(b, h) + aoff + m * 2048 + k * 1024); } while (0)
; #define PG8_LDB(dst, b, h) do { _Pragma("unroll") for (int n = 0; n < 2; ++n) _Pragma("unroll") for (int k = 0; k < 2; ++k) dst[n][k] = *(const PG8_LAS bf16x8*)(lds + PG8_SB(b, h) + boff + n * 2048 + k * 1024); } while (0)
; #define PG8_MMA(ai, bj, At, Bt) do { __builtin_amdgcn_s_setprio(1); _Pragma("unroll") for (int m = 0; m < 4; ++m) _Pragma("unroll") for (int n = 0; n < 2; ++n) _Pragma("unroll") for (int k = 0; k < 2; ++k) \
;         acc[ai][bj][m][n] = __builtin_amdgcn_mfma_f32_16x16x32_bf16(Bt[n][k], At[m][k], acc[ai][bj][m][n], 0, 0, 0); __builtin_amdgcn_s_setprio(0); } while (0)
; #define PG8_BAR __builtin_amdgcn_s_barrier()
; template <class Epi, class Sched, bool ALIGN_EPI = false, bool SP2 = false>
; __device__ __forceinline__ void gemm_phase(PG8_LAS unsigned char* lds, const Gemm g, const Sched& S, const Epi& E) {
;     ...
;         const bool has_next = S.next(ui + 1, nxt);
;         const char* nA = has_next ? (const char*)g.A + (size_t)nxt.pm * tstepA : cA; const char* nB = has_next ? (const char*)g.Bt + (size_t)nxt.pn * tstepB : cB;
;         for (int t = 0; t < nt; t += 2) {
;             const bool last = (t == nt - 2);
;             const char* a1 = cA + (size_t)(t + 1) * kstep;
;             const char* a2 = last ? nA : cA + (size_t)(t + 2) * kstep; const char* b2 = last ? nB : cB + (size_t)(t + 2) * kstep;
;             const char* a3 = a2 + kstep; const char* b3 = b2 + kstep;
;             if (last && has_next) S.a_ready(nxt);
;             if constexpr (SP2) {
;             PG8_LDB(B0, 0, 0); PG8_LDB(B1, 0, 1); PG8_SCHED; PG8_LDA(At, 0, 0); PG8_STAGE(PG8_SA(1, 1), a1 + hstepA, voffA);
;             PG8_WAIT_V(8); PG8_WAIT_L(0); PG8_BAR; PG8_MMA(0, 0, At, B0); PG8_MMA(0, 1, At, B1); PG8_BAR; PG8_SCHED;
;             PG8_LDA(At, 0, 1); PG8_STAGE(PG8_SB(0, 0), b2, voffB); PG8_STAGE(PG8_SB(0, 1), b2 + hstepB, voffB); PG8_STAGE(PG8_SA(0, 0), a2, voffA);
.LBB0_2386:
	s_ashr_i32 s13, s12, 31
	s_lshl_b64 s[14:15], s[12:13], 20
	s_add_u32 s14, s86, s14
	s_addc_u32 s15, s87, s15
	s_and_b64 s[16:17], s[4:5], exec
	s_cselect_b32 s13, s15, s21
	s_cselect_b32 s42, s14, s20
	s_ashr_i32 s11, s10, 31
	s_lshl_b64 s[16:17], s[10:11], 20
	v_readlane_b32 s24, v254, 0
	v_readlane_b32 s25, v254, 1
	s_add_u32 s16, s24, s16
	s_addc_u32 s17, s25, s17
	s_and_b64 s[24:25], s[4:5], exec
	s_cselect_b32 s11, s17, s23
	s_cselect_b32 s43, s16, s22
	s_add_u32 s20, s20, 0x80080
	s_addc_u32 s21, s21, 0
	s_add_u32 s44, s22, 0x100
	s_addc_u32 s45, s23, 0
	s_mov_b32 s46, -2
	ds_read_b128 v[154:157], v150
	ds_read_b128 v[158:161], v150 offset:1024
	ds_read_b128 v[162:165], v150 offset:2048
	ds_read_b128 v[166:169], v150 offset:3072
	ds_read_b128 v[170:173], v151
	ds_read_b128 v[174:177], v151 offset:1024
	ds_read_b128 v[178:181], v151 offset:2048
	ds_read_b128 v[182:185], v151 offset:3072
	s_add_u32 s22, s20, 0xfff80080
	s_addc_u32 s23, s21, -1
	s_cmp_eq_u32 s46, 28
	s_cselect_b32 s25, s13, s23
	s_cselect_b32 s24, s42, s22
	s_cselect_b32 s23, s11, s45
	s_cselect_b32 s22, s43, s44
	v_lshl_add_u64 v[146:147], s[20:21], 0, v[138:139]
	s_add_i32 m0, s19, 0xc000
	ds_read_b128 v[186:189], v152
	ds_read_b128 v[190:193], v152 offset:1024
	ds_read_b128 v[194:197], v152 offset:2048
	ds_read_b128 v[198:201], v152 offset:3072
	ds_read_b128 v[202:205], v152 offset:4096
	ds_read_b128 v[210:213], v152 offset:5120
	ds_read_b128 v[214:217], v152 offset:6144
	ds_read_b128 v[218:221], v152 offset:7168
	global_load_lds_dwordx4 v[146:147], off
	v_lshl_add_u64 v[146:147], s[20:21], 0, v[140:141]
	s_add_i32 m0, s19, 0xe000
	s_nop 0
	global_load_lds_dwordx4 v[146:147], off
	s_waitcnt vmcnt(8)
	s_waitcnt lgkmcnt(0)
	s_barrier
	s_setprio 1
	s_waitcnt lgkmcnt(0)
	v_mfma_f32_16x16x32_bf16 v[126:129], v[154:157], v[186:189], 0
	v_mfma_f32_16x16x32_bf16 v[122:125], v[162:165], v[186:189], 0
	v_mfma_f32_16x16x32_bf16 v[110:113], v[154:157], v[194:197], 0
	v_mfma_f32_16x16x32_bf16 v[106:109], v[162:165], v[194:197], 0
	v_mfma_f32_16x16x32_bf16 v[94:97], v[154:157], v[202:205], 0
	v_mfma_f32_16x16x32_bf16 v[90:93], v[162:165], v[202:205], 0
	v_mfma_f32_16x16x32_bf16 v[78:81], v[154:157], v[214:217], 0
	v_mfma_f32_16x16x32_bf16 v[74:77], v[162:165], v[214:217], 0
	v_mfma_f32_16x16x32_bf16 v[126:129], v[158:161], v[190:193], v[126:129]
	v_mfma_f32_16x16x32_bf16 v[122:125], v[166:169], v[190:193], v[122:125]
	v_mfma_f32_16x16x32_bf16 v[110:113], v[158:161], v[198:201], v[110:113]
	v_mfma_f32_16x16x32_bf16 v[106:109], v[166:169], v[198:201], v[106:109]
	v_mfma_f32_16x16x32_bf16 v[94:97], v[158:161], v[210:213], v[94:97]
	v_mfma_f32_16x16x32_bf16 v[90:93], v[166:169], v[210:213], v[90:93]
	v_mfma_f32_16x16x32_bf16 v[78:81], v[158:161], v[218:221], v[78:81]
	v_mfma_f32_16x16x32_bf16 v[74:77], v[166:169], v[218:221], v[74:77]
	s_setprio 0
	s_setprio 1
	v_mfma_f32_16x16x32_bf16 v[118:121], v[170:173], v[186:189], 0
	v_mfma_f32_16x16x32_bf16 v[114:117], v[178:181], v[186:189], 0
	v_mfma_f32_16x16x32_bf16 v[102:105], v[170:173], v[194:197], 0
	v_mfma_f32_16x16x32_bf16 v[98:101], v[178:181], v[194:197], 0
	v_mfma_f32_16x16x32_bf16 v[86:89], v[170:173], v[202:205], 0
	v_mfma_f32_16x16x32_bf16 v[82:85], v[178:181], v[202:205], 0
	v_mfma_f32_16x16x32_bf16 v[70:73], v[170:173], v[214:217], 0
	v_mfma_f32_16x16x32_bf16 v[66:69], v[178:181], v[214:217], 0
	v_mfma_f32_16x16x32_bf16 v[118:121], v[174:177], v[190:193], v[118:121]
	v_mfma_f32_16x16x32_bf16 v[114:117], v[182:185], v[190:193], v[114:117]
	v_mfma_f32_16x16x32_bf16 v[102:105], v[174:177], v[198:201], v[102:105]
	v_mfma_f32_16x16x32_bf16 v[98:101], v[182:185], v[198:201], v[98:101]
	v_mfma_f32_16x16x32_bf16 v[86:89], v[174:177], v[210:213], v[86:89]
	v_mfma_f32_16x16x32_bf16 v[82:85], v[182:185], v[210:213], v[82:85]
	v_mfma_f32_16x16x32_bf16 v[70:73], v[174:177], v[218:221], v[70:73]
	v_mfma_f32_16x16x32_bf16 v[66:69], v[182:185], v[218:221], v[66:69]
	s_setprio 0
	s_barrier
	s_add_i32 s47, s38, s27
	v_lshl_add_u64 v[146:147], s[22:23], 0, v[134:135]
	s_mov_b32 m0, s47
	ds_read_b128 v[186:189], v152 offset:16384
	ds_read_b128 v[190:193], v152 offset:17408
	ds_read_b128 v[194:197], v152 offset:18432
	ds_read_b128 v[198:201], v152 offset:19456
	ds_read_b128 v[202:205], v152 offset:20480
	ds_read_b128 v[210:213], v152 offset:21504
	ds_read_b128 v[214:217], v152 offset:22528
	ds_read_b128 v[218:221], v152 offset:23552
	global_load_lds_dwordx4 v[146:147], off
	s_add_i32 m0, s47, 0x2000
	s_add_u32 s48, s22, 0x80000
	v_lshl_add_u64 v[206:207], s[22:23], 0, v[130:131]
	s_addc_u32 s49, s23, 0
	s_add_i32 s47, s39, s27
	global_load_lds_dwordx4 v[206:207], off
	v_lshl_add_u64 v[222:223], s[48:49], 0, v[134:135]
	s_mov_b32 m0, s47
	v_lshl_add_u64 v[224:225], s[24:25], 0, v[132:133]
	global_load_lds_dwordx4 v[222:223], off
	v_lshl_add_u64 v[222:223], s[48:49], 0, v[130:131]
	s_add_i32 m0, s47, 0x2000
	s_nop 0
	global_load_lds_dwordx4 v[222:223], off
	v_lshl_add_u64 v[222:223], s[24:25], 0, v[136:137]
	s_mov_b32 m0, s19
	s_nop 0
	global_load_lds_dwordx4 v[222:223], off
	s_mov_b32 m0, s30
	s_nop 0
	global_load_lds_dwordx4 v[224:225], off
	s_waitcnt vmcnt(8)
	s_waitcnt lgkmcnt(0)
	s_barrier
; #define PG8_STAGE(bufoff, gbase, voff) do { _Pragma("unroll") for (int _i = 0; _i < 2; ++_i) \
;         __builtin_amdgcn_global_load_lds((const unsigned*)((const char*)(gbase) + (voff)[_i]), (PG8_LAS unsigned*)(lds + (bufoff) + ldsw + _i * 8192), 16, 0, 0); } while (0)
; #define PG8_LDA(dst, b, h) do { _Pragma("unroll") for (int m = 0; m < 4; ++m) _Pragma("unroll") for (int k = 0; k < 2; ++k) dst[m][k] = *(const PG8_LAS bf16x8*)(lds + PG8_SA(b, h) + aoff + m * 2048 + k * 1024); } while (0)
; #define PG8_LDB(dst, b, h) do { _Pragma("unroll") for (int n = 0; n < 2; ++n) _Pragma("unroll") for (int k = 0; k < 2; ++k) dst[n][k] = *(const PG8_LAS bf16x8*)(lds + PG8_SB(b, h) + boff + n * 2048 + k * 1024); } while (0)
; #define PG8_MMA(ai, bj, At, Bt) do { __builtin_amdgcn_s_setprio(1); _Pragma("unroll") for (int m = 0; m < 4; ++m) _Pragma("unroll") for (int n = 0; n < 2; ++n) _Pragma("unroll") for (int k = 0; k < 2; ++k) \
;         acc[ai][bj][m][n] = __builtin_amdgcn_mfma_f32_16x16x32_bf16(Bt[n][k], At[m][k], acc[ai][bj][m][n], 0, 0, 0); __builtin_amdgcn_s_setprio(0); } while (0)
; #define PG8_WAIT_V(n) asm volatile("s_waitcnt vmcnt(" #n ")" ::: "memory")
; #define PG8_WAIT_L(n) asm volatile("s_waitcnt lgkmcnt(" #n ")" ::: "memory")
; #define PG8_BAR __builtin_amdgcn_s_barrier()
; #define PG8_SCHED __builtin_amdgcn_sched_barrier(0)
; template <class Epi, class Sched, bool ALIGN_EPI = false, bool SP2 = false>
; __device__ __forceinline__ void gemm_phase(PG8_LAS unsigned char* lds, const Gemm g, const Sched& S, const Epi& E) {
;     ...
;             PG8_LDA(At, 0, 1); PG8_STAGE(PG8_SB(0, 0), b2, voffB); PG8_STAGE(PG8_SB(0, 1), b2 + hstepB, voffB); PG8_STAGE(PG8_SA(0, 0), a2, voffA);
;             PG8_WAIT_V(8); PG8_WAIT_L(0); PG8_BAR; PG8_MMA(1, 0, At, B0); PG8_MMA(1, 1, At, B1); PG8_BAR; PG8_SCHED;
;             PG8_LDB(B0, 1, 0); PG8_LDB(B1, 1, 1); PG8_SCHED; PG8_LDA(At, 1, 0); PG8_STAGE(PG8_SA(0, 1), a2 + hstepA, voffA);
;             PG8_WAIT_V(8); PG8_WAIT_L(0); PG8_BAR; PG8_MMA(0, 0, At, B0); PG8_MMA(0, 1, At, B1); PG8_BAR; PG8_SCHED;
	s_setprio 1
	s_waitcnt lgkmcnt(0)
	v_mfma_f32_16x16x32_bf16 v[62:65], v[154:157], v[186:189], 0
	v_mfma_f32_16x16x32_bf16 v[58:61], v[162:165], v[186:189], 0
	v_mfma_f32_16x16x32_bf16 v[46:49], v[154:157], v[194:197], 0
	v_mfma_f32_16x16x32_bf16 v[42:45], v[162:165], v[194:197], 0
	v_mfma_f32_16x16x32_bf16 v[30:33], v[154:157], v[202:205], 0
	v_mfma_f32_16x16x32_bf16 v[26:29], v[162:165], v[202:205], 0
	v_mfma_f32_16x16x32_bf16 v[14:17], v[154:157], v[214:217], 0
	v_mfma_f32_16x16x32_bf16 v[10:13], v[162:165], v[214:217], 0
	v_mfma_f32_16x16x32_bf16 v[62:65], v[158:161], v[190:193], v[62:65]
	v_mfma_f32_16x16x32_bf16 v[58:61], v[166:169], v[190:193], v[58:61]
	v_mfma_f32_16x16x32_bf16 v[46:49], v[158:161], v[198:201], v[46:49]
	v_mfma_f32_16x16x32_bf16 v[42:45], v[166:169], v[198:201], v[42:45]
	v_mfma_f32_16x16x32_bf16 v[30:33], v[158:161], v[210:213], v[30:33]
	v_mfma_f32_16x16x32_bf16 v[26:29], v[166:169], v[210:213], v[26:29]
	v_mfma_f32_16x16x32_bf16 v[14:17], v[158:161], v[218:221], v[14:17]
	v_mfma_f32_16x16x32_bf16 v[10:13], v[166:169], v[218:221], v[10:13]
	s_setprio 0
	s_setprio 1
	v_mfma_f32_16x16x32_bf16 v[54:57], v[170:173], v[186:189], 0
	v_mfma_f32_16x16x32_bf16 v[50:53], v[178:181], v[186:189], 0
	v_mfma_f32_16x16x32_bf16 v[38:41], v[170:173], v[194:197], 0
	v_mfma_f32_16x16x32_bf16 v[34:37], v[178:181], v[194:197], 0
	v_mfma_f32_16x16x32_bf16 v[22:25], v[170:173], v[202:205], 0
	v_mfma_f32_16x16x32_bf16 v[18:21], v[178:181], v[202:205], 0
	v_mfma_f32_16x16x32_bf16 v[6:9], v[170:173], v[214:217], 0
	v_mfma_f32_16x16x32_bf16 v[2:5], v[178:181], v[214:217], 0
	v_mfma_f32_16x16x32_bf16 v[54:57], v[174:177], v[190:193], v[54:57]
	v_mfma_f32_16x16x32_bf16 v[50:53], v[182:185], v[190:193], v[50:53]
	v_mfma_f32_16x16x32_bf16 v[38:41], v[174:177], v[198:201], v[38:41]
	v_mfma_f32_16x16x32_bf16 v[34:37], v[182:185], v[198:201], v[34:37]
	v_mfma_f32_16x16x32_bf16 v[22:25], v[174:177], v[210:213], v[22:25]
	v_mfma_f32_16x16x32_bf16 v[18:21], v[182:185], v[210:213], v[18:21]
	v_mfma_f32_16x16x32_bf16 v[6:9], v[174:177], v[218:221], v[6:9]
	v_mfma_f32_16x16x32_bf16 v[2:5], v[182:185], v[218:221], v[2:5]
	s_setprio 0
	s_barrier
	s_add_i32 s47, 0, 0x18000
	v_add_u32_e32 v153, s47, v148
	s_add_i32 s48, 0, 0x1c000
	ds_read_b128 v[154:157], v153
	ds_read_b128 v[158:161], v153 offset:1024
	ds_read_b128 v[162:165], v153 offset:2048
	ds_read_b128 v[166:169], v153 offset:3072
	v_add_u32_e32 v153, s48, v148
	ds_read_b128 v[170:173], v153
	ds_read_b128 v[174:177], v153 offset:1024
	ds_read_b128 v[178:181], v153 offset:2048
	ds_read_b128 v[182:185], v153 offset:3072
	s_add_u32 s24, s24, 0x80000
	s_addc_u32 s25, s25, 0
	s_mov_b32 m0, s31
	v_lshl_add_u64 v[226:227], s[24:25], 0, v[136:137]
	ds_read_b128 v[186:189], v152 offset:32768
	ds_read_b128 v[190:193], v152 offset:33792
	ds_read_b128 v[194:197], v152 offset:34816
	ds_read_b128 v[198:201], v152 offset:35840
	ds_read_b128 v[202:205], v152 offset:36864
	ds_read_b128 v[210:213], v152 offset:37888
	ds_read_b128 v[214:217], v152 offset:38912
	ds_read_b128 v[218:221], v152 offset:39936
	global_load_lds_dwordx4 v[226:227], off
	v_lshl_add_u64 v[226:227], s[24:25], 0, v[132:133]
	s_mov_b32 m0, s33
	s_nop 0
	global_load_lds_dwordx4 v[226:227], off
	s_waitcnt vmcnt(8)
	s_waitcnt lgkmcnt(0)
	s_barrier
	s_setprio 1
	s_waitcnt lgkmcnt(0)
	v_mfma_f32_16x16x32_bf16 v[126:129], v[154:157], v[186:189], v[126:129]
	v_mfma_f32_16x16x32_bf16 v[122:125], v[162:165], v[186:189], v[122:125]
	v_mfma_f32_16x16x32_bf16 v[110:113], v[154:157], v[194:197], v[110:113]
	v_mfma_f32_16x16x32_bf16 v[106:109], v[162:165], v[194:197], v[106:109]
	v_mfma_f32_16x16x32_bf16 v[94:97], v[154:157], v[202:205], v[94:97]
	v_mfma_f32_16x16x32_bf16 v[90:93], v[162:165], v[202:205], v[90:93]
	v_mfma_f32_16x16x32_bf16 v[78:81], v[154:157], v[214:217], v[78:81]
	v_mfma_f32_16x16x32_bf16 v[74:77], v[162:165], v[214:217], v[74:77]
	v_mfma_f32_16x16x32_bf16 v[126:129], v[158:161], v[190:193], v[126:129]
	v_mfma_f32_16x16x32_bf16 v[122:125], v[166:169], v[190:193], v[122:125]
	v_mfma_f32_16x16x32_bf16 v[110:113], v[158:161], v[198:201], v[110:113]
	v_mfma_f32_16x16x32_bf16 v[106:109], v[166:169], v[198:201], v[106:109]
	v_mfma_f32_16x16x32_bf16 v[94:97], v[158:161], v[210:213], v[94:97]
	v_mfma_f32_16x16x32_bf16 v[90:93], v[166:169], v[210:213], v[90:93]
	v_mfma_f32_16x16x32_bf16 v[78:81], v[158:161], v[218:221], v[78:81]
	v_mfma_f32_16x16x32_bf16 v[74:77], v[166:169], v[218:221], v[74:77]
	s_setprio 0
	s_setprio 1
	v_mfma_f32_16x16x32_bf16 v[118:121], v[170:173], v[186:189], v[118:121]
	v_mfma_f32_16x16x32_bf16 v[114:117], v[178:181], v[186:189], v[114:117]
	v_mfma_f32_16x16x32_bf16 v[102:105], v[170:173], v[194:197], v[102:105]
	v_mfma_f32_16x16x32_bf16 v[98:101], v[178:181], v[194:197], v[98:101]
	v_mfma_f32_16x16x32_bf16 v[86:89], v[170:173], v[202:205], v[86:89]
	v_mfma_f32_16x16x32_bf16 v[82:85], v[178:181], v[202:205], v[82:85]
	v_mfma_f32_16x16x32_bf16 v[70:73], v[170:173], v[214:217], v[70:73]
	v_mfma_f32_16x16x32_bf16 v[66:69], v[178:181], v[214:217], v[66:69]
	v_mfma_f32_16x16x32_bf16 v[118:121], v[174:177], v[190:193], v[118:121]
	v_mfma_f32_16x16x32_bf16 v[114:117], v[182:185], v[190:193], v[114:117]
	v_mfma_f32_16x16x32_bf16 v[102:105], v[174:177], v[198:201], v[102:105]
	v_mfma_f32_16x16x32_bf16 v[98:101], v[182:185], v[198:201], v[98:101]
	v_mfma_f32_16x16x32_bf16 v[86:89], v[174:177], v[210:213], v[86:89]
	v_mfma_f32_16x16x32_bf16 v[82:85], v[182:185], v[210:213], v[82:85]
	v_mfma_f32_16x16x32_bf16 v[70:73], v[174:177], v[218:221], v[70:73]
	v_mfma_f32_16x16x32_bf16 v[66:69], v[182:185], v[218:221], v[66:69]
	s_setprio 0
	s_barrier
; #define PG8_STAGE(bufoff, gbase, voff) do { _Pragma("unroll") for (int _i = 0; _i < 2; ++_i) \
;         __builtin_amdgcn_global_load_lds((const unsigned*)((const char*)(gbase) + (voff)[_i]), (PG8_LAS unsigned*)(lds + (bufoff) + ldsw + _i * 8192), 16, 0, 0); } while (0)
; #define PG8_LDA(dst, b, h) do { _Pragma("unroll") for (int m = 0; m < 4; ++m) _Pragma("unroll") for (int k = 0; k < 2; ++k) dst[m][k] = *(const PG8_LAS bf16x8*)(lds + PG8_SA(b, h) + aoff + m * 2048 + k * 1024); } while (0)
; #define PG8_LDB(dst, b, h) do { _Pragma("unroll") for (int n = 0; n < 2; ++n) _Pragma("unroll") for (int k = 0; k < 2; ++k) dst[n][k] = *(const PG8_LAS bf16x8*)(lds + PG8_SB(b, h) + boff + n * 2048 + k * 1024); } while (0)
; template <class Epi, class Sched, bool ALIGN_EPI = false, bool SP2 = false>
; __device__ __forceinline__ void gemm_phase(PG8_LAS unsigned char* lds, const Gemm g, const Sched& S, const Epi& E) {
;     ...
;         for (int t = 0; t < nt; t += 2) {
;             const bool last = (t == nt - 2);
;             const char* a1 = cA + (size_t)(t + 1) * kstep;
;             const char* a2 = last ? nA : cA + (size_t)(t + 2) * kstep; const char* b2 = last ? nB : cB + (size_t)(t + 2) * kstep;
;             const char* a3 = a2 + kstep; const char* b3 = b2 + kstep;
;             if (last && has_next) S.a_ready(nxt);
;             if constexpr (SP2) {
;             PG8_LDB(B0, 0, 0); PG8_LDB(B1, 0, 1); PG8_SCHED; PG8_LDA(At, 0, 0); PG8_STAGE(PG8_SA(1, 1), a1 + hstepA, voffA);
;             PG8_WAIT_V(8); PG8_WAIT_L(0); PG8_BAR; PG8_MMA(0, 0, At, B0); PG8_MMA(0, 1, At, B1); PG8_BAR; PG8_SCHED;
;             PG8_LDA(At, 0, 1); PG8_STAGE(PG8_SB(0, 0), b2, voffB); PG8_STAGE(PG8_SB(0, 1), b2 + hstepB, voffB); PG8_STAGE(PG8_SA(0, 0), a2, voffA);
;             PG8_WAIT_V(8); PG8_WAIT_L(0); PG8_BAR; PG8_MMA(1, 0, At, B0); PG8_MMA(1, 1, At, B1); PG8_BAR; PG8_SCHED;
;             PG8_LDB(B0, 1, 0); PG8_LDB(B1, 1, 1); PG8_SCHED; PG8_LDA(At, 1, 0); PG8_STAGE(PG8_SA(0, 1), a2 + hstepA, voffA);
;             PG8_WAIT_V(8); PG8_WAIT_L(0); PG8_BAR; PG8_MMA(0, 0, At, B0); PG8_MMA(0, 1, At, B1); PG8_BAR; PG8_SCHED;
;             PG8_LDA(At, 1, 1); PG8_STAGE(PG8_SB(1, 0), b3, voffB); PG8_STAGE(PG8_SB(1, 1), b3 + hstepB, voffB); PG8_STAGE(PG8_SA(1, 0), a3, voffA);
;             PG8_WAIT_V(8); PG8_WAIT_L(0); PG8_BAR; PG8_MMA(1, 0, At, B0); PG8_MMA(1, 1, At, B1); PG8_BAR; PG8_SCHED;
	s_add_i32 s24, s47, s27
	v_lshl_add_u64 v[146:147], v[146:147], 0, s[2:3]
	s_mov_b32 m0, s24
	ds_read_b128 v[186:189], v152 offset:49152
	ds_read_b128 v[190:193], v152 offset:50176
	ds_read_b128 v[194:197], v152 offset:51200
	ds_read_b128 v[198:201], v152 offset:52224
	ds_read_b128 v[202:205], v152 offset:53248
	ds_read_b128 v[210:213], v152 offset:54272
	ds_read_b128 v[214:217], v152 offset:55296
	ds_read_b128 v[218:221], v152 offset:56320
	global_load_lds_dwordx4 v[146:147], off
	s_add_i32 m0, s24, 0x2000
	s_add_u32 s22, s22, 0x80080
	v_lshl_add_u64 v[146:147], v[206:207], 0, s[2:3]
	s_addc_u32 s23, s23, 0
	s_add_i32 s24, s48, s27
	global_load_lds_dwordx4 v[146:147], off
	v_lshl_add_u64 v[146:147], s[22:23], 0, v[134:135]
	s_mov_b32 m0, s24
	s_nop 0
	global_load_lds_dwordx4 v[146:147], off
	v_lshl_add_u64 v[146:147], s[22:23], 0, v[130:131]
	s_add_i32 m0, s24, 0x2000
	s_nop 0
	global_load_lds_dwordx4 v[146:147], off
	v_lshl_add_u64 v[146:147], v[222:223], 0, s[2:3]
	s_mov_b32 m0, s35
	s_nop 0
	global_load_lds_dwordx4 v[146:147], off
	v_lshl_add_u64 v[146:147], v[224:225], 0, s[2:3]
	s_mov_b32 m0, s36
	s_nop 0
	global_load_lds_dwordx4 v[146:147], off
	s_waitcnt vmcnt(8)
	s_waitcnt lgkmcnt(0)
	s_barrier
	s_setprio 1
	s_waitcnt lgkmcnt(0)
	v_mfma_f32_16x16x32_bf16 v[62:65], v[154:157], v[186:189], v[62:65]
	v_mfma_f32_16x16x32_bf16 v[58:61], v[162:165], v[186:189], v[58:61]
	v_mfma_f32_16x16x32_bf16 v[46:49], v[154:157], v[194:197], v[46:49]
	v_mfma_f32_16x16x32_bf16 v[42:45], v[162:165], v[194:197], v[42:45]
	v_mfma_f32_16x16x32_bf16 v[30:33], v[154:157], v[202:205], v[30:33]
	v_mfma_f32_16x16x32_bf16 v[26:29], v[162:165], v[202:205], v[26:29]
	v_mfma_f32_16x16x32_bf16 v[14:17], v[154:157], v[214:217], v[14:17]
	v_mfma_f32_16x16x32_bf16 v[10:13], v[162:165], v[214:217], v[10:13]
	v_mfma_f32_16x16x32_bf16 v[62:65], v[158:161], v[190:193], v[62:65]
	v_mfma_f32_16x16x32_bf16 v[58:61], v[166:169], v[190:193], v[58:61]
	v_mfma_f32_16x16x32_bf16 v[46:49], v[158:161], v[198:201], v[46:49]
	v_mfma_f32_16x16x32_bf16 v[42:45], v[166:169], v[198:201], v[42:45]
	v_mfma_f32_16x16x32_bf16 v[30:33], v[158:161], v[210:213], v[30:33]
	v_mfma_f32_16x16x32_bf16 v[26:29], v[166:169], v[210:213], v[26:29]
	v_mfma_f32_16x16x32_bf16 v[14:17], v[158:161], v[218:221], v[14:17]
	v_mfma_f32_16x16x32_bf16 v[10:13], v[166:169], v[218:221], v[10:13]
	s_setprio 0
	s_setprio 1
	v_mfma_f32_16x16x32_bf16 v[54:57], v[170:173], v[186:189], v[54:57]
	v_mfma_f32_16x16x32_bf16 v[50:53], v[178:181], v[186:189], v[50:53]
	v_mfma_f32_16x16x32_bf16 v[38:41], v[170:173], v[194:197], v[38:41]
	v_mfma_f32_16x16x32_bf16 v[34:37], v[178:181], v[194:197], v[34:37]
	v_mfma_f32_16x16x32_bf16 v[22:25], v[170:173], v[202:205], v[22:25]
	v_mfma_f32_16x16x32_bf16 v[18:21], v[178:181], v[202:205], v[18:21]
	v_mfma_f32_16x16x32_bf16 v[6:9], v[170:173], v[214:217], v[6:9]
	v_mfma_f32_16x16x32_bf16 v[2:5], v[178:181], v[214:217], v[2:5]
	v_mfma_f32_16x16x32_bf16 v[54:57], v[174:177], v[190:193], v[54:57]
	v_mfma_f32_16x16x32_bf16 v[50:53], v[182:185], v[190:193], v[50:53]
	v_mfma_f32_16x16x32_bf16 v[38:41], v[174:177], v[198:201], v[38:41]
	v_mfma_f32_16x16x32_bf16 v[34:37], v[182:185], v[198:201], v[34:37]
	v_mfma_f32_16x16x32_bf16 v[22:25], v[174:177], v[210:213], v[22:25]
	v_mfma_f32_16x16x32_bf16 v[18:21], v[182:185], v[210:213], v[18:21]
	v_mfma_f32_16x16x32_bf16 v[6:9], v[174:177], v[218:221], v[6:9]
	v_mfma_f32_16x16x32_bf16 v[2:5], v[182:185], v[218:221], v[2:5]
	s_setprio 0
	s_barrier
	s_add_i32 s46, s46, 2
	s_add_u32 s20, s20, 0x100
	s_addc_u32 s21, s21, 0
	s_add_u32 s44, s44, 0x100
	s_addc_u32 s45, s45, 0
	s_cmp_gt_u32 s46, 29
	s_cbranch_scc1 .Lpeel_exit_25
	.p2align 6

; #define PG8_STAGE(bufoff, gbase, voff) do { _Pragma("unroll") for (int _i = 0; _i < 2; ++_i) \
;         __builtin_amdgcn_global_load_lds((const unsigned*)((const char*)(gbase) + (voff)[_i]), (PG8_LAS unsigned*)(lds + (bufoff) + ldsw + _i * 8192), 16, 0, 0); } while (0)
; #define PG8_LDA(dst, b, h) do { _Pragma("unroll") for (int m = 0; m < 4; ++m) _Pragma("unroll") for (int k = 0; k < 2; ++k) dst[m][k] = *(const PG8_LAS bf16x8*)(lds + PG8_SA(b, h) + aoff + m * 2048 + k * 1024); } while (0)
; #define PG8_LDB(dst, b, h) do { _Pragma("unroll") for (int n = 0; n < 2; ++n) _Pragma("unroll") for (int k = 0; k < 2; ++k) dst[n][k] = *(const PG8_LAS bf16x8*)(lds + PG8_SB(b, h) + boff + n * 2048 + k * 1024); } while (0)
; #define PG8_MMA(ai, bj, At, Bt) do { __builtin_amdgcn_s_setprio(1); _Pragma("unroll") for (int m = 0; m < 4; ++m) _Pragma("unroll") for (int n = 0; n < 2; ++n) _Pragma("unroll") for (int k = 0; k < 2; ++k) \
;         acc[ai][bj][m][n] = __builtin_amdgcn_mfma_f32_16x16x32_bf16(Bt[n][k], At[m][k], acc[ai][bj][m][n], 0, 0, 0); __builtin_amdgcn_s_setprio(0); } while (0)
; #define PG8_BAR __builtin_amdgcn_s_barrier()
; template <class Epi, class Sched, bool ALIGN_EPI = false, bool SP2 = false>
; __device__ __forceinline__ void gemm_phase(PG8_LAS unsigned char* lds, const Gemm g, const Sched& S, const Epi& E) {
;     ...
;         const bool has_next = S.next(ui + 1, nxt);
;         const char* nA = has_next ? (const char*)g.A + (size_t)nxt.pm * tstepA : cA; const char* nB = has_next ? (const char*)g.Bt + (size_t)nxt.pn * tstepB : cB;
;         for (int t = 0; t < nt; t += 2) {
;             const bool last = (t == nt - 2);
;             const char* a1 = cA + (size_t)(t + 1) * kstep;
;             const char* a2 = last ? nA : cA + (size_t)(t + 2) * kstep; const char* b2 = last ? nB : cB + (size_t)(t + 2) * kstep;
;             const char* a3 = a2 + kstep; const char* b3 = b2 + kstep;
;             if (last && has_next) S.a_ready(nxt);
;             if constexpr (SP2) {
;             PG8_LDB(B0, 0, 0); PG8_LDB(B1, 0, 1); PG8_SCHED; PG8_LDA(At, 0, 0); PG8_STAGE(PG8_SA(1, 1), a1 + hstepA, voffA);
;             PG8_WAIT_V(8); PG8_WAIT_L(0); PG8_BAR; PG8_MMA(0, 0, At, B0); PG8_MMA(0, 1, At, B1); PG8_BAR; PG8_SCHED;
;             PG8_LDA(At, 0, 1); PG8_STAGE(PG8_SB(0, 0), b2, voffB); PG8_STAGE(PG8_SB(0, 1), b2 + hstepB, voffB); PG8_STAGE(PG8_SA(0, 0), a2, voffA);
.LBB0_2486:
	s_add_u32 s22, s22, 0x160080
	s_addc_u32 s23, s23, 0
	s_add_u32 s51, s24, 0x100
	s_addc_u32 s52, s25, 0
	s_mov_b32 s53, -2
	ds_read_b128 v[152:155], v148
	ds_read_b128 v[156:159], v148 offset:1024
	ds_read_b128 v[160:163], v148 offset:2048
	ds_read_b128 v[164:167], v148 offset:3072
	ds_read_b128 v[168:171], v149
	ds_read_b128 v[172:175], v149 offset:1024
	ds_read_b128 v[176:179], v149 offset:2048
	ds_read_b128 v[180:183], v149 offset:3072
	s_add_u32 s24, s22, 0xffea0080
	s_addc_u32 s25, s23, -1
	s_cmpk_eq_i32 s53, 0x54
	s_cselect_b32 s27, s7, s25
	s_cselect_b32 s26, s6, s24
	s_cselect_b32 s25, s21, s52
	s_cselect_b32 s24, s20, s51
	v_lshl_add_u64 v[218:219], s[22:23], 0, v[138:139]
	s_add_i32 m0, s33, 0xc000
	ds_read_b128 v[184:187], v150
	ds_read_b128 v[188:191], v150 offset:1024
	ds_read_b128 v[192:195], v150 offset:2048
	ds_read_b128 v[196:199], v150 offset:3072
	ds_read_b128 v[200:203], v150 offset:4096
	ds_read_b128 v[204:207], v150 offset:5120
	ds_read_b128 v[210:213], v150 offset:6144
	ds_read_b128 v[214:217], v150 offset:7168
	global_load_lds_dwordx4 v[218:219], off
	v_lshl_add_u64 v[218:219], s[22:23], 0, v[140:141]
	s_add_i32 m0, s33, 0xe000
	s_nop 0
	global_load_lds_dwordx4 v[218:219], off
	s_waitcnt vmcnt(8)
	s_waitcnt lgkmcnt(0)
	s_barrier
	s_setprio 1
	s_waitcnt lgkmcnt(0)
	v_mfma_f32_16x16x32_bf16 v[126:129], v[152:155], v[184:187], 0
	v_mfma_f32_16x16x32_bf16 v[122:125], v[160:163], v[184:187], 0
	v_mfma_f32_16x16x32_bf16 v[118:121], v[152:155], v[192:195], 0
	v_mfma_f32_16x16x32_bf16 v[114:117], v[160:163], v[192:195], 0
	v_mfma_f32_16x16x32_bf16 v[102:105], v[152:155], v[200:203], 0
	v_mfma_f32_16x16x32_bf16 v[98:101], v[160:163], v[200:203], 0
	v_mfma_f32_16x16x32_bf16 v[86:89], v[152:155], v[210:213], 0
	v_mfma_f32_16x16x32_bf16 v[82:85], v[160:163], v[210:213], 0
	v_mfma_f32_16x16x32_bf16 v[126:129], v[156:159], v[188:191], v[126:129]
	v_mfma_f32_16x16x32_bf16 v[122:125], v[164:167], v[188:191], v[122:125]
	v_mfma_f32_16x16x32_bf16 v[118:121], v[156:159], v[196:199], v[118:121]
	v_mfma_f32_16x16x32_bf16 v[114:117], v[164:167], v[196:199], v[114:117]
	v_mfma_f32_16x16x32_bf16 v[102:105], v[156:159], v[204:207], v[102:105]
	v_mfma_f32_16x16x32_bf16 v[98:101], v[164:167], v[204:207], v[98:101]
	v_mfma_f32_16x16x32_bf16 v[86:89], v[156:159], v[214:217], v[86:89]
	v_mfma_f32_16x16x32_bf16 v[82:85], v[164:167], v[214:217], v[82:85]
	s_setprio 0
	s_setprio 1
	v_mfma_f32_16x16x32_bf16 v[110:113], v[168:171], v[184:187], 0
	v_mfma_f32_16x16x32_bf16 v[106:109], v[176:179], v[184:187], 0
	v_mfma_f32_16x16x32_bf16 v[94:97], v[168:171], v[192:195], 0
	v_mfma_f32_16x16x32_bf16 v[90:93], v[176:179], v[192:195], 0
	v_mfma_f32_16x16x32_bf16 v[78:81], v[168:171], v[200:203], 0
	v_mfma_f32_16x16x32_bf16 v[74:77], v[176:179], v[200:203], 0
	v_mfma_f32_16x16x32_bf16 v[70:73], v[168:171], v[210:213], 0
	v_mfma_f32_16x16x32_bf16 v[66:69], v[176:179], v[210:213], 0
	v_mfma_f32_16x16x32_bf16 v[110:113], v[172:175], v[188:191], v[110:113]
	v_mfma_f32_16x16x32_bf16 v[106:109], v[180:183], v[188:191], v[106:109]
	v_mfma_f32_16x16x32_bf16 v[94:97], v[172:175], v[196:199], v[94:97]
	v_mfma_f32_16x16x32_bf16 v[90:93], v[180:183], v[196:199], v[90:93]
	v_mfma_f32_16x16x32_bf16 v[78:81], v[172:175], v[204:207], v[78:81]
	v_mfma_f32_16x16x32_bf16 v[74:77], v[180:183], v[204:207], v[74:77]
	v_mfma_f32_16x16x32_bf16 v[70:73], v[172:175], v[214:217], v[70:73]
	v_mfma_f32_16x16x32_bf16 v[66:69], v[180:183], v[214:217], v[66:69]
	s_setprio 0
	s_barrier
	s_add_i32 s54, s41, s29
	v_lshl_add_u64 v[218:219], s[24:25], 0, v[134:135]
	s_mov_b32 m0, s54
	ds_read_b128 v[184:187], v150 offset:16384
	ds_read_b128 v[188:191], v150 offset:17408
	ds_read_b128 v[192:195], v150 offset:18432
	ds_read_b128 v[196:199], v150 offset:19456
	ds_read_b128 v[200:203], v150 offset:20480
	ds_read_b128 v[204:207], v150 offset:21504
	ds_read_b128 v[210:213], v150 offset:22528
	ds_read_b128 v[214:217], v150 offset:23552
	global_load_lds_dwordx4 v[218:219], off
	s_add_i32 m0, s54, 0x2000
	s_add_u32 s54, s24, 0x160000
	v_lshl_add_u64 v[220:221], s[24:25], 0, v[130:131]
	s_addc_u32 s55, s25, 0
	s_add_i32 s56, s42, s29
	global_load_lds_dwordx4 v[220:221], off
	v_lshl_add_u64 v[222:223], s[54:55], 0, v[134:135]
	s_mov_b32 m0, s56
	v_lshl_add_u64 v[224:225], s[26:27], 0, v[132:133]
	global_load_lds_dwordx4 v[222:223], off
	v_lshl_add_u64 v[222:223], s[54:55], 0, v[130:131]
	s_add_i32 m0, s56, 0x2000
	s_nop 0
	global_load_lds_dwordx4 v[222:223], off
	v_lshl_add_u64 v[222:223], s[26:27], 0, v[136:137]
	s_mov_b32 m0, s33
	s_nop 0
	global_load_lds_dwordx4 v[222:223], off
	s_mov_b32 m0, s34
	s_nop 0
	global_load_lds_dwordx4 v[224:225], off
	s_waitcnt vmcnt(8)
	s_waitcnt lgkmcnt(0)
	s_barrier
; #define PG8_STAGE(bufoff, gbase, voff) do { _Pragma("unroll") for (int _i = 0; _i < 2; ++_i) \
;         __builtin_amdgcn_global_load_lds((const unsigned*)((const char*)(gbase) + (voff)[_i]), (PG8_LAS unsigned*)(lds + (bufoff) + ldsw + _i * 8192), 16, 0, 0); } while (0)
; #define PG8_LDA(dst, b, h) do { _Pragma("unroll") for (int m = 0; m < 4; ++m) _Pragma("unroll") for (int k = 0; k < 2; ++k) dst[m][k] = *(const PG8_LAS bf16x8*)(lds + PG8_SA(b, h) + aoff + m * 2048 + k * 1024); } while (0)
; #define PG8_LDB(dst, b, h) do { _Pragma("unroll") for (int n = 0; n < 2; ++n) _Pragma("unroll") for (int k = 0; k < 2; ++k) dst[n][k] = *(const PG8_LAS bf16x8*)(lds + PG8_SB(b, h) + boff + n * 2048 + k * 1024); } while (0)
; #define PG8_MMA(ai, bj, At, Bt) do { __builtin_amdgcn_s_setprio(1); _Pragma("unroll") for (int m = 0; m < 4; ++m) _Pragma("unroll") for (int n = 0; n < 2; ++n) _Pragma("unroll") for (int k = 0; k < 2; ++k) \
;         acc[ai][bj][m][n] = __builtin_amdgcn_mfma_f32_16x16x32_bf16(Bt[n][k], At[m][k], acc[ai][bj][m][n], 0, 0, 0); __builtin_amdgcn_s_setprio(0); } while (0)
; #define PG8_WAIT_V(n) asm volatile("s_waitcnt vmcnt(" #n ")" ::: "memory")
; #define PG8_WAIT_L(n) asm volatile("s_waitcnt lgkmcnt(" #n ")" ::: "memory")
; #define PG8_BAR __builtin_amdgcn_s_barrier()
; #define PG8_SCHED __builtin_amdgcn_sched_barrier(0)
; template <class Epi, class Sched, bool ALIGN_EPI = false, bool SP2 = false>
; __device__ __forceinline__ void gemm_phase(PG8_LAS unsigned char* lds, const Gemm g, const Sched& S, const Epi& E) {
;     ...
;             PG8_LDA(At, 0, 1); PG8_STAGE(PG8_SB(0, 0), b2, voffB); PG8_STAGE(PG8_SB(0, 1), b2 + hstepB, voffB); PG8_STAGE(PG8_SA(0, 0), a2, voffA);
;             PG8_WAIT_V(8); PG8_WAIT_L(0); PG8_BAR; PG8_MMA(1, 0, At, B0); PG8_MMA(1, 1, At, B1); PG8_BAR; PG8_SCHED;
;             PG8_LDB(B0, 1, 0); PG8_LDB(B1, 1, 1); PG8_SCHED; PG8_LDA(At, 1, 0); PG8_STAGE(PG8_SA(0, 1), a2 + hstepA, voffA);
;             PG8_WAIT_V(8); PG8_WAIT_L(0); PG8_BAR; PG8_MMA(0, 0, At, B0); PG8_MMA(0, 1, At, B1); PG8_BAR; PG8_SCHED;
	s_setprio 1
	s_waitcnt lgkmcnt(0)
	v_mfma_f32_16x16x32_bf16 v[62:65], v[152:155], v[184:187], 0
	v_mfma_f32_16x16x32_bf16 v[58:61], v[160:163], v[184:187], 0
	v_mfma_f32_16x16x32_bf16 v[54:57], v[152:155], v[192:195], 0
	v_mfma_f32_16x16x32_bf16 v[50:53], v[160:163], v[192:195], 0
	v_mfma_f32_16x16x32_bf16 v[38:41], v[152:155], v[200:203], 0
	v_mfma_f32_16x16x32_bf16 v[34:37], v[160:163], v[200:203], 0
	v_mfma_f32_16x16x32_bf16 v[22:25], v[152:155], v[210:213], 0
	v_mfma_f32_16x16x32_bf16 v[18:21], v[160:163], v[210:213], 0
	v_mfma_f32_16x16x32_bf16 v[62:65], v[156:159], v[188:191], v[62:65]
	v_mfma_f32_16x16x32_bf16 v[58:61], v[164:167], v[188:191], v[58:61]
	v_mfma_f32_16x16x32_bf16 v[54:57], v[156:159], v[196:199], v[54:57]
	v_mfma_f32_16x16x32_bf16 v[50:53], v[164:167], v[196:199], v[50:53]
	v_mfma_f32_16x16x32_bf16 v[38:41], v[156:159], v[204:207], v[38:41]
	v_mfma_f32_16x16x32_bf16 v[34:37], v[164:167], v[204:207], v[34:37]
	v_mfma_f32_16x16x32_bf16 v[22:25], v[156:159], v[214:217], v[22:25]
	v_mfma_f32_16x16x32_bf16 v[18:21], v[164:167], v[214:217], v[18:21]
	s_setprio 0
	s_setprio 1
	v_mfma_f32_16x16x32_bf16 v[46:49], v[168:171], v[184:187], 0
	v_mfma_f32_16x16x32_bf16 v[42:45], v[176:179], v[184:187], 0
	v_mfma_f32_16x16x32_bf16 v[30:33], v[168:171], v[192:195], 0
	v_mfma_f32_16x16x32_bf16 v[26:29], v[176:179], v[192:195], 0
	v_mfma_f32_16x16x32_bf16 v[14:17], v[168:171], v[200:203], 0
	v_mfma_f32_16x16x32_bf16 v[10:13], v[176:179], v[200:203], 0
	v_mfma_f32_16x16x32_bf16 v[6:9], v[168:171], v[210:213], 0
	v_mfma_f32_16x16x32_bf16 v[2:5], v[176:179], v[210:213], 0
	v_mfma_f32_16x16x32_bf16 v[46:49], v[172:175], v[188:191], v[46:49]
	v_mfma_f32_16x16x32_bf16 v[42:45], v[180:183], v[188:191], v[42:45]
	v_mfma_f32_16x16x32_bf16 v[30:33], v[172:175], v[196:199], v[30:33]
	v_mfma_f32_16x16x32_bf16 v[26:29], v[180:183], v[196:199], v[26:29]
	v_mfma_f32_16x16x32_bf16 v[14:17], v[172:175], v[204:207], v[14:17]
	v_mfma_f32_16x16x32_bf16 v[10:13], v[180:183], v[204:207], v[10:13]
	v_mfma_f32_16x16x32_bf16 v[6:9], v[172:175], v[214:217], v[6:9]
	v_mfma_f32_16x16x32_bf16 v[2:5], v[180:183], v[214:217], v[2:5]
	s_setprio 0
	s_barrier
	s_add_i32 s54, 0, 0x18000
	v_add_u32_e32 v151, s54, v146
	s_add_i32 s55, 0, 0x1c000
	ds_read_b128 v[152:155], v151
	ds_read_b128 v[156:159], v151 offset:1024
	ds_read_b128 v[160:163], v151 offset:2048
	ds_read_b128 v[164:167], v151 offset:3072
	v_add_u32_e32 v151, s55, v146
	ds_read_b128 v[168:171], v151
	ds_read_b128 v[172:175], v151 offset:1024
	ds_read_b128 v[176:179], v151 offset:2048
	ds_read_b128 v[180:183], v151 offset:3072
	s_add_u32 s26, s26, 0x160000
	s_addc_u32 s27, s27, 0
	s_mov_b32 m0, s35
	v_lshl_add_u64 v[226:227], s[26:27], 0, v[136:137]
	ds_read_b128 v[184:187], v150 offset:32768
	ds_read_b128 v[188:191], v150 offset:33792
	ds_read_b128 v[192:195], v150 offset:34816
	ds_read_b128 v[196:199], v150 offset:35840
	ds_read_b128 v[200:203], v150 offset:36864
	ds_read_b128 v[204:207], v150 offset:37888
	ds_read_b128 v[210:213], v150 offset:38912
	ds_read_b128 v[214:217], v150 offset:39936
	global_load_lds_dwordx4 v[226:227], off
	v_lshl_add_u64 v[226:227], s[26:27], 0, v[132:133]
	s_mov_b32 m0, s36
	s_nop 0
	global_load_lds_dwordx4 v[226:227], off
	s_waitcnt vmcnt(8)
	s_waitcnt lgkmcnt(0)
	s_barrier
	s_setprio 1
	s_waitcnt lgkmcnt(0)
	v_mfma_f32_16x16x32_bf16 v[126:129], v[152:155], v[184:187], v[126:129]
	v_mfma_f32_16x16x32_bf16 v[122:125], v[160:163], v[184:187], v[122:125]
	v_mfma_f32_16x16x32_bf16 v[118:121], v[152:155], v[192:195], v[118:121]
	v_mfma_f32_16x16x32_bf16 v[114:117], v[160:163], v[192:195], v[114:117]
	v_mfma_f32_16x16x32_bf16 v[102:105], v[152:155], v[200:203], v[102:105]
	v_mfma_f32_16x16x32_bf16 v[98:101], v[160:163], v[200:203], v[98:101]
	v_mfma_f32_16x16x32_bf16 v[86:89], v[152:155], v[210:213], v[86:89]
	v_mfma_f32_16x16x32_bf16 v[82:85], v[160:163], v[210:213], v[82:85]
	v_mfma_f32_16x16x32_bf16 v[126:129], v[156:159], v[188:191], v[126:129]
	v_mfma_f32_16x16x32_bf16 v[122:125], v[164:167], v[188:191], v[122:125]
	v_mfma_f32_16x16x32_bf16 v[118:121], v[156:159], v[196:199], v[118:121]
	v_mfma_f32_16x16x32_bf16 v[114:117], v[164:167], v[196:199], v[114:117]
	v_mfma_f32_16x16x32_bf16 v[102:105], v[156:159], v[204:207], v[102:105]
	v_mfma_f32_16x16x32_bf16 v[98:101], v[164:167], v[204:207], v[98:101]
	v_mfma_f32_16x16x32_bf16 v[86:89], v[156:159], v[214:217], v[86:89]
	v_mfma_f32_16x16x32_bf16 v[82:85], v[164:167], v[214:217], v[82:85]
	s_setprio 0
	s_setprio 1
	v_mfma_f32_16x16x32_bf16 v[110:113], v[168:171], v[184:187], v[110:113]
	v_mfma_f32_16x16x32_bf16 v[106:109], v[176:179], v[184:187], v[106:109]
	v_mfma_f32_16x16x32_bf16 v[94:97], v[168:171], v[192:195], v[94:97]
	v_mfma_f32_16x16x32_bf16 v[90:93], v[176:179], v[192:195], v[90:93]
	v_mfma_f32_16x16x32_bf16 v[78:81], v[168:171], v[200:203], v[78:81]
	v_mfma_f32_16x16x32_bf16 v[74:77], v[176:179], v[200:203], v[74:77]
	v_mfma_f32_16x16x32_bf16 v[70:73], v[168:171], v[210:213], v[70:73]
	v_mfma_f32_16x16x32_bf16 v[66:69], v[176:179], v[210:213], v[66:69]
	v_mfma_f32_16x16x32_bf16 v[110:113], v[172:175], v[188:191], v[110:113]
	v_mfma_f32_16x16x32_bf16 v[106:109], v[180:183], v[188:191], v[106:109]
	v_mfma_f32_16x16x32_bf16 v[94:97], v[172:175], v[196:199], v[94:97]
	v_mfma_f32_16x16x32_bf16 v[90:93], v[180:183], v[196:199], v[90:93]
	v_mfma_f32_16x16x32_bf16 v[78:81], v[172:175], v[204:207], v[78:81]
	v_mfma_f32_16x16x32_bf16 v[74:77], v[180:183], v[204:207], v[74:77]
	v_mfma_f32_16x16x32_bf16 v[70:73], v[172:175], v[214:217], v[70:73]
	v_mfma_f32_16x16x32_bf16 v[66:69], v[180:183], v[214:217], v[66:69]
	s_setprio 0
	s_barrier
; #define PG8_STAGE(bufoff, gbase, voff) do { _Pragma("unroll") for (int _i = 0; _i < 2; ++_i) \
;         __builtin_amdgcn_global_load_lds((const unsigned*)((const char*)(gbase) + (voff)[_i]), (PG8_LAS unsigned*)(lds + (bufoff) + ldsw + _i * 8192), 16, 0, 0); } while (0)
; #define PG8_LDA(dst, b, h) do { _Pragma("unroll") for (int m = 0; m < 4; ++m) _Pragma("unroll") for (int k = 0; k < 2; ++k) dst[m][k] = *(const PG8_LAS bf16x8*)(lds + PG8_SA(b, h) + aoff + m * 2048 + k * 1024); } while (0)
; #define PG8_LDB(dst, b, h) do { _Pragma("unroll") for (int n = 0; n < 2; ++n) _Pragma("unroll") for (int k = 0; k < 2; ++k) dst[n][k] = *(const PG8_LAS bf16x8*)(lds + PG8_SB(b, h) + boff + n * 2048 + k * 1024); } while (0)
; template <class Epi, class Sched, bool ALIGN_EPI = false, bool SP2 = false>
; __device__ __forceinline__ void gemm_phase(PG8_LAS unsigned char* lds, const Gemm g, const Sched& S, const Epi& E) {
;     ...
;         for (int t = 0; t < nt; t += 2) {
;             const bool last = (t == nt - 2);
;             const char* a1 = cA + (size_t)(t + 1) * kstep;
;             const char* a2 = last ? nA : cA + (size_t)(t + 2) * kstep; const char* b2 = last ? nB : cB + (size_t)(t + 2) * kstep;
;             const char* a3 = a2 + kstep; const char* b3 = b2 + kstep;
;             if (last && has_next) S.a_ready(nxt);
;             if constexpr (SP2) {
;             PG8_LDB(B0, 0, 0); PG8_LDB(B1, 0, 1); PG8_SCHED; PG8_LDA(At, 0, 0); PG8_STAGE(PG8_SA(1, 1), a1 + hstepA, voffA);
;             PG8_WAIT_V(8); PG8_WAIT_L(0); PG8_BAR; PG8_MMA(0, 0, At, B0); PG8_MMA(0, 1, At, B1); PG8_BAR; PG8_SCHED;
;             PG8_LDA(At, 0, 1); PG8_STAGE(PG8_SB(0, 0), b2, voffB); PG8_STAGE(PG8_SB(0, 1), b2 + hstepB, voffB); PG8_STAGE(PG8_SA(0, 0), a2, voffA);
;             PG8_WAIT_V(8); PG8_WAIT_L(0); PG8_BAR; PG8_MMA(1, 0, At, B0); PG8_MMA(1, 1, At, B1); PG8_BAR; PG8_SCHED;
;             PG8_LDB(B0, 1, 0); PG8_LDB(B1, 1, 1); PG8_SCHED; PG8_LDA(At, 1, 0); PG8_STAGE(PG8_SA(0, 1), a2 + hstepA, voffA);
;             PG8_WAIT_V(8); PG8_WAIT_L(0); PG8_BAR; PG8_MMA(0, 0, At, B0); PG8_MMA(0, 1, At, B1); PG8_BAR; PG8_SCHED;
;             PG8_LDA(At, 1, 1); PG8_STAGE(PG8_SB(1, 0), b3, voffB); PG8_STAGE(PG8_SB(1, 1), b3 + hstepB, voffB); PG8_STAGE(PG8_SA(1, 0), a3, voffA);
;             PG8_WAIT_V(8); PG8_WAIT_L(0); PG8_BAR; PG8_MMA(1, 0, At, B0); PG8_MMA(1, 1, At, B1); PG8_BAR; PG8_SCHED;
	s_add_i32 s26, s54, s29
	v_lshl_add_u64 v[218:219], v[218:219], 0, s[8:9]
	s_mov_b32 m0, s26
	ds_read_b128 v[184:187], v150 offset:49152
	ds_read_b128 v[188:191], v150 offset:50176
	ds_read_b128 v[192:195], v150 offset:51200
	ds_read_b128 v[196:199], v150 offset:52224
	ds_read_b128 v[200:203], v150 offset:53248
	ds_read_b128 v[204:207], v150 offset:54272
	ds_read_b128 v[210:213], v150 offset:55296
	ds_read_b128 v[214:217], v150 offset:56320
	global_load_lds_dwordx4 v[218:219], off
	s_add_i32 m0, s26, 0x2000
	s_add_u32 s24, s24, 0x160080
	v_lshl_add_u64 v[218:219], v[220:221], 0, s[8:9]
	s_addc_u32 s25, s25, 0
	s_add_i32 s26, s55, s29
	global_load_lds_dwordx4 v[218:219], off
	v_lshl_add_u64 v[218:219], s[24:25], 0, v[134:135]
	s_mov_b32 m0, s26
	s_nop 0
	global_load_lds_dwordx4 v[218:219], off
	v_lshl_add_u64 v[218:219], s[24:25], 0, v[130:131]
	s_add_i32 m0, s26, 0x2000
	s_nop 0
	global_load_lds_dwordx4 v[218:219], off
	v_lshl_add_u64 v[218:219], v[222:223], 0, s[8:9]
	s_mov_b32 m0, s38
	s_nop 0
	global_load_lds_dwordx4 v[218:219], off
	v_lshl_add_u64 v[218:219], v[224:225], 0, s[8:9]
	s_mov_b32 m0, s39
	s_nop 0
	global_load_lds_dwordx4 v[218:219], off
	s_waitcnt vmcnt(8)
	s_waitcnt lgkmcnt(0)
	s_barrier
	s_setprio 1
	s_waitcnt lgkmcnt(0)
	v_mfma_f32_16x16x32_bf16 v[62:65], v[152:155], v[184:187], v[62:65]
	v_mfma_f32_16x16x32_bf16 v[58:61], v[160:163], v[184:187], v[58:61]
	v_mfma_f32_16x16x32_bf16 v[54:57], v[152:155], v[192:195], v[54:57]
	v_mfma_f32_16x16x32_bf16 v[50:53], v[160:163], v[192:195], v[50:53]
	v_mfma_f32_16x16x32_bf16 v[38:41], v[152:155], v[200:203], v[38:41]
	v_mfma_f32_16x16x32_bf16 v[34:37], v[160:163], v[200:203], v[34:37]
	v_mfma_f32_16x16x32_bf16 v[22:25], v[152:155], v[210:213], v[22:25]
	v_mfma_f32_16x16x32_bf16 v[18:21], v[160:163], v[210:213], v[18:21]
	v_mfma_f32_16x16x32_bf16 v[62:65], v[156:159], v[188:191], v[62:65]
	v_mfma_f32_16x16x32_bf16 v[58:61], v[164:167], v[188:191], v[58:61]
	v_mfma_f32_16x16x32_bf16 v[54:57], v[156:159], v[196:199], v[54:57]
	v_mfma_f32_16x16x32_bf16 v[50:53], v[164:167], v[196:199], v[50:53]
	v_mfma_f32_16x16x32_bf16 v[38:41], v[156:159], v[204:207], v[38:41]
	v_mfma_f32_16x16x32_bf16 v[34:37], v[164:167], v[204:207], v[34:37]
	v_mfma_f32_16x16x32_bf16 v[22:25], v[156:159], v[214:217], v[22:25]
	v_mfma_f32_16x16x32_bf16 v[18:21], v[164:167], v[214:217], v[18:21]
	s_setprio 0
	s_setprio 1
	v_mfma_f32_16x16x32_bf16 v[46:49], v[168:171], v[184:187], v[46:49]
	v_mfma_f32_16x16x32_bf16 v[42:45], v[176:179], v[184:187], v[42:45]
	v_mfma_f32_16x16x32_bf16 v[30:33], v[168:171], v[192:195], v[30:33]
	v_mfma_f32_16x16x32_bf16 v[26:29], v[176:179], v[192:195], v[26:29]
	v_mfma_f32_16x16x32_bf16 v[14:17], v[168:171], v[200:203], v[14:17]
	v_mfma_f32_16x16x32_bf16 v[10:13], v[176:179], v[200:203], v[10:13]
	v_mfma_f32_16x16x32_bf16 v[6:9], v[168:171], v[210:213], v[6:9]
	v_mfma_f32_16x16x32_bf16 v[2:5], v[176:179], v[210:213], v[2:5]
	v_mfma_f32_16x16x32_bf16 v[46:49], v[172:175], v[188:191], v[46:49]
	v_mfma_f32_16x16x32_bf16 v[42:45], v[180:183], v[188:191], v[42:45]
	v_mfma_f32_16x16x32_bf16 v[30:33], v[172:175], v[196:199], v[30:33]
	v_mfma_f32_16x16x32_bf16 v[26:29], v[180:183], v[196:199], v[26:29]
	v_mfma_f32_16x16x32_bf16 v[14:17], v[172:175], v[204:207], v[14:17]
	v_mfma_f32_16x16x32_bf16 v[10:13], v[180:183], v[204:207], v[10:13]
	v_mfma_f32_16x16x32_bf16 v[6:9], v[172:175], v[214:217], v[6:9]
	v_mfma_f32_16x16x32_bf16 v[2:5], v[180:183], v[214:217], v[2:5]
	s_setprio 0
	s_barrier
	s_add_i32 s53, s53, 2
	s_add_u32 s22, s22, 0x100
	s_addc_u32 s23, s23, 0
	s_add_u32 s51, s51, 0x100
	s_addc_u32 s52, s52, 0
	s_cmpk_gt_u32 s53, 0x55
	s_cbranch_scc1 .Lpeel_exit_26
	.p2align 6

; #define PG8_STAGE(bufoff, gbase, voff) do { _Pragma("unroll") for (int _i = 0; _i < 2; ++_i) \
;         __builtin_amdgcn_global_load_lds((const unsigned*)((const char*)(gbase) + (voff)[_i]), (PG8_LAS unsigned*)(lds + (bufoff) + ldsw + _i * 8192), 16, 0, 0); } while (0)
; #define PG8_LDA(dst, b, h) do { _Pragma("unroll") for (int m = 0; m < 4; ++m) _Pragma("unroll") for (int k = 0; k < 2; ++k) dst[m][k] = *(const PG8_LAS bf16x8*)(lds + PG8_SA(b, h) + aoff + m * 2048 + k * 1024); } while (0)
; #define PG8_LDB(dst, b, h) do { _Pragma("unroll") for (int n = 0; n < 2; ++n) _Pragma("unroll") for (int k = 0; k < 2; ++k) dst[n][k] = *(const PG8_LAS bf16x8*)(lds + PG8_SB(b, h) + boff + n * 2048 + k * 1024); } while (0)
; #define PG8_MMA(ai, bj, At, Bt) do { __builtin_amdgcn_s_setprio(1); _Pragma("unroll") for (int m = 0; m < 4; ++m) _Pragma("unroll") for (int n = 0; n < 2; ++n) _Pragma("unroll") for (int k = 0; k < 2; ++k) \
;         acc[ai][bj][m][n] = __builtin_amdgcn_mfma_f32_16x16x32_bf16(Bt[n][k], At[m][k], acc[ai][bj][m][n], 0, 0, 0); __builtin_amdgcn_s_setprio(0); } while (0)
; #define PG8_BAR __builtin_amdgcn_s_barrier()
; template <class Epi, class Sched, bool ALIGN_EPI = false, bool SP2 = false>
; __device__ __forceinline__ void gemm_phase(PG8_LAS unsigned char* lds, const Gemm g, const Sched& S, const Epi& E) {
;     ...
;         const bool has_next = S.next(ui + 1, nxt);
;         const char* nA = has_next ? (const char*)g.A + (size_t)nxt.pm * tstepA : cA; const char* nB = has_next ? (const char*)g.Bt + (size_t)nxt.pn * tstepB : cB;
;         for (int t = 0; t < nt; t += 2) {
;             const bool last = (t == nt - 2);
;             const char* a1 = cA + (size_t)(t + 1) * kstep;
;             const char* a2 = last ? nA : cA + (size_t)(t + 2) * kstep; const char* b2 = last ? nB : cB + (size_t)(t + 2) * kstep;
;             const char* a3 = a2 + kstep; const char* b3 = b2 + kstep;
;             if (last && has_next) S.a_ready(nxt);
;             if constexpr (SP2) {
;             PG8_LDB(B0, 0, 0); PG8_LDB(B1, 0, 1); PG8_SCHED; PG8_LDA(At, 0, 0); PG8_STAGE(PG8_SA(1, 1), a1 + hstepA, voffA);
;             PG8_WAIT_V(8); PG8_WAIT_L(0); PG8_BAR; PG8_MMA(0, 0, At, B0); PG8_MMA(0, 1, At, B1); PG8_BAR; PG8_SCHED;
;             PG8_LDA(At, 0, 1); PG8_STAGE(PG8_SB(0, 0), b2, voffB); PG8_STAGE(PG8_SB(0, 1), b2 + hstepB, voffB); PG8_STAGE(PG8_SA(0, 0), a2, voffA);
.LBB0_2614:
	s_ashr_i32 s15, s14, 31
	s_lshl_b64 s[16:17], s[14:15], 20
	s_add_u32 s16, s86, s16
	s_addc_u32 s17, s87, s17
	s_and_b64 s[18:19], s[4:5], exec
	s_cselect_b32 s15, s17, s23
	s_cselect_b32 s44, s16, s22
	s_ashr_i32 s13, s12, 31
	s_lshl_b64 s[18:19], s[12:13], 20
	s_add_u32 s18, s62, s18
	s_addc_u32 s19, s63, s19
	s_and_b64 s[26:27], s[4:5], exec
	s_cselect_b32 s13, s19, s25
	s_cselect_b32 s45, s18, s24
	s_add_u32 s22, s22, 0x80080
	s_addc_u32 s23, s23, 0
	s_add_u32 s46, s24, 0x100
	s_addc_u32 s47, s25, 0
	s_mov_b32 s48, -2
	ds_read_b128 v[130:133], v166
	ds_read_b128 v[134:137], v166 offset:1024
	ds_read_b128 v[138:141], v166 offset:2048
	ds_read_b128 v[142:145], v166 offset:3072
	ds_read_b128 v[170:173], v167
	ds_read_b128 v[174:177], v167 offset:1024
	ds_read_b128 v[178:181], v167 offset:2048
	ds_read_b128 v[182:185], v167 offset:3072
	s_add_u32 s24, s22, 0xfff80080
	s_addc_u32 s25, s23, -1
	s_cmp_eq_u32 s48, 28
	s_cselect_b32 s27, s15, s25
	s_cselect_b32 s26, s44, s24
	s_cselect_b32 s25, s13, s47
	s_cselect_b32 s24, s45, s46
	v_lshl_add_u64 v[162:163], s[22:23], 0, v[154:155]
	s_add_i32 m0, s21, 0xc000
	ds_read_b128 v[186:189], v168
	ds_read_b128 v[190:193], v168 offset:1024
	ds_read_b128 v[194:197], v168 offset:2048
	ds_read_b128 v[198:201], v168 offset:3072
	ds_read_b128 v[202:205], v168 offset:4096
	ds_read_b128 v[210:213], v168 offset:5120
	ds_read_b128 v[214:217], v168 offset:6144
	ds_read_b128 v[218:221], v168 offset:7168
	global_load_lds_dwordx4 v[162:163], off
	v_lshl_add_u64 v[162:163], s[22:23], 0, v[156:157]
	s_add_i32 m0, s21, 0xe000
	s_nop 0
	global_load_lds_dwordx4 v[162:163], off
	s_waitcnt vmcnt(8)
	s_waitcnt lgkmcnt(0)
	s_barrier
	s_setprio 1
	s_waitcnt lgkmcnt(0)
	v_mfma_f32_16x16x32_bf16 v[126:129], v[130:133], v[186:189], 0
	v_mfma_f32_16x16x32_bf16 v[122:125], v[138:141], v[186:189], 0
	v_mfma_f32_16x16x32_bf16 v[118:121], v[130:133], v[194:197], 0
	v_mfma_f32_16x16x32_bf16 v[114:117], v[138:141], v[194:197], 0
	v_mfma_f32_16x16x32_bf16 v[110:113], v[130:133], v[202:205], 0
	v_mfma_f32_16x16x32_bf16 v[102:105], v[138:141], v[202:205], 0
	v_mfma_f32_16x16x32_bf16 v[94:97], v[130:133], v[214:217], 0
	v_mfma_f32_16x16x32_bf16 v[86:89], v[138:141], v[214:217], 0
	v_mfma_f32_16x16x32_bf16 v[126:129], v[134:137], v[190:193], v[126:129]
	v_mfma_f32_16x16x32_bf16 v[122:125], v[142:145], v[190:193], v[122:125]
	v_mfma_f32_16x16x32_bf16 v[118:121], v[134:137], v[198:201], v[118:121]
	v_mfma_f32_16x16x32_bf16 v[114:117], v[142:145], v[198:201], v[114:117]
	v_mfma_f32_16x16x32_bf16 v[110:113], v[134:137], v[210:213], v[110:113]
	v_mfma_f32_16x16x32_bf16 v[102:105], v[142:145], v[210:213], v[102:105]
	v_mfma_f32_16x16x32_bf16 v[94:97], v[134:137], v[218:221], v[94:97]
	v_mfma_f32_16x16x32_bf16 v[86:89], v[142:145], v[218:221], v[86:89]
	s_setprio 0
	s_setprio 1
	v_mfma_f32_16x16x32_bf16 v[106:109], v[170:173], v[186:189], 0
	v_mfma_f32_16x16x32_bf16 v[98:101], v[178:181], v[186:189], 0
	v_mfma_f32_16x16x32_bf16 v[90:93], v[170:173], v[194:197], 0
	v_mfma_f32_16x16x32_bf16 v[82:85], v[178:181], v[194:197], 0
	v_mfma_f32_16x16x32_bf16 v[78:81], v[170:173], v[202:205], 0
	v_mfma_f32_16x16x32_bf16 v[74:77], v[178:181], v[202:205], 0
	v_mfma_f32_16x16x32_bf16 v[70:73], v[170:173], v[214:217], 0
	v_mfma_f32_16x16x32_bf16 v[66:69], v[178:181], v[214:217], 0
	v_mfma_f32_16x16x32_bf16 v[106:109], v[174:177], v[190:193], v[106:109]
	v_mfma_f32_16x16x32_bf16 v[98:101], v[182:185], v[190:193], v[98:101]
	v_mfma_f32_16x16x32_bf16 v[90:93], v[174:177], v[198:201], v[90:93]
	v_mfma_f32_16x16x32_bf16 v[82:85], v[182:185], v[198:201], v[82:85]
	v_mfma_f32_16x16x32_bf16 v[78:81], v[174:177], v[210:213], v[78:81]
	v_mfma_f32_16x16x32_bf16 v[74:77], v[182:185], v[210:213], v[74:77]
	v_mfma_f32_16x16x32_bf16 v[70:73], v[174:177], v[218:221], v[70:73]
	v_mfma_f32_16x16x32_bf16 v[66:69], v[182:185], v[218:221], v[66:69]
	s_setprio 0
	s_barrier
	s_add_i32 s49, s40, s29
	v_lshl_add_u64 v[162:163], s[24:25], 0, v[150:151]
	s_mov_b32 m0, s49
	ds_read_b128 v[186:189], v168 offset:16384
	ds_read_b128 v[190:193], v168 offset:17408
	ds_read_b128 v[194:197], v168 offset:18432
	ds_read_b128 v[198:201], v168 offset:19456
	ds_read_b128 v[202:205], v168 offset:20480
	ds_read_b128 v[210:213], v168 offset:21504
	ds_read_b128 v[214:217], v168 offset:22528
	ds_read_b128 v[218:221], v168 offset:23552
	global_load_lds_dwordx4 v[162:163], off
	s_add_i32 m0, s49, 0x2000
	s_add_u32 s50, s24, 0x80000
	v_lshl_add_u64 v[206:207], s[24:25], 0, v[146:147]
	s_addc_u32 s51, s25, 0
	s_add_i32 s49, s41, s29
	global_load_lds_dwordx4 v[206:207], off
	v_lshl_add_u64 v[222:223], s[50:51], 0, v[150:151]
	s_mov_b32 m0, s49
	v_lshl_add_u64 v[224:225], s[26:27], 0, v[148:149]
	global_load_lds_dwordx4 v[222:223], off
	v_lshl_add_u64 v[222:223], s[50:51], 0, v[146:147]
	s_add_i32 m0, s49, 0x2000
	s_nop 0
	global_load_lds_dwordx4 v[222:223], off
	v_lshl_add_u64 v[222:223], s[26:27], 0, v[152:153]
	s_mov_b32 m0, s21
	s_nop 0
	global_load_lds_dwordx4 v[222:223], off
	s_mov_b32 m0, s33
	s_nop 0
	global_load_lds_dwordx4 v[224:225], off
	s_waitcnt vmcnt(8)
	s_waitcnt lgkmcnt(0)
	s_barrier
; #define PG8_STAGE(bufoff, gbase, voff) do { _Pragma("unroll") for (int _i = 0; _i < 2; ++_i) \
;         __builtin_amdgcn_global_load_lds((const unsigned*)((const char*)(gbase) + (voff)[_i]), (PG8_LAS unsigned*)(lds + (bufoff) + ldsw + _i * 8192), 16, 0, 0); } while (0)
; #define PG8_LDA(dst, b, h) do { _Pragma("unroll") for (int m = 0; m < 4; ++m) _Pragma("unroll") for (int k = 0; k < 2; ++k) dst[m][k] = *(const PG8_LAS bf16x8*)(lds + PG8_SA(b, h) + aoff + m * 2048 + k * 1024); } while (0)
; #define PG8_LDB(dst, b, h) do { _Pragma("unroll") for (int n = 0; n < 2; ++n) _Pragma("unroll") for (int k = 0; k < 2; ++k) dst[n][k] = *(const PG8_LAS bf16x8*)(lds + PG8_SB(b, h) + boff + n * 2048 + k * 1024); } while (0)
; #define PG8_MMA(ai, bj, At, Bt) do { __builtin_amdgcn_s_setprio(1); _Pragma("unroll") for (int m = 0; m < 4; ++m) _Pragma("unroll") for (int n = 0; n < 2; ++n) _Pragma("unroll") for (int k = 0; k < 2; ++k) \
;         acc[ai][bj][m][n] = __builtin_amdgcn_mfma_f32_16x16x32_bf16(Bt[n][k], At[m][k], acc[ai][bj][m][n], 0, 0, 0); __builtin_amdgcn_s_setprio(0); } while (0)
; #define PG8_WAIT_V(n) asm volatile("s_waitcnt vmcnt(" #n ")" ::: "memory")
; #define PG8_WAIT_L(n) asm volatile("s_waitcnt lgkmcnt(" #n ")" ::: "memory")
; #define PG8_BAR __builtin_amdgcn_s_barrier()
; #define PG8_SCHED __builtin_amdgcn_sched_barrier(0)
; template <class Epi, class Sched, bool ALIGN_EPI = false, bool SP2 = false>
; __device__ __forceinline__ void gemm_phase(PG8_LAS unsigned char* lds, const Gemm g, const Sched& S, const Epi& E) {
;     ...
;             PG8_LDA(At, 0, 1); PG8_STAGE(PG8_SB(0, 0), b2, voffB); PG8_STAGE(PG8_SB(0, 1), b2 + hstepB, voffB); PG8_STAGE(PG8_SA(0, 0), a2, voffA);
;             PG8_WAIT_V(8); PG8_WAIT_L(0); PG8_BAR; PG8_MMA(1, 0, At, B0); PG8_MMA(1, 1, At, B1); PG8_BAR; PG8_SCHED;
;             PG8_LDB(B0, 1, 0); PG8_LDB(B1, 1, 1); PG8_SCHED; PG8_LDA(At, 1, 0); PG8_STAGE(PG8_SA(0, 1), a2 + hstepA, voffA);
;             PG8_WAIT_V(8); PG8_WAIT_L(0); PG8_BAR; PG8_MMA(0, 0, At, B0); PG8_MMA(0, 1, At, B1); PG8_BAR; PG8_SCHED;
	s_setprio 1
	s_waitcnt lgkmcnt(0)
	v_mfma_f32_16x16x32_bf16 v[62:65], v[130:133], v[186:189], 0
	v_mfma_f32_16x16x32_bf16 v[58:61], v[138:141], v[186:189], 0
	v_mfma_f32_16x16x32_bf16 v[54:57], v[130:133], v[194:197], 0
	v_mfma_f32_16x16x32_bf16 v[46:49], v[138:141], v[194:197], 0
	v_mfma_f32_16x16x32_bf16 v[38:41], v[130:133], v[202:205], 0
	v_mfma_f32_16x16x32_bf16 v[30:33], v[138:141], v[202:205], 0
	v_mfma_f32_16x16x32_bf16 v[22:25], v[130:133], v[214:217], 0
	v_mfma_f32_16x16x32_bf16 v[14:17], v[138:141], v[214:217], 0
	v_mfma_f32_16x16x32_bf16 v[62:65], v[134:137], v[190:193], v[62:65]
	v_mfma_f32_16x16x32_bf16 v[58:61], v[142:145], v[190:193], v[58:61]
	v_mfma_f32_16x16x32_bf16 v[54:57], v[134:137], v[198:201], v[54:57]
	v_mfma_f32_16x16x32_bf16 v[46:49], v[142:145], v[198:201], v[46:49]
	v_mfma_f32_16x16x32_bf16 v[38:41], v[134:137], v[210:213], v[38:41]
	v_mfma_f32_16x16x32_bf16 v[30:33], v[142:145], v[210:213], v[30:33]
	v_mfma_f32_16x16x32_bf16 v[22:25], v[134:137], v[218:221], v[22:25]
	v_mfma_f32_16x16x32_bf16 v[14:17], v[142:145], v[218:221], v[14:17]
	s_setprio 0
	s_setprio 1
	v_mfma_f32_16x16x32_bf16 v[50:53], v[170:173], v[186:189], 0
	v_mfma_f32_16x16x32_bf16 v[42:45], v[178:181], v[186:189], 0
	v_mfma_f32_16x16x32_bf16 v[34:37], v[170:173], v[194:197], 0
	v_mfma_f32_16x16x32_bf16 v[26:29], v[178:181], v[194:197], 0
	v_mfma_f32_16x16x32_bf16 v[18:21], v[170:173], v[202:205], 0
	v_mfma_f32_16x16x32_bf16 v[10:13], v[178:181], v[202:205], 0
	v_mfma_f32_16x16x32_bf16 v[6:9], v[170:173], v[214:217], 0
	v_mfma_f32_16x16x32_bf16 v[2:5], v[178:181], v[214:217], 0
	v_mfma_f32_16x16x32_bf16 v[50:53], v[174:177], v[190:193], v[50:53]
	v_mfma_f32_16x16x32_bf16 v[42:45], v[182:185], v[190:193], v[42:45]
	v_mfma_f32_16x16x32_bf16 v[34:37], v[174:177], v[198:201], v[34:37]
	v_mfma_f32_16x16x32_bf16 v[26:29], v[182:185], v[198:201], v[26:29]
	v_mfma_f32_16x16x32_bf16 v[18:21], v[174:177], v[210:213], v[18:21]
	v_mfma_f32_16x16x32_bf16 v[10:13], v[182:185], v[210:213], v[10:13]
	v_mfma_f32_16x16x32_bf16 v[6:9], v[174:177], v[218:221], v[6:9]
	v_mfma_f32_16x16x32_bf16 v[2:5], v[182:185], v[218:221], v[2:5]
	s_setprio 0
	s_barrier
	s_add_i32 s49, 0, 0x18000
	s_add_i32 s50, 0, 0x1c000
	v_add_u32_e32 v142, s49, v164
	v_add_u32_e32 v169, s50, v164
	ds_read_b128 v[130:133], v142
	ds_read_b128 v[134:137], v142 offset:1024
	ds_read_b128 v[138:141], v142 offset:2048
	ds_read_b128 v[142:145], v142 offset:3072
	ds_read_b128 v[170:173], v169
	ds_read_b128 v[174:177], v169 offset:1024
	ds_read_b128 v[178:181], v169 offset:2048
	ds_read_b128 v[182:185], v169 offset:3072
	s_add_u32 s26, s26, 0x80000
	s_addc_u32 s27, s27, 0
	s_mov_b32 m0, s34
	v_lshl_add_u64 v[226:227], s[26:27], 0, v[152:153]
	ds_read_b128 v[186:189], v168 offset:32768
	ds_read_b128 v[190:193], v168 offset:33792
	ds_read_b128 v[194:197], v168 offset:34816
	ds_read_b128 v[198:201], v168 offset:35840
	ds_read_b128 v[202:205], v168 offset:36864
	ds_read_b128 v[210:213], v168 offset:37888
	ds_read_b128 v[214:217], v168 offset:38912
	ds_read_b128 v[218:221], v168 offset:39936
	global_load_lds_dwordx4 v[226:227], off
	v_lshl_add_u64 v[226:227], s[26:27], 0, v[148:149]
	s_mov_b32 m0, s35
	s_nop 0
	global_load_lds_dwordx4 v[226:227], off
	s_waitcnt vmcnt(8)
	s_waitcnt lgkmcnt(0)
	s_barrier
	s_setprio 1
	s_waitcnt lgkmcnt(0)
	v_mfma_f32_16x16x32_bf16 v[126:129], v[130:133], v[186:189], v[126:129]
	v_mfma_f32_16x16x32_bf16 v[122:125], v[138:141], v[186:189], v[122:125]
	v_mfma_f32_16x16x32_bf16 v[118:121], v[130:133], v[194:197], v[118:121]
	v_mfma_f32_16x16x32_bf16 v[114:117], v[138:141], v[194:197], v[114:117]
	v_mfma_f32_16x16x32_bf16 v[110:113], v[130:133], v[202:205], v[110:113]
	v_mfma_f32_16x16x32_bf16 v[102:105], v[138:141], v[202:205], v[102:105]
	v_mfma_f32_16x16x32_bf16 v[94:97], v[130:133], v[214:217], v[94:97]
	v_mfma_f32_16x16x32_bf16 v[86:89], v[138:141], v[214:217], v[86:89]
	v_mfma_f32_16x16x32_bf16 v[126:129], v[134:137], v[190:193], v[126:129]
	v_mfma_f32_16x16x32_bf16 v[122:125], v[142:145], v[190:193], v[122:125]
	v_mfma_f32_16x16x32_bf16 v[118:121], v[134:137], v[198:201], v[118:121]
	v_mfma_f32_16x16x32_bf16 v[114:117], v[142:145], v[198:201], v[114:117]
	v_mfma_f32_16x16x32_bf16 v[110:113], v[134:137], v[210:213], v[110:113]
	v_mfma_f32_16x16x32_bf16 v[102:105], v[142:145], v[210:213], v[102:105]
	v_mfma_f32_16x16x32_bf16 v[94:97], v[134:137], v[218:221], v[94:97]
	v_mfma_f32_16x16x32_bf16 v[86:89], v[142:145], v[218:221], v[86:89]
	s_setprio 0
	s_setprio 1
	v_mfma_f32_16x16x32_bf16 v[106:109], v[170:173], v[186:189], v[106:109]
	v_mfma_f32_16x16x32_bf16 v[98:101], v[178:181], v[186:189], v[98:101]
	v_mfma_f32_16x16x32_bf16 v[90:93], v[170:173], v[194:197], v[90:93]
	v_mfma_f32_16x16x32_bf16 v[82:85], v[178:181], v[194:197], v[82:85]
	v_mfma_f32_16x16x32_bf16 v[78:81], v[170:173], v[202:205], v[78:81]
	v_mfma_f32_16x16x32_bf16 v[74:77], v[178:181], v[202:205], v[74:77]
	v_mfma_f32_16x16x32_bf16 v[70:73], v[170:173], v[214:217], v[70:73]
	v_mfma_f32_16x16x32_bf16 v[66:69], v[178:181], v[214:217], v[66:69]
	v_mfma_f32_16x16x32_bf16 v[106:109], v[174:177], v[190:193], v[106:109]
	v_mfma_f32_16x16x32_bf16 v[98:101], v[182:185], v[190:193], v[98:101]
	v_mfma_f32_16x16x32_bf16 v[90:93], v[174:177], v[198:201], v[90:93]
	v_mfma_f32_16x16x32_bf16 v[82:85], v[182:185], v[198:201], v[82:85]
	v_mfma_f32_16x16x32_bf16 v[78:81], v[174:177], v[210:213], v[78:81]
	v_mfma_f32_16x16x32_bf16 v[74:77], v[182:185], v[210:213], v[74:77]
	v_mfma_f32_16x16x32_bf16 v[70:73], v[174:177], v[218:221], v[70:73]
	v_mfma_f32_16x16x32_bf16 v[66:69], v[182:185], v[218:221], v[66:69]
	s_setprio 0
	s_barrier
; #define PG8_STAGE(bufoff, gbase, voff) do { _Pragma("unroll") for (int _i = 0; _i < 2; ++_i) \
;         __builtin_amdgcn_global_load_lds((const unsigned*)((const char*)(gbase) + (voff)[_i]), (PG8_LAS unsigned*)(lds + (bufoff) + ldsw + _i * 8192), 16, 0, 0); } while (0)
; #define PG8_LDA(dst, b, h) do { _Pragma("unroll") for (int m = 0; m < 4; ++m) _Pragma("unroll") for (int k = 0; k < 2; ++k) dst[m][k] = *(const PG8_LAS bf16x8*)(lds + PG8_SA(b, h) + aoff + m * 2048 + k * 1024); } while (0)
; #define PG8_LDB(dst, b, h) do { _Pragma("unroll") for (int n = 0; n < 2; ++n) _Pragma("unroll") for (int k = 0; k < 2; ++k) dst[n][k] = *(const PG8_LAS bf16x8*)(lds + PG8_SB(b, h) + boff + n * 2048 + k * 1024); } while (0)
; template <class Epi, class Sched, bool ALIGN_EPI = false, bool SP2 = false>
; __device__ __forceinline__ void gemm_phase(PG8_LAS unsigned char* lds, const Gemm g, const Sched& S, const Epi& E) {
;     ...
;         for (int t = 0; t < nt; t += 2) {
;             const bool last = (t == nt - 2);
;             const char* a1 = cA + (size_t)(t + 1) * kstep;
;             const char* a2 = last ? nA : cA + (size_t)(t + 2) * kstep; const char* b2 = last ? nB : cB + (size_t)(t + 2) * kstep;
;             const char* a3 = a2 + kstep; const char* b3 = b2 + kstep;
;             if (last && has_next) S.a_ready(nxt);
;             if constexpr (SP2) {
;             PG8_LDB(B0, 0, 0); PG8_LDB(B1, 0, 1); PG8_SCHED; PG8_LDA(At, 0, 0); PG8_STAGE(PG8_SA(1, 1), a1 + hstepA, voffA);
;             PG8_WAIT_V(8); PG8_WAIT_L(0); PG8_BAR; PG8_MMA(0, 0, At, B0); PG8_MMA(0, 1, At, B1); PG8_BAR; PG8_SCHED;
;             PG8_LDA(At, 0, 1); PG8_STAGE(PG8_SB(0, 0), b2, voffB); PG8_STAGE(PG8_SB(0, 1), b2 + hstepB, voffB); PG8_STAGE(PG8_SA(0, 0), a2, voffA);
;             PG8_WAIT_V(8); PG8_WAIT_L(0); PG8_BAR; PG8_MMA(1, 0, At, B0); PG8_MMA(1, 1, At, B1); PG8_BAR; PG8_SCHED;
;             PG8_LDB(B0, 1, 0); PG8_LDB(B1, 1, 1); PG8_SCHED; PG8_LDA(At, 1, 0); PG8_STAGE(PG8_SA(0, 1), a2 + hstepA, voffA);
;             PG8_WAIT_V(8); PG8_WAIT_L(0); PG8_BAR; PG8_MMA(0, 0, At, B0); PG8_MMA(0, 1, At, B1); PG8_BAR; PG8_SCHED;
;             PG8_LDA(At, 1, 1); PG8_STAGE(PG8_SB(1, 0), b3, voffB); PG8_STAGE(PG8_SB(1, 1), b3 + hstepB, voffB); PG8_STAGE(PG8_SA(1, 0), a3, voffA);
;             PG8_WAIT_V(8); PG8_WAIT_L(0); PG8_BAR; PG8_MMA(1, 0, At, B0); PG8_MMA(1, 1, At, B1); PG8_BAR; PG8_SCHED;
	s_add_i32 s26, s49, s29
	v_lshl_add_u64 v[162:163], v[162:163], 0, s[8:9]
	s_mov_b32 m0, s26
	ds_read_b128 v[186:189], v168 offset:49152
	ds_read_b128 v[190:193], v168 offset:50176
	ds_read_b128 v[194:197], v168 offset:51200
	ds_read_b128 v[198:201], v168 offset:52224
	ds_read_b128 v[202:205], v168 offset:53248
	ds_read_b128 v[210:213], v168 offset:54272
	ds_read_b128 v[214:217], v168 offset:55296
	ds_read_b128 v[218:221], v168 offset:56320
	global_load_lds_dwordx4 v[162:163], off
	s_add_i32 m0, s26, 0x2000
	s_add_u32 s24, s24, 0x80080
	v_lshl_add_u64 v[162:163], v[206:207], 0, s[8:9]
	s_addc_u32 s25, s25, 0
	s_add_i32 s26, s50, s29
	global_load_lds_dwordx4 v[162:163], off
	v_lshl_add_u64 v[162:163], s[24:25], 0, v[150:151]
	s_mov_b32 m0, s26
	s_nop 0
	global_load_lds_dwordx4 v[162:163], off
	v_lshl_add_u64 v[162:163], s[24:25], 0, v[146:147]
	s_add_i32 m0, s26, 0x2000
	s_nop 0
	global_load_lds_dwordx4 v[162:163], off
	v_lshl_add_u64 v[162:163], v[222:223], 0, s[8:9]
	s_mov_b32 m0, s37
	s_nop 0
	global_load_lds_dwordx4 v[162:163], off
	v_lshl_add_u64 v[162:163], v[224:225], 0, s[8:9]
	s_mov_b32 m0, s38
	s_nop 0
	global_load_lds_dwordx4 v[162:163], off
	s_waitcnt vmcnt(8)
	s_waitcnt lgkmcnt(0)
	s_barrier
	s_setprio 1
	s_waitcnt lgkmcnt(0)
	v_mfma_f32_16x16x32_bf16 v[62:65], v[130:133], v[186:189], v[62:65]
	v_mfma_f32_16x16x32_bf16 v[58:61], v[138:141], v[186:189], v[58:61]
	v_mfma_f32_16x16x32_bf16 v[54:57], v[130:133], v[194:197], v[54:57]
	v_mfma_f32_16x16x32_bf16 v[46:49], v[138:141], v[194:197], v[46:49]
	v_mfma_f32_16x16x32_bf16 v[38:41], v[130:133], v[202:205], v[38:41]
	v_mfma_f32_16x16x32_bf16 v[30:33], v[138:141], v[202:205], v[30:33]
	v_mfma_f32_16x16x32_bf16 v[22:25], v[130:133], v[214:217], v[22:25]
	v_mfma_f32_16x16x32_bf16 v[14:17], v[138:141], v[214:217], v[14:17]
	v_mfma_f32_16x16x32_bf16 v[62:65], v[134:137], v[190:193], v[62:65]
	v_mfma_f32_16x16x32_bf16 v[58:61], v[142:145], v[190:193], v[58:61]
	v_mfma_f32_16x16x32_bf16 v[54:57], v[134:137], v[198:201], v[54:57]
	v_mfma_f32_16x16x32_bf16 v[46:49], v[142:145], v[198:201], v[46:49]
	v_mfma_f32_16x16x32_bf16 v[38:41], v[134:137], v[210:213], v[38:41]
	v_mfma_f32_16x16x32_bf16 v[30:33], v[142:145], v[210:213], v[30:33]
	v_mfma_f32_16x16x32_bf16 v[22:25], v[134:137], v[218:221], v[22:25]
	v_mfma_f32_16x16x32_bf16 v[14:17], v[142:145], v[218:221], v[14:17]
	s_setprio 0
	s_setprio 1
	v_mfma_f32_16x16x32_bf16 v[50:53], v[170:173], v[186:189], v[50:53]
	v_mfma_f32_16x16x32_bf16 v[42:45], v[178:181], v[186:189], v[42:45]
	v_mfma_f32_16x16x32_bf16 v[34:37], v[170:173], v[194:197], v[34:37]
	v_mfma_f32_16x16x32_bf16 v[26:29], v[178:181], v[194:197], v[26:29]
	v_mfma_f32_16x16x32_bf16 v[18:21], v[170:173], v[202:205], v[18:21]
	v_mfma_f32_16x16x32_bf16 v[10:13], v[178:181], v[202:205], v[10:13]
	v_mfma_f32_16x16x32_bf16 v[6:9], v[170:173], v[214:217], v[6:9]
	v_mfma_f32_16x16x32_bf16 v[2:5], v[178:181], v[214:217], v[2:5]
	v_mfma_f32_16x16x32_bf16 v[50:53], v[174:177], v[190:193], v[50:53]
	v_mfma_f32_16x16x32_bf16 v[42:45], v[182:185], v[190:193], v[42:45]
	v_mfma_f32_16x16x32_bf16 v[34:37], v[174:177], v[198:201], v[34:37]
	v_mfma_f32_16x16x32_bf16 v[26:29], v[182:185], v[198:201], v[26:29]
	v_mfma_f32_16x16x32_bf16 v[18:21], v[174:177], v[210:213], v[18:21]
	v_mfma_f32_16x16x32_bf16 v[10:13], v[182:185], v[210:213], v[10:13]
	v_mfma_f32_16x16x32_bf16 v[6:9], v[174:177], v[218:221], v[6:9]
	v_mfma_f32_16x16x32_bf16 v[2:5], v[182:185], v[218:221], v[2:5]
	s_setprio 0
	s_barrier
	s_add_i32 s48, s48, 2
	s_add_u32 s22, s22, 0x100
	s_addc_u32 s23, s23, 0
	s_add_u32 s46, s46, 0x100
	s_addc_u32 s47, s47, 0
	s_cmp_gt_u32 s48, 29
	s_cbranch_scc1 .Lpeel_exit_28
	.p2align 6

; #define PG8_STAGE(bufoff, gbase, voff) do { _Pragma("unroll") for (int _i = 0; _i < 2; ++_i) \
;         __builtin_amdgcn_global_load_lds((const unsigned*)((const char*)(gbase) + (voff)[_i]), (PG8_LAS unsigned*)(lds + (bufoff) + ldsw + _i * 8192), 16, 0, 0); } while (0)
; #define PG8_LDA(dst, b, h) do { _Pragma("unroll") for (int m = 0; m < 4; ++m) _Pragma("unroll") for (int k = 0; k < 2; ++k) dst[m][k] = *(const PG8_LAS bf16x8*)(lds + PG8_SA(b, h) + aoff + m * 2048 + k * 1024); } while (0)
; #define PG8_LDB(dst, b, h) do { _Pragma("unroll") for (int n = 0; n < 2; ++n) _Pragma("unroll") for (int k = 0; k < 2; ++k) dst[n][k] = *(const PG8_LAS bf16x8*)(lds + PG8_SB(b, h) + boff + n * 2048 + k * 1024); } while (0)
; #define PG8_MMA(ai, bj, At, Bt) do { __builtin_amdgcn_s_setprio(1); _Pragma("unroll") for (int m = 0; m < 4; ++m) _Pragma("unroll") for (int n = 0; n < 2; ++n) _Pragma("unroll") for (int k = 0; k < 2; ++k) \
;         acc[ai][bj][m][n] = __builtin_amdgcn_mfma_f32_16x16x32_bf16(Bt[n][k], At[m][k], acc[ai][bj][m][n], 0, 0, 0); __builtin_amdgcn_s_setprio(0); } while (0)
; #define PG8_BAR __builtin_amdgcn_s_barrier()
; template <class Epi, class Sched, bool ALIGN_EPI = false, bool SP2 = false>
; __device__ __forceinline__ void gemm_phase(PG8_LAS unsigned char* lds, const Gemm g, const Sched& S, const Epi& E) {
;     ...
;         const bool has_next = S.next(ui + 1, nxt);
;         const char* nA = has_next ? (const char*)g.A + (size_t)nxt.pm * tstepA : cA; const char* nB = has_next ? (const char*)g.Bt + (size_t)nxt.pn * tstepB : cB;
;         for (int t = 0; t < nt; t += 2) {
;             const bool last = (t == nt - 2);
;             const char* a1 = cA + (size_t)(t + 1) * kstep;
;             const char* a2 = last ? nA : cA + (size_t)(t + 2) * kstep; const char* b2 = last ? nB : cB + (size_t)(t + 2) * kstep;
;             const char* a3 = a2 + kstep; const char* b3 = b2 + kstep;
;             if (last && has_next) S.a_ready(nxt);
;             if constexpr (SP2) {
;             PG8_LDB(B0, 0, 0); PG8_LDB(B1, 0, 1); PG8_SCHED; PG8_LDA(At, 0, 0); PG8_STAGE(PG8_SA(1, 1), a1 + hstepA, voffA);
;             PG8_WAIT_V(8); PG8_WAIT_L(0); PG8_BAR; PG8_MMA(0, 0, At, B0); PG8_MMA(0, 1, At, B1); PG8_BAR; PG8_SCHED;
;             PG8_LDA(At, 0, 1); PG8_STAGE(PG8_SB(0, 0), b2, voffB); PG8_STAGE(PG8_SB(0, 1), b2 + hstepB, voffB); PG8_STAGE(PG8_SA(0, 0), a2, voffA);
.LBB0_3371:
	s_ashr_i32 s23, s22, 31
	s_lshl_b64 s[24:25], s[22:23], 20
	s_add_u32 s24, s86, s24
	s_addc_u32 s25, s87, s25
	s_and_b64 s[26:27], s[4:5], exec
	s_cselect_b32 s23, s25, s31
	s_cselect_b32 s55, s24, s30
	s_ashr_i32 s21, s20, 31
	s_lshl_b64 s[26:27], s[20:21], 20
	s_add_u32 s26, s88, s26
	s_addc_u32 s27, s89, s27
	s_and_b64 s[36:37], s[4:5], exec
	s_cselect_b32 s21, s27, s35
	s_cselect_b32 s56, s26, s34
	s_add_u32 s30, s30, 0x80080
	s_addc_u32 s31, s31, 0
	s_add_u32 s57, s34, 0x100
	s_addc_u32 s58, s35, 0
	s_mov_b32 s59, -2
	ds_read_b128 v[130:133], v164
	ds_read_b128 v[134:137], v164 offset:1024
	ds_read_b128 v[138:141], v164 offset:2048
	ds_read_b128 v[142:145], v164 offset:3072
	ds_read_b128 v[168:171], v165
	ds_read_b128 v[172:175], v165 offset:1024
	ds_read_b128 v[176:179], v165 offset:2048
	ds_read_b128 v[180:183], v165 offset:3072
	s_add_u32 s34, s30, 0xfff80080
	s_addc_u32 s35, s31, -1
	s_cmp_eq_u32 s59, 28
	s_cselect_b32 s37, s23, s35
	s_cselect_b32 s36, s55, s34
	s_cselect_b32 s35, s21, s58
	s_cselect_b32 s34, s56, s57
	v_lshl_add_u64 v[218:219], s[30:31], 0, v[154:155]
	s_add_i32 m0, s29, 0xc000
	ds_read_b128 v[184:187], v166
	ds_read_b128 v[188:191], v166 offset:1024
	ds_read_b128 v[192:195], v166 offset:2048
	ds_read_b128 v[196:199], v166 offset:3072
	ds_read_b128 v[200:203], v166 offset:4096
	ds_read_b128 v[204:207], v166 offset:5120
	ds_read_b128 v[210:213], v166 offset:6144
	ds_read_b128 v[214:217], v166 offset:7168
	global_load_lds_dwordx4 v[218:219], off
	v_lshl_add_u64 v[218:219], s[30:31], 0, v[156:157]
	s_add_i32 m0, s29, 0xe000
	s_nop 0
	global_load_lds_dwordx4 v[218:219], off
	s_waitcnt vmcnt(8)
	s_waitcnt lgkmcnt(0)
	s_barrier
	s_setprio 1
	s_waitcnt lgkmcnt(0)
	v_mfma_f32_16x16x32_bf16 v[126:129], v[130:133], v[184:187], 0
	v_mfma_f32_16x16x32_bf16 v[122:125], v[138:141], v[184:187], 0
	v_mfma_f32_16x16x32_bf16 v[118:121], v[130:133], v[192:195], 0
	v_mfma_f32_16x16x32_bf16 v[114:117], v[138:141], v[192:195], 0
	v_mfma_f32_16x16x32_bf16 v[110:113], v[130:133], v[200:203], 0
	v_mfma_f32_16x16x32_bf16 v[102:105], v[138:141], v[200:203], 0
	v_mfma_f32_16x16x32_bf16 v[94:97], v[130:133], v[210:213], 0
	v_mfma_f32_16x16x32_bf16 v[86:89], v[138:141], v[210:213], 0
	v_mfma_f32_16x16x32_bf16 v[126:129], v[134:137], v[188:191], v[126:129]
	v_mfma_f32_16x16x32_bf16 v[122:125], v[142:145], v[188:191], v[122:125]
	v_mfma_f32_16x16x32_bf16 v[118:121], v[134:137], v[196:199], v[118:121]
	v_mfma_f32_16x16x32_bf16 v[114:117], v[142:145], v[196:199], v[114:117]
	v_mfma_f32_16x16x32_bf16 v[110:113], v[134:137], v[204:207], v[110:113]
	v_mfma_f32_16x16x32_bf16 v[102:105], v[142:145], v[204:207], v[102:105]
	v_mfma_f32_16x16x32_bf16 v[94:97], v[134:137], v[214:217], v[94:97]
	v_mfma_f32_16x16x32_bf16 v[86:89], v[142:145], v[214:217], v[86:89]
	s_setprio 0
	s_setprio 1
	v_mfma_f32_16x16x32_bf16 v[106:109], v[168:171], v[184:187], 0
	v_mfma_f32_16x16x32_bf16 v[98:101], v[176:179], v[184:187], 0
	v_mfma_f32_16x16x32_bf16 v[90:93], v[168:171], v[192:195], 0
	v_mfma_f32_16x16x32_bf16 v[82:85], v[176:179], v[192:195], 0
	v_mfma_f32_16x16x32_bf16 v[78:81], v[168:171], v[200:203], 0
	v_mfma_f32_16x16x32_bf16 v[74:77], v[176:179], v[200:203], 0
	v_mfma_f32_16x16x32_bf16 v[70:73], v[168:171], v[210:213], 0
	v_mfma_f32_16x16x32_bf16 v[66:69], v[176:179], v[210:213], 0
	v_mfma_f32_16x16x32_bf16 v[106:109], v[172:175], v[188:191], v[106:109]
	v_mfma_f32_16x16x32_bf16 v[98:101], v[180:183], v[188:191], v[98:101]
	v_mfma_f32_16x16x32_bf16 v[90:93], v[172:175], v[196:199], v[90:93]
	v_mfma_f32_16x16x32_bf16 v[82:85], v[180:183], v[196:199], v[82:85]
	v_mfma_f32_16x16x32_bf16 v[78:81], v[172:175], v[204:207], v[78:81]
	v_mfma_f32_16x16x32_bf16 v[74:77], v[180:183], v[204:207], v[74:77]
	v_mfma_f32_16x16x32_bf16 v[70:73], v[172:175], v[214:217], v[70:73]
	v_mfma_f32_16x16x32_bf16 v[66:69], v[180:183], v[214:217], v[66:69]
	s_setprio 0
	s_barrier
	s_add_i32 s60, s48, s38
	v_lshl_add_u64 v[218:219], s[34:35], 0, v[150:151]
	s_mov_b32 m0, s60
	ds_read_b128 v[184:187], v166 offset:16384
	ds_read_b128 v[188:191], v166 offset:17408
	ds_read_b128 v[192:195], v166 offset:18432
	ds_read_b128 v[196:199], v166 offset:19456
	ds_read_b128 v[200:203], v166 offset:20480
	ds_read_b128 v[204:207], v166 offset:21504
	ds_read_b128 v[210:213], v166 offset:22528
	ds_read_b128 v[214:217], v166 offset:23552
	global_load_lds_dwordx4 v[218:219], off
	s_add_i32 m0, s60, 0x2000
	s_add_u32 s60, s34, 0x80000
	v_lshl_add_u64 v[220:221], s[34:35], 0, v[146:147]
	s_addc_u32 s61, s35, 0
	s_add_i32 s62, s49, s38
	global_load_lds_dwordx4 v[220:221], off
	v_lshl_add_u64 v[222:223], s[60:61], 0, v[150:151]
	s_mov_b32 m0, s62
	v_lshl_add_u64 v[224:225], s[36:37], 0, v[148:149]
	global_load_lds_dwordx4 v[222:223], off
	v_lshl_add_u64 v[222:223], s[60:61], 0, v[146:147]
	s_add_i32 m0, s62, 0x2000
	s_nop 0
	global_load_lds_dwordx4 v[222:223], off
	v_lshl_add_u64 v[222:223], s[36:37], 0, v[152:153]
	s_mov_b32 m0, s29
	s_nop 0
	global_load_lds_dwordx4 v[222:223], off
	s_mov_b32 m0, s41
	s_nop 0
	global_load_lds_dwordx4 v[224:225], off
	s_waitcnt vmcnt(8)
	s_waitcnt lgkmcnt(0)
	s_barrier
; #define PG8_STAGE(bufoff, gbase, voff) do { _Pragma("unroll") for (int _i = 0; _i < 2; ++_i) \
;         __builtin_amdgcn_global_load_lds((const unsigned*)((const char*)(gbase) + (voff)[_i]), (PG8_LAS unsigned*)(lds + (bufoff) + ldsw + _i * 8192), 16, 0, 0); } while (0)
; #define PG8_LDA(dst, b, h) do { _Pragma("unroll") for (int m = 0; m < 4; ++m) _Pragma("unroll") for (int k = 0; k < 2; ++k) dst[m][k] = *(const PG8_LAS bf16x8*)(lds + PG8_SA(b, h) + aoff + m * 2048 + k * 1024); } while (0)
; #define PG8_LDB(dst, b, h) do { _Pragma("unroll") for (int n = 0; n < 2; ++n) _Pragma("unroll") for (int k = 0; k < 2; ++k) dst[n][k] = *(const PG8_LAS bf16x8*)(lds + PG8_SB(b, h) + boff + n * 2048 + k * 1024); } while (0)
; #define PG8_MMA(ai, bj, At, Bt) do { __builtin_amdgcn_s_setprio(1); _Pragma("unroll") for (int m = 0; m < 4; ++m) _Pragma("unroll") for (int n = 0; n < 2; ++n) _Pragma("unroll") for (int k = 0; k < 2; ++k) \
;         acc[ai][bj][m][n] = __builtin_amdgcn_mfma_f32_16x16x32_bf16(Bt[n][k], At[m][k], acc[ai][bj][m][n], 0, 0, 0); __builtin_amdgcn_s_setprio(0); } while (0)
; #define PG8_WAIT_V(n) asm volatile("s_waitcnt vmcnt(" #n ")" ::: "memory")
; #define PG8_WAIT_L(n) asm volatile("s_waitcnt lgkmcnt(" #n ")" ::: "memory")
; #define PG8_BAR __builtin_amdgcn_s_barrier()
; #define PG8_SCHED __builtin_amdgcn_sched_barrier(0)
; template <class Epi, class Sched, bool ALIGN_EPI = false, bool SP2 = false>
; __device__ __forceinline__ void gemm_phase(PG8_LAS unsigned char* lds, const Gemm g, const Sched& S, const Epi& E) {
;     ...
;             PG8_LDA(At, 0, 1); PG8_STAGE(PG8_SB(0, 0), b2, voffB); PG8_STAGE(PG8_SB(0, 1), b2 + hstepB, voffB); PG8_STAGE(PG8_SA(0, 0), a2, voffA);
;             PG8_WAIT_V(8); PG8_WAIT_L(0); PG8_BAR; PG8_MMA(1, 0, At, B0); PG8_MMA(1, 1, At, B1); PG8_BAR; PG8_SCHED;
;             PG8_LDB(B0, 1, 0); PG8_LDB(B1, 1, 1); PG8_SCHED; PG8_LDA(At, 1, 0); PG8_STAGE(PG8_SA(0, 1), a2 + hstepA, voffA);
;             PG8_WAIT_V(8); PG8_WAIT_L(0); PG8_BAR; PG8_MMA(0, 0, At, B0); PG8_MMA(0, 1, At, B1); PG8_BAR; PG8_SCHED;
	s_setprio 1
	s_waitcnt lgkmcnt(0)
	v_mfma_f32_16x16x32_bf16 v[62:65], v[130:133], v[184:187], 0
	v_mfma_f32_16x16x32_bf16 v[58:61], v[138:141], v[184:187], 0
	v_mfma_f32_16x16x32_bf16 v[54:57], v[130:133], v[192:195], 0
	v_mfma_f32_16x16x32_bf16 v[46:49], v[138:141], v[192:195], 0
	v_mfma_f32_16x16x32_bf16 v[38:41], v[130:133], v[200:203], 0
	v_mfma_f32_16x16x32_bf16 v[30:33], v[138:141], v[200:203], 0
	v_mfma_f32_16x16x32_bf16 v[22:25], v[130:133], v[210:213], 0
	v_mfma_f32_16x16x32_bf16 v[14:17], v[138:141], v[210:213], 0
	v_mfma_f32_16x16x32_bf16 v[62:65], v[134:137], v[188:191], v[62:65]
	v_mfma_f32_16x16x32_bf16 v[58:61], v[142:145], v[188:191], v[58:61]
	v_mfma_f32_16x16x32_bf16 v[54:57], v[134:137], v[196:199], v[54:57]
	v_mfma_f32_16x16x32_bf16 v[46:49], v[142:145], v[196:199], v[46:49]
	v_mfma_f32_16x16x32_bf16 v[38:41], v[134:137], v[204:207], v[38:41]
	v_mfma_f32_16x16x32_bf16 v[30:33], v[142:145], v[204:207], v[30:33]
	v_mfma_f32_16x16x32_bf16 v[22:25], v[134:137], v[214:217], v[22:25]
	v_mfma_f32_16x16x32_bf16 v[14:17], v[142:145], v[214:217], v[14:17]
	s_setprio 0
	s_setprio 1
	v_mfma_f32_16x16x32_bf16 v[50:53], v[168:171], v[184:187], 0
	v_mfma_f32_16x16x32_bf16 v[42:45], v[176:179], v[184:187], 0
	v_mfma_f32_16x16x32_bf16 v[34:37], v[168:171], v[192:195], 0
	v_mfma_f32_16x16x32_bf16 v[26:29], v[176:179], v[192:195], 0
	v_mfma_f32_16x16x32_bf16 v[18:21], v[168:171], v[200:203], 0
	v_mfma_f32_16x16x32_bf16 v[10:13], v[176:179], v[200:203], 0
	v_mfma_f32_16x16x32_bf16 v[6:9], v[168:171], v[210:213], 0
	v_mfma_f32_16x16x32_bf16 v[2:5], v[176:179], v[210:213], 0
	v_mfma_f32_16x16x32_bf16 v[50:53], v[172:175], v[188:191], v[50:53]
	v_mfma_f32_16x16x32_bf16 v[42:45], v[180:183], v[188:191], v[42:45]
	v_mfma_f32_16x16x32_bf16 v[34:37], v[172:175], v[196:199], v[34:37]
	v_mfma_f32_16x16x32_bf16 v[26:29], v[180:183], v[196:199], v[26:29]
	v_mfma_f32_16x16x32_bf16 v[18:21], v[172:175], v[204:207], v[18:21]
	v_mfma_f32_16x16x32_bf16 v[10:13], v[180:183], v[204:207], v[10:13]
	v_mfma_f32_16x16x32_bf16 v[6:9], v[172:175], v[214:217], v[6:9]
	v_mfma_f32_16x16x32_bf16 v[2:5], v[180:183], v[214:217], v[2:5]
	s_setprio 0
	s_barrier
	s_add_i32 s60, 0, 0x18000
	s_add_i32 s61, 0, 0x1c000
	v_add_u32_e32 v142, s60, v162
	v_add_u32_e32 v167, s61, v162
	ds_read_b128 v[130:133], v142
	ds_read_b128 v[134:137], v142 offset:1024
	ds_read_b128 v[138:141], v142 offset:2048
	ds_read_b128 v[142:145], v142 offset:3072
	ds_read_b128 v[168:171], v167
	ds_read_b128 v[172:175], v167 offset:1024
	ds_read_b128 v[176:179], v167 offset:2048
	ds_read_b128 v[180:183], v167 offset:3072
	s_add_u32 s36, s36, 0x80000
	s_addc_u32 s37, s37, 0
	s_mov_b32 m0, s42
	v_lshl_add_u64 v[226:227], s[36:37], 0, v[152:153]
	ds_read_b128 v[184:187], v166 offset:32768
	ds_read_b128 v[188:191], v166 offset:33792
	ds_read_b128 v[192:195], v166 offset:34816
	ds_read_b128 v[196:199], v166 offset:35840
	ds_read_b128 v[200:203], v166 offset:36864
	ds_read_b128 v[204:207], v166 offset:37888
	ds_read_b128 v[210:213], v166 offset:38912
	ds_read_b128 v[214:217], v166 offset:39936
	global_load_lds_dwordx4 v[226:227], off
	v_lshl_add_u64 v[226:227], s[36:37], 0, v[148:149]
	s_mov_b32 m0, s43
	s_nop 0
	global_load_lds_dwordx4 v[226:227], off
	s_waitcnt vmcnt(8)
	s_waitcnt lgkmcnt(0)
	s_barrier
	s_setprio 1
	s_waitcnt lgkmcnt(0)
	v_mfma_f32_16x16x32_bf16 v[126:129], v[130:133], v[184:187], v[126:129]
	v_mfma_f32_16x16x32_bf16 v[122:125], v[138:141], v[184:187], v[122:125]
	v_mfma_f32_16x16x32_bf16 v[118:121], v[130:133], v[192:195], v[118:121]
	v_mfma_f32_16x16x32_bf16 v[114:117], v[138:141], v[192:195], v[114:117]
	v_mfma_f32_16x16x32_bf16 v[110:113], v[130:133], v[200:203], v[110:113]
	v_mfma_f32_16x16x32_bf16 v[102:105], v[138:141], v[200:203], v[102:105]
	v_mfma_f32_16x16x32_bf16 v[94:97], v[130:133], v[210:213], v[94:97]
	v_mfma_f32_16x16x32_bf16 v[86:89], v[138:141], v[210:213], v[86:89]
	v_mfma_f32_16x16x32_bf16 v[126:129], v[134:137], v[188:191], v[126:129]
	v_mfma_f32_16x16x32_bf16 v[122:125], v[142:145], v[188:191], v[122:125]
	v_mfma_f32_16x16x32_bf16 v[118:121], v[134:137], v[196:199], v[118:121]
	v_mfma_f32_16x16x32_bf16 v[114:117], v[142:145], v[196:199], v[114:117]
	v_mfma_f32_16x16x32_bf16 v[110:113], v[134:137], v[204:207], v[110:113]
	v_mfma_f32_16x16x32_bf16 v[102:105], v[142:145], v[204:207], v[102:105]
	v_mfma_f32_16x16x32_bf16 v[94:97], v[134:137], v[214:217], v[94:97]
	v_mfma_f32_16x16x32_bf16 v[86:89], v[142:145], v[214:217], v[86:89]
	s_setprio 0
	s_setprio 1
	v_mfma_f32_16x16x32_bf16 v[106:109], v[168:171], v[184:187], v[106:109]
	v_mfma_f32_16x16x32_bf16 v[98:101], v[176:179], v[184:187], v[98:101]
	v_mfma_f32_16x16x32_bf16 v[90:93], v[168:171], v[192:195], v[90:93]
	v_mfma_f32_16x16x32_bf16 v[82:85], v[176:179], v[192:195], v[82:85]
	v_mfma_f32_16x16x32_bf16 v[78:81], v[168:171], v[200:203], v[78:81]
	v_mfma_f32_16x16x32_bf16 v[74:77], v[176:179], v[200:203], v[74:77]
	v_mfma_f32_16x16x32_bf16 v[70:73], v[168:171], v[210:213], v[70:73]
	v_mfma_f32_16x16x32_bf16 v[66:69], v[176:179], v[210:213], v[66:69]
	v_mfma_f32_16x16x32_bf16 v[106:109], v[172:175], v[188:191], v[106:109]
	v_mfma_f32_16x16x32_bf16 v[98:101], v[180:183], v[188:191], v[98:101]
	v_mfma_f32_16x16x32_bf16 v[90:93], v[172:175], v[196:199], v[90:93]
	v_mfma_f32_16x16x32_bf16 v[82:85], v[180:183], v[196:199], v[82:85]
	v_mfma_f32_16x16x32_bf16 v[78:81], v[172:175], v[204:207], v[78:81]
	v_mfma_f32_16x16x32_bf16 v[74:77], v[180:183], v[204:207], v[74:77]
	v_mfma_f32_16x16x32_bf16 v[70:73], v[172:175], v[214:217], v[70:73]
	v_mfma_f32_16x16x32_bf16 v[66:69], v[180:183], v[214:217], v[66:69]
	s_setprio 0
	s_barrier
; #define PG8_STAGE(bufoff, gbase, voff) do { _Pragma("unroll") for (int _i = 0; _i < 2; ++_i) \
;         __builtin_amdgcn_global_load_lds((const unsigned*)((const char*)(gbase) + (voff)[_i]), (PG8_LAS unsigned*)(lds + (bufoff) + ldsw + _i * 8192), 16, 0, 0); } while (0)
; #define PG8_LDA(dst, b, h) do { _Pragma("unroll") for (int m = 0; m < 4; ++m) _Pragma("unroll") for (int k = 0; k < 2; ++k) dst[m][k] = *(const PG8_LAS bf16x8*)(lds + PG8_SA(b, h) + aoff + m * 2048 + k * 1024); } while (0)
; #define PG8_LDB(dst, b, h) do { _Pragma("unroll") for (int n = 0; n < 2; ++n) _Pragma("unroll") for (int k = 0; k < 2; ++k) dst[n][k] = *(const PG8_LAS bf16x8*)(lds + PG8_SB(b, h) + boff + n * 2048 + k * 1024); } while (0)
; template <class Epi, class Sched, bool ALIGN_EPI = false, bool SP2 = false>
; __device__ __forceinline__ void gemm_phase(PG8_LAS unsigned char* lds, const Gemm g, const Sched& S, const Epi& E) {
;     ...
;         for (int t = 0; t < nt; t += 2) {
;             const bool last = (t == nt - 2);
;             const char* a1 = cA + (size_t)(t + 1) * kstep;
;             const char* a2 = last ? nA : cA + (size_t)(t + 2) * kstep; const char* b2 = last ? nB : cB + (size_t)(t + 2) * kstep;
;             const char* a3 = a2 + kstep; const char* b3 = b2 + kstep;
;             if (last && has_next) S.a_ready(nxt);
;             if constexpr (SP2) {
;             PG8_LDB(B0, 0, 0); PG8_LDB(B1, 0, 1); PG8_SCHED; PG8_LDA(At, 0, 0); PG8_STAGE(PG8_SA(1, 1), a1 + hstepA, voffA);
;             PG8_WAIT_V(8); PG8_WAIT_L(0); PG8_BAR; PG8_MMA(0, 0, At, B0); PG8_MMA(0, 1, At, B1); PG8_BAR; PG8_SCHED;
;             PG8_LDA(At, 0, 1); PG8_STAGE(PG8_SB(0, 0), b2, voffB); PG8_STAGE(PG8_SB(0, 1), b2 + hstepB, voffB); PG8_STAGE(PG8_SA(0, 0), a2, voffA);
;             PG8_WAIT_V(8); PG8_WAIT_L(0); PG8_BAR; PG8_MMA(1, 0, At, B0); PG8_MMA(1, 1, At, B1); PG8_BAR; PG8_SCHED;
;             PG8_LDB(B0, 1, 0); PG8_LDB(B1, 1, 1); PG8_SCHED; PG8_LDA(At, 1, 0); PG8_STAGE(PG8_SA(0, 1), a2 + hstepA, voffA);
;             PG8_WAIT_V(8); PG8_WAIT_L(0); PG8_BAR; PG8_MMA(0, 0, At, B0); PG8_MMA(0, 1, At, B1); PG8_BAR; PG8_SCHED;
;             PG8_LDA(At, 1, 1); PG8_STAGE(PG8_SB(1, 0), b3, voffB); PG8_STAGE(PG8_SB(1, 1), b3 + hstepB, voffB); PG8_STAGE(PG8_SA(1, 0), a3, voffA);
;             PG8_WAIT_V(8); PG8_WAIT_L(0); PG8_BAR; PG8_MMA(1, 0, At, B0); PG8_MMA(1, 1, At, B1); PG8_BAR; PG8_SCHED;
	s_add_i32 s36, s60, s38
	v_lshl_add_u64 v[218:219], v[218:219], 0, s[10:11]
	s_mov_b32 m0, s36
	ds_read_b128 v[184:187], v166 offset:49152
	ds_read_b128 v[188:191], v166 offset:50176
	ds_read_b128 v[192:195], v166 offset:51200
	ds_read_b128 v[196:199], v166 offset:52224
	ds_read_b128 v[200:203], v166 offset:53248
	ds_read_b128 v[204:207], v166 offset:54272
	ds_read_b128 v[210:213], v166 offset:55296
	ds_read_b128 v[214:217], v166 offset:56320
	global_load_lds_dwordx4 v[218:219], off
	s_add_i32 m0, s36, 0x2000
	s_add_u32 s34, s34, 0x80080
	v_lshl_add_u64 v[218:219], v[220:221], 0, s[10:11]
	s_addc_u32 s35, s35, 0
	s_add_i32 s36, s61, s38
	global_load_lds_dwordx4 v[218:219], off
	v_lshl_add_u64 v[218:219], s[34:35], 0, v[150:151]
	s_mov_b32 m0, s36
	s_nop 0
	global_load_lds_dwordx4 v[218:219], off
	v_lshl_add_u64 v[218:219], s[34:35], 0, v[146:147]
	s_add_i32 m0, s36, 0x2000
	s_nop 0
	global_load_lds_dwordx4 v[218:219], off
	v_lshl_add_u64 v[218:219], v[222:223], 0, s[10:11]
	s_mov_b32 m0, s45
	s_nop 0
	global_load_lds_dwordx4 v[218:219], off
	v_lshl_add_u64 v[218:219], v[224:225], 0, s[10:11]
	s_mov_b32 m0, s46
	s_nop 0
	global_load_lds_dwordx4 v[218:219], off
	s_waitcnt vmcnt(8)
	s_waitcnt lgkmcnt(0)
	s_barrier
	s_setprio 1
	s_waitcnt lgkmcnt(0)
	v_mfma_f32_16x16x32_bf16 v[62:65], v[130:133], v[184:187], v[62:65]
	v_mfma_f32_16x16x32_bf16 v[58:61], v[138:141], v[184:187], v[58:61]
	v_mfma_f32_16x16x32_bf16 v[54:57], v[130:133], v[192:195], v[54:57]
	v_mfma_f32_16x16x32_bf16 v[46:49], v[138:141], v[192:195], v[46:49]
	v_mfma_f32_16x16x32_bf16 v[38:41], v[130:133], v[200:203], v[38:41]
	v_mfma_f32_16x16x32_bf16 v[30:33], v[138:141], v[200:203], v[30:33]
	v_mfma_f32_16x16x32_bf16 v[22:25], v[130:133], v[210:213], v[22:25]
	v_mfma_f32_16x16x32_bf16 v[14:17], v[138:141], v[210:213], v[14:17]
	v_mfma_f32_16x16x32_bf16 v[62:65], v[134:137], v[188:191], v[62:65]
	v_mfma_f32_16x16x32_bf16 v[58:61], v[142:145], v[188:191], v[58:61]
	v_mfma_f32_16x16x32_bf16 v[54:57], v[134:137], v[196:199], v[54:57]
	v_mfma_f32_16x16x32_bf16 v[46:49], v[142:145], v[196:199], v[46:49]
	v_mfma_f32_16x16x32_bf16 v[38:41], v[134:137], v[204:207], v[38:41]
	v_mfma_f32_16x16x32_bf16 v[30:33], v[142:145], v[204:207], v[30:33]
	v_mfma_f32_16x16x32_bf16 v[22:25], v[134:137], v[214:217], v[22:25]
	v_mfma_f32_16x16x32_bf16 v[14:17], v[142:145], v[214:217], v[14:17]
	s_setprio 0
	s_setprio 1
	v_mfma_f32_16x16x32_bf16 v[50:53], v[168:171], v[184:187], v[50:53]
	v_mfma_f32_16x16x32_bf16 v[42:45], v[176:179], v[184:187], v[42:45]
	v_mfma_f32_16x16x32_bf16 v[34:37], v[168:171], v[192:195], v[34:37]
	v_mfma_f32_16x16x32_bf16 v[26:29], v[176:179], v[192:195], v[26:29]
	v_mfma_f32_16x16x32_bf16 v[18:21], v[168:171], v[200:203], v[18:21]
	v_mfma_f32_16x16x32_bf16 v[10:13], v[176:179], v[200:203], v[10:13]
	v_mfma_f32_16x16x32_bf16 v[6:9], v[168:171], v[210:213], v[6:9]
	v_mfma_f32_16x16x32_bf16 v[2:5], v[176:179], v[210:213], v[2:5]
	v_mfma_f32_16x16x32_bf16 v[50:53], v[172:175], v[188:191], v[50:53]
	v_mfma_f32_16x16x32_bf16 v[42:45], v[180:183], v[188:191], v[42:45]
	v_mfma_f32_16x16x32_bf16 v[34:37], v[172:175], v[196:199], v[34:37]
	v_mfma_f32_16x16x32_bf16 v[26:29], v[180:183], v[196:199], v[26:29]
	v_mfma_f32_16x16x32_bf16 v[18:21], v[172:175], v[204:207], v[18:21]
	v_mfma_f32_16x16x32_bf16 v[10:13], v[180:183], v[204:207], v[10:13]
	v_mfma_f32_16x16x32_bf16 v[6:9], v[172:175], v[214:217], v[6:9]
	v_mfma_f32_16x16x32_bf16 v[2:5], v[180:183], v[214:217], v[2:5]
	s_setprio 0
	s_barrier
	s_add_i32 s59, s59, 2
	s_add_u32 s30, s30, 0x100
	s_addc_u32 s31, s31, 0
	s_add_u32 s57, s57, 0x100
	s_addc_u32 s58, s58, 0
	s_cmp_gt_u32 s59, 29
	s_cbranch_scc1 .Lpeel_exit_32
	.p2align 6

; #define PG8_STAGE(bufoff, gbase, voff) do { _Pragma("unroll") for (int _i = 0; _i < 2; ++_i) \
;         __builtin_amdgcn_global_load_lds((const unsigned*)((const char*)(gbase) + (voff)[_i]), (PG8_LAS unsigned*)(lds + (bufoff) + ldsw + _i * 8192), 16, 0, 0); } while (0)
; #define PG8_LDA(dst, b, h) do { _Pragma("unroll") for (int m = 0; m < 4; ++m) _Pragma("unroll") for (int k = 0; k < 2; ++k) dst[m][k] = *(const PG8_LAS bf16x8*)(lds + PG8_SA(b, h) + aoff + m * 2048 + k * 1024); } while (0)
; #define PG8_LDB(dst, b, h) do { _Pragma("unroll") for (int n = 0; n < 2; ++n) _Pragma("unroll") for (int k = 0; k < 2; ++k) dst[n][k] = *(const PG8_LAS bf16x8*)(lds + PG8_SB(b, h) + boff + n * 2048 + k * 1024); } while (0)
; #define PG8_MMA(ai, bj, At, Bt) do { __builtin_amdgcn_s_setprio(1); _Pragma("unroll") for (int m = 0; m < 4; ++m) _Pragma("unroll") for (int n = 0; n < 2; ++n) _Pragma("unroll") for (int k = 0; k < 2; ++k) \
;         acc[ai][bj][m][n] = __builtin_amdgcn_mfma_f32_16x16x32_bf16(Bt[n][k], At[m][k], acc[ai][bj][m][n], 0, 0, 0); __builtin_amdgcn_s_setprio(0); } while (0)
; #define PG8_BAR __builtin_amdgcn_s_barrier()
; template <class Epi, class Sched, bool ALIGN_EPI = false, bool SP2 = false>
; __device__ __forceinline__ void gemm_phase(PG8_LAS unsigned char* lds, const Gemm g, const Sched& S, const Epi& E) {
;     ...
;         const bool has_next = S.next(ui + 1, nxt);
;         const char* nA = has_next ? (const char*)g.A + (size_t)nxt.pm * tstepA : cA; const char* nB = has_next ? (const char*)g.Bt + (size_t)nxt.pn * tstepB : cB;
;         for (int t = 0; t < nt; t += 2) {
;             const bool last = (t == nt - 2);
;             const char* a1 = cA + (size_t)(t + 1) * kstep;
;             const char* a2 = last ? nA : cA + (size_t)(t + 2) * kstep; const char* b2 = last ? nB : cB + (size_t)(t + 2) * kstep;
;             const char* a3 = a2 + kstep; const char* b3 = b2 + kstep;
;             if (last && has_next) S.a_ready(nxt);
;             if constexpr (SP2) {
;             PG8_LDB(B0, 0, 0); PG8_LDB(B1, 0, 1); PG8_SCHED; PG8_LDA(At, 0, 0); PG8_STAGE(PG8_SA(1, 1), a1 + hstepA, voffA);
;             PG8_WAIT_V(8); PG8_WAIT_L(0); PG8_BAR; PG8_MMA(0, 0, At, B0); PG8_MMA(0, 1, At, B1); PG8_BAR; PG8_SCHED;
;             PG8_LDA(At, 0, 1); PG8_STAGE(PG8_SB(0, 0), b2, voffB); PG8_STAGE(PG8_SB(0, 1), b2 + hstepB, voffB); PG8_STAGE(PG8_SA(0, 0), a2, voffA);
.LBB0_3499:
	s_ashr_i32 s13, s12, 31
	s_lshl_b64 s[14:15], s[12:13], 20
	s_add_u32 s14, s86, s14
	s_addc_u32 s15, s87, s15
	s_and_b64 s[16:17], s[4:5], exec
	s_cselect_b32 s13, s15, s21
	s_cselect_b32 s44, s14, s20
	s_ashr_i32 s11, s10, 31
	s_lshl_b64 s[16:17], s[10:11], 20
	s_add_u32 s16, s27, s16
	s_addc_u32 s17, s28, s17
	s_and_b64 s[24:25], s[4:5], exec
	s_cselect_b32 s11, s17, s23
	s_cselect_b32 s45, s16, s22
	s_add_u32 s20, s20, 0x80080
	s_addc_u32 s21, s21, 0
	s_add_u32 s46, s22, 0x100
	s_addc_u32 s47, s23, 0
	s_mov_b32 s48, -2
	ds_read_b128 v[154:157], v150
	ds_read_b128 v[158:161], v150 offset:1024
	ds_read_b128 v[162:165], v150 offset:2048
	ds_read_b128 v[166:169], v150 offset:3072
	ds_read_b128 v[170:173], v151
	ds_read_b128 v[174:177], v151 offset:1024
	ds_read_b128 v[178:181], v151 offset:2048
	ds_read_b128 v[182:185], v151 offset:3072
	s_add_u32 s22, s20, 0xfff80080
	s_addc_u32 s23, s21, -1
	s_cmp_eq_u32 s48, 28
	s_cselect_b32 s25, s13, s23
	s_cselect_b32 s24, s44, s22
	s_cselect_b32 s23, s11, s47
	s_cselect_b32 s22, s45, s46
	v_lshl_add_u64 v[146:147], s[20:21], 0, v[138:139]
	s_add_i32 m0, s19, 0xc000
	ds_read_b128 v[186:189], v152
	ds_read_b128 v[190:193], v152 offset:1024
	ds_read_b128 v[194:197], v152 offset:2048
	ds_read_b128 v[198:201], v152 offset:3072
	ds_read_b128 v[202:205], v152 offset:4096
	ds_read_b128 v[210:213], v152 offset:5120
	ds_read_b128 v[214:217], v152 offset:6144
	ds_read_b128 v[218:221], v152 offset:7168
	global_load_lds_dwordx4 v[146:147], off
	v_lshl_add_u64 v[146:147], s[20:21], 0, v[140:141]
	s_add_i32 m0, s19, 0xe000
	s_nop 0
	global_load_lds_dwordx4 v[146:147], off
	s_waitcnt vmcnt(8)
	s_waitcnt lgkmcnt(0)
	s_barrier
	s_setprio 1
	s_waitcnt lgkmcnt(0)
	v_mfma_f32_16x16x32_bf16 v[126:129], v[154:157], v[186:189], 0
	v_mfma_f32_16x16x32_bf16 v[122:125], v[162:165], v[186:189], 0
	v_mfma_f32_16x16x32_bf16 v[110:113], v[154:157], v[194:197], 0
	v_mfma_f32_16x16x32_bf16 v[106:109], v[162:165], v[194:197], 0
	v_mfma_f32_16x16x32_bf16 v[94:97], v[154:157], v[202:205], 0
	v_mfma_f32_16x16x32_bf16 v[90:93], v[162:165], v[202:205], 0
	v_mfma_f32_16x16x32_bf16 v[78:81], v[154:157], v[214:217], 0
	v_mfma_f32_16x16x32_bf16 v[74:77], v[162:165], v[214:217], 0
	v_mfma_f32_16x16x32_bf16 v[126:129], v[158:161], v[190:193], v[126:129]
	v_mfma_f32_16x16x32_bf16 v[122:125], v[166:169], v[190:193], v[122:125]
	v_mfma_f32_16x16x32_bf16 v[110:113], v[158:161], v[198:201], v[110:113]
	v_mfma_f32_16x16x32_bf16 v[106:109], v[166:169], v[198:201], v[106:109]
	v_mfma_f32_16x16x32_bf16 v[94:97], v[158:161], v[210:213], v[94:97]
	v_mfma_f32_16x16x32_bf16 v[90:93], v[166:169], v[210:213], v[90:93]
	v_mfma_f32_16x16x32_bf16 v[78:81], v[158:161], v[218:221], v[78:81]
	v_mfma_f32_16x16x32_bf16 v[74:77], v[166:169], v[218:221], v[74:77]
	s_setprio 0
	s_setprio 1
	v_mfma_f32_16x16x32_bf16 v[118:121], v[170:173], v[186:189], 0
	v_mfma_f32_16x16x32_bf16 v[114:117], v[178:181], v[186:189], 0
	v_mfma_f32_16x16x32_bf16 v[102:105], v[170:173], v[194:197], 0
	v_mfma_f32_16x16x32_bf16 v[98:101], v[178:181], v[194:197], 0
	v_mfma_f32_16x16x32_bf16 v[86:89], v[170:173], v[202:205], 0
	v_mfma_f32_16x16x32_bf16 v[82:85], v[178:181], v[202:205], 0
	v_mfma_f32_16x16x32_bf16 v[70:73], v[170:173], v[214:217], 0
	v_mfma_f32_16x16x32_bf16 v[66:69], v[178:181], v[214:217], 0
	v_mfma_f32_16x16x32_bf16 v[118:121], v[174:177], v[190:193], v[118:121]
	v_mfma_f32_16x16x32_bf16 v[114:117], v[182:185], v[190:193], v[114:117]
	v_mfma_f32_16x16x32_bf16 v[102:105], v[174:177], v[198:201], v[102:105]
	v_mfma_f32_16x16x32_bf16 v[98:101], v[182:185], v[198:201], v[98:101]
	v_mfma_f32_16x16x32_bf16 v[86:89], v[174:177], v[210:213], v[86:89]
	v_mfma_f32_16x16x32_bf16 v[82:85], v[182:185], v[210:213], v[82:85]
	v_mfma_f32_16x16x32_bf16 v[70:73], v[174:177], v[218:221], v[70:73]
	v_mfma_f32_16x16x32_bf16 v[66:69], v[182:185], v[218:221], v[66:69]
	s_setprio 0
	s_barrier
	s_add_i32 s49, s40, s29
	v_lshl_add_u64 v[146:147], s[22:23], 0, v[134:135]
	s_mov_b32 m0, s49
	ds_read_b128 v[186:189], v152 offset:16384
	ds_read_b128 v[190:193], v152 offset:17408
	ds_read_b128 v[194:197], v152 offset:18432
	ds_read_b128 v[198:201], v152 offset:19456
	ds_read_b128 v[202:205], v152 offset:20480
	ds_read_b128 v[210:213], v152 offset:21504
	ds_read_b128 v[214:217], v152 offset:22528
	ds_read_b128 v[218:221], v152 offset:23552
	global_load_lds_dwordx4 v[146:147], off
	s_add_i32 m0, s49, 0x2000
	s_add_u32 s50, s22, 0x80000
	v_lshl_add_u64 v[206:207], s[22:23], 0, v[130:131]
	s_addc_u32 s51, s23, 0
	s_add_i32 s49, s41, s29
	global_load_lds_dwordx4 v[206:207], off
	v_lshl_add_u64 v[222:223], s[50:51], 0, v[134:135]
	s_mov_b32 m0, s49
	v_lshl_add_u64 v[224:225], s[24:25], 0, v[132:133]
	global_load_lds_dwordx4 v[222:223], off
	v_lshl_add_u64 v[222:223], s[50:51], 0, v[130:131]
	s_add_i32 m0, s49, 0x2000
	s_nop 0
	global_load_lds_dwordx4 v[222:223], off
	v_lshl_add_u64 v[222:223], s[24:25], 0, v[136:137]
	s_mov_b32 m0, s19
	s_nop 0
	global_load_lds_dwordx4 v[222:223], off
	s_mov_b32 m0, s33
	s_nop 0
	global_load_lds_dwordx4 v[224:225], off
	s_waitcnt vmcnt(8)
	s_waitcnt lgkmcnt(0)
	s_barrier
; #define PG8_STAGE(bufoff, gbase, voff) do { _Pragma("unroll") for (int _i = 0; _i < 2; ++_i) \
;         __builtin_amdgcn_global_load_lds((const unsigned*)((const char*)(gbase) + (voff)[_i]), (PG8_LAS unsigned*)(lds + (bufoff) + ldsw + _i * 8192), 16, 0, 0); } while (0)
; #define PG8_LDA(dst, b, h) do { _Pragma("unroll") for (int m = 0; m < 4; ++m) _Pragma("unroll") for (int k = 0; k < 2; ++k) dst[m][k] = *(const PG8_LAS bf16x8*)(lds + PG8_SA(b, h) + aoff + m * 2048 + k * 1024); } while (0)
; #define PG8_LDB(dst, b, h) do { _Pragma("unroll") for (int n = 0; n < 2; ++n) _Pragma("unroll") for (int k = 0; k < 2; ++k) dst[n][k] = *(const PG8_LAS bf16x8*)(lds + PG8_SB(b, h) + boff + n * 2048 + k * 1024); } while (0)
; #define PG8_MMA(ai, bj, At, Bt) do { __builtin_amdgcn_s_setprio(1); _Pragma("unroll") for (int m = 0; m < 4; ++m) _Pragma("unroll") for (int n = 0; n < 2; ++n) _Pragma("unroll") for (int k = 0; k < 2; ++k) \
;         acc[ai][bj][m][n] = __builtin_amdgcn_mfma_f32_16x16x32_bf16(Bt[n][k], At[m][k], acc[ai][bj][m][n], 0, 0, 0); __builtin_amdgcn_s_setprio(0); } while (0)
; #define PG8_WAIT_V(n) asm volatile("s_waitcnt vmcnt(" #n ")" ::: "memory")
; #define PG8_WAIT_L(n) asm volatile("s_waitcnt lgkmcnt(" #n ")" ::: "memory")
; #define PG8_BAR __builtin_amdgcn_s_barrier()
; #define PG8_SCHED __builtin_amdgcn_sched_barrier(0)
; template <class Epi, class Sched, bool ALIGN_EPI = false, bool SP2 = false>
; __device__ __forceinline__ void gemm_phase(PG8_LAS unsigned char* lds, const Gemm g, const Sched& S, const Epi& E) {
;     ...
;             PG8_LDA(At, 0, 1); PG8_STAGE(PG8_SB(0, 0), b2, voffB); PG8_STAGE(PG8_SB(0, 1), b2 + hstepB, voffB); PG8_STAGE(PG8_SA(0, 0), a2, voffA);
;             PG8_WAIT_V(8); PG8_WAIT_L(0); PG8_BAR; PG8_MMA(1, 0, At, B0); PG8_MMA(1, 1, At, B1); PG8_BAR; PG8_SCHED;
;             PG8_LDB(B0, 1, 0); PG8_LDB(B1, 1, 1); PG8_SCHED; PG8_LDA(At, 1, 0); PG8_STAGE(PG8_SA(0, 1), a2 + hstepA, voffA);
;             PG8_WAIT_V(8); PG8_WAIT_L(0); PG8_BAR; PG8_MMA(0, 0, At, B0); PG8_MMA(0, 1, At, B1); PG8_BAR; PG8_SCHED;
	s_setprio 1
	s_waitcnt lgkmcnt(0)
	v_mfma_f32_16x16x32_bf16 v[62:65], v[154:157], v[186:189], 0
	v_mfma_f32_16x16x32_bf16 v[58:61], v[162:165], v[186:189], 0
	v_mfma_f32_16x16x32_bf16 v[46:49], v[154:157], v[194:197], 0
	v_mfma_f32_16x16x32_bf16 v[42:45], v[162:165], v[194:197], 0
	v_mfma_f32_16x16x32_bf16 v[30:33], v[154:157], v[202:205], 0
	v_mfma_f32_16x16x32_bf16 v[26:29], v[162:165], v[202:205], 0
	v_mfma_f32_16x16x32_bf16 v[14:17], v[154:157], v[214:217], 0
	v_mfma_f32_16x16x32_bf16 v[10:13], v[162:165], v[214:217], 0
	v_mfma_f32_16x16x32_bf16 v[62:65], v[158:161], v[190:193], v[62:65]
	v_mfma_f32_16x16x32_bf16 v[58:61], v[166:169], v[190:193], v[58:61]
	v_mfma_f32_16x16x32_bf16 v[46:49], v[158:161], v[198:201], v[46:49]
	v_mfma_f32_16x16x32_bf16 v[42:45], v[166:169], v[198:201], v[42:45]
	v_mfma_f32_16x16x32_bf16 v[30:33], v[158:161], v[210:213], v[30:33]
	v_mfma_f32_16x16x32_bf16 v[26:29], v[166:169], v[210:213], v[26:29]
	v_mfma_f32_16x16x32_bf16 v[14:17], v[158:161], v[218:221], v[14:17]
	v_mfma_f32_16x16x32_bf16 v[10:13], v[166:169], v[218:221], v[10:13]
	s_setprio 0
	s_setprio 1
	v_mfma_f32_16x16x32_bf16 v[54:57], v[170:173], v[186:189], 0
	v_mfma_f32_16x16x32_bf16 v[50:53], v[178:181], v[186:189], 0
	v_mfma_f32_16x16x32_bf16 v[38:41], v[170:173], v[194:197], 0
	v_mfma_f32_16x16x32_bf16 v[34:37], v[178:181], v[194:197], 0
	v_mfma_f32_16x16x32_bf16 v[22:25], v[170:173], v[202:205], 0
	v_mfma_f32_16x16x32_bf16 v[18:21], v[178:181], v[202:205], 0
	v_mfma_f32_16x16x32_bf16 v[6:9], v[170:173], v[214:217], 0
	v_mfma_f32_16x16x32_bf16 v[2:5], v[178:181], v[214:217], 0
	v_mfma_f32_16x16x32_bf16 v[54:57], v[174:177], v[190:193], v[54:57]
	v_mfma_f32_16x16x32_bf16 v[50:53], v[182:185], v[190:193], v[50:53]
	v_mfma_f32_16x16x32_bf16 v[38:41], v[174:177], v[198:201], v[38:41]
	v_mfma_f32_16x16x32_bf16 v[34:37], v[182:185], v[198:201], v[34:37]
	v_mfma_f32_16x16x32_bf16 v[22:25], v[174:177], v[210:213], v[22:25]
	v_mfma_f32_16x16x32_bf16 v[18:21], v[182:185], v[210:213], v[18:21]
	v_mfma_f32_16x16x32_bf16 v[6:9], v[174:177], v[218:221], v[6:9]
	v_mfma_f32_16x16x32_bf16 v[2:5], v[182:185], v[218:221], v[2:5]
	s_setprio 0
	s_barrier
	s_add_i32 s49, 0, 0x18000
	v_add_u32_e32 v153, s49, v148
	s_add_i32 s50, 0, 0x1c000
	ds_read_b128 v[154:157], v153
	ds_read_b128 v[158:161], v153 offset:1024
	ds_read_b128 v[162:165], v153 offset:2048
	ds_read_b128 v[166:169], v153 offset:3072
	v_add_u32_e32 v153, s50, v148
	ds_read_b128 v[170:173], v153
	ds_read_b128 v[174:177], v153 offset:1024
	ds_read_b128 v[178:181], v153 offset:2048
	ds_read_b128 v[182:185], v153 offset:3072
	s_add_u32 s24, s24, 0x80000
	s_addc_u32 s25, s25, 0
	s_mov_b32 m0, s34
	v_lshl_add_u64 v[226:227], s[24:25], 0, v[136:137]
	ds_read_b128 v[186:189], v152 offset:32768
	ds_read_b128 v[190:193], v152 offset:33792
	ds_read_b128 v[194:197], v152 offset:34816
	ds_read_b128 v[198:201], v152 offset:35840
	ds_read_b128 v[202:205], v152 offset:36864
	ds_read_b128 v[210:213], v152 offset:37888
	ds_read_b128 v[214:217], v152 offset:38912
	ds_read_b128 v[218:221], v152 offset:39936
	global_load_lds_dwordx4 v[226:227], off
	v_lshl_add_u64 v[226:227], s[24:25], 0, v[132:133]
	s_mov_b32 m0, s35
	s_nop 0
	global_load_lds_dwordx4 v[226:227], off
	s_waitcnt vmcnt(8)
	s_waitcnt lgkmcnt(0)
	s_barrier
	s_setprio 1
	s_waitcnt lgkmcnt(0)
	v_mfma_f32_16x16x32_bf16 v[126:129], v[154:157], v[186:189], v[126:129]
	v_mfma_f32_16x16x32_bf16 v[122:125], v[162:165], v[186:189], v[122:125]
	v_mfma_f32_16x16x32_bf16 v[110:113], v[154:157], v[194:197], v[110:113]
	v_mfma_f32_16x16x32_bf16 v[106:109], v[162:165], v[194:197], v[106:109]
	v_mfma_f32_16x16x32_bf16 v[94:97], v[154:157], v[202:205], v[94:97]
	v_mfma_f32_16x16x32_bf16 v[90:93], v[162:165], v[202:205], v[90:93]
	v_mfma_f32_16x16x32_bf16 v[78:81], v[154:157], v[214:217], v[78:81]
	v_mfma_f32_16x16x32_bf16 v[74:77], v[162:165], v[214:217], v[74:77]
	v_mfma_f32_16x16x32_bf16 v[126:129], v[158:161], v[190:193], v[126:129]
	v_mfma_f32_16x16x32_bf16 v[122:125], v[166:169], v[190:193], v[122:125]
	v_mfma_f32_16x16x32_bf16 v[110:113], v[158:161], v[198:201], v[110:113]
	v_mfma_f32_16x16x32_bf16 v[106:109], v[166:169], v[198:201], v[106:109]
	v_mfma_f32_16x16x32_bf16 v[94:97], v[158:161], v[210:213], v[94:97]
	v_mfma_f32_16x16x32_bf16 v[90:93], v[166:169], v[210:213], v[90:93]
	v_mfma_f32_16x16x32_bf16 v[78:81], v[158:161], v[218:221], v[78:81]
	v_mfma_f32_16x16x32_bf16 v[74:77], v[166:169], v[218:221], v[74:77]
	s_setprio 0
	s_setprio 1
	v_mfma_f32_16x16x32_bf16 v[118:121], v[170:173], v[186:189], v[118:121]
	v_mfma_f32_16x16x32_bf16 v[114:117], v[178:181], v[186:189], v[114:117]
	v_mfma_f32_16x16x32_bf16 v[102:105], v[170:173], v[194:197], v[102:105]
	v_mfma_f32_16x16x32_bf16 v[98:101], v[178:181], v[194:197], v[98:101]
	v_mfma_f32_16x16x32_bf16 v[86:89], v[170:173], v[202:205], v[86:89]
	v_mfma_f32_16x16x32_bf16 v[82:85], v[178:181], v[202:205], v[82:85]
	v_mfma_f32_16x16x32_bf16 v[70:73], v[170:173], v[214:217], v[70:73]
	v_mfma_f32_16x16x32_bf16 v[66:69], v[178:181], v[214:217], v[66:69]
	v_mfma_f32_16x16x32_bf16 v[118:121], v[174:177], v[190:193], v[118:121]
	v_mfma_f32_16x16x32_bf16 v[114:117], v[182:185], v[190:193], v[114:117]
	v_mfma_f32_16x16x32_bf16 v[102:105], v[174:177], v[198:201], v[102:105]
	v_mfma_f32_16x16x32_bf16 v[98:101], v[182:185], v[198:201], v[98:101]
	v_mfma_f32_16x16x32_bf16 v[86:89], v[174:177], v[210:213], v[86:89]
	v_mfma_f32_16x16x32_bf16 v[82:85], v[182:185], v[210:213], v[82:85]
	v_mfma_f32_16x16x32_bf16 v[70:73], v[174:177], v[218:221], v[70:73]
	v_mfma_f32_16x16x32_bf16 v[66:69], v[182:185], v[218:221], v[66:69]
	s_setprio 0
	s_barrier
; #define PG8_STAGE(bufoff, gbase, voff) do { _Pragma("unroll") for (int _i = 0; _i < 2; ++_i) \
;         __builtin_amdgcn_global_load_lds((const unsigned*)((const char*)(gbase) + (voff)[_i]), (PG8_LAS unsigned*)(lds + (bufoff) + ldsw + _i * 8192), 16, 0, 0); } while (0)
; #define PG8_LDA(dst, b, h) do { _Pragma("unroll") for (int m = 0; m < 4; ++m) _Pragma("unroll") for (int k = 0; k < 2; ++k) dst[m][k] = *(const PG8_LAS bf16x8*)(lds + PG8_SA(b, h) + aoff + m * 2048 + k * 1024); } while (0)
; #define PG8_MMA(ai, bj, At, Bt) do { __builtin_amdgcn_s_setprio(1); _Pragma("unroll") for (int m = 0; m < 4; ++m) _Pragma("unroll") for (int n = 0; n < 2; ++n) _Pragma("unroll") for (int k = 0; k < 2; ++k) \
;         acc[ai][bj][m][n] = __builtin_amdgcn_mfma_f32_16x16x32_bf16(Bt[n][k], At[m][k], acc[ai][bj][m][n], 0, 0, 0); __builtin_amdgcn_s_setprio(0); } while (0)
; #define PG8_WAIT_V(n) asm volatile("s_waitcnt vmcnt(" #n ")" ::: "memory")
; #define PG8_WAIT_L(n) asm volatile("s_waitcnt lgkmcnt(" #n ")" ::: "memory")
; #define PG8_BAR __builtin_amdgcn_s_barrier()
; #define PG8_SCHED __builtin_amdgcn_sched_barrier(0)
; template <class Epi, class Sched, bool ALIGN_EPI = false, bool SP2 = false>
; __device__ __forceinline__ void gemm_phase(PG8_LAS unsigned char* lds, const Gemm g, const Sched& S, const Epi& E) {
;     ...
;         for (int t = 0; t < nt; t += 2) {
;             const bool last = (t == nt - 2);
;     ...
;             PG8_LDA(At, 1, 1); PG8_STAGE(PG8_SB(1, 0), b3, voffB); PG8_STAGE(PG8_SB(1, 1), b3 + hstepB, voffB); PG8_STAGE(PG8_SA(1, 0), a3, voffA);
;             PG8_WAIT_V(8); PG8_WAIT_L(0); PG8_BAR; PG8_MMA(1, 0, At, B0); PG8_MMA(1, 1, At, B1); PG8_BAR; PG8_SCHED;
	s_add_i32 s24, s49, s29
	v_lshl_add_u64 v[146:147], v[146:147], 0, s[6:7]
	s_mov_b32 m0, s24
	ds_read_b128 v[186:189], v152 offset:49152
	ds_read_b128 v[190:193], v152 offset:50176
	ds_read_b128 v[194:197], v152 offset:51200
	ds_read_b128 v[198:201], v152 offset:52224
	ds_read_b128 v[202:205], v152 offset:53248
	ds_read_b128 v[210:213], v152 offset:54272
	ds_read_b128 v[214:217], v152 offset:55296
	ds_read_b128 v[218:221], v152 offset:56320
	global_load_lds_dwordx4 v[146:147], off
	s_add_i32 m0, s24, 0x2000
	s_add_u32 s22, s22, 0x80080
	v_lshl_add_u64 v[146:147], v[206:207], 0, s[6:7]
	s_addc_u32 s23, s23, 0
	s_add_i32 s24, s50, s29
	global_load_lds_dwordx4 v[146:147], off
	v_lshl_add_u64 v[146:147], s[22:23], 0, v[134:135]
	s_mov_b32 m0, s24
	s_nop 0
	global_load_lds_dwordx4 v[146:147], off
	v_lshl_add_u64 v[146:147], s[22:23], 0, v[130:131]
	s_add_i32 m0, s24, 0x2000
	s_nop 0
	global_load_lds_dwordx4 v[146:147], off
	v_lshl_add_u64 v[146:147], v[222:223], 0, s[6:7]
	s_mov_b32 m0, s37
	s_nop 0
	global_load_lds_dwordx4 v[146:147], off
	v_lshl_add_u64 v[146:147], v[224:225], 0, s[6:7]
	s_mov_b32 m0, s38
	s_nop 0
	global_load_lds_dwordx4 v[146:147], off
	s_waitcnt vmcnt(8)
	s_waitcnt lgkmcnt(0)
	s_barrier
	s_setprio 1
	s_waitcnt lgkmcnt(0)
	v_mfma_f32_16x16x32_bf16 v[62:65], v[154:157], v[186:189], v[62:65]
	v_mfma_f32_16x16x32_bf16 v[58:61], v[162:165], v[186:189], v[58:61]
	v_mfma_f32_16x16x32_bf16 v[46:49], v[154:157], v[194:197], v[46:49]
	v_mfma_f32_16x16x32_bf16 v[42:45], v[162:165], v[194:197], v[42:45]
	v_mfma_f32_16x16x32_bf16 v[30:33], v[154:157], v[202:205], v[30:33]
	v_mfma_f32_16x16x32_bf16 v[26:29], v[162:165], v[202:205], v[26:29]
	v_mfma_f32_16x16x32_bf16 v[14:17], v[154:157], v[214:217], v[14:17]
	v_mfma_f32_16x16x32_bf16 v[10:13], v[162:165], v[214:217], v[10:13]
	v_mfma_f32_16x16x32_bf16 v[62:65], v[158:161], v[190:193], v[62:65]
	v_mfma_f32_16x16x32_bf16 v[58:61], v[166:169], v[190:193], v[58:61]
	v_mfma_f32_16x16x32_bf16 v[46:49], v[158:161], v[198:201], v[46:49]
	v_mfma_f32_16x16x32_bf16 v[42:45], v[166:169], v[198:201], v[42:45]
	v_mfma_f32_16x16x32_bf16 v[30:33], v[158:161], v[210:213], v[30:33]
	v_mfma_f32_16x16x32_bf16 v[26:29], v[166:169], v[210:213], v[26:29]
	v_mfma_f32_16x16x32_bf16 v[14:17], v[158:161], v[218:221], v[14:17]
	v_mfma_f32_16x16x32_bf16 v[10:13], v[166:169], v[218:221], v[10:13]
	s_setprio 0
	s_setprio 1
	v_mfma_f32_16x16x32_bf16 v[54:57], v[170:173], v[186:189], v[54:57]
	v_mfma_f32_16x16x32_bf16 v[50:53], v[178:181], v[186:189], v[50:53]
	v_mfma_f32_16x16x32_bf16 v[38:41], v[170:173], v[194:197], v[38:41]
	v_mfma_f32_16x16x32_bf16 v[34:37], v[178:181], v[194:197], v[34:37]
	v_mfma_f32_16x16x32_bf16 v[22:25], v[170:173], v[202:205], v[22:25]
	v_mfma_f32_16x16x32_bf16 v[18:21], v[178:181], v[202:205], v[18:21]
	v_mfma_f32_16x16x32_bf16 v[6:9], v[170:173], v[214:217], v[6:9]
	v_mfma_f32_16x16x32_bf16 v[2:5], v[178:181], v[214:217], v[2:5]
	v_mfma_f32_16x16x32_bf16 v[54:57], v[174:177], v[190:193], v[54:57]
	v_mfma_f32_16x16x32_bf16 v[50:53], v[182:185], v[190:193], v[50:53]
	v_mfma_f32_16x16x32_bf16 v[38:41], v[174:177], v[198:201], v[38:41]
	v_mfma_f32_16x16x32_bf16 v[34:37], v[182:185], v[198:201], v[34:37]
	v_mfma_f32_16x16x32_bf16 v[22:25], v[174:177], v[210:213], v[22:25]
	v_mfma_f32_16x16x32_bf16 v[18:21], v[182:185], v[210:213], v[18:21]
	v_mfma_f32_16x16x32_bf16 v[6:9], v[174:177], v[218:221], v[6:9]
	v_mfma_f32_16x16x32_bf16 v[2:5], v[182:185], v[218:221], v[2:5]
	s_setprio 0
	s_barrier
	s_add_i32 s48, s48, 2
	s_add_u32 s20, s20, 0x100
	s_addc_u32 s21, s21, 0
	s_add_u32 s46, s46, 0x100
	s_addc_u32 s47, s47, 0
	s_cmp_gt_u32 s48, 29
	s_cbranch_scc1 .Lpeel_exit_34
	.p2align 6

; #define PG8_STAGE(bufoff, gbase, voff) do { _Pragma("unroll") for (int _i = 0; _i < 2; ++_i) \
;         __builtin_amdgcn_global_load_lds((const unsigned*)((const char*)(gbase) + (voff)[_i]), (PG8_LAS unsigned*)(lds + (bufoff) + ldsw + _i * 8192), 16, 0, 0); } while (0)
; #define PG8_LDA(dst, b, h) do { _Pragma("unroll") for (int m = 0; m < 4; ++m) _Pragma("unroll") for (int k = 0; k < 2; ++k) dst[m][k] = *(const PG8_LAS bf16x8*)(lds + PG8_SA(b, h) + aoff + m * 2048 + k * 1024); } while (0)
; #define PG8_LDB(dst, b, h) do { _Pragma("unroll") for (int n = 0; n < 2; ++n) _Pragma("unroll") for (int k = 0; k < 2; ++k) dst[n][k] = *(const PG8_LAS bf16x8*)(lds + PG8_SB(b, h) + boff + n * 2048 + k * 1024); } while (0)
; #define PG8_MMA(ai, bj, At, Bt) do { __builtin_amdgcn_s_setprio(1); _Pragma("unroll") for (int m = 0; m < 4; ++m) _Pragma("unroll") for (int n = 0; n < 2; ++n) _Pragma("unroll") for (int k = 0; k < 2; ++k) \
;         acc[ai][bj][m][n] = __builtin_amdgcn_mfma_f32_16x16x32_bf16(Bt[n][k], At[m][k], acc[ai][bj][m][n], 0, 0, 0); __builtin_amdgcn_s_setprio(0); } while (0)
; #define PG8_WAIT_V(n) asm volatile("s_waitcnt vmcnt(" #n ")" ::: "memory")
; #define PG8_WAIT_L(n) asm volatile("s_waitcnt lgkmcnt(" #n ")" ::: "memory")
; #define PG8_BAR __builtin_amdgcn_s_barrier()
; #define PG8_SCHED __builtin_amdgcn_sched_barrier(0)
; template <class Epi, class Sched, bool ALIGN_EPI = false, bool SP2 = false>
; __device__ __forceinline__ void gemm_phase(PG8_LAS unsigned char* lds, const Gemm g, const Sched& S, const Epi& E) {
;     ...
;             PG8_LDB(B0, 0, 0); PG8_LDB(B1, 0, 1); PG8_SCHED; PG8_LDA(At, 0, 0); PG8_STAGE(PG8_SA(1, 1), a1 + hstepA, voffA);
;             PG8_WAIT_V(8); PG8_WAIT_L(0); PG8_BAR; PG8_MMA(0, 0, At, B0); PG8_MMA(0, 1, At, B1); PG8_BAR; PG8_SCHED;
;             PG8_LDA(At, 0, 1); PG8_STAGE(PG8_SB(0, 0), b2, voffB); PG8_STAGE(PG8_SB(0, 1), b2 + hstepB, voffB); PG8_STAGE(PG8_SA(0, 0), a2, voffA);
;     ...
; #pragma unroll
;         for (int a = 0; a < 2; ++a)
; #pragma unroll
;             for (int b = 0; b < 2; ++b)
; #pragma unroll
;                 for (int m = 0; m < 4; ++m)
; #pragma unroll
;                     for (int n = 0; n < 2; ++n) acc[a][b][m][n] = (f32x4){0.f, 0.f, 0.f, 0.f};
.LBB0_3570:
	s_add_u32 s22, s22, 0x160080
	s_addc_u32 s23, s23, 0
	s_add_u32 s53, s24, 0x100
	s_addc_u32 s54, s25, 0
	s_mov_b32 s55, -2
	ds_read_b128 v[152:155], v148
	ds_read_b128 v[156:159], v148 offset:1024
	ds_read_b128 v[160:163], v148 offset:2048
	ds_read_b128 v[164:167], v148 offset:3072
	ds_read_b128 v[168:171], v149
	ds_read_b128 v[172:175], v149 offset:1024
	ds_read_b128 v[176:179], v149 offset:2048
	ds_read_b128 v[180:183], v149 offset:3072
	s_add_u32 s24, s22, 0xffea0080
	s_addc_u32 s25, s23, -1
	s_cmpk_eq_i32 s55, 0x54
	s_cselect_b32 s27, s7, s25
	s_cselect_b32 s26, s6, s24
	s_cselect_b32 s25, s21, s54
	s_cselect_b32 s24, s20, s53
	v_lshl_add_u64 v[218:219], s[22:23], 0, v[138:139]
	s_add_i32 m0, s35, 0xc000
	ds_read_b128 v[184:187], v150
	ds_read_b128 v[188:191], v150 offset:1024
	ds_read_b128 v[192:195], v150 offset:2048
	ds_read_b128 v[196:199], v150 offset:3072
	ds_read_b128 v[200:203], v150 offset:4096
	ds_read_b128 v[204:207], v150 offset:5120
	ds_read_b128 v[210:213], v150 offset:6144
	ds_read_b128 v[214:217], v150 offset:7168
	global_load_lds_dwordx4 v[218:219], off
	v_lshl_add_u64 v[218:219], s[22:23], 0, v[140:141]
	s_add_i32 m0, s35, 0xe000
	s_nop 0
	global_load_lds_dwordx4 v[218:219], off
	s_waitcnt vmcnt(8)
	s_waitcnt lgkmcnt(0)
	s_barrier
	s_setprio 1
	s_waitcnt lgkmcnt(0)
	v_mfma_f32_16x16x32_bf16 v[126:129], v[152:155], v[184:187], 0
	v_mfma_f32_16x16x32_bf16 v[122:125], v[160:163], v[184:187], 0
	v_mfma_f32_16x16x32_bf16 v[118:121], v[152:155], v[192:195], 0
	v_mfma_f32_16x16x32_bf16 v[114:117], v[160:163], v[192:195], 0
	v_mfma_f32_16x16x32_bf16 v[102:105], v[152:155], v[200:203], 0
	v_mfma_f32_16x16x32_bf16 v[98:101], v[160:163], v[200:203], 0
	v_mfma_f32_16x16x32_bf16 v[86:89], v[152:155], v[210:213], 0
	v_mfma_f32_16x16x32_bf16 v[82:85], v[160:163], v[210:213], 0
	v_mfma_f32_16x16x32_bf16 v[126:129], v[156:159], v[188:191], v[126:129]
	v_mfma_f32_16x16x32_bf16 v[122:125], v[164:167], v[188:191], v[122:125]
	v_mfma_f32_16x16x32_bf16 v[118:121], v[156:159], v[196:199], v[118:121]
	v_mfma_f32_16x16x32_bf16 v[114:117], v[164:167], v[196:199], v[114:117]
	v_mfma_f32_16x16x32_bf16 v[102:105], v[156:159], v[204:207], v[102:105]
	v_mfma_f32_16x16x32_bf16 v[98:101], v[164:167], v[204:207], v[98:101]
	v_mfma_f32_16x16x32_bf16 v[86:89], v[156:159], v[214:217], v[86:89]
	v_mfma_f32_16x16x32_bf16 v[82:85], v[164:167], v[214:217], v[82:85]
	s_setprio 0
	s_setprio 1
	v_mfma_f32_16x16x32_bf16 v[110:113], v[168:171], v[184:187], 0
	v_mfma_f32_16x16x32_bf16 v[106:109], v[176:179], v[184:187], 0
	v_mfma_f32_16x16x32_bf16 v[94:97], v[168:171], v[192:195], 0
	v_mfma_f32_16x16x32_bf16 v[90:93], v[176:179], v[192:195], 0
	v_mfma_f32_16x16x32_bf16 v[78:81], v[168:171], v[200:203], 0
	v_mfma_f32_16x16x32_bf16 v[74:77], v[176:179], v[200:203], 0
	v_mfma_f32_16x16x32_bf16 v[70:73], v[168:171], v[210:213], 0
	v_mfma_f32_16x16x32_bf16 v[66:69], v[176:179], v[210:213], 0
	v_mfma_f32_16x16x32_bf16 v[110:113], v[172:175], v[188:191], v[110:113]
	v_mfma_f32_16x16x32_bf16 v[106:109], v[180:183], v[188:191], v[106:109]
	v_mfma_f32_16x16x32_bf16 v[94:97], v[172:175], v[196:199], v[94:97]
	v_mfma_f32_16x16x32_bf16 v[90:93], v[180:183], v[196:199], v[90:93]
	v_mfma_f32_16x16x32_bf16 v[78:81], v[172:175], v[204:207], v[78:81]
	v_mfma_f32_16x16x32_bf16 v[74:77], v[180:183], v[204:207], v[74:77]
	v_mfma_f32_16x16x32_bf16 v[70:73], v[172:175], v[214:217], v[70:73]
	v_mfma_f32_16x16x32_bf16 v[66:69], v[180:183], v[214:217], v[66:69]
	s_setprio 0
	s_barrier
	s_add_i32 s56, s43, s31
	v_lshl_add_u64 v[218:219], s[24:25], 0, v[134:135]
	s_mov_b32 m0, s56
	ds_read_b128 v[184:187], v150 offset:16384
	ds_read_b128 v[188:191], v150 offset:17408
	ds_read_b128 v[192:195], v150 offset:18432
	ds_read_b128 v[196:199], v150 offset:19456
	ds_read_b128 v[200:203], v150 offset:20480
	ds_read_b128 v[204:207], v150 offset:21504
	ds_read_b128 v[210:213], v150 offset:22528
	ds_read_b128 v[214:217], v150 offset:23552
	global_load_lds_dwordx4 v[218:219], off
	s_add_i32 m0, s56, 0x2000
	s_add_u32 s56, s24, 0x160000
	v_lshl_add_u64 v[220:221], s[24:25], 0, v[130:131]
	s_addc_u32 s57, s25, 0
	s_add_i32 s58, s44, s31
	global_load_lds_dwordx4 v[220:221], off
	v_lshl_add_u64 v[222:223], s[56:57], 0, v[134:135]
	s_mov_b32 m0, s58
	v_lshl_add_u64 v[224:225], s[26:27], 0, v[132:133]
	global_load_lds_dwordx4 v[222:223], off
	v_lshl_add_u64 v[222:223], s[56:57], 0, v[130:131]
	s_add_i32 m0, s58, 0x2000
	s_nop 0
	global_load_lds_dwordx4 v[222:223], off
	v_lshl_add_u64 v[222:223], s[26:27], 0, v[136:137]
	s_mov_b32 m0, s35
	s_nop 0
	global_load_lds_dwordx4 v[222:223], off
	s_mov_b32 m0, s36
	s_nop 0
	global_load_lds_dwordx4 v[224:225], off
	s_waitcnt vmcnt(8)
	s_waitcnt lgkmcnt(0)
	s_barrier
; #define PG8_STAGE(bufoff, gbase, voff) do { _Pragma("unroll") for (int _i = 0; _i < 2; ++_i) \
;         __builtin_amdgcn_global_load_lds((const unsigned*)((const char*)(gbase) + (voff)[_i]), (PG8_LAS unsigned*)(lds + (bufoff) + ldsw + _i * 8192), 16, 0, 0); } while (0)
; #define PG8_LDA(dst, b, h) do { _Pragma("unroll") for (int m = 0; m < 4; ++m) _Pragma("unroll") for (int k = 0; k < 2; ++k) dst[m][k] = *(const PG8_LAS bf16x8*)(lds + PG8_SA(b, h) + aoff + m * 2048 + k * 1024); } while (0)
; #define PG8_LDB(dst, b, h) do { _Pragma("unroll") for (int n = 0; n < 2; ++n) _Pragma("unroll") for (int k = 0; k < 2; ++k) dst[n][k] = *(const PG8_LAS bf16x8*)(lds + PG8_SB(b, h) + boff + n * 2048 + k * 1024); } while (0)
; #define PG8_MMA(ai, bj, At, Bt) do { __builtin_amdgcn_s_setprio(1); _Pragma("unroll") for (int m = 0; m < 4; ++m) _Pragma("unroll") for (int n = 0; n < 2; ++n) _Pragma("unroll") for (int k = 0; k < 2; ++k) \
;         acc[ai][bj][m][n] = __builtin_amdgcn_mfma_f32_16x16x32_bf16(Bt[n][k], At[m][k], acc[ai][bj][m][n], 0, 0, 0); __builtin_amdgcn_s_setprio(0); } while (0)
; #define PG8_WAIT_V(n) asm volatile("s_waitcnt vmcnt(" #n ")" ::: "memory")
; #define PG8_WAIT_L(n) asm volatile("s_waitcnt lgkmcnt(" #n ")" ::: "memory")
; #define PG8_BAR __builtin_amdgcn_s_barrier()
; #define PG8_SCHED __builtin_amdgcn_sched_barrier(0)
; template <class Epi, class Sched, bool ALIGN_EPI = false, bool SP2 = false>
; __device__ __forceinline__ void gemm_phase(PG8_LAS unsigned char* lds, const Gemm g, const Sched& S, const Epi& E) {
;     ...
;             PG8_WAIT_V(8); PG8_WAIT_L(0); PG8_BAR; PG8_MMA(1, 0, At, B0); PG8_MMA(1, 1, At, B1); PG8_BAR; PG8_SCHED;
;             PG8_LDB(B0, 1, 0); PG8_LDB(B1, 1, 1); PG8_SCHED; PG8_LDA(At, 1, 0); PG8_STAGE(PG8_SA(0, 1), a2 + hstepA, voffA);
;             PG8_WAIT_V(8); PG8_WAIT_L(0); PG8_BAR; PG8_MMA(0, 0, At, B0); PG8_MMA(0, 1, At, B1); PG8_BAR; PG8_SCHED;
	s_setprio 1
	s_waitcnt lgkmcnt(0)
	v_mfma_f32_16x16x32_bf16 v[62:65], v[152:155], v[184:187], 0
	v_mfma_f32_16x16x32_bf16 v[58:61], v[160:163], v[184:187], 0
	v_mfma_f32_16x16x32_bf16 v[54:57], v[152:155], v[192:195], 0
	v_mfma_f32_16x16x32_bf16 v[50:53], v[160:163], v[192:195], 0
	v_mfma_f32_16x16x32_bf16 v[38:41], v[152:155], v[200:203], 0
	v_mfma_f32_16x16x32_bf16 v[34:37], v[160:163], v[200:203], 0
	v_mfma_f32_16x16x32_bf16 v[22:25], v[152:155], v[210:213], 0
	v_mfma_f32_16x16x32_bf16 v[18:21], v[160:163], v[210:213], 0
	v_mfma_f32_16x16x32_bf16 v[62:65], v[156:159], v[188:191], v[62:65]
	v_mfma_f32_16x16x32_bf16 v[58:61], v[164:167], v[188:191], v[58:61]
	v_mfma_f32_16x16x32_bf16 v[54:57], v[156:159], v[196:199], v[54:57]
	v_mfma_f32_16x16x32_bf16 v[50:53], v[164:167], v[196:199], v[50:53]
	v_mfma_f32_16x16x32_bf16 v[38:41], v[156:159], v[204:207], v[38:41]
	v_mfma_f32_16x16x32_bf16 v[34:37], v[164:167], v[204:207], v[34:37]
	v_mfma_f32_16x16x32_bf16 v[22:25], v[156:159], v[214:217], v[22:25]
	v_mfma_f32_16x16x32_bf16 v[18:21], v[164:167], v[214:217], v[18:21]
	s_setprio 0
	s_setprio 1
	v_mfma_f32_16x16x32_bf16 v[46:49], v[168:171], v[184:187], 0
	v_mfma_f32_16x16x32_bf16 v[42:45], v[176:179], v[184:187], 0
	v_mfma_f32_16x16x32_bf16 v[30:33], v[168:171], v[192:195], 0
	v_mfma_f32_16x16x32_bf16 v[26:29], v[176:179], v[192:195], 0
	v_mfma_f32_16x16x32_bf16 v[14:17], v[168:171], v[200:203], 0
	v_mfma_f32_16x16x32_bf16 v[10:13], v[176:179], v[200:203], 0
	v_mfma_f32_16x16x32_bf16 v[6:9], v[168:171], v[210:213], 0
	v_mfma_f32_16x16x32_bf16 v[2:5], v[176:179], v[210:213], 0
	v_mfma_f32_16x16x32_bf16 v[46:49], v[172:175], v[188:191], v[46:49]
	v_mfma_f32_16x16x32_bf16 v[42:45], v[180:183], v[188:191], v[42:45]
	v_mfma_f32_16x16x32_bf16 v[30:33], v[172:175], v[196:199], v[30:33]
	v_mfma_f32_16x16x32_bf16 v[26:29], v[180:183], v[196:199], v[26:29]
	v_mfma_f32_16x16x32_bf16 v[14:17], v[172:175], v[204:207], v[14:17]
	v_mfma_f32_16x16x32_bf16 v[10:13], v[180:183], v[204:207], v[10:13]
	v_mfma_f32_16x16x32_bf16 v[6:9], v[172:175], v[214:217], v[6:9]
	v_mfma_f32_16x16x32_bf16 v[2:5], v[180:183], v[214:217], v[2:5]
	s_setprio 0
	s_barrier
	s_add_i32 s56, 0, 0x18000
	v_add_u32_e32 v151, s56, v146
	s_add_i32 s57, 0, 0x1c000
	ds_read_b128 v[152:155], v151
	ds_read_b128 v[156:159], v151 offset:1024
	ds_read_b128 v[160:163], v151 offset:2048
	ds_read_b128 v[164:167], v151 offset:3072
	v_add_u32_e32 v151, s57, v146
	ds_read_b128 v[168:171], v151
	ds_read_b128 v[172:175], v151 offset:1024
	ds_read_b128 v[176:179], v151 offset:2048
	ds_read_b128 v[180:183], v151 offset:3072
	s_add_u32 s26, s26, 0x160000
	s_addc_u32 s27, s27, 0
	s_mov_b32 m0, s37
	v_lshl_add_u64 v[226:227], s[26:27], 0, v[136:137]
	ds_read_b128 v[184:187], v150 offset:32768
	ds_read_b128 v[188:191], v150 offset:33792
	ds_read_b128 v[192:195], v150 offset:34816
	ds_read_b128 v[196:199], v150 offset:35840
	ds_read_b128 v[200:203], v150 offset:36864
	ds_read_b128 v[204:207], v150 offset:37888
	ds_read_b128 v[210:213], v150 offset:38912
	ds_read_b128 v[214:217], v150 offset:39936
	global_load_lds_dwordx4 v[226:227], off
	v_lshl_add_u64 v[226:227], s[26:27], 0, v[132:133]
	s_mov_b32 m0, s38
	s_nop 0
	global_load_lds_dwordx4 v[226:227], off
	s_waitcnt vmcnt(8)
	s_waitcnt lgkmcnt(0)
	s_barrier
	s_setprio 1
	s_waitcnt lgkmcnt(0)
	v_mfma_f32_16x16x32_bf16 v[126:129], v[152:155], v[184:187], v[126:129]
	v_mfma_f32_16x16x32_bf16 v[122:125], v[160:163], v[184:187], v[122:125]
	v_mfma_f32_16x16x32_bf16 v[118:121], v[152:155], v[192:195], v[118:121]
	v_mfma_f32_16x16x32_bf16 v[114:117], v[160:163], v[192:195], v[114:117]
	v_mfma_f32_16x16x32_bf16 v[102:105], v[152:155], v[200:203], v[102:105]
	v_mfma_f32_16x16x32_bf16 v[98:101], v[160:163], v[200:203], v[98:101]
	v_mfma_f32_16x16x32_bf16 v[86:89], v[152:155], v[210:213], v[86:89]
	v_mfma_f32_16x16x32_bf16 v[82:85], v[160:163], v[210:213], v[82:85]
	v_mfma_f32_16x16x32_bf16 v[126:129], v[156:159], v[188:191], v[126:129]
	v_mfma_f32_16x16x32_bf16 v[122:125], v[164:167], v[188:191], v[122:125]
	v_mfma_f32_16x16x32_bf16 v[118:121], v[156:159], v[196:199], v[118:121]
	v_mfma_f32_16x16x32_bf16 v[114:117], v[164:167], v[196:199], v[114:117]
	v_mfma_f32_16x16x32_bf16 v[102:105], v[156:159], v[204:207], v[102:105]
	v_mfma_f32_16x16x32_bf16 v[98:101], v[164:167], v[204:207], v[98:101]
	v_mfma_f32_16x16x32_bf16 v[86:89], v[156:159], v[214:217], v[86:89]
	v_mfma_f32_16x16x32_bf16 v[82:85], v[164:167], v[214:217], v[82:85]
	s_setprio 0
	s_setprio 1
	v_mfma_f32_16x16x32_bf16 v[110:113], v[168:171], v[184:187], v[110:113]
	v_mfma_f32_16x16x32_bf16 v[106:109], v[176:179], v[184:187], v[106:109]
	v_mfma_f32_16x16x32_bf16 v[94:97], v[168:171], v[192:195], v[94:97]
	v_mfma_f32_16x16x32_bf16 v[90:93], v[176:179], v[192:195], v[90:93]
	v_mfma_f32_16x16x32_bf16 v[78:81], v[168:171], v[200:203], v[78:81]
	v_mfma_f32_16x16x32_bf16 v[74:77], v[176:179], v[200:203], v[74:77]
	v_mfma_f32_16x16x32_bf16 v[70:73], v[168:171], v[210:213], v[70:73]
	v_mfma_f32_16x16x32_bf16 v[66:69], v[176:179], v[210:213], v[66:69]
	v_mfma_f32_16x16x32_bf16 v[110:113], v[172:175], v[188:191], v[110:113]
	v_mfma_f32_16x16x32_bf16 v[106:109], v[180:183], v[188:191], v[106:109]
	v_mfma_f32_16x16x32_bf16 v[94:97], v[172:175], v[196:199], v[94:97]
	v_mfma_f32_16x16x32_bf16 v[90:93], v[180:183], v[196:199], v[90:93]
	v_mfma_f32_16x16x32_bf16 v[78:81], v[172:175], v[204:207], v[78:81]
	v_mfma_f32_16x16x32_bf16 v[74:77], v[180:183], v[204:207], v[74:77]
	v_mfma_f32_16x16x32_bf16 v[70:73], v[172:175], v[214:217], v[70:73]
	v_mfma_f32_16x16x32_bf16 v[66:69], v[180:183], v[214:217], v[66:69]
	s_setprio 0
	s_barrier
; #define PG8_STAGE(bufoff, gbase, voff) do { _Pragma("unroll") for (int _i = 0; _i < 2; ++_i) \
;         __builtin_amdgcn_global_load_lds((const unsigned*)((const char*)(gbase) + (voff)[_i]), (PG8_LAS unsigned*)(lds + (bufoff) + ldsw + _i * 8192), 16, 0, 0); } while (0)
; #define PG8_LDA(dst, b, h) do { _Pragma("unroll") for (int m = 0; m < 4; ++m) _Pragma("unroll") for (int k = 0; k < 2; ++k) dst[m][k] = *(const PG8_LAS bf16x8*)(lds + PG8_SA(b, h) + aoff + m * 2048 + k * 1024); } while (0)
; #define PG8_MMA(ai, bj, At, Bt) do { __builtin_amdgcn_s_setprio(1); _Pragma("unroll") for (int m = 0; m < 4; ++m) _Pragma("unroll") for (int n = 0; n < 2; ++n) _Pragma("unroll") for (int k = 0; k < 2; ++k) \
;         acc[ai][bj][m][n] = __builtin_amdgcn_mfma_f32_16x16x32_bf16(Bt[n][k], At[m][k], acc[ai][bj][m][n], 0, 0, 0); __builtin_amdgcn_s_setprio(0); } while (0)
; #define PG8_WAIT_V(n) asm volatile("s_waitcnt vmcnt(" #n ")" ::: "memory")
; #define PG8_WAIT_L(n) asm volatile("s_waitcnt lgkmcnt(" #n ")" ::: "memory")
; #define PG8_BAR __builtin_amdgcn_s_barrier()
; #define PG8_SCHED __builtin_amdgcn_sched_barrier(0)
; template <class Epi, class Sched, bool ALIGN_EPI = false, bool SP2 = false>
; __device__ __forceinline__ void gemm_phase(PG8_LAS unsigned char* lds, const Gemm g, const Sched& S, const Epi& E) {
;     ...
;         for (int t = 0; t < nt; t += 2) {
;             const bool last = (t == nt - 2);
;     ...
;             PG8_LDA(At, 1, 1); PG8_STAGE(PG8_SB(1, 0), b3, voffB); PG8_STAGE(PG8_SB(1, 1), b3 + hstepB, voffB); PG8_STAGE(PG8_SA(1, 0), a3, voffA);
;             PG8_WAIT_V(8); PG8_WAIT_L(0); PG8_BAR; PG8_MMA(1, 0, At, B0); PG8_MMA(1, 1, At, B1); PG8_BAR; PG8_SCHED;
	s_add_i32 s26, s56, s31
	v_lshl_add_u64 v[218:219], v[218:219], 0, s[8:9]
	s_mov_b32 m0, s26
	ds_read_b128 v[184:187], v150 offset:49152
	ds_read_b128 v[188:191], v150 offset:50176
	ds_read_b128 v[192:195], v150 offset:51200
	ds_read_b128 v[196:199], v150 offset:52224
	ds_read_b128 v[200:203], v150 offset:53248
	ds_read_b128 v[204:207], v150 offset:54272
	ds_read_b128 v[210:213], v150 offset:55296
	ds_read_b128 v[214:217], v150 offset:56320
	global_load_lds_dwordx4 v[218:219], off
	s_add_i32 m0, s26, 0x2000
	s_add_u32 s24, s24, 0x160080
	v_lshl_add_u64 v[218:219], v[220:221], 0, s[8:9]
	s_addc_u32 s25, s25, 0
	s_add_i32 s26, s57, s31
	global_load_lds_dwordx4 v[218:219], off
	v_lshl_add_u64 v[218:219], s[24:25], 0, v[134:135]
	s_mov_b32 m0, s26
	s_nop 0
	global_load_lds_dwordx4 v[218:219], off
	v_lshl_add_u64 v[218:219], s[24:25], 0, v[130:131]
	s_add_i32 m0, s26, 0x2000
	s_nop 0
	global_load_lds_dwordx4 v[218:219], off
	v_lshl_add_u64 v[218:219], v[222:223], 0, s[8:9]
	s_mov_b32 m0, s40
	s_nop 0
	global_load_lds_dwordx4 v[218:219], off
	v_lshl_add_u64 v[218:219], v[224:225], 0, s[8:9]
	s_mov_b32 m0, s41
	s_nop 0
	global_load_lds_dwordx4 v[218:219], off
	s_waitcnt vmcnt(8)
	s_waitcnt lgkmcnt(0)
	s_barrier
	s_setprio 1
	s_waitcnt lgkmcnt(0)
	v_mfma_f32_16x16x32_bf16 v[62:65], v[152:155], v[184:187], v[62:65]
	v_mfma_f32_16x16x32_bf16 v[58:61], v[160:163], v[184:187], v[58:61]
	v_mfma_f32_16x16x32_bf16 v[54:57], v[152:155], v[192:195], v[54:57]
	v_mfma_f32_16x16x32_bf16 v[50:53], v[160:163], v[192:195], v[50:53]
	v_mfma_f32_16x16x32_bf16 v[38:41], v[152:155], v[200:203], v[38:41]
	v_mfma_f32_16x16x32_bf16 v[34:37], v[160:163], v[200:203], v[34:37]
	v_mfma_f32_16x16x32_bf16 v[22:25], v[152:155], v[210:213], v[22:25]
	v_mfma_f32_16x16x32_bf16 v[18:21], v[160:163], v[210:213], v[18:21]
	v_mfma_f32_16x16x32_bf16 v[62:65], v[156:159], v[188:191], v[62:65]
	v_mfma_f32_16x16x32_bf16 v[58:61], v[164:167], v[188:191], v[58:61]
	v_mfma_f32_16x16x32_bf16 v[54:57], v[156:159], v[196:199], v[54:57]
	v_mfma_f32_16x16x32_bf16 v[50:53], v[164:167], v[196:199], v[50:53]
	v_mfma_f32_16x16x32_bf16 v[38:41], v[156:159], v[204:207], v[38:41]
	v_mfma_f32_16x16x32_bf16 v[34:37], v[164:167], v[204:207], v[34:37]
	v_mfma_f32_16x16x32_bf16 v[22:25], v[156:159], v[214:217], v[22:25]
	v_mfma_f32_16x16x32_bf16 v[18:21], v[164:167], v[214:217], v[18:21]
	s_setprio 0
	s_setprio 1
	v_mfma_f32_16x16x32_bf16 v[46:49], v[168:171], v[184:187], v[46:49]
	v_mfma_f32_16x16x32_bf16 v[42:45], v[176:179], v[184:187], v[42:45]
	v_mfma_f32_16x16x32_bf16 v[30:33], v[168:171], v[192:195], v[30:33]
	v_mfma_f32_16x16x32_bf16 v[26:29], v[176:179], v[192:195], v[26:29]
	v_mfma_f32_16x16x32_bf16 v[14:17], v[168:171], v[200:203], v[14:17]
	v_mfma_f32_16x16x32_bf16 v[10:13], v[176:179], v[200:203], v[10:13]
	v_mfma_f32_16x16x32_bf16 v[6:9], v[168:171], v[210:213], v[6:9]
	v_mfma_f32_16x16x32_bf16 v[2:5], v[176:179], v[210:213], v[2:5]
	v_mfma_f32_16x16x32_bf16 v[46:49], v[172:175], v[188:191], v[46:49]
	v_mfma_f32_16x16x32_bf16 v[42:45], v[180:183], v[188:191], v[42:45]
	v_mfma_f32_16x16x32_bf16 v[30:33], v[172:175], v[196:199], v[30:33]
	v_mfma_f32_16x16x32_bf16 v[26:29], v[180:183], v[196:199], v[26:29]
	v_mfma_f32_16x16x32_bf16 v[14:17], v[172:175], v[204:207], v[14:17]
	v_mfma_f32_16x16x32_bf16 v[10:13], v[180:183], v[204:207], v[10:13]
	v_mfma_f32_16x16x32_bf16 v[6:9], v[172:175], v[214:217], v[6:9]
	v_mfma_f32_16x16x32_bf16 v[2:5], v[180:183], v[214:217], v[2:5]
	s_setprio 0
	s_barrier
	s_add_i32 s55, s55, 2
	s_add_u32 s22, s22, 0x100
	s_addc_u32 s23, s23, 0
	s_add_u32 s53, s53, 0x100
	s_addc_u32 s54, s54, 0
	s_cmpk_gt_u32 s55, 0x55
	s_cbranch_scc1 .Lpeel_exit_35
	.p2align 6
